# phase-style s_setprio in attention/MLP loops (raise at QK reads, lower at tile barrier) + GEMM compute-phase priority
# speedup vs baseline: 1.0693x; 1.0182x over previous
.LBB0_6:
	s_mov_b32 s2, 0
	v_writelane_b32 v243, s0, 3
	s_waitcnt lgkmcnt(0)
	s_mov_b32 s54, s96
	s_setprio 0
	s_barrier
	v_writelane_b32 v243, s1, 4
	s_cmp_lg_u32 s33, 0
	s_cbranch_scc1 .Lflag_done
	s_add_u32 s8, s34, 0xd203800
	s_addc_u32 s9, s35, 0
	v_cmp_eq_u32_e32 vcc, 0, v206
	s_and_saveexec_b64 s[10:11], vcc
	v_mov_b32_e32 v2, 0x5eedb10c
	v_mov_b32_e32 v3, 0
	global_store_dword v3, v2, s[8:9] sc1
	s_or_b64 exec, exec, s[10:11]

.LBB0_42:
	s_and_b64 vcc, exec, s[0:1]
	s_cbranch_vccz .LBB0_25
	s_setprio 0
	s_barrier
	s_and_saveexec_b64 s[0:1], s[4:5]
	s_cbranch_execz .LBB0_46
	s_mov_b64 s[2:3], 0
	v_mov_b64_e32 v[2:3], v[18:19]
	v_mov_b32_e32 v4, v46
	v_mov_b32_e32 v5, v15

.LBB0_46:
	s_or_b64 exec, exec, s[0:1]
	s_mul_hi_i32 s0, s95, 0x2aaaaaab
	s_lshr_b32 s1, s0, 31
	s_ashr_i32 s2, s0, 3
	s_add_i32 s2, s2, s1
	s_mul_i32 s0, s2, 48
	s_sub_i32 s0, s95, s0
	v_lshl_or_b32 v24, s0, 6, v1
	v_ashrrev_i32_e32 v25, 31, v24
	v_lshlrev_b64 v[2:3], 2, v[24:25]
	v_mad_i64_i32 v[2:3], s[0:1], s2, v55, v[2:3]
	v_mov_b32_e32 v32, 0
	v_lshl_add_u64 v[26:27], v[20:21], 0, v[2:3]
	s_mov_b64 s[8:9], 0
	v_mov_b32_e32 v56, v48
	v_mov_b32_e32 v57, v47
	v_mov_b32_e32 v33, v32
	v_mov_b32_e32 v28, v32
	v_mov_b32_e32 v29, v32
	v_mov_b32_e32 v30, v32
	v_mov_b32_e32 v31, v32
	v_mov_b32_e32 v36, v32
	v_mov_b32_e32 v37, v32
	s_waitcnt lgkmcnt(0)
	s_setprio 0
	s_barrier
.LBB0_47:
	v_add_co_u32_e32 v2, vcc, 0xfffa3000, v26
	s_mov_b32 s0, 0xffff4000
	s_nop 0
	v_addc_co_u32_e32 v3, vcc, -1, v27, vcc
	global_load_dword v66, v[2:3], off
	v_add_co_u32_e32 v2, vcc, 0xfffa6000, v26
	v_add_u32_e32 v57, 32, v57
	s_nop 0
	v_addc_co_u32_e32 v3, vcc, -1, v27, vcc
	global_load_dword v22, v[2:3], off
	v_add_co_u32_e32 v2, vcc, 0xfffa9000, v26
	s_nop 1
	v_addc_co_u32_e32 v3, vcc, -1, v27, vcc
	global_load_dword v68, v[2:3], off
	v_add_co_u32_e32 v2, vcc, 0xfffac000, v26
	s_nop 1
	v_addc_co_u32_e32 v3, vcc, -1, v27, vcc
	global_load_dword v70, v[2:3], off
	ds_read_b128 v[38:41], v56
	ds_read_b128 v[10:13], v56 offset:16
	ds_read_b128 v[6:9], v56 offset:32
	ds_read_b128 v[2:5], v56 offset:48
	ds_read_b128 v[58:61], v56 offset:4096
	s_waitcnt lgkmcnt(4)
	v_mov_b32_e32 v34, v38
	s_waitcnt lgkmcnt(0)
	v_mov_b32_e32 v35, v58
	v_mov_b32_e32 v58, v39
	s_waitcnt vmcnt(2)
	v_pk_mul_f32 v[38:39], v[22:23], v[58:59] op_sel_hi:[0,1]
	v_pk_fma_f32 v[34:35], v[66:67], v[34:35], v[38:39] op_sel_hi:[0,1,1]
	v_mov_b32_e32 v38, v40
	v_mov_b32_e32 v39, v60
	v_mov_b32_e32 v60, v41
	s_waitcnt vmcnt(1)
	v_pk_fma_f32 v[34:35], v[68:69], v[38:39], v[34:35] op_sel_hi:[0,1,1]
	s_waitcnt vmcnt(0)
	v_pk_fma_f32 v[34:35], v[70:71], v[60:61], v[34:35] op_sel_hi:[0,1,1]
	ds_read_b128 v[58:61], v56 offset:8192
	ds_read_b128 v[62:65], v56 offset:12288
	v_pk_add_f32 v[40:41], v[28:29], v[34:35]
	s_waitcnt lgkmcnt(1)
	v_mov_b32_e32 v28, v58
	s_waitcnt lgkmcnt(0)
	v_mov_b32_e32 v29, v62
	v_mov_b32_e32 v62, v59
	v_pk_mul_f32 v[34:35], v[22:23], v[62:63] op_sel_hi:[0,1]
	v_pk_fma_f32 v[28:29], v[66:67], v[28:29], v[34:35] op_sel_hi:[0,1,1]
	v_mov_b32_e32 v34, v60
	v_mov_b32_e32 v35, v64
	v_pk_fma_f32 v[28:29], v[68:69], v[34:35], v[28:29] op_sel_hi:[0,1,1]
	v_mov_b32_e32 v64, v61
	v_pk_fma_f32 v[28:29], v[70:71], v[64:65], v[28:29] op_sel_hi:[0,1,1]
	v_pk_add_f32 v[38:39], v[30:31], v[28:29]
	ds_read_b128 v[28:31], v56 offset:16384
	ds_read_b128 v[58:61], v56 offset:20480
	s_waitcnt lgkmcnt(1)
	v_mov_b32_e32 v34, v28
	s_waitcnt lgkmcnt(0)
	v_mov_b32_e32 v35, v58
	v_mov_b32_e32 v58, v29
	v_pk_mul_f32 v[28:29], v[22:23], v[58:59] op_sel_hi:[0,1]
	v_pk_fma_f32 v[28:29], v[66:67], v[34:35], v[28:29] op_sel_hi:[0,1,1]
	v_mov_b32_e32 v34, v30
	v_mov_b32_e32 v35, v60
	v_pk_fma_f32 v[28:29], v[68:69], v[34:35], v[28:29] op_sel_hi:[0,1,1]
	v_mov_b32_e32 v60, v31
	v_pk_fma_f32 v[28:29], v[70:71], v[60:61], v[28:29] op_sel_hi:[0,1,1]
	v_pk_add_f32 v[28:29], v[36:37], v[28:29]
	ds_read_b128 v[34:37], v56 offset:24576
	v_mov_b32_e32 v67, v22
	v_mov_b32_e32 v69, v70
	s_waitcnt lgkmcnt(0)
	v_mul_f32_e32 v30, v66, v34
	v_mul_f32_e32 v58, v22, v35
	v_mul_f32_e32 v60, v68, v36
	v_mul_f32_e32 v62, v70, v37
	ds_read_b128 v[34:37], v56 offset:28672
	s_waitcnt lgkmcnt(0)
	v_pk_mul_f32 v[34:35], v[66:67], v[34:35]
	v_pk_mul_f32 v[36:37], v[68:69], v[36:37]
	v_mov_b32_e32 v31, v34
	v_mov_b32_e32 v59, v35
	v_pk_add_f32 v[30:31], v[30:31], v[58:59]
	v_mov_b32_e32 v61, v36
	v_pk_add_f32 v[30:31], v[30:31], v[60:61]
	v_mov_b32_e32 v63, v37
	v_pk_add_f32 v[30:31], v[30:31], v[62:63]
	ds_read_b128 v[58:61], v56 offset:4112
	v_pk_add_f32 v[30:31], v[32:33], v[30:31]
	v_add_co_u32_e32 v32, vcc, s70, v26
	v_mov_b32_e32 v62, v10
	s_nop 0
	v_addc_co_u32_e32 v33, vcc, -1, v27, vcc
	v_add_co_u32_e32 v34, vcc, s71, v26
	global_load_dword v32, v[32:33], off
	s_nop 0
	v_addc_co_u32_e32 v35, vcc, -1, v27, vcc
	global_load_dword v22, v[34:35], off
	v_add_co_u32_e32 v34, vcc, s72, v26
	s_waitcnt lgkmcnt(0)
	v_mov_b32_e32 v63, v58
	v_addc_co_u32_e32 v35, vcc, -1, v27, vcc
	v_add_co_u32_e32 v36, vcc, s73, v26
	global_load_dword v34, v[34:35], off
	s_nop 0
	v_addc_co_u32_e32 v37, vcc, -1, v27, vcc
	global_load_dword v36, v[36:37], off
	v_mov_b32_e32 v58, v11
	s_waitcnt vmcnt(2)
	v_pk_mul_f32 v[10:11], v[22:23], v[58:59] op_sel_hi:[0,1]
	v_pk_fma_f32 v[10:11], v[32:33], v[62:63], v[10:11] op_sel_hi:[0,1,1]
	v_mov_b32_e32 v58, v12
	v_mov_b32_e32 v59, v60
	v_mov_b32_e32 v60, v13
	s_waitcnt vmcnt(1)
	v_pk_fma_f32 v[10:11], v[34:35], v[58:59], v[10:11] op_sel_hi:[0,1,1]
	s_waitcnt vmcnt(0)
	v_pk_fma_f32 v[10:11], v[36:37], v[60:61], v[10:11] op_sel_hi:[0,1,1]
	ds_read_b128 v[58:61], v56 offset:8208
	ds_read_b128 v[62:65], v56 offset:12304
	v_pk_add_f32 v[10:11], v[40:41], v[10:11]
	s_waitcnt lgkmcnt(1)
	v_mov_b32_e32 v12, v58
	s_waitcnt lgkmcnt(0)
	v_mov_b32_e32 v13, v62
	v_mov_b32_e32 v62, v59
	v_pk_mul_f32 v[40:41], v[22:23], v[62:63] op_sel_hi:[0,1]
	v_pk_fma_f32 v[12:13], v[32:33], v[12:13], v[40:41] op_sel_hi:[0,1,1]
	v_mov_b32_e32 v40, v60
	v_mov_b32_e32 v41, v64
	v_pk_fma_f32 v[12:13], v[34:35], v[40:41], v[12:13] op_sel_hi:[0,1,1]
	v_mov_b32_e32 v64, v61
	v_pk_fma_f32 v[12:13], v[36:37], v[64:65], v[12:13] op_sel_hi:[0,1,1]
	v_pk_add_f32 v[62:63], v[38:39], v[12:13]
	ds_read_b128 v[38:41], v56 offset:16400
	ds_read_b128 v[58:61], v56 offset:20496
	s_waitcnt lgkmcnt(1)
	v_mov_b32_e32 v12, v38
	s_waitcnt lgkmcnt(0)
	v_mov_b32_e32 v13, v58
	v_mov_b32_e32 v58, v39
	v_pk_mul_f32 v[38:39], v[22:23], v[58:59] op_sel_hi:[0,1]
	v_pk_fma_f32 v[12:13], v[32:33], v[12:13], v[38:39] op_sel_hi:[0,1,1]
	v_mov_b32_e32 v38, v40
	v_mov_b32_e32 v39, v60
	v_pk_fma_f32 v[12:13], v[34:35], v[38:39], v[12:13] op_sel_hi:[0,1,1]
	v_mov_b32_e32 v60, v41
	ds_read_b128 v[38:41], v56 offset:24592
	v_pk_fma_f32 v[12:13], v[36:37], v[60:61], v[12:13] op_sel_hi:[0,1,1]
	v_pk_add_f32 v[58:59], v[28:29], v[12:13]
	v_mov_b32_e32 v33, v22
	v_mov_b32_e32 v35, v36
	s_waitcnt lgkmcnt(0)
	v_mul_f32_e32 v12, v32, v38
	v_mul_f32_e32 v28, v22, v39
	v_mul_f32_e32 v60, v34, v40
	v_mul_f32_e32 v64, v36, v41
	ds_read_b128 v[38:41], v56 offset:28688
	s_waitcnt lgkmcnt(0)
	v_pk_mul_f32 v[32:33], v[32:33], v[38:39]
	v_pk_mul_f32 v[34:35], v[34:35], v[40:41]
	v_mov_b32_e32 v13, v32
	v_mov_b32_e32 v29, v33
	v_pk_add_f32 v[12:13], v[12:13], v[28:29]
	v_mov_b32_e32 v61, v34
	v_pk_add_f32 v[12:13], v[12:13], v[60:61]
	v_mov_b32_e32 v65, v35
	v_pk_add_f32 v[12:13], v[12:13], v[64:65]
	s_nop 0
	v_pk_add_f32 v[32:33], v[30:31], v[12:13]
	v_add_co_u32_e32 v12, vcc, s74, v26
	ds_read_b128 v[28:31], v56 offset:4128
	s_nop 0
	v_addc_co_u32_e32 v13, vcc, -1, v27, vcc
	global_load_dword v34, v[12:13], off
	v_add_co_u32_e32 v12, vcc, s75, v26
	s_nop 1
	v_addc_co_u32_e32 v13, vcc, -1, v27, vcc
	global_load_dword v22, v[12:13], off
	v_add_co_u32_e32 v12, vcc, s76, v26
	s_nop 1
	v_addc_co_u32_e32 v13, vcc, -1, v27, vcc
	global_load_dword v36, v[12:13], off
	v_add_co_u32_e32 v12, vcc, s77, v26
	s_nop 1
	v_addc_co_u32_e32 v13, vcc, -1, v27, vcc
	global_load_dword v38, v[12:13], off
	s_waitcnt lgkmcnt(0)
	v_mov_b32_e32 v13, v28
	v_mov_b32_e32 v28, v7
	v_mov_b32_e32 v12, v6
	s_waitcnt vmcnt(2)
	v_pk_mul_f32 v[6:7], v[22:23], v[28:29] op_sel_hi:[0,1]
	v_pk_fma_f32 v[6:7], v[34:35], v[12:13], v[6:7] op_sel_hi:[0,1,1]
	v_mov_b32_e32 v12, v8
	v_mov_b32_e32 v13, v30
	v_mov_b32_e32 v30, v9
	s_waitcnt vmcnt(1)
	v_pk_fma_f32 v[6:7], v[36:37], v[12:13], v[6:7] op_sel_hi:[0,1,1]
	s_waitcnt vmcnt(0)
	v_pk_fma_f32 v[6:7], v[38:39], v[30:31], v[6:7] op_sel_hi:[0,1,1]
	v_pk_add_f32 v[12:13], v[10:11], v[6:7]
	ds_read_b128 v[6:9], v56 offset:8224
	ds_read_b128 v[28:31], v56 offset:12320
	s_waitcnt lgkmcnt(1)
	v_mov_b32_e32 v10, v6
	s_waitcnt lgkmcnt(0)
	v_mov_b32_e32 v11, v28
	v_mov_b32_e32 v28, v7
	v_pk_mul_f32 v[6:7], v[22:23], v[28:29] op_sel_hi:[0,1]
	v_pk_fma_f32 v[6:7], v[34:35], v[10:11], v[6:7] op_sel_hi:[0,1,1]
	v_mov_b32_e32 v10, v8
	v_mov_b32_e32 v11, v30
	v_pk_fma_f32 v[6:7], v[36:37], v[10:11], v[6:7] op_sel_hi:[0,1,1]
	v_mov_b32_e32 v30, v9
	v_pk_fma_f32 v[6:7], v[38:39], v[30:31], v[6:7] op_sel_hi:[0,1,1]
	v_pk_add_f32 v[10:11], v[62:63], v[6:7]
	ds_read_b128 v[6:9], v56 offset:16416
	ds_read_b128 v[28:31], v56 offset:20512
	s_waitcnt lgkmcnt(1)
	v_mov_b32_e32 v40, v6
	s_waitcnt lgkmcnt(0)
	v_mov_b32_e32 v41, v28
	v_mov_b32_e32 v28, v7
	v_pk_mul_f32 v[6:7], v[22:23], v[28:29] op_sel_hi:[0,1]
	v_pk_fma_f32 v[6:7], v[34:35], v[40:41], v[6:7] op_sel_hi:[0,1,1]
	v_mov_b32_e32 v28, v8
	v_mov_b32_e32 v29, v30
	v_pk_fma_f32 v[6:7], v[36:37], v[28:29], v[6:7] op_sel_hi:[0,1,1]
	v_mov_b32_e32 v30, v9
	v_pk_fma_f32 v[6:7], v[38:39], v[30:31], v[6:7] op_sel_hi:[0,1,1]
	ds_read_b128 v[28:31], v56 offset:24608
	v_pk_add_f32 v[8:9], v[58:59], v[6:7]
	v_mov_b32_e32 v35, v22
	v_mov_b32_e32 v37, v38
	s_waitcnt lgkmcnt(0)
	v_mul_f32_e32 v6, v34, v28
	v_mul_f32_e32 v40, v22, v29
	v_mul_f32_e32 v58, v36, v30
	v_mul_f32_e32 v60, v38, v31
	ds_read_b128 v[28:31], v56 offset:28704
	v_mov_b32_e32 v38, v2
	s_waitcnt lgkmcnt(0)
	v_pk_mul_f32 v[28:29], v[34:35], v[28:29]
	v_pk_mul_f32 v[30:31], v[36:37], v[30:31]
	v_mov_b32_e32 v7, v28
	v_mov_b32_e32 v41, v29
	v_pk_add_f32 v[6:7], v[6:7], v[40:41]
	v_mov_b32_e32 v59, v30
	v_pk_add_f32 v[6:7], v[6:7], v[58:59]
	v_mov_b32_e32 v61, v31
	v_add_co_u32_e32 v28, vcc, s78, v26
	v_pk_add_f32 v[6:7], v[6:7], v[60:61]
	s_nop 0
	v_addc_co_u32_e32 v29, vcc, -1, v27, vcc
	v_pk_add_f32 v[6:7], v[32:33], v[6:7]
	global_load_dword v32, v[28:29], off
	v_add_co_u32_e32 v28, vcc, s79, v26
	s_nop 1
	v_addc_co_u32_e32 v29, vcc, -1, v27, vcc
	global_load_dword v22, v[28:29], off
	v_add_co_u32_e32 v28, vcc, s80, v26
	s_nop 1
	v_addc_co_u32_e32 v29, vcc, -1, v27, vcc
	global_load_dword v34, v[28:29], off
	v_add_co_u32_e32 v28, vcc, s81, v26
	s_nop 1
	v_addc_co_u32_e32 v29, vcc, -1, v27, vcc
	global_load_dword v36, v[28:29], off
	ds_read_b128 v[28:31], v56 offset:4144
	s_waitcnt lgkmcnt(0)
	v_mov_b32_e32 v39, v28
	v_mov_b32_e32 v28, v3
	s_waitcnt vmcnt(2)
	v_pk_mul_f32 v[2:3], v[22:23], v[28:29] op_sel_hi:[0,1]
	v_pk_fma_f32 v[2:3], v[32:33], v[38:39], v[2:3] op_sel_hi:[0,1,1]
	v_mov_b32_e32 v28, v4
	v_mov_b32_e32 v29, v30
	v_mov_b32_e32 v30, v5
	s_waitcnt vmcnt(1)
	v_pk_fma_f32 v[2:3], v[34:35], v[28:29], v[2:3] op_sel_hi:[0,1,1]
	s_waitcnt vmcnt(0)
	v_pk_fma_f32 v[2:3], v[36:37], v[30:31], v[2:3] op_sel_hi:[0,1,1]
	v_pk_add_f32 v[38:39], v[12:13], v[2:3]
	ds_read_b128 v[2:5], v56 offset:8240
	ds_read_b128 v[28:31], v56 offset:12336
	s_waitcnt lgkmcnt(1)
	v_mov_b32_e32 v12, v2
	s_waitcnt lgkmcnt(0)
	v_mov_b32_e32 v13, v28
	v_mov_b32_e32 v28, v3
	v_pk_mul_f32 v[2:3], v[22:23], v[28:29] op_sel_hi:[0,1]
	v_pk_fma_f32 v[2:3], v[32:33], v[12:13], v[2:3] op_sel_hi:[0,1,1]
	v_mov_b32_e32 v12, v4
	v_mov_b32_e32 v13, v30
	v_pk_fma_f32 v[2:3], v[34:35], v[12:13], v[2:3] op_sel_hi:[0,1,1]
	v_mov_b32_e32 v30, v5
	v_pk_fma_f32 v[2:3], v[36:37], v[30:31], v[2:3] op_sel_hi:[0,1,1]
	v_pk_add_f32 v[28:29], v[10:11], v[2:3]
	ds_read_b128 v[2:5], v56 offset:16432
	ds_read_b128 v[10:13], v56 offset:20528
	s_waitcnt lgkmcnt(1)
	v_mov_b32_e32 v30, v2
	s_waitcnt lgkmcnt(0)
	v_mov_b32_e32 v31, v10
	v_mov_b32_e32 v10, v3
	v_pk_mul_f32 v[2:3], v[22:23], v[10:11] op_sel_hi:[0,1]
	v_pk_fma_f32 v[2:3], v[32:33], v[30:31], v[2:3] op_sel_hi:[0,1,1]
	v_mov_b32_e32 v10, v4
	v_mov_b32_e32 v11, v12
	v_pk_fma_f32 v[2:3], v[34:35], v[10:11], v[2:3] op_sel_hi:[0,1,1]
	v_mov_b32_e32 v12, v5
	v_pk_fma_f32 v[2:3], v[36:37], v[12:13], v[2:3] op_sel_hi:[0,1,1]
	v_pk_add_f32 v[12:13], v[8:9], v[2:3]
	ds_read_b128 v[2:5], v56 offset:24624
	v_mov_b32_e32 v33, v22
	v_mov_b32_e32 v35, v36
	s_waitcnt lgkmcnt(0)
	v_mul_f32_e32 v8, v32, v2
	v_mul_f32_e32 v10, v22, v3
	v_mul_f32_e32 v30, v34, v4
	v_mul_f32_e32 v40, v36, v5
	ds_read_b128 v[2:5], v56 offset:28720
	s_waitcnt lgkmcnt(0)
	v_pk_mul_f32 v[2:3], v[32:33], v[2:3]
	v_pk_mul_f32 v[4:5], v[34:35], v[4:5]
	v_mov_b32_e32 v9, v2
	v_mov_b32_e32 v11, v3
	v_pk_add_f32 v[2:3], v[8:9], v[10:11]
	v_mov_b32_e32 v31, v4
	v_pk_add_f32 v[2:3], v[2:3], v[30:31]
	v_mov_b32_e32 v41, v5
	v_pk_add_f32 v[2:3], v[2:3], v[40:41]
	s_nop 0
	v_pk_add_f32 v[32:33], v[6:7], v[2:3]
	v_add_co_u32_e32 v2, vcc, s82, v26
	s_nop 1
	v_addc_co_u32_e32 v3, vcc, -1, v27, vcc
	global_load_dword v34, v[2:3], off
	v_add_co_u32_e32 v2, vcc, s83, v26
	s_nop 1
	v_addc_co_u32_e32 v3, vcc, -1, v27, vcc
	global_load_dword v22, v[2:3], off
	v_add_co_u32_e32 v2, vcc, s84, v26
	s_nop 1
	v_addc_co_u32_e32 v3, vcc, -1, v27, vcc
	global_load_dword v36, v[2:3], off
	v_add_co_u32_e32 v2, vcc, s85, v26
	s_nop 1
	v_addc_co_u32_e32 v3, vcc, -1, v27, vcc
	global_load_dword v40, v[2:3], off
	ds_read_b128 v[2:5], v56 offset:64
	ds_read_b128 v[6:9], v56 offset:4160
	s_waitcnt lgkmcnt(1)
	v_mov_b32_e32 v10, v2
	s_waitcnt lgkmcnt(0)
	v_mov_b32_e32 v11, v6
	v_mov_b32_e32 v6, v3
	s_waitcnt vmcnt(2)
	v_pk_mul_f32 v[2:3], v[22:23], v[6:7] op_sel_hi:[0,1]
	v_pk_fma_f32 v[2:3], v[34:35], v[10:11], v[2:3] op_sel_hi:[0,1,1]
	v_mov_b32_e32 v6, v4
	v_mov_b32_e32 v7, v8
	v_mov_b32_e32 v8, v5
	s_waitcnt vmcnt(1)
	v_pk_fma_f32 v[2:3], v[36:37], v[6:7], v[2:3] op_sel_hi:[0,1,1]
	s_waitcnt vmcnt(0)
	v_pk_fma_f32 v[2:3], v[40:41], v[8:9], v[2:3] op_sel_hi:[0,1,1]
	v_pk_add_f32 v[6:7], v[38:39], v[2:3]
	ds_read_b128 v[2:5], v56 offset:8256
	ds_read_b128 v[8:11], v56 offset:12352
	s_waitcnt lgkmcnt(1)
	v_mov_b32_e32 v30, v2
	s_waitcnt lgkmcnt(0)
	v_mov_b32_e32 v31, v8
	v_mov_b32_e32 v8, v3
	v_pk_mul_f32 v[2:3], v[22:23], v[8:9] op_sel_hi:[0,1]
	v_pk_fma_f32 v[2:3], v[34:35], v[30:31], v[2:3] op_sel_hi:[0,1,1]
	v_mov_b32_e32 v8, v4
	v_mov_b32_e32 v9, v10
	v_pk_fma_f32 v[2:3], v[36:37], v[8:9], v[2:3] op_sel_hi:[0,1,1]
	v_mov_b32_e32 v10, v5
	v_pk_fma_f32 v[2:3], v[40:41], v[10:11], v[2:3] op_sel_hi:[0,1,1]
	v_pk_add_f32 v[4:5], v[28:29], v[2:3]
	ds_read_b128 v[8:11], v56 offset:16448
	ds_read_b128 v[28:31], v56 offset:20544
	s_waitcnt lgkmcnt(1)
	v_mov_b32_e32 v2, v8
	s_waitcnt lgkmcnt(0)
	v_mov_b32_e32 v3, v28
	v_mov_b32_e32 v28, v9
	v_pk_mul_f32 v[8:9], v[22:23], v[28:29] op_sel_hi:[0,1]
	v_pk_fma_f32 v[2:3], v[34:35], v[2:3], v[8:9] op_sel_hi:[0,1,1]
	v_mov_b32_e32 v8, v10
	v_mov_b32_e32 v9, v30
	v_pk_fma_f32 v[2:3], v[36:37], v[8:9], v[2:3] op_sel_hi:[0,1,1]
	v_mov_b32_e32 v30, v11
	ds_read_b128 v[8:11], v56 offset:24640
	v_pk_fma_f32 v[2:3], v[40:41], v[30:31], v[2:3] op_sel_hi:[0,1,1]
	v_pk_add_f32 v[2:3], v[12:13], v[2:3]
	v_mov_b32_e32 v37, v40
	v_mov_b32_e32 v35, v22
	s_waitcnt lgkmcnt(0)
	v_mul_f32_e32 v12, v34, v8
	v_mul_f32_e32 v28, v22, v9
	v_mul_f32_e32 v30, v36, v10
	v_mul_f32_e32 v38, v40, v11
	ds_read_b128 v[8:11], v56 offset:28736
	s_waitcnt lgkmcnt(0)
	v_pk_mul_f32 v[10:11], v[36:37], v[10:11]
	v_pk_mul_f32 v[8:9], v[34:35], v[8:9]
	v_mov_b32_e32 v31, v10
	v_add_co_u32_e32 v10, vcc, s86, v26
	v_mov_b32_e32 v13, v8
	v_mov_b32_e32 v29, v9
	v_mov_b32_e32 v39, v11
	v_addc_co_u32_e32 v11, vcc, -1, v27, vcc
	v_pk_add_f32 v[8:9], v[12:13], v[28:29]
	v_add_co_u32_e32 v12, vcc, s87, v26
	global_load_dword v10, v[10:11], off
	s_nop 0
	v_addc_co_u32_e32 v13, vcc, -1, v27, vcc
	v_add_co_u32_e32 v28, vcc, s88, v26
	global_load_dword v12, v[12:13], off
	s_nop 0
	v_addc_co_u32_e32 v29, vcc, -1, v27, vcc
	v_pk_add_f32 v[8:9], v[8:9], v[30:31]
	v_add_co_u32_e32 v30, vcc, s89, v26
	global_load_dword v28, v[28:29], off
	s_nop 0
	v_addc_co_u32_e32 v31, vcc, -1, v27, vcc
	global_load_dword v22, v[30:31], off
	v_pk_add_f32 v[8:9], v[8:9], v[38:39]
	s_nop 0
	v_pk_add_f32 v[8:9], v[32:33], v[8:9]
	ds_read_b128 v[30:33], v56 offset:80
	ds_read_b128 v[34:37], v56 offset:4176
	s_waitcnt lgkmcnt(1)
	v_mov_b32_e32 v38, v30
	s_waitcnt lgkmcnt(0)
	v_mov_b32_e32 v39, v34
	v_mov_b32_e32 v34, v31
	s_waitcnt vmcnt(2)
	v_pk_mul_f32 v[30:31], v[12:13], v[34:35] op_sel_hi:[0,1]
	v_pk_fma_f32 v[30:31], v[10:11], v[38:39], v[30:31] op_sel_hi:[0,1,1]
	v_mov_b32_e32 v34, v32
	v_mov_b32_e32 v35, v36
	v_mov_b32_e32 v36, v33
	s_waitcnt vmcnt(1)
	v_pk_fma_f32 v[30:31], v[28:29], v[34:35], v[30:31] op_sel_hi:[0,1,1]
	s_waitcnt vmcnt(0)
	v_pk_fma_f32 v[30:31], v[22:23], v[36:37], v[30:31] op_sel_hi:[0,1,1]
	v_pk_add_f32 v[6:7], v[6:7], v[30:31]
	ds_read_b128 v[30:33], v56 offset:8272
	ds_read_b128 v[34:37], v56 offset:12368
	s_waitcnt lgkmcnt(1)
	v_mov_b32_e32 v38, v30
	s_waitcnt lgkmcnt(0)
	v_mov_b32_e32 v39, v34
	v_mov_b32_e32 v34, v31
	v_pk_mul_f32 v[30:31], v[12:13], v[34:35] op_sel_hi:[0,1]
	v_pk_fma_f32 v[30:31], v[10:11], v[38:39], v[30:31] op_sel_hi:[0,1,1]
	v_mov_b32_e32 v34, v32
	v_mov_b32_e32 v35, v36
	v_pk_fma_f32 v[30:31], v[28:29], v[34:35], v[30:31] op_sel_hi:[0,1,1]
	v_mov_b32_e32 v36, v33
	v_pk_fma_f32 v[30:31], v[22:23], v[36:37], v[30:31] op_sel_hi:[0,1,1]
	ds_read_b128 v[32:35], v56 offset:16464
	ds_read_b128 v[36:39], v56 offset:20560
	v_pk_add_f32 v[30:31], v[4:5], v[30:31]
	s_waitcnt lgkmcnt(1)
	v_mov_b32_e32 v4, v32
	s_waitcnt lgkmcnt(0)
	v_mov_b32_e32 v5, v36
	v_mov_b32_e32 v36, v33
	v_pk_mul_f32 v[32:33], v[12:13], v[36:37] op_sel_hi:[0,1]
	v_pk_fma_f32 v[4:5], v[10:11], v[4:5], v[32:33] op_sel_hi:[0,1,1]
	v_mov_b32_e32 v32, v34
	v_mov_b32_e32 v33, v38
	v_pk_fma_f32 v[4:5], v[28:29], v[32:33], v[4:5] op_sel_hi:[0,1,1]
	v_mov_b32_e32 v38, v35
	v_pk_fma_f32 v[4:5], v[22:23], v[38:39], v[4:5] op_sel_hi:[0,1,1]
	v_pk_add_f32 v[32:33], v[2:3], v[4:5]
	ds_read_b128 v[2:5], v56 offset:24656
	v_mov_b32_e32 v11, v12
	v_mov_b32_e32 v29, v22
	s_waitcnt lgkmcnt(0)
	v_mul_f32_e32 v34, v10, v2
	v_mul_f32_e32 v36, v12, v3
	v_mul_f32_e32 v38, v28, v4
	v_mul_f32_e32 v40, v22, v5
	ds_read_b128 v[2:5], v56 offset:28752
	s_waitcnt lgkmcnt(0)
	v_pk_mul_f32 v[2:3], v[10:11], v[2:3]
	v_pk_mul_f32 v[4:5], v[28:29], v[4:5]
	v_mov_b32_e32 v35, v2
	v_mov_b32_e32 v37, v3
	v_pk_add_f32 v[2:3], v[34:35], v[36:37]
	v_mov_b32_e32 v39, v4
	v_pk_add_f32 v[2:3], v[2:3], v[38:39]
	v_mov_b32_e32 v41, v5
	v_pk_add_f32 v[2:3], v[2:3], v[40:41]
	s_nop 0
	v_pk_add_f32 v[28:29], v[8:9], v[2:3]
	v_add_co_u32_e32 v2, vcc, s90, v26
	s_nop 1
	v_addc_co_u32_e32 v3, vcc, -1, v27, vcc
	global_load_dword v34, v[2:3], off
	v_add_co_u32_e32 v2, vcc, s91, v26
	s_nop 1
	v_addc_co_u32_e32 v3, vcc, -1, v27, vcc
	global_load_dword v22, v[2:3], off
	v_add_co_u32_e32 v2, vcc, s92, v26
	s_nop 1
	v_addc_co_u32_e32 v3, vcc, -1, v27, vcc
	global_load_dword v38, v[2:3], off
	v_add_co_u32_e32 v2, vcc, s0, v26
	s_nop 1
	v_addc_co_u32_e32 v3, vcc, -1, v27, vcc
	global_load_dword v40, v[2:3], off
	ds_read_b128 v[2:5], v56 offset:96
	ds_read_b128 v[8:11], v56 offset:4192
	s_waitcnt lgkmcnt(1)
	v_mov_b32_e32 v12, v2
	s_waitcnt lgkmcnt(0)
	v_mov_b32_e32 v13, v8
	v_mov_b32_e32 v8, v3
	s_waitcnt vmcnt(2)
	v_pk_mul_f32 v[2:3], v[22:23], v[8:9] op_sel_hi:[0,1]
	v_pk_fma_f32 v[2:3], v[34:35], v[12:13], v[2:3] op_sel_hi:[0,1,1]
	v_mov_b32_e32 v8, v4
	v_mov_b32_e32 v9, v10
	v_mov_b32_e32 v10, v5
	s_waitcnt vmcnt(1)
	v_pk_fma_f32 v[2:3], v[38:39], v[8:9], v[2:3] op_sel_hi:[0,1,1]
	s_waitcnt vmcnt(0)
	v_pk_fma_f32 v[2:3], v[40:41], v[10:11], v[2:3] op_sel_hi:[0,1,1]
	v_pk_add_f32 v[4:5], v[6:7], v[2:3]
	ds_read_b128 v[6:9], v56 offset:8288
	ds_read_b128 v[10:13], v56 offset:12384
	s_waitcnt lgkmcnt(1)
	v_mov_b32_e32 v2, v6
	s_waitcnt lgkmcnt(0)
	v_mov_b32_e32 v3, v10
	v_mov_b32_e32 v10, v7
	v_pk_mul_f32 v[6:7], v[22:23], v[10:11] op_sel_hi:[0,1]
	v_pk_fma_f32 v[2:3], v[34:35], v[2:3], v[6:7] op_sel_hi:[0,1,1]
	v_mov_b32_e32 v6, v8
	v_mov_b32_e32 v7, v12
	v_pk_fma_f32 v[2:3], v[38:39], v[6:7], v[2:3] op_sel_hi:[0,1,1]
	v_mov_b32_e32 v12, v9
	v_pk_fma_f32 v[2:3], v[40:41], v[12:13], v[2:3] op_sel_hi:[0,1,1]
	ds_read_b128 v[6:9], v56 offset:16480
	ds_read_b128 v[10:13], v56 offset:20576
	v_pk_add_f32 v[2:3], v[30:31], v[2:3]
	s_waitcnt lgkmcnt(1)
	v_mov_b32_e32 v30, v6
	s_waitcnt lgkmcnt(0)
	v_mov_b32_e32 v31, v10
	v_mov_b32_e32 v10, v7
	v_pk_mul_f32 v[6:7], v[22:23], v[10:11] op_sel_hi:[0,1]
	v_pk_fma_f32 v[6:7], v[34:35], v[30:31], v[6:7] op_sel_hi:[0,1,1]
	v_mov_b32_e32 v10, v8
	v_mov_b32_e32 v11, v12
	v_pk_fma_f32 v[6:7], v[38:39], v[10:11], v[6:7] op_sel_hi:[0,1,1]
	v_mov_b32_e32 v12, v9
	v_pk_fma_f32 v[6:7], v[40:41], v[12:13], v[6:7] op_sel_hi:[0,1,1]
	v_pk_add_f32 v[36:37], v[32:33], v[6:7]
	ds_read_b128 v[6:9], v56 offset:24672
	v_mov_b32_e32 v35, v22
	v_mov_b32_e32 v39, v40
	s_waitcnt lgkmcnt(0)
	v_mul_f32_e32 v10, v34, v6
	v_mul_f32_e32 v12, v22, v7
	v_mul_f32_e32 v30, v38, v8
	v_mul_f32_e32 v32, v40, v9
	ds_read_b128 v[6:9], v56 offset:28768
	s_waitcnt lgkmcnt(0)
	v_pk_mul_f32 v[6:7], v[34:35], v[6:7]
	v_pk_mul_f32 v[8:9], v[38:39], v[8:9]
	v_mov_b32_e32 v11, v6
	v_mov_b32_e32 v13, v7
	v_pk_add_f32 v[6:7], v[10:11], v[12:13]
	v_mov_b32_e32 v31, v8
	v_pk_add_f32 v[6:7], v[6:7], v[30:31]
	v_mov_b32_e32 v33, v9
	v_pk_add_f32 v[6:7], v[6:7], v[32:33]
	s_nop 0
	v_pk_add_f32 v[10:11], v[28:29], v[6:7]
	v_add_co_u32_e32 v6, vcc, s93, v26
	s_nop 1
	v_addc_co_u32_e32 v7, vcc, -1, v27, vcc
	global_load_dword v12, v[6:7], off
	v_add_co_u32_e32 v6, vcc, s94, v26
	s_nop 1
	v_addc_co_u32_e32 v7, vcc, -1, v27, vcc
	global_load_dword v22, v[6:7], off
	v_add_co_u32_e32 v6, vcc, s68, v26
	s_nop 1
	v_addc_co_u32_e32 v7, vcc, -1, v27, vcc
	global_load_dword v32, v[6:7], off
	global_load_dword v34, v[26:27], off
	ds_read_b128 v[6:9], v56 offset:112
	ds_read_b128 v[28:31], v56 offset:4208
	v_cmp_ge_i32_e32 vcc, v57, v45
	v_lshl_add_u64 v[26:27], v[26:27], 0, s[52:53]
	s_or_b64 s[8:9], vcc, s[8:9]
	s_waitcnt lgkmcnt(1)
	v_mov_b32_e32 v38, v6
	s_waitcnt lgkmcnt(0)
	v_mov_b32_e32 v39, v28
	v_mov_b32_e32 v28, v7
	s_waitcnt vmcnt(2)
	v_pk_mul_f32 v[6:7], v[22:23], v[28:29] op_sel_hi:[0,1]
	v_pk_fma_f32 v[6:7], v[12:13], v[38:39], v[6:7] op_sel_hi:[0,1,1]
	v_mov_b32_e32 v28, v8
	v_mov_b32_e32 v29, v30
	v_mov_b32_e32 v30, v9
	s_waitcnt vmcnt(1)
	v_pk_fma_f32 v[6:7], v[32:33], v[28:29], v[6:7] op_sel_hi:[0,1,1]
	s_waitcnt vmcnt(0)
	v_pk_fma_f32 v[6:7], v[34:35], v[30:31], v[6:7] op_sel_hi:[0,1,1]
	v_pk_add_f32 v[28:29], v[4:5], v[6:7]
	ds_read_b128 v[4:7], v56 offset:8304
	ds_read_b128 v[38:41], v56 offset:12400
	s_waitcnt lgkmcnt(1)
	v_mov_b32_e32 v8, v4
	s_waitcnt lgkmcnt(0)
	v_mov_b32_e32 v9, v38
	v_mov_b32_e32 v38, v5
	v_pk_mul_f32 v[4:5], v[22:23], v[38:39] op_sel_hi:[0,1]
	v_pk_fma_f32 v[4:5], v[12:13], v[8:9], v[4:5] op_sel_hi:[0,1,1]
	v_mov_b32_e32 v8, v6
	v_mov_b32_e32 v9, v40
	v_pk_fma_f32 v[4:5], v[32:33], v[8:9], v[4:5] op_sel_hi:[0,1,1]
	v_mov_b32_e32 v40, v7
	v_pk_fma_f32 v[4:5], v[34:35], v[40:41], v[4:5] op_sel_hi:[0,1,1]
	v_pk_add_f32 v[30:31], v[2:3], v[4:5]
	ds_read_b128 v[2:5], v56 offset:16496
	ds_read_b128 v[6:9], v56 offset:20592
	s_waitcnt lgkmcnt(1)
	v_mov_b32_e32 v38, v2
	s_waitcnt lgkmcnt(0)
	v_mov_b32_e32 v39, v6
	v_mov_b32_e32 v6, v3
	v_pk_mul_f32 v[2:3], v[22:23], v[6:7] op_sel_hi:[0,1]
	v_pk_fma_f32 v[2:3], v[12:13], v[38:39], v[2:3] op_sel_hi:[0,1,1]
	v_mov_b32_e32 v6, v4
	v_mov_b32_e32 v7, v8
	v_pk_fma_f32 v[2:3], v[32:33], v[6:7], v[2:3] op_sel_hi:[0,1,1]
	v_mov_b32_e32 v8, v5
	v_pk_fma_f32 v[2:3], v[34:35], v[8:9], v[2:3] op_sel_hi:[0,1,1]
	v_pk_add_f32 v[36:37], v[36:37], v[2:3]
	ds_read_b128 v[2:5], v56 offset:24688
	v_mov_b32_e32 v13, v22
	v_mov_b32_e32 v33, v34
	s_waitcnt lgkmcnt(0)
	v_mul_f32_e32 v6, v12, v2
	v_mul_f32_e32 v8, v22, v3
	v_mul_f32_e32 v38, v32, v4
	v_mul_f32_e32 v40, v34, v5
	ds_read_b128 v[2:5], v56 offset:28784
	v_add_u32_e32 v56, 0x80, v56
	s_waitcnt lgkmcnt(0)
	v_pk_mul_f32 v[2:3], v[12:13], v[2:3]
	v_pk_mul_f32 v[4:5], v[32:33], v[4:5]
	v_mov_b32_e32 v7, v2
	v_mov_b32_e32 v9, v3
	v_pk_add_f32 v[2:3], v[6:7], v[8:9]
	v_mov_b32_e32 v39, v4
	v_pk_add_f32 v[2:3], v[2:3], v[38:39]
	v_mov_b32_e32 v41, v5
	v_pk_add_f32 v[2:3], v[2:3], v[40:41]
	s_nop 0
	v_pk_add_f32 v[32:33], v[10:11], v[2:3]
	s_andn2_b64 exec, exec, s[8:9]
	s_cbranch_execnz .LBB0_47
	s_or_b64 exec, exec, s[8:9]
	s_setprio 0
	s_barrier
	ds_write2st64_b32 v51, v28, v29 offset1:1
	ds_write2st64_b32 v51, v30, v31 offset0:2 offset1:3
	ds_write2st64_b32 v51, v36, v37 offset0:4 offset1:5
	ds_write2st64_b32 v51, v32, v33 offset0:6 offset1:7
	s_waitcnt lgkmcnt(0)
	s_setprio 0
	s_barrier
	s_and_saveexec_b64 s[0:1], s[6:7]
	s_cbranch_execz .LBB0_24
	s_mul_i32 s3, s2, 0xc00
	v_add_u32_e32 v2, s3, v24
	v_ashrrev_i32_e32 v3, 31, v2
	s_lshl_b32 s8, s2, 3
	v_lshl_add_u64 v[2:3], v[2:3], 2, s[44:45]
	v_lshl_add_u64 v[4:5], v[24:25], 2, s[50:51]
	s_mov_b64 s[2:3], 0
	v_mov_b32_e32 v6, v46
	v_mov_b32_e32 v7, v14

.LBB0_128:
	s_or_b64 exec, exec, s[10:11]
	v_lshl_add_u32 v34, v38, 6, v38
	v_add_lshl_u32 v34, v34, v39, 2
	s_setprio 0
	s_barrier
	s_waitcnt vmcnt(0)
	ds_write2_b32 v34, v6, v7 offset1:1
	ds_write2_b32 v34, v8, v9 offset0:2 offset1:3
	v_add_u32_e32 v6, 0x4140, v34
	ds_write2_b32 v6, v2, v3 offset1:1
	v_add_u32_e32 v2, 0x4148, v34
	ds_write2_b32 v2, v4, v5 offset1:1
	v_add_u32_e32 v2, 0x1040, v34
	ds_write2_b32 v2, v14, v15 offset1:1
	v_add_u32_e32 v2, 0x1048, v34
	ds_write2_b32 v2, v16, v17 offset1:1
	v_add_u32_e32 v2, 0x5180, v34
	ds_write2_b32 v2, v10, v11 offset1:1
	v_add_u32_e32 v2, 0x5188, v34
	ds_write2_b32 v2, v12, v13 offset1:1
	v_add_u32_e32 v2, 0x2080, v34
	ds_write2_b32 v2, v22, v23 offset1:1
	v_add_u32_e32 v2, 0x2088, v34
	ds_write2_b32 v2, v24, v25 offset1:1
	v_add_u32_e32 v2, 0x61c0, v34
	ds_write2_b32 v2, v18, v19 offset1:1
	v_add_u32_e32 v2, 0x61c8, v34
	ds_write2_b32 v2, v20, v21 offset1:1
	v_add_u32_e32 v2, 0x30c0, v34
	ds_write2_b32 v2, v30, v31 offset1:1
	v_add_u32_e32 v2, 0x30c8, v34
	ds_write2_b32 v2, v32, v33 offset1:1
	v_add_u32_e32 v2, 0x7200, v34
	v_lshlrev_b32_e32 v3, 4, v1
	ds_write2_b32 v2, v26, v27 offset1:1
	v_add_u32_e32 v2, 0x7208, v34
	v_and_b32_e32 v3, 48, v3
	ds_write2_b32 v2, v28, v29 offset1:1
	v_ashrrev_i32_e32 v2, 2, v1
	v_and_b32_e32 v1, -4, v1
	v_mul_u32_u24_e32 v4, 0x41, v3
	v_lshl_add_u32 v1, v4, 2, v1
	v_add_u32_e32 v6, 0x400, v1
	v_add_u32_e32 v20, s17, v2
	s_waitcnt lgkmcnt(0)
	s_setprio 0
	s_barrier
	ds_read2_b32 v[8:9], v1 offset1:65
	ds_read2_b32 v[4:5], v1 offset0:130 offset1:195
	ds_read2_b32 v[10:11], v6 offset0:4 offset1:69
	ds_read2_b32 v[6:7], v6 offset0:134 offset1:199
	v_add_u32_e32 v14, 0x800, v1
	v_add_u32_e32 v18, 0xc00, v1
	v_ashrrev_i32_e32 v21, 31, v20
	ds_read2_b32 v[12:13], v14 offset0:8 offset1:73
	ds_read2_b32 v[14:15], v14 offset0:138 offset1:203
	ds_read2_b32 v[16:17], v18 offset0:12 offset1:77
	ds_read2_b32 v[18:19], v18 offset0:142 offset1:207
	v_mul_lo_u32 v22, s2, v21
	v_mul_lo_u32 v23, s3, v20
	v_mad_u64_u32 v[20:21], s[0:1], s2, v20, 0
	v_add3_u32 v21, v21, v22, v23
	v_lshl_add_u64 v[20:21], v[20:21], 1, s[8:9]
	v_lshl_add_u64 v[20:21], s[6:7], 1, v[20:21]
	v_lshlrev_b32_e32 v34, 1, v3
	v_lshl_add_u64 v[20:21], v[20:21], 0, v[34:35]
	s_waitcnt lgkmcnt(4)
	v_cvt_pk_bf16_f32 v7, v6, v7
	v_cvt_pk_bf16_f32 v6, v10, v11
	v_cvt_pk_bf16_f32 v5, v4, v5
	v_cvt_pk_bf16_f32 v4, v8, v9
	global_store_dwordx4 v[20:21], v[4:7], off
	s_andn2_b64 vcc, exec, s[12:13]
	s_waitcnt lgkmcnt(0)
	v_cvt_pk_bf16_f32 v7, v18, v19
	v_cvt_pk_bf16_f32 v6, v16, v17
	v_cvt_pk_bf16_f32 v5, v14, v15
	v_cvt_pk_bf16_f32 v4, v12, v13
	global_store_dwordx4 v[20:21], v[4:7], off offset:16
	s_cbranch_vccnz .LBB0_57
	v_add_u32_e32 v3, 0x4000, v1
	ds_read2_b32 v[6:7], v3 offset0:80 offset1:145
	v_add_u32_e32 v3, 0x4200, v1
	ds_read2_b32 v[8:9], v3 offset0:82 offset1:147
	v_add_u32_e32 v3, 0x4400, v1
	ds_read2_b32 v[10:11], v3 offset0:84 offset1:149
	v_add_u32_e32 v3, 0x4600, v1
	ds_read2_b32 v[4:5], v3 offset0:86 offset1:151
	v_add_u32_e32 v3, 0x4800, v1
	ds_read2_b32 v[12:13], v3 offset0:88 offset1:153
	v_add_u32_e32 v3, 0x4a00, v1
	ds_read2_b32 v[14:15], v3 offset0:90 offset1:155
	v_add_u32_e32 v3, 0x4c00, v1
	v_add_u32_e32 v1, 0x4e00, v1
	ds_read2_b32 v[18:19], v1 offset0:94 offset1:159
	v_add_u32_e32 v1, s70, v2
	v_ashrrev_i32_e32 v2, 31, v1
	ds_read2_b32 v[16:17], v3 offset0:92 offset1:157
	v_mul_lo_u32 v20, s42, v2
	v_mul_lo_u32 v21, s43, v1
	v_mad_u64_u32 v[2:3], s[0:1], s42, v1, 0
	v_add3_u32 v3, v3, v20, v21
	v_lshl_add_u64 v[2:3], v[2:3], 1, s[22:23]
	s_mov_b32 s17, s7
	v_lshl_add_u64 v[2:3], s[16:17], 1, v[2:3]
	v_lshl_add_u64 v[20:21], v[2:3], 0, v[34:35]
	s_waitcnt lgkmcnt(4)
	v_cvt_pk_bf16_f32 v5, v4, v5
	v_cvt_pk_bf16_f32 v4, v10, v11
	v_cvt_pk_bf16_f32 v3, v8, v9
	v_cvt_pk_bf16_f32 v2, v6, v7
	global_store_dwordx4 v[20:21], v[2:5], off
	s_waitcnt lgkmcnt(1)
	s_nop 0
	v_cvt_pk_bf16_f32 v5, v18, v19
	s_waitcnt lgkmcnt(0)
	v_cvt_pk_bf16_f32 v4, v16, v17
	v_cvt_pk_bf16_f32 v3, v14, v15
	v_cvt_pk_bf16_f32 v2, v12, v13
	global_store_dwordx4 v[20:21], v[2:5], off offset:16
	s_branch .LBB0_57

.LBB0_132:
.LBB0_133:
	v_lshrrev_b32_e32 v1, 20, v0
	v_lshrrev_b32_e32 v0, 10, v0
	v_or_b32_e32 v0, v0, v1
	s_movk_i32 s0, 0x3ff
	v_and_or_b32 v0, v0, s0, v206
	v_cmp_eq_u32_e32 vcc, 0, v0
	s_waitcnt lgkmcnt(0)
	s_setprio 0
	s_barrier
	s_and_saveexec_b64 s[0:1], vcc
	v_readlane_b32 s10, v243, 3
	v_readlane_b32 s11, v243, 4
	s_cbranch_execz .LBB0_143
	s_add_u32 s2, s34, 0xd203800
	s_addc_u32 s3, s35, 0
	v_mov_b32_e32 v2, 0
	s_mov_b32 s4, 0

.Linitok:
.LBB0_143:
	s_or_b64 exec, exec, s[0:1]
	s_add_u32 s0, s34, 0xd200000
	s_setprio 0
	s_barrier
	s_getreg_b32 s2, hwreg(HW_REG_XCC_ID, 0, 4)
	s_addc_u32 s1, s35, 0
	s_and_b32 s7, s2, 15
	s_lshl_b32 s6, s7, 6
	s_mov_b32 s77, 0
	s_mov_b64 s[2:3], exec
	v_readlane_b32 s4, v243, 1
	v_readlane_b32 s5, v243, 2
	s_and_b64 s[4:5], s[2:3], s[4:5]
	s_mov_b64 exec, s[4:5]
	s_cbranch_execz .LBB0_146
	s_mov_b64 s[4:5], exec
	v_mbcnt_lo_u32_b32 v0, s4, 0
	v_mbcnt_hi_u32_b32 v0, s5, v0
	v_cmp_eq_u32_e32 vcc, 0, v0
	s_and_b64 s[8:9], exec, vcc
	s_mov_b64 exec, s[8:9]
	s_cbranch_execz .LBB0_146
	s_lshl_b32 s8, s6, 2
	s_bcnt1_i32_b64 s4, s[4:5]
	v_mov_b32_e32 v0, s8
	v_mov_b32_e32 v1, s4
	global_atomic_add v0, v1, s[0:1] offset:1024

.Lgs0_217:
	s_waitcnt vmcnt(0)
	s_waitcnt lgkmcnt(0)
	s_setprio 0
	s_barrier
	s_mov_b64 s[18:19], exec
	v_readlane_b32 s2, v243, 1
	v_readlane_b32 s3, v243, 2
	s_and_b64 s[2:3], s[18:19], s[2:3]
	s_mov_b64 exec, s[2:3]
	s_cbranch_execz .Lgs0_269
	s_waitcnt vmcnt(0) expcnt(0) lgkmcnt(0)
	ds_read_b32 v3, v1 offset:55296
	ds_read_b32 v2, v1 offset:55300
	s_waitcnt lgkmcnt(1)
	v_cmp_ne_u32_e32 vcc, 0, v3
	s_cbranch_vccnz .Lgs0_233
	s_mov_b32 s4, 1
	s_branch .Lgs0_221

.Lgs0_269:
	s_or_b64 exec, exec, s[18:19]
	s_waitcnt lgkmcnt(0)
	s_setprio 0
	s_barrier
	s_branch .LBB0_149

.LBB0_148:
	s_or_b64 exec, exec, s[18:19]
	s_add_i32 s12, s12, 1
	s_cmp_eq_u32 s12, 4
	s_waitcnt lgkmcnt(0)
	s_setprio 0
	s_barrier
	s_cbranch_scc0 .LBB0_149
	s_getpc_b64 s[98:99]

.LBB0_166:
	s_setprio 0
	s_barrier
	s_and_saveexec_b64 s[48:49], s[40:41]
	s_cbranch_execz .LBB0_176
	s_lshl_b32 s3, s2, 3
	s_mov_b64 s[52:53], -1
	v_mov_b32_e32 v3, v130
	v_mov_b32_e32 v2, v154
	s_and_saveexec_b64 s[50:51], s[42:43]
	s_cbranch_execz .LBB0_173
	s_mov_b32 s8, s3
	s_mov_b64 s[52:53], 0
	v_mov_b32_e32 v4, v152
	v_mov_b32_e32 v5, v154
	v_mov_b64_e32 v[2:3], v[130:131]

.LBB0_176:
	s_or_b64 exec, exec, s[48:49]
	s_waitcnt lgkmcnt(0)
	s_setprio 0
	s_barrier
	ds_read_b128 v[2:5], v145
	ds_read_b128 v[6:9], v145 offset:16
	ds_read_b128 v[10:13], v145 offset:32
	ds_read_b128 v[14:17], v145 offset:48
	s_waitcnt vmcnt(4)
	ds_read_b128 v[18:21], v145 offset:4096
	ds_read_b128 v[22:25], v145 offset:4112
	ds_read_b128 v[26:29], v145 offset:4128
	ds_read_b128 v[30:33], v145 offset:4144
	ds_read_b128 v[34:37], v145 offset:8192
	ds_read_b128 v[38:41], v145 offset:8208
	ds_read_b128 v[42:45], v145 offset:8224
	ds_read_b128 v[46:49], v145 offset:8240
	ds_read_b128 v[50:53], v145 offset:12288
	ds_read_b128 v[54:57], v145 offset:12304
	ds_read_b128 v[58:61], v145 offset:12320
	ds_read_b128 v[62:65], v145 offset:12336
	ds_read_b128 v[66:69], v145 offset:16384
	ds_read_b128 v[70:73], v145 offset:16400
	ds_read_b128 v[74:77], v145 offset:16416
	ds_read_b128 v[78:81], v145 offset:16432
	ds_read_b128 v[82:85], v145 offset:20480
	ds_read_b128 v[86:89], v145 offset:20496
	ds_read_b128 v[90:93], v145 offset:20512
	ds_read_b128 v[94:97], v145 offset:20528
	ds_read_b128 v[98:101], v145 offset:24576
	ds_read_b128 v[102:105], v145 offset:24592
	ds_read_b128 v[106:109], v145 offset:24608
	ds_read_b128 v[110:113], v145 offset:24624
	ds_read_b128 v[114:117], v145 offset:28672
	ds_read_b128 v[118:121], v145 offset:28688
	ds_read_b128 v[122:125], v145 offset:28704
	ds_read_b128 v[126:129], v145 offset:28720
	v_lshl_add_u32 v138, s7, 5, v144
	s_mov_b32 s3, s77
	s_lshl_b64 s[2:3], s[2:3], 17
	v_ashrrev_i32_e32 v139, 31, v138
	v_lshl_add_u64 v[136:137], v[138:139], 2, s[2:3]
	v_lshl_add_u64 v[140:141], v[132:133], 0, s[22:23]
	v_lshlrev_b64 v[138:139], 11, v[138:139]
	v_lshl_add_u64 v[138:139], v[140:141], 0, v[138:139]
	v_lshl_add_u64 v[138:139], s[76:77], 1, v[138:139]
	s_mov_b32 s7, 8
	s_branch .LBB0_178

.LBB0_217:
	s_or_b64 exec, exec, s[22:23]
	s_waitcnt vmcnt(0)
	s_waitcnt lgkmcnt(0)
	s_setprio 0
	s_barrier
	s_mov_b64 s[18:19], exec
	v_readlane_b32 s2, v243, 1
	v_readlane_b32 s3, v243, 2
	s_and_b64 s[2:3], s[18:19], s[2:3]
	s_mov_b64 exec, s[2:3]
	s_cbranch_execz .LBB0_269
	s_waitcnt vmcnt(0) expcnt(0) lgkmcnt(0)
	ds_read_b32 v3, v1 offset:55296
	ds_read_b32 v2, v1 offset:55300
	s_waitcnt lgkmcnt(1)
	v_cmp_ne_u32_e32 vcc, 0, v3
	s_cbranch_vccnz .LBB0_233
	s_mov_b32 s4, 1
	s_branch .LBB0_221

.LBB0_269:
	s_or_b64 exec, exec, s[18:19]
	s_waitcnt lgkmcnt(0)
	s_setprio 0
	s_barrier

.LBB0_280:
	s_barrier
	s_waitcnt vmcnt(9)
	ds_write_b128 v186, v[142:145]
	ds_write_b128 v186, v[134:137] offset:4608
	ds_write_b128 v186, v[130:133] offset:9216
	s_waitcnt vmcnt(7)
	ds_write_b128 v186, v[146:149] offset:13824
	ds_write_b128 v186, v[138:141] offset:18432
	s_waitcnt vmcnt(6)
	ds_write_b128 v186, v[150:153] offset:23040
	s_waitcnt vmcnt(5)
	ds_write_b128 v186, v[154:157] offset:27648
	s_waitcnt vmcnt(4)
	ds_write_b128 v186, v[158:161] offset:32256
	s_waitcnt vmcnt(3)
	ds_write_b128 v186, v[162:165] offset:36864
	s_waitcnt vmcnt(2)
	ds_write_b128 v186, v[166:169] offset:41472
	s_waitcnt vmcnt(1)
	ds_write_b128 v186, v[170:173] offset:46080
	s_waitcnt vmcnt(0)
	ds_write_b128 v186, v[174:177] offset:50688
	s_waitcnt lgkmcnt(0)
	s_barrier
	s_setprio 2
	s_mov_b32 vcc_hi, 0
	ds_read_b128 v[244:247], v230
	ds_read_b128 v[210:213], v231 offset:18432
	ds_read_b128 v[248:251], v230 offset:4608
	ds_read_b128 v[214:217], v231 offset:23040
	ds_read_b128 v[218:221], v231 offset:27648
	ds_read_b128 v[222:225], v231 offset:32256
	s_waitcnt lgkmcnt(4)
	v_mfma_f32_32x32x16_bf16 v[114:129], v[210:213], v[244:247], v[114:129]
	s_add_u32 vcc_lo, s22, 0xd400080
	v_lshl_add_u64 v[240:241], v[204:205], 0, vcc
	global_load_dwordx4 v[142:145], v[240:241], off
	ds_read_b128 v[252:255], v230 offset:32
	s_waitcnt lgkmcnt(4)
	v_mfma_f32_32x32x16_bf16 v[82:97], v[210:213], v[248:251], v[82:97]
	s_add_u32 vcc_lo, s22, 0xd410080
	v_lshl_add_u64 v[178:179], v[204:205], 0, vcc
	global_load_dwordx4 v[134:137], v[178:179], off
	ds_read_b128 v[210:213], v231 offset:18464
	s_waitcnt lgkmcnt(4)
	v_mfma_f32_32x32x16_bf16 v[98:113], v[214:217], v[244:247], v[98:113]
	s_add_u32 vcc_lo, s22, 0xd420080
	v_lshl_add_u64 v[240:241], v[204:205], 0, vcc
	global_load_dwordx4 v[130:133], v[240:241], off
	ds_read_b128 v[232:235], v230 offset:4640
	v_mfma_f32_32x32x16_bf16 v[66:81], v[214:217], v[248:251], v[66:81]
	s_add_u32 vcc_lo, s22, 0xd430080
	v_lshl_add_u64 v[178:179], v[204:205], 0, vcc
	global_load_dwordx4 v[146:149], v[178:179], off
	ds_read_b128 v[214:217], v231 offset:23072
	s_waitcnt lgkmcnt(5)
	v_mfma_f32_32x32x16_bf16 v[50:65], v[218:221], v[244:247], v[50:65]
	s_add_u32 vcc_lo, s22, 0xac00080
	v_lshl_add_u64 v[240:241], v[202:203], 0, vcc
	global_load_dwordx4 v[138:141], v[240:241], off
	v_mfma_f32_32x32x16_bf16 v[18:33], v[218:221], v[248:251], v[18:33]
	s_add_u32 vcc_lo, s22, 0xac10080
	v_lshl_add_u64 v[178:179], v[202:203], 0, vcc
	global_load_dwordx4 v[150:153], v[178:179], off
	ds_read_b128 v[218:221], v231 offset:27680
	s_waitcnt lgkmcnt(5)
	v_mfma_f32_32x32x16_bf16 v[34:49], v[222:225], v[244:247], v[34:49]
	s_add_u32 vcc_lo, s22, 0xac20080
	v_lshl_add_u64 v[240:241], v[202:203], 0, vcc
	global_load_dwordx4 v[154:157], v[240:241], off
	v_mfma_f32_32x32x16_bf16 v[2:17], v[222:225], v[248:251], v[2:17]
	s_add_u32 vcc_lo, s22, 0xac30080
	v_lshl_add_u64 v[178:179], v[202:203], 0, vcc
	global_load_dwordx4 v[158:161], v[178:179], off
	ds_read_b128 v[222:225], v231 offset:32288
	s_waitcnt lgkmcnt(4)
	v_mfma_f32_32x32x16_bf16 v[114:129], v[210:213], v[252:255], v[114:129]
	s_add_u32 vcc_lo, s22, 0xac40080
	v_lshl_add_u64 v[240:241], v[202:203], 0, vcc
	global_load_dwordx4 v[162:165], v[240:241], off
	ds_read_b128 v[244:247], v230 offset:64
	s_waitcnt lgkmcnt(4)
	v_mfma_f32_32x32x16_bf16 v[82:97], v[210:213], v[232:235], v[82:97]
	s_add_u32 vcc_lo, s22, 0xac50080
	v_lshl_add_u64 v[178:179], v[202:203], 0, vcc
	global_load_dwordx4 v[166:169], v[178:179], off
	ds_read_b128 v[210:213], v231 offset:18496
	s_waitcnt lgkmcnt(4)
	v_mfma_f32_32x32x16_bf16 v[98:113], v[214:217], v[252:255], v[98:113]
	s_add_u32 vcc_lo, s22, 0xac60080
	v_lshl_add_u64 v[240:241], v[202:203], 0, vcc
	global_load_dwordx4 v[170:173], v[240:241], off
	ds_read_b128 v[248:251], v230 offset:4672
	v_mfma_f32_32x32x16_bf16 v[66:81], v[214:217], v[232:235], v[66:81]
	s_add_u32 vcc_lo, s22, 0xac70080
	v_lshl_add_u64 v[178:179], v[202:203], 0, vcc
	global_load_dwordx4 v[174:177], v[178:179], off
	ds_read_b128 v[214:217], v231 offset:23104
	s_waitcnt lgkmcnt(5)
	v_mfma_f32_32x32x16_bf16 v[50:65], v[218:221], v[252:255], v[50:65]
	v_mfma_f32_32x32x16_bf16 v[18:33], v[218:221], v[232:235], v[18:33]
	ds_read_b128 v[218:221], v231 offset:27712
	s_waitcnt lgkmcnt(5)
	v_mfma_f32_32x32x16_bf16 v[34:49], v[222:225], v[252:255], v[34:49]
	v_mfma_f32_32x32x16_bf16 v[2:17], v[222:225], v[232:235], v[2:17]
	ds_read_b128 v[222:225], v231 offset:32320
	s_waitcnt lgkmcnt(4)
	v_mfma_f32_32x32x16_bf16 v[114:129], v[210:213], v[244:247], v[114:129]
	ds_read_b128 v[252:255], v230 offset:96
	s_waitcnt lgkmcnt(4)
	v_mfma_f32_32x32x16_bf16 v[82:97], v[210:213], v[248:251], v[82:97]
	ds_read_b128 v[210:213], v231 offset:18528
	s_waitcnt lgkmcnt(4)
	v_mfma_f32_32x32x16_bf16 v[98:113], v[214:217], v[244:247], v[98:113]
	ds_read_b128 v[232:235], v230 offset:4704
	v_mfma_f32_32x32x16_bf16 v[66:81], v[214:217], v[248:251], v[66:81]
	ds_read_b128 v[214:217], v231 offset:23136
	s_waitcnt lgkmcnt(5)
	v_mfma_f32_32x32x16_bf16 v[50:65], v[218:221], v[244:247], v[50:65]
	v_mfma_f32_32x32x16_bf16 v[18:33], v[218:221], v[248:251], v[18:33]
	ds_read_b128 v[218:221], v231 offset:27744
	s_waitcnt lgkmcnt(5)
	v_mfma_f32_32x32x16_bf16 v[34:49], v[222:225], v[244:247], v[34:49]
	v_mfma_f32_32x32x16_bf16 v[2:17], v[222:225], v[248:251], v[2:17]
	ds_read_b128 v[222:225], v231 offset:32352
	s_waitcnt lgkmcnt(4)
	v_mfma_f32_32x32x16_bf16 v[114:129], v[210:213], v[252:255], v[114:129]
	s_waitcnt lgkmcnt(3)
	v_mfma_f32_32x32x16_bf16 v[82:97], v[210:213], v[232:235], v[82:97]
	s_waitcnt lgkmcnt(2)
	v_mfma_f32_32x32x16_bf16 v[98:113], v[214:217], v[252:255], v[98:113]
	v_mfma_f32_32x32x16_bf16 v[66:81], v[214:217], v[232:235], v[66:81]
	s_waitcnt lgkmcnt(1)
	v_mfma_f32_32x32x16_bf16 v[50:65], v[218:221], v[252:255], v[50:65]
	v_mfma_f32_32x32x16_bf16 v[18:33], v[218:221], v[232:235], v[18:33]
	s_waitcnt lgkmcnt(0)
	v_mfma_f32_32x32x16_bf16 v[34:49], v[222:225], v[252:255], v[34:49]
	v_mfma_f32_32x32x16_bf16 v[2:17], v[222:225], v[232:235], v[2:17]
	s_setprio 0
	s_add_u32 s22, s22, 0x80
	s_addc_u32 s23, s23, 0
	s_cmpk_eq_i32 s22, 0x780
	s_cbranch_scc0 .LBB0_280
	v_mov_b32_e32 v210, 64
	v_xor_b32_e32 v211, 32, v209
	v_xor_b32_e32 v212, 16, v209
	v_xor_b32_e32 v213, 8, v209
	v_xor_b32_e32 v214, 4, v209
	v_xor_b32_e32 v215, 2, v209
	v_xor_b32_e32 v216, 1, v209
	v_mov_b32_e32 v217, 2
	v_bfrev_b32_e32 v218, 32
	v_bfrev_b32_e32 v219, 64
	v_mov_b32_e32 v220, 0xff800000
	v_mov_b32_e32 v221, 0x80
	v_mov_b32_e32 v222, 0x200
	v_mov_b32_e32 v223, 0x2000
	v_mov_b32_e32 v224, 0x461c4000
	v_mov_b32_e32 v225, 0x63
	v_mov_b64_e32 v[178:179], 0xf500000
	s_setprio 0
	s_barrier
	s_waitcnt vmcnt(11)
	ds_write_b128 v186, v[142:145]
	s_waitcnt vmcnt(10)
	ds_write_b128 v186, v[134:137] offset:4608
	s_waitcnt vmcnt(9)
	ds_write_b128 v186, v[130:133] offset:9216
	s_waitcnt vmcnt(8)
	ds_write_b128 v186, v[146:149] offset:13824
	s_waitcnt vmcnt(7)
	ds_write_b128 v186, v[138:141] offset:18432
	s_waitcnt vmcnt(6)
	ds_write_b128 v186, v[150:153] offset:23040
	s_waitcnt vmcnt(5)
	ds_write_b128 v186, v[154:157] offset:27648
	s_waitcnt vmcnt(4)
	ds_write_b128 v186, v[158:161] offset:32256
	s_waitcnt vmcnt(3)
	ds_write_b128 v186, v[162:165] offset:36864
	s_waitcnt vmcnt(2)
	ds_write_b128 v186, v[166:169] offset:41472
	s_waitcnt vmcnt(1)
	ds_write_b128 v186, v[170:173] offset:46080
	s_waitcnt vmcnt(0)
	ds_write_b128 v186, v[174:177] offset:50688
	s_waitcnt lgkmcnt(0)
	s_setprio 0
	s_barrier
	s_setprio 1
	ds_read_b128 v[130:133], v230 offset:4608
	ds_read_b128 v[134:137], v231 offset:23040
	ds_read_b128 v[138:141], v230
	ds_read_b128 v[142:145], v230 offset:32
	ds_read_b128 v[146:149], v231 offset:18432
	ds_read_b128 v[150:153], v231 offset:18464
	s_waitcnt lgkmcnt(1)
	v_mfma_f32_32x32x16_bf16 v[114:129], v[146:149], v[138:141], v[114:129]
	v_mfma_f32_32x32x16_bf16 v[82:97], v[146:149], v[130:133], v[82:97]
	v_mfma_f32_32x32x16_bf16 v[98:113], v[134:137], v[138:141], v[98:113]
	v_mfma_f32_32x32x16_bf16 v[66:81], v[134:137], v[130:133], v[66:81]
	ds_read_b128 v[134:137], v231 offset:27648
	ds_read_b128 v[146:149], v231 offset:32256
	s_waitcnt lgkmcnt(1)
	v_mfma_f32_32x32x16_bf16 v[50:65], v[134:137], v[138:141], v[50:65]
	v_mfma_f32_32x32x16_bf16 v[18:33], v[134:137], v[130:133], v[18:33]
	s_waitcnt lgkmcnt(0)
	v_mfma_f32_32x32x16_bf16 v[2:17], v[146:149], v[130:133], v[2:17]
	ds_read_b128 v[130:133], v230 offset:4640
	ds_read_b128 v[134:137], v231 offset:23072
	v_mfma_f32_32x32x16_bf16 v[34:49], v[146:149], v[138:141], v[34:49]
	s_waitcnt lgkmcnt(0)
	v_mfma_f32_32x32x16_bf16 v[98:113], v[134:137], v[142:145], v[98:113]
	v_mfma_f32_32x32x16_bf16 v[66:81], v[134:137], v[130:133], v[66:81]
	ds_read_b128 v[134:137], v231 offset:27680
	ds_read_b128 v[138:141], v231 offset:32288
	v_mfma_f32_32x32x16_bf16 v[114:129], v[150:153], v[142:145], v[114:129]
	v_mfma_f32_32x32x16_bf16 v[82:97], v[150:153], v[130:133], v[82:97]
	s_waitcnt lgkmcnt(1)
	v_mfma_f32_32x32x16_bf16 v[50:65], v[134:137], v[142:145], v[50:65]
	v_mfma_f32_32x32x16_bf16 v[18:33], v[134:137], v[130:133], v[18:33]
	s_waitcnt lgkmcnt(0)
	v_mfma_f32_32x32x16_bf16 v[34:49], v[138:141], v[142:145], v[34:49]
	v_mfma_f32_32x32x16_bf16 v[2:17], v[138:141], v[130:133], v[2:17]
	ds_read_b128 v[130:133], v230 offset:64
	ds_read_b128 v[134:137], v230 offset:4672
	ds_read_b128 v[138:141], v231 offset:18496
	ds_read_b128 v[142:145], v231 offset:23104
	s_waitcnt lgkmcnt(1)
	v_mfma_f32_32x32x16_bf16 v[114:129], v[138:141], v[130:133], v[114:129]
	v_mfma_f32_32x32x16_bf16 v[82:97], v[138:141], v[134:137], v[82:97]
	s_waitcnt lgkmcnt(0)
	v_mfma_f32_32x32x16_bf16 v[98:113], v[142:145], v[130:133], v[98:113]
	v_mfma_f32_32x32x16_bf16 v[66:81], v[142:145], v[134:137], v[66:81]
	ds_read_b128 v[138:141], v231 offset:27712
	ds_read_b128 v[142:145], v231 offset:32320
	s_waitcnt lgkmcnt(1)
	v_mfma_f32_32x32x16_bf16 v[50:65], v[138:141], v[130:133], v[50:65]
	v_mfma_f32_32x32x16_bf16 v[18:33], v[138:141], v[134:137], v[18:33]
	s_waitcnt lgkmcnt(0)
	v_mfma_f32_32x32x16_bf16 v[34:49], v[142:145], v[130:133], v[34:49]
	v_mfma_f32_32x32x16_bf16 v[2:17], v[142:145], v[134:137], v[2:17]
	ds_read_b128 v[130:133], v230 offset:96
	ds_read_b128 v[134:137], v230 offset:4704
	ds_read_b128 v[138:141], v231 offset:18528
	ds_read_b128 v[142:145], v231 offset:23136
	s_waitcnt lgkmcnt(1)
	v_mfma_f32_32x32x16_bf16 v[114:129], v[138:141], v[130:133], v[114:129]
	v_mfma_f32_32x32x16_bf16 v[82:97], v[138:141], v[134:137], v[82:97]
	s_waitcnt lgkmcnt(0)
	v_mfma_f32_32x32x16_bf16 v[98:113], v[142:145], v[130:133], v[98:113]
	v_mfma_f32_32x32x16_bf16 v[66:81], v[142:145], v[134:137], v[66:81]
	ds_read_b128 v[138:141], v231 offset:27744
	ds_read_b128 v[142:145], v231 offset:32352
	s_waitcnt lgkmcnt(0)
	s_setprio 0
	s_barrier
	v_mfma_f32_32x32x16_bf16 v[18:33], v[138:141], v[134:137], v[18:33]
	v_mfma_f32_32x32x16_bf16 v[2:17], v[142:145], v[134:137], v[2:17]
	v_add_u32_e32 v136, s2, v187
	v_ashrrev_i32_e32 v134, 11, v136
	v_and_b32_e32 v157, 0x7c0, v136
	v_mfma_f32_32x32x16_bf16 v[50:65], v[138:141], v[130:133], v[50:65]
	v_or_b32_e32 v138, s3, v191
	v_ashrrev_i32_e32 v139, 31, v138
	v_ashrrev_i32_e32 v159, 6, v138
	v_mfma_f32_32x32x16_bf16 v[34:49], v[142:145], v[130:133], v[34:49]
	v_or_b32_e32 v132, v136, v189
	v_ashrrev_i32_e32 v133, 31, v132
	v_lshl_add_u64 v[142:143], v[132:133], 2, s[40:41]
	global_load_dword v132, v[142:143], off
	v_lshlrev_b32_e32 v130, 12, v134
	v_ashrrev_i32_e32 v131, 31, v130
	v_lshl_add_u64 v[130:131], v[130:131], 2, s[42:43]
	v_lshl_add_u64 v[130:131], v[138:139], 2, v[130:131]
	v_lshl_add_u64 v[140:141], v[130:131], 0, v[0:1]
	s_waitcnt vmcnt(0)
	v_fmamk_f32 v132, v132, 0x3a800000, v208
	v_cmp_gt_f32_e32 vcc, s84, v132
	v_mul_f32_e32 v133, 0x4b800000, v132
	s_nop 0
	v_cndmask_b32_e32 v132, v132, v133, vcc
	v_rsq_f32_e32 v132, v132
	s_nop 0
	v_mul_f32_e32 v133, 0x45800000, v132
	v_cndmask_b32_e32 v156, v132, v133, vcc
	global_load_dword v132, v[142:143], off offset:128
	s_waitcnt vmcnt(0)
	v_fmamk_f32 v132, v132, 0x3a800000, v208
	v_cmp_gt_f32_e32 vcc, s84, v132
	v_mul_f32_e32 v133, 0x4b800000, v132
	s_nop 0
	v_cndmask_b32_e32 v132, v132, v133, vcc
	v_rsq_f32_e32 v132, v132
	s_nop 0
	v_mul_f32_e32 v133, 0x45800000, v132
	v_cndmask_b32_e32 v158, v132, v133, vcc
	global_load_dwordx4 v[150:153], v[140:141], off
	global_load_dwordx4 v[160:163], v[140:141], off offset:32
	global_load_dwordx4 v[164:167], v[140:141], off offset:64
	global_load_dwordx4 v[130:133], v[140:141], off offset:96
	global_load_dwordx4 v[168:171], v[140:141], off offset:128
	v_cmp_lt_i32_e32 vcc, 31, v159
	s_waitcnt vmcnt(4)
	v_pk_fma_f32 v[148:149], v[114:115], v[156:157], v[150:151] op_sel_hi:[1,0,1]
	v_pk_fma_f32 v[114:115], v[82:83], v[158:159], v[150:151] op_sel_hi:[1,0,1]
	v_pk_fma_f32 v[150:151], v[116:117], v[156:157], v[152:153] op_sel_hi:[1,0,1]
	v_pk_fma_f32 v[116:117], v[84:85], v[158:159], v[152:153] op_sel_hi:[1,0,1]
	s_waitcnt vmcnt(0)
	v_pk_fma_f32 v[144:145], v[98:99], v[156:157], v[168:169] op_sel_hi:[1,0,1]
	v_pk_fma_f32 v[98:99], v[66:67], v[158:159], v[168:169] op_sel_hi:[1,0,1]
	v_pk_fma_f32 v[146:147], v[100:101], v[156:157], v[170:171] op_sel_hi:[1,0,1]
	v_pk_fma_f32 v[100:101], v[68:69], v[158:159], v[170:171] op_sel_hi:[1,0,1]
	global_load_dwordx4 v[66:69], v[140:141], off offset:160
	v_pk_fma_f32 v[152:153], v[118:119], v[156:157], v[160:161] op_sel_hi:[1,0,1]
	v_pk_fma_f32 v[154:155], v[120:121], v[156:157], v[162:163] op_sel_hi:[1,0,1]
	v_pk_fma_f32 v[122:123], v[122:123], v[156:157], v[164:165] op_sel_hi:[1,0,1]
	v_pk_fma_f32 v[124:125], v[124:125], v[156:157], v[166:167] op_sel_hi:[1,0,1]
	v_pk_fma_f32 v[126:127], v[126:127], v[156:157], v[130:131] op_sel_hi:[1,0,1]
	v_pk_fma_f32 v[84:85], v[94:95], v[158:159], v[130:131] op_sel_hi:[1,0,1]
	v_pk_fma_f32 v[128:129], v[128:129], v[156:157], v[132:133] op_sel_hi:[1,0,1]
	s_waitcnt vmcnt(0)
	v_pk_fma_f32 v[118:119], v[102:103], v[156:157], v[66:67] op_sel_hi:[1,0,1]
	v_pk_fma_f32 v[70:71], v[70:71], v[158:159], v[66:67] op_sel_hi:[1,0,1]
	v_pk_fma_f32 v[120:121], v[104:105], v[156:157], v[68:69] op_sel_hi:[1,0,1]
	v_pk_fma_f32 v[72:73], v[72:73], v[158:159], v[68:69] op_sel_hi:[1,0,1]
	global_load_dwordx4 v[66:69], v[140:141], off offset:192
	v_pk_fma_f32 v[102:103], v[86:87], v[158:159], v[160:161] op_sel_hi:[1,0,1]
	v_pk_fma_f32 v[104:105], v[88:89], v[158:159], v[162:163] op_sel_hi:[1,0,1]
	v_pk_fma_f32 v[88:89], v[90:91], v[158:159], v[164:165] op_sel_hi:[1,0,1]
	v_pk_fma_f32 v[90:91], v[92:93], v[158:159], v[166:167] op_sel_hi:[1,0,1]
	v_pk_fma_f32 v[86:87], v[96:97], v[158:159], v[132:133] op_sel_hi:[1,0,1]
	s_waitcnt vmcnt(0)
	v_pk_fma_f32 v[106:107], v[106:107], v[156:157], v[66:67] op_sel_hi:[1,0,1]
	v_pk_fma_f32 v[66:67], v[74:75], v[158:159], v[66:67] op_sel_hi:[1,0,1]
	v_pk_fma_f32 v[108:109], v[108:109], v[156:157], v[68:69] op_sel_hi:[1,0,1]
	v_pk_fma_f32 v[68:69], v[76:77], v[158:159], v[68:69] op_sel_hi:[1,0,1]
	global_load_dwordx4 v[74:77], v[140:141], off offset:224
	s_waitcnt vmcnt(0)
	v_pk_fma_f32 v[110:111], v[110:111], v[156:157], v[74:75] op_sel_hi:[1,0,1]
	v_pk_fma_f32 v[82:83], v[78:79], v[158:159], v[74:75] op_sel_hi:[1,0,1]
	v_pk_fma_f32 v[94:95], v[112:113], v[156:157], v[76:77] op_sel_hi:[1,0,1]
	v_pk_fma_f32 v[80:81], v[80:81], v[158:159], v[76:77] op_sel_hi:[1,0,1]
	s_and_saveexec_b64 s[2:3], vcc
	s_xor_b64 s[2:3], exec, s[2:3]
	s_cbranch_execz .LBB0_287
	v_cmp_lt_u32_e32 vcc, 47, v159
	v_cvt_pk_bf16_f32 v74, v152, s0
	v_cvt_pk_bf16_f32 v75, v153, s0
	v_cvt_pk_bf16_f32 v76, v154, s0
	v_cvt_pk_bf16_f32 v77, v155, s0
	s_and_saveexec_b64 s[8:9], vcc
	s_xor_b64 s[22:23], exec, s[8:9]
	s_cbranch_execz .LBB0_284
	s_mov_b32 s8, 0x5040100
	v_cvt_pk_bf16_f32 v93, v150, v151
	v_cvt_pk_bf16_f32 v92, v148, v149
	v_perm_b32 v77, v77, v76, s8
	v_perm_b32 v76, v75, v74, s8
	ds_write2_b64 v226, v[92:93], v[76:77] offset1:2
	v_cvt_pk_bf16_f32 v75, v124, v125
	v_cvt_pk_bf16_f32 v74, v122, v123
	v_cvt_pk_bf16_f32 v77, v128, v129
	v_cvt_pk_bf16_f32 v76, v126, v127
	ds_write2_b64 v226, v[74:75], v[76:77] offset0:4 offset1:6
	v_cvt_pk_bf16_f32 v75, v146, v147
	v_cvt_pk_bf16_f32 v74, v144, v145
	v_cvt_pk_bf16_f32 v77, v120, v121
	v_cvt_pk_bf16_f32 v76, v118, v119
	ds_write2_b64 v226, v[74:75], v[76:77] offset0:8 offset1:10
	v_cvt_pk_bf16_f32 v75, v108, v109
	v_cvt_pk_bf16_f32 v74, v106, v107
	v_cvt_pk_bf16_f32 v77, v94, v95
	v_cvt_pk_bf16_f32 v76, v110, v111
	v_ashrrev_i32_e32 v137, 31, v136
	ds_write2_b64 v226, v[74:75], v[76:77] offset0:12 offset1:14
	v_cvt_pk_bf16_f32 v75, v116, v117
	v_cvt_pk_bf16_f32 v74, v114, v115
	v_cvt_pk_bf16_f32 v77, v104, v105
	v_cvt_pk_bf16_f32 v76, v102, v103
	v_add_u32_e32 v92, 0x1000, v226
	v_lshlrev_b64 v[78:79], 11, v[136:137]
	ds_write2_b64 v92, v[74:75], v[76:77] offset0:64 offset1:66
	v_cvt_pk_bf16_f32 v75, v90, v91
	v_cvt_pk_bf16_f32 v74, v88, v89
	v_cvt_pk_bf16_f32 v77, v86, v87
	v_cvt_pk_bf16_f32 v76, v84, v85
	v_lshl_add_u64 v[78:79], s[38:39], 0, v[78:79]
	v_mov_b32_e32 v139, v1
	ds_write2_b64 v92, v[74:75], v[76:77] offset0:68 offset1:70
	v_cvt_pk_bf16_f32 v75, v100, v101
	v_cvt_pk_bf16_f32 v74, v98, v99
	v_cvt_pk_bf16_f32 v73, v72, v73
	v_cvt_pk_bf16_f32 v72, v70, v71
	v_cvt_pk_bf16_f32 v69, v68, v69
	v_cvt_pk_bf16_f32 v68, v66, v67
	v_cvt_pk_bf16_f32 v67, v80, v81
	v_cvt_pk_bf16_f32 v66, v82, v83
	v_lshl_add_u64 v[78:79], v[138:139], 1, v[78:79]
	ds_write2_b64 v92, v[74:75], v[72:73] offset0:72 offset1:74
	ds_write2_b64 v92, v[68:69], v[66:67] offset0:76 offset1:78
	v_lshlrev_b32_e32 v66, 1, v188
	v_mov_b32_e32 v67, v1
	v_lshl_add_u64 v[66:67], v[78:79], 0, v[66:67]
	v_lshlrev_b32_e32 v68, 1, v180
	v_mov_b32_e32 v69, v1
	v_lshl_add_u64 v[74:75], v[66:67], 0, v[68:69]
	ds_read_b128 v[66:69], v227
	ds_read_b128 v[70:73], v227 offset:1152
	s_mov_b32 s8, 0x7ffe000
	v_add_co_u32_e32 v76, vcc, s8, v74
	s_mov_b32 s8, 0x8002000
	s_nop 0
	v_addc_co_u32_e32 v77, vcc, 0, v75, vcc
	s_waitcnt lgkmcnt(1)
	global_store_dwordx4 v[76:77], v[66:69], off offset:2048
	s_nop 1
	v_add_co_u32_e32 v66, vcc, s8, v74
	s_mov_b32 s8, 0x8006000
	s_nop 0
	v_addc_co_u32_e32 v67, vcc, 0, v75, vcc
	s_waitcnt lgkmcnt(0)
	global_store_dwordx4 v[66:67], v[70:73], off offset:2048
	ds_read_b128 v[66:69], v227 offset:2304
	ds_read_b128 v[70:73], v227 offset:3456
	v_add_co_u32_e32 v76, vcc, s8, v74
	s_mov_b32 s8, 0x800a000
	s_nop 0
	v_addc_co_u32_e32 v77, vcc, 0, v75, vcc
	s_waitcnt lgkmcnt(1)
	global_store_dwordx4 v[76:77], v[66:69], off offset:2048
	s_nop 1
	v_add_co_u32_e32 v66, vcc, s8, v74
	s_mov_b32 s8, 0x800e000
	s_nop 0
	v_addc_co_u32_e32 v67, vcc, 0, v75, vcc
	s_waitcnt lgkmcnt(0)
	global_store_dwordx4 v[66:67], v[70:73], off offset:2048
	ds_read_b128 v[66:69], v227 offset:4608
	ds_read_b128 v[70:73], v227 offset:5760
	v_add_co_u32_e32 v76, vcc, s8, v74
	s_nop 1
	v_addc_co_u32_e32 v77, vcc, 0, v75, vcc
	s_waitcnt lgkmcnt(1)
	global_store_dwordx4 v[76:77], v[66:69], off offset:2048
	s_nop 1
	v_add_co_u32_e32 v66, vcc, 0x8012000, v74
	s_nop 1
	v_addc_co_u32_e32 v67, vcc, 0, v75, vcc
	s_waitcnt lgkmcnt(0)
	global_store_dwordx4 v[66:67], v[70:73], off offset:2048
	ds_read_b128 v[66:69], v227 offset:6912
	ds_read_b128 v[70:73], v227 offset:8064
	v_add_co_u32_e32 v76, vcc, 0x8016000, v74
	s_nop 1
	v_addc_co_u32_e32 v77, vcc, 0, v75, vcc
	s_waitcnt lgkmcnt(1)
	global_store_dwordx4 v[76:77], v[66:69], off offset:2048
	s_nop 1
	v_add_co_u32_e32 v66, vcc, 0x801a000, v74
	s_nop 1
	v_addc_co_u32_e32 v67, vcc, 0, v75, vcc
	s_waitcnt lgkmcnt(0)
	global_store_dwordx4 v[66:67], v[70:73], off offset:2048

.LBB0_314:
	s_barrier
	s_waitcnt vmcnt(9)
	ds_write_b128 v186, v[142:145]
	ds_write_b128 v186, v[134:137] offset:4608
	ds_write_b128 v186, v[130:133] offset:9216
	s_waitcnt vmcnt(7)
	ds_write_b128 v186, v[146:149] offset:13824
	ds_write_b128 v186, v[138:141] offset:18432
	s_waitcnt vmcnt(6)
	ds_write_b128 v186, v[150:153] offset:23040
	s_waitcnt vmcnt(5)
	ds_write_b128 v186, v[154:157] offset:27648
	s_waitcnt vmcnt(4)
	ds_write_b128 v186, v[158:161] offset:32256
	s_waitcnt vmcnt(3)
	ds_write_b128 v186, v[162:165] offset:36864
	s_waitcnt vmcnt(2)
	ds_write_b128 v186, v[166:169] offset:41472
	s_waitcnt vmcnt(1)
	ds_write_b128 v186, v[170:173] offset:46080
	s_waitcnt vmcnt(0)
	ds_write_b128 v186, v[174:177] offset:50688
	s_waitcnt lgkmcnt(0)
	s_barrier
	s_setprio 2
	s_mov_b32 vcc_hi, 0
	ds_read_b128 v[244:247], v229
	ds_read_b128 v[210:213], v230 offset:18432
	ds_read_b128 v[248:251], v229 offset:4608
	ds_read_b128 v[214:217], v230 offset:23040
	ds_read_b128 v[218:221], v230 offset:27648
	ds_read_b128 v[222:225], v230 offset:32256
	s_waitcnt lgkmcnt(4)
	v_mfma_f32_32x32x16_bf16 v[114:129], v[210:213], v[244:247], v[114:129]
	s_add_u32 vcc_lo, s22, 0xd400080
	v_lshl_add_u64 v[240:241], v[202:203], 0, vcc
	global_load_dwordx4 v[142:145], v[240:241], off
	ds_read_b128 v[252:255], v229 offset:32
	s_waitcnt lgkmcnt(4)
	v_mfma_f32_32x32x16_bf16 v[98:113], v[210:213], v[248:251], v[98:113]
	s_add_u32 vcc_lo, s22, 0xd410080
	v_lshl_add_u64 v[178:179], v[202:203], 0, vcc
	global_load_dwordx4 v[134:137], v[178:179], off
	ds_read_b128 v[210:213], v230 offset:18464
	s_waitcnt lgkmcnt(4)
	v_mfma_f32_32x32x16_bf16 v[82:97], v[214:217], v[244:247], v[82:97]
	s_add_u32 vcc_lo, s22, 0xd420080
	v_lshl_add_u64 v[240:241], v[202:203], 0, vcc
	global_load_dwordx4 v[130:133], v[240:241], off
	ds_read_b128 v[232:235], v229 offset:4640
	v_mfma_f32_32x32x16_bf16 v[66:81], v[214:217], v[248:251], v[66:81]
	s_add_u32 vcc_lo, s22, 0xd430080
	v_lshl_add_u64 v[178:179], v[202:203], 0, vcc
	global_load_dwordx4 v[146:149], v[178:179], off
	ds_read_b128 v[214:217], v230 offset:23072
	s_waitcnt lgkmcnt(5)
	v_mfma_f32_32x32x16_bf16 v[50:65], v[218:221], v[244:247], v[50:65]
	s_add_u32 vcc_lo, s22, 0xa000080
	v_lshl_add_u64 v[240:241], v[200:201], 0, vcc
	global_load_dwordx4 v[138:141], v[240:241], off
	v_mfma_f32_32x32x16_bf16 v[34:49], v[218:221], v[248:251], v[34:49]
	s_add_u32 vcc_lo, s22, 0xa010080
	v_lshl_add_u64 v[178:179], v[200:201], 0, vcc
	global_load_dwordx4 v[150:153], v[178:179], off
	ds_read_b128 v[218:221], v230 offset:27680
	s_waitcnt lgkmcnt(5)
	v_mfma_f32_32x32x16_bf16 v[18:33], v[222:225], v[244:247], v[18:33]
	s_add_u32 vcc_lo, s22, 0xa020080
	v_lshl_add_u64 v[240:241], v[200:201], 0, vcc
	global_load_dwordx4 v[154:157], v[240:241], off
	v_mfma_f32_32x32x16_bf16 v[2:17], v[222:225], v[248:251], v[2:17]
	s_add_u32 vcc_lo, s22, 0xa030080
	v_lshl_add_u64 v[178:179], v[200:201], 0, vcc
	global_load_dwordx4 v[158:161], v[178:179], off
	ds_read_b128 v[222:225], v230 offset:32288
	s_waitcnt lgkmcnt(4)
	v_mfma_f32_32x32x16_bf16 v[114:129], v[210:213], v[252:255], v[114:129]
	s_add_u32 vcc_lo, s22, 0xa040080
	v_lshl_add_u64 v[240:241], v[200:201], 0, vcc
	global_load_dwordx4 v[162:165], v[240:241], off
	ds_read_b128 v[244:247], v229 offset:64
	s_waitcnt lgkmcnt(4)
	v_mfma_f32_32x32x16_bf16 v[98:113], v[210:213], v[232:235], v[98:113]
	s_add_u32 vcc_lo, s22, 0xa050080
	v_lshl_add_u64 v[178:179], v[200:201], 0, vcc
	global_load_dwordx4 v[166:169], v[178:179], off
	ds_read_b128 v[210:213], v230 offset:18496
	s_waitcnt lgkmcnt(4)
	v_mfma_f32_32x32x16_bf16 v[82:97], v[214:217], v[252:255], v[82:97]
	s_add_u32 vcc_lo, s22, 0xa060080
	v_lshl_add_u64 v[240:241], v[200:201], 0, vcc
	global_load_dwordx4 v[170:173], v[240:241], off
	ds_read_b128 v[248:251], v229 offset:4672
	v_mfma_f32_32x32x16_bf16 v[66:81], v[214:217], v[232:235], v[66:81]
	s_add_u32 vcc_lo, s22, 0xa070080
	v_lshl_add_u64 v[178:179], v[200:201], 0, vcc
	global_load_dwordx4 v[174:177], v[178:179], off
	ds_read_b128 v[214:217], v230 offset:23104
	s_waitcnt lgkmcnt(5)
	v_mfma_f32_32x32x16_bf16 v[50:65], v[218:221], v[252:255], v[50:65]
	v_mfma_f32_32x32x16_bf16 v[34:49], v[218:221], v[232:235], v[34:49]
	ds_read_b128 v[218:221], v230 offset:27712
	s_waitcnt lgkmcnt(5)
	v_mfma_f32_32x32x16_bf16 v[18:33], v[222:225], v[252:255], v[18:33]
	v_mfma_f32_32x32x16_bf16 v[2:17], v[222:225], v[232:235], v[2:17]
	ds_read_b128 v[222:225], v230 offset:32320
	s_waitcnt lgkmcnt(4)
	v_mfma_f32_32x32x16_bf16 v[114:129], v[210:213], v[244:247], v[114:129]
	ds_read_b128 v[252:255], v229 offset:96
	s_waitcnt lgkmcnt(4)
	v_mfma_f32_32x32x16_bf16 v[98:113], v[210:213], v[248:251], v[98:113]
	ds_read_b128 v[210:213], v230 offset:18528
	s_waitcnt lgkmcnt(4)
	v_mfma_f32_32x32x16_bf16 v[82:97], v[214:217], v[244:247], v[82:97]
	ds_read_b128 v[232:235], v229 offset:4704
	v_mfma_f32_32x32x16_bf16 v[66:81], v[214:217], v[248:251], v[66:81]
	ds_read_b128 v[214:217], v230 offset:23136
	s_waitcnt lgkmcnt(5)
	v_mfma_f32_32x32x16_bf16 v[50:65], v[218:221], v[244:247], v[50:65]
	v_mfma_f32_32x32x16_bf16 v[34:49], v[218:221], v[248:251], v[34:49]
	ds_read_b128 v[218:221], v230 offset:27744
	s_waitcnt lgkmcnt(5)
	v_mfma_f32_32x32x16_bf16 v[18:33], v[222:225], v[244:247], v[18:33]
	v_mfma_f32_32x32x16_bf16 v[2:17], v[222:225], v[248:251], v[2:17]
	ds_read_b128 v[222:225], v230 offset:32352
	s_waitcnt lgkmcnt(4)
	v_mfma_f32_32x32x16_bf16 v[114:129], v[210:213], v[252:255], v[114:129]
	s_waitcnt lgkmcnt(3)
	v_mfma_f32_32x32x16_bf16 v[98:113], v[210:213], v[232:235], v[98:113]
	s_waitcnt lgkmcnt(2)
	v_mfma_f32_32x32x16_bf16 v[82:97], v[214:217], v[252:255], v[82:97]
	v_mfma_f32_32x32x16_bf16 v[66:81], v[214:217], v[232:235], v[66:81]
	s_waitcnt lgkmcnt(1)
	v_mfma_f32_32x32x16_bf16 v[50:65], v[218:221], v[252:255], v[50:65]
	v_mfma_f32_32x32x16_bf16 v[34:49], v[218:221], v[232:235], v[34:49]
	s_waitcnt lgkmcnt(0)
	v_mfma_f32_32x32x16_bf16 v[18:33], v[222:225], v[252:255], v[18:33]
	v_mfma_f32_32x32x16_bf16 v[2:17], v[222:225], v[232:235], v[2:17]
	s_setprio 0
	s_add_u32 s22, s22, 0x80
	s_addc_u32 s23, s23, 0
	s_cmpk_eq_i32 s22, 0x780
	s_cbranch_scc0 .LBB0_314
	v_mov_b32_e32 v210, 64
	v_xor_b32_e32 v211, 32, v209
	v_xor_b32_e32 v212, 16, v209
	v_xor_b32_e32 v213, 8, v209
	v_xor_b32_e32 v214, 4, v209
	v_xor_b32_e32 v215, 2, v209
	v_xor_b32_e32 v216, 1, v209
	v_mov_b32_e32 v217, 2
	v_bfrev_b32_e32 v218, 32
	v_bfrev_b32_e32 v219, 64
	v_mov_b32_e32 v220, 0xff800000
	v_mov_b32_e32 v221, 0x80
	v_mov_b32_e32 v222, 0x200
	v_mov_b32_e32 v223, 0x2000
	v_mov_b32_e32 v224, 0x461c4000
	v_mov_b32_e32 v225, 0x63
	v_mov_b64_e32 v[178:179], 0xf500000
	s_setprio 0
	s_barrier
	s_waitcnt vmcnt(11)
	ds_write_b128 v186, v[142:145]
	s_waitcnt vmcnt(10)
	ds_write_b128 v186, v[134:137] offset:4608
	s_waitcnt vmcnt(9)
	ds_write_b128 v186, v[130:133] offset:9216
	s_waitcnt vmcnt(8)
	ds_write_b128 v186, v[146:149] offset:13824
	s_waitcnt vmcnt(7)
	ds_write_b128 v186, v[138:141] offset:18432
	s_waitcnt vmcnt(6)
	ds_write_b128 v186, v[150:153] offset:23040
	s_waitcnt vmcnt(5)
	ds_write_b128 v186, v[154:157] offset:27648
	s_waitcnt vmcnt(4)
	ds_write_b128 v186, v[158:161] offset:32256
	s_waitcnt vmcnt(3)
	ds_write_b128 v186, v[162:165] offset:36864
	s_waitcnt vmcnt(2)
	ds_write_b128 v186, v[166:169] offset:41472
	s_waitcnt vmcnt(1)
	ds_write_b128 v186, v[170:173] offset:46080
	s_waitcnt vmcnt(0)
	ds_write_b128 v186, v[174:177] offset:50688
	s_waitcnt lgkmcnt(0)
	s_setprio 0
	s_barrier
	s_setprio 1
	ds_read_b128 v[130:133], v230 offset:18432
	ds_read_b128 v[134:137], v229
	ds_read_b128 v[138:141], v229 offset:32
	ds_read_b128 v[142:145], v230 offset:18464
	ds_read_b128 v[146:149], v229 offset:4608
	ds_read_b128 v[150:153], v229 offset:4640
	s_waitcnt lgkmcnt(4)
	v_mfma_f32_32x32x16_bf16 v[114:129], v[130:133], v[134:137], v[114:129]
	v_add_u32_e32 v170, s2, v187
	v_or_b32_e32 v168, s3, v204
	v_ashrrev_i32_e32 v172, 11, v170
	v_ashrrev_i32_e32 v173, 6, v168
	v_lshlrev_b32_e32 v174, 12, v172
	v_or_b32_e32 v166, v170, v189
	v_and_b32_e32 v200, 0x7c0, v170
	s_waitcnt lgkmcnt(1)
	v_mfma_f32_32x32x16_bf16 v[98:113], v[130:133], v[146:149], v[98:113]
	ds_read_b128 v[130:133], v230 offset:23040
	ds_read_b128 v[154:157], v230 offset:23072
	v_cmp_gt_i32_e32 vcc, 47, v173
	v_ashrrev_i32_e32 v169, 31, v168
	v_ashrrev_i32_e32 v175, 31, v174
	v_ashrrev_i32_e32 v167, 31, v166
	v_lshlrev_b32_e32 v0, 2, v188
	s_waitcnt lgkmcnt(1)
	v_mfma_f32_32x32x16_bf16 v[82:97], v[130:133], v[134:137], v[82:97]
	v_mfma_f32_32x32x16_bf16 v[66:81], v[130:133], v[146:149], v[66:81]
	ds_read_b128 v[130:133], v230 offset:27648
	ds_read_b128 v[158:161], v230 offset:27680
	s_waitcnt lgkmcnt(1)
	v_mfma_f32_32x32x16_bf16 v[50:65], v[130:133], v[134:137], v[50:65]
	v_mfma_f32_32x32x16_bf16 v[34:49], v[130:133], v[146:149], v[34:49]
	ds_read_b128 v[130:133], v230 offset:32256
	ds_read_b128 v[162:165], v230 offset:32288
	s_waitcnt lgkmcnt(1)
	v_mfma_f32_32x32x16_bf16 v[18:33], v[130:133], v[134:137], v[18:33]
	v_mfma_f32_32x32x16_bf16 v[2:17], v[130:133], v[146:149], v[2:17]
	v_mfma_f32_32x32x16_bf16 v[114:129], v[142:145], v[138:141], v[114:129]
	v_mfma_f32_32x32x16_bf16 v[98:113], v[142:145], v[150:153], v[98:113]
	v_mfma_f32_32x32x16_bf16 v[82:97], v[154:157], v[138:141], v[82:97]
	v_mfma_f32_32x32x16_bf16 v[66:81], v[154:157], v[150:153], v[66:81]
	v_mfma_f32_32x32x16_bf16 v[50:65], v[158:161], v[138:141], v[50:65]
	v_mfma_f32_32x32x16_bf16 v[34:49], v[158:161], v[150:153], v[34:49]
	s_waitcnt lgkmcnt(0)
	v_mfma_f32_32x32x16_bf16 v[18:33], v[162:165], v[138:141], v[18:33]
	ds_read_b128 v[130:133], v230 offset:18496
	ds_read_b128 v[134:137], v229 offset:64
	ds_read_b128 v[138:141], v229 offset:96
	ds_read_b128 v[142:145], v230 offset:18528
	v_mfma_f32_32x32x16_bf16 v[2:17], v[162:165], v[150:153], v[2:17]
	ds_read_b128 v[146:149], v229 offset:4672
	ds_read_b128 v[150:153], v229 offset:4704
	s_waitcnt lgkmcnt(4)
	v_mfma_f32_32x32x16_bf16 v[114:129], v[130:133], v[134:137], v[114:129]
	s_waitcnt lgkmcnt(1)
	v_mfma_f32_32x32x16_bf16 v[98:113], v[130:133], v[146:149], v[98:113]
	ds_read_b128 v[130:133], v230 offset:23104
	ds_read_b128 v[154:157], v230 offset:23136
	s_waitcnt lgkmcnt(1)
	v_mfma_f32_32x32x16_bf16 v[82:97], v[130:133], v[134:137], v[82:97]
	v_mfma_f32_32x32x16_bf16 v[66:81], v[130:133], v[146:149], v[66:81]
	ds_read_b128 v[130:133], v230 offset:27712
	ds_read_b128 v[158:161], v230 offset:27744
	s_waitcnt lgkmcnt(1)
	v_mfma_f32_32x32x16_bf16 v[50:65], v[130:133], v[134:137], v[50:65]
	v_mfma_f32_32x32x16_bf16 v[34:49], v[130:133], v[146:149], v[34:49]
	ds_read_b128 v[130:133], v230 offset:32320
	ds_read_b128 v[162:165], v230 offset:32352
	s_waitcnt lgkmcnt(0)
	s_setprio 0
	s_barrier
	v_mfma_f32_32x32x16_bf16 v[18:33], v[130:133], v[134:137], v[18:33]
	v_mfma_f32_32x32x16_bf16 v[2:17], v[130:133], v[146:149], v[2:17]
	v_mfma_f32_32x32x16_bf16 v[114:129], v[142:145], v[138:141], v[114:129]
	v_mfma_f32_32x32x16_bf16 v[98:113], v[142:145], v[150:153], v[98:113]
	v_mfma_f32_32x32x16_bf16 v[82:97], v[154:157], v[138:141], v[82:97]
	v_mfma_f32_32x32x16_bf16 v[66:81], v[154:157], v[150:153], v[66:81]
	v_mfma_f32_32x32x16_bf16 v[50:65], v[158:161], v[138:141], v[50:65]
	v_mfma_f32_32x32x16_bf16 v[34:49], v[158:161], v[150:153], v[34:49]
	v_mfma_f32_32x32x16_bf16 v[18:33], v[162:165], v[138:141], v[18:33]
	v_mfma_f32_32x32x16_bf16 v[2:17], v[162:165], v[150:153], v[2:17]
	s_and_saveexec_b64 s[54:55], vcc
	s_cbranch_execz .LBB0_370
	v_lshl_add_u64 v[130:131], v[174:175], 2, s[42:43]
	v_lshl_add_u64 v[130:131], v[168:169], 2, v[130:131]
	v_lshl_add_u64 v[132:133], v[166:167], 2, s[40:41]
	v_lshl_add_u64 v[130:131], v[130:131], 0, v[0:1]
	global_load_dword v163, v[132:133], off
	global_load_dword v162, v[132:133], off offset:128
	global_load_dwordx4 v[158:161], v[130:131], off
	global_load_dwordx4 v[154:157], v[130:131], off offset:32
	global_load_dwordx4 v[150:153], v[130:131], off offset:64
	global_load_dwordx4 v[146:149], v[130:131], off offset:96
	global_load_dwordx4 v[142:145], v[130:131], off offset:128
	global_load_dwordx4 v[138:141], v[130:131], off offset:160
	global_load_dwordx4 v[134:137], v[130:131], off offset:192
	s_nop 0
	global_load_dwordx4 v[130:133], v[130:131], off offset:224
	v_cmp_lt_i32_e32 vcc, 7, v173
	s_and_saveexec_b64 s[2:3], vcc
	s_xor_b64 s[60:61], exec, s[2:3]
	s_cbranch_execz .LBB0_356
	s_movk_i32 s2, 0x200
	v_cmp_ne_u32_e32 vcc, s2, v168
	s_and_saveexec_b64 s[2:3], vcc
	s_xor_b64 s[2:3], exec, s[2:3]
	s_cbranch_execz .LBB0_353
	v_cmp_lt_u32_e32 vcc, 17, v173
	s_and_saveexec_b64 s[6:7], vcc
	s_xor_b64 s[62:63], exec, s[6:7]
	s_cbranch_execz .LBB0_350
	v_cmp_lt_u32_e32 vcc, 25, v173
	s_and_saveexec_b64 s[6:7], vcc
	s_xor_b64 s[64:65], exec, s[6:7]
	s_cbranch_execz .LBB0_347
	v_cmp_lt_u32_e32 vcc, 27, v173
	s_and_saveexec_b64 s[6:7], vcc
	s_xor_b64 s[66:67], exec, s[6:7]
	s_cbranch_execz .LBB0_344
	v_cmp_lt_u32_e32 vcc, 29, v173
	s_and_saveexec_b64 s[6:7], vcc
	s_xor_b64 s[68:69], exec, s[6:7]
	s_cbranch_execz .LBB0_341
	v_cmp_lt_u32_e32 vcc, 31, v173
	s_and_saveexec_b64 s[6:7], vcc
	s_xor_b64 s[70:71], exec, s[6:7]
	s_cbranch_execz .LBB0_338
	v_cmp_lt_u32_e32 vcc, 33, v173
	s_and_saveexec_b64 s[6:7], vcc
	s_xor_b64 s[72:73], exec, s[6:7]
	s_cbranch_execz .LBB0_335
	v_cmp_lt_u32_e32 vcc, 35, v173
	s_and_saveexec_b64 s[6:7], vcc
	s_xor_b64 s[58:59], exec, s[6:7]
	s_cbranch_execz .LBB0_332
	v_cmp_lt_u32_e32 vcc, 37, v173
	s_and_saveexec_b64 s[6:7], vcc
	s_xor_b64 s[22:23], exec, s[6:7]
	s_cbranch_execz .LBB0_329
	s_movk_i32 s6, 0xb80
	v_cmp_ne_u32_e32 vcc, s6, v168
	v_mov_b32_e32 v171, 0
	v_mov_b64_e32 v[176:177], 0
	s_mov_b64 s[56:57], 0
	s_and_saveexec_b64 s[74:75], vcc
	s_cbranch_execz .LBB0_328
	v_ashrrev_i32_e32 v171, 31, v170
	v_lshlrev_b64 v[164:165], 10, v[170:171]
	v_lshl_add_u64 v[164:165], s[38:39], 0, v[164:165]
	v_mov_b32_e32 v176, v168
	v_mov_b32_e32 v177, v1
	v_lshl_add_u64 v[164:165], v[176:177], 1, v[164:165]
	s_mov_b64 s[6:7], 0x4ffed00
	s_mov_b64 s[56:57], exec
	v_lshl_add_u64 v[176:177], v[164:165], 0, s[6:7]
	v_mov_b32_e32 v171, 0x200

.LBB0_423:
	s_waitcnt vmcnt(0)
	s_setprio 0
	s_barrier
	s_mov_b64 s[18:19], exec
	v_readlane_b32 s2, v243, 1
	v_readlane_b32 s3, v243, 2
	s_and_b64 s[2:3], s[18:19], s[2:3]
	s_mov_b64 exec, s[2:3]
	s_cbranch_execz .LBB0_475
	s_waitcnt vmcnt(0) expcnt(0) lgkmcnt(0)
	ds_read_b32 v3, v1 offset:55296
	ds_read_b32 v2, v1 offset:55300
	s_waitcnt lgkmcnt(1)
	v_cmp_ne_u32_e32 vcc, 0, v3
	s_cbranch_vccnz .LBB0_439
	s_mov_b32 s4, 1
	s_branch .LBB0_427

.LBB0_475:
	s_or_b64 exec, exec, s[18:19]
	s_bitcmp0_b32 s12, 0
	s_mov_b64 s[2:3], -1
	s_waitcnt lgkmcnt(0)
	s_setprio 0
	s_barrier
	v_writelane_b32 v242, s12, 16
	s_cbranch_scc1 .LBB0_577
	v_readlane_b32 s6, v243, 3
	v_readlane_b32 s7, v243, 4
	s_load_dwordx2 s[4:5], s[6:7], 0x98
	s_mov_b64 s[2:3], s[6:7]
	s_waitcnt lgkmcnt(0)
	v_readlane_b32 s5, v243, 0
	s_mov_b32 s6, s12
	s_load_dwordx2 s[34:35], s[2:3], 0x90
	s_not_b32 s3, s5
	s_ashr_i32 s2, s6, 1
	s_add_i32 s6, s4, s3
	s_mov_b32 s13, 0
	s_waitcnt lgkmcnt(0)
	s_add_u32 s36, s34, 0x2000000
	s_addc_u32 s37, s35, 0
	s_ashr_i32 s3, s2, 31
	s_lshl_b64 s[2:3], s[2:3], 18
	s_add_u32 s2, s34, s2
	s_addc_u32 s3, s35, s3
	s_add_u32 s7, s2, 0xd100000
	s_addc_u32 s8, s3, 0
	s_add_u32 s9, s34, 0x4000000
	s_addc_u32 s10, s35, 0
	s_add_u32 s11, s34, 0x6000000
	s_addc_u32 s12, s35, 0
	s_add_u32 s18, s34, 0x8000000
	s_addc_u32 s19, s35, 0
	s_mov_b32 s2, 0
	s_branch .LBB0_478

.LBB0_495:
	s_andn2_saveexec_b64 s[2:3], s[2:3]
	v_lshlrev_b32_e64 v0, v38, -1
	v_not_b32_e32 v101, v0
	s_or_b64 exec, exec, s[2:3]
	s_lshl_b32 s22, s22, 6
	s_lshl_b64 s[2:3], s[76:77], 22
	s_add_u32 s16, s9, s2
	s_addc_u32 s17, s10, s3
	s_lshl_b32 s72, s22, 1
	v_mov_b32_e32 v0, v206
	s_add_u32 s16, s16, s72
	s_addc_u32 s17, s17, 0
	v_ashrrev_i32_e32 v18, 3, v0
	s_lshl_b32 s23, s76, 10
	v_lshlrev_b32_e32 v2, 3, v0
	v_ashrrev_i32_e32 v19, 31, v18
	s_or_b32 s76, s22, s23
	v_and_b32_e32 v4, 56, v2
	v_lshlrev_b64 v[20:21], 11, v[18:19]
	v_add_u32_e32 v14, 32, v18
	s_lshl_b64 s[22:23], s[76:77], 12
	v_lshl_add_u64 v[2:3], s[16:17], 0, v[20:21]
	v_lshlrev_b32_e32 v104, 1, v4
	v_mov_b32_e32 v105, v1
	v_ashrrev_i32_e32 v15, 31, v14
	s_add_u32 s38, s11, s22
	v_lshl_add_u64 v[22:23], v[2:3], 0, v[104:105]
	v_lshlrev_b64 v[2:3], 11, v[14:15]
	s_addc_u32 s39, s12, s23
	v_lshl_add_u64 v[2:3], s[16:17], 0, v[2:3]
	v_lshlrev_b64 v[24:25], 12, v[18:19]
	v_lshlrev_b64 v[14:15], 12, v[14:15]
	v_add_co_u32_e32 v30, vcc, s78, v22
	v_lshl_add_u64 v[6:7], v[2:3], 0, v[104:105]
	v_lshl_add_u64 v[10:11], s[38:39], 0, v[24:25]
	v_lshl_add_u64 v[14:15], s[38:39], 0, v[14:15]
	v_addc_co_u32_e32 v31, vcc, 0, v23, vcc
	s_setprio 0
	s_barrier
	global_load_dwordx4 v[2:5], v[22:23], off
	s_nop 0
	global_load_dwordx4 v[6:9], v[6:7], off
	v_lshl_add_u64 v[26:27], v[10:11], 0, v[104:105]
	v_lshl_add_u64 v[28:29], v[14:15], 0, v[104:105]
	v_add_co_u32_e32 v22, vcc, s79, v22
	global_load_dwordx4 v[10:13], v[26:27], off
	global_load_dwordx4 v[14:17], v[28:29], off
	v_addc_co_u32_e32 v23, vcc, 0, v23, vcc
	global_load_dwordx4 v[82:85], v[30:31], off
	global_load_dwordx4 v[86:89], v[22:23], off
	global_load_dwordx4 v[90:93], v[26:27], off offset:128
	global_load_dwordx4 v[94:97], v[28:29], off offset:128
	s_lshl_b32 s15, s15, 1
	s_or_b32 s76, s15, 1
	s_add_u32 s16, s34, s22
	s_addc_u32 s17, s35, s23
	s_lshl_b32 s14, s14, 3
	s_and_b32 s14, s14, 0x780
	v_lshlrev_b32_e32 v22, 1, v37
	v_lshrrev_b32_e32 v23, 1, v37
	s_add_u32 s14, s34, s14
	v_bfe_u32 v19, v37, 5, 1
	v_and_b32_e32 v26, 19, v37
	v_and_b32_e32 v22, 8, v22
	v_and_b32_e32 v23, 4, v23
	v_mul_lo_u32 v115, v18, s21
	v_lshl_add_u64 v[106:107], s[16:17], 0, v[24:25]
	s_addc_u32 s16, s35, 0
	v_lshlrev_b32_e32 v102, 3, v19
	v_or3_b32 v19, v23, v26, v22
	v_add_u32_e32 v18, v115, v104
	s_add_u32 s2, s14, s2
	v_lshrrev_b32_e32 v27, 2, v37
	v_and_or_b32 v28, v37, 63, 32
	v_add_u32_e32 v29, v103, v36
	v_mul_u32_u24_e32 v116, 0x90, v19
	s_addc_u32 s3, s16, s3
	v_mov_b32_e32 v19, v1
	v_and_b32_e32 v112, 8, v27
	v_mul_u32_u24_e32 v113, 0x90, v28
	v_sub_u32_e32 v114, v29, v102
	v_and_b32_e32 v0, 7, v0
	v_lshl_add_u64 v[108:109], s[2:3], 0, v[20:21]
	v_mov_b32_e32 v20, v1
	v_mov_b32_e32 v21, v1
	v_mov_b32_e32 v22, v1
	v_mov_b32_e32 v23, v1
	v_mov_b32_e32 v24, v1
	v_mov_b32_e32 v25, v1
	v_mov_b32_e32 v26, v1
	v_mov_b32_e32 v27, v1
	v_mov_b32_e32 v28, v1
	s_waitcnt vmcnt(7)
	ds_write_b128 v18, v[2:5]
	s_waitcnt vmcnt(6)
	ds_write_b128 v18, v[6:9] offset:4608
	s_waitcnt vmcnt(5)
	ds_write_b128 v18, v[10:13] offset:9216
	s_waitcnt vmcnt(4)
	ds_write_b128 v18, v[14:17] offset:13824
	v_mov_b32_e32 v18, v1
	v_mov_b32_e32 v29, v1
	v_mov_b32_e32 v30, v1
	v_mov_b32_e32 v31, v1
	v_mov_b32_e32 v32, v1
	v_mov_b32_e32 v33, v1
	v_mov_b64_e32 v[2:3], v[18:19]
	s_mov_b32 s73, 0
	v_mul_u32_u24_e32 v105, 0x90, v36
	v_and_b32_e32 v110, 0xffffff00, v103
	v_or_b32_e32 v111, 31, v103
	v_lshlrev_b32_e32 v0, 4, v0
	v_mov_b32_e32 v117, 0
	v_mov_b32_e32 v119, 0xff800000
	s_mov_b64 s[74:75], -1
	v_mov_b32_e32 v118, 0
	v_mov_b64_e32 v[4:5], v[20:21]
	v_mov_b64_e32 v[6:7], v[22:23]
	v_mov_b64_e32 v[8:9], v[24:25]
	v_mov_b64_e32 v[10:11], v[26:27]
	v_mov_b64_e32 v[12:13], v[28:29]
	v_mov_b64_e32 v[14:15], v[30:31]
	v_mov_b64_e32 v[16:17], v[32:33]
	s_mov_b32 s14, 0
	s_waitcnt lgkmcnt(0)
	s_setprio 0
	s_barrier
	s_and_b32 s16, s14, 1
	s_cmp_gt_u32 s14, s15
	s_cbranch_scc0 .LBB0_499
	s_branch .LBB0_500

.LBB0_506:
	s_or_b64 exec, exec, s[2:3]
	s_mulk_i32 s16, 0x4800
	v_cmp_lt_i32_e32 vcc, 1, v34
	s_and_saveexec_b64 s[2:3], vcc
	s_xor_b64 s[22:23], exec, s[2:3]
	s_cbranch_execz .LBB0_516
	v_cmp_lt_i32_e32 vcc, 2, v34
	s_and_saveexec_b64 s[2:3], vcc
	s_xor_b64 s[2:3], exec, s[2:3]
	s_cbranch_execz .LBB0_511
	v_add3_u32 v124, s16, v100, v116
	s_setprio 1
	ds_read_b128 v[34:37], v124
	ds_read_b128 v[38:41], v124 offset:16
	ds_read_b128 v[42:45], v124 offset:32
	ds_read_b128 v[46:49], v124 offset:48
	v_cmp_lt_i32_e32 vcc, v211, v210
	s_waitcnt lgkmcnt(3)
	v_mfma_f32_32x32x16_bf16 v[50:65], v[34:37], v[78:81], 0
	ds_read_b128 v[34:37], v124 offset:4608
	ds_read_b128 v[120:123], v124 offset:4624
	s_waitcnt lgkmcnt(4)
	v_mfma_f32_32x32x16_bf16 v[50:65], v[38:41], v[74:77], v[50:65]
	s_waitcnt lgkmcnt(3)
	v_mfma_f32_32x32x16_bf16 v[50:65], v[42:45], v[70:73], v[50:65]
	s_waitcnt lgkmcnt(2)
	v_mfma_f32_32x32x16_bf16 v[50:65], v[46:49], v[66:69], v[50:65]
	s_waitcnt lgkmcnt(1)
	v_mfma_f32_32x32x16_bf16 v[34:49], v[34:37], v[78:81], 0
	s_waitcnt lgkmcnt(0)
	v_mfma_f32_32x32x16_bf16 v[34:49], v[120:123], v[74:77], v[34:49]
	ds_read_b128 v[120:123], v124 offset:4640
	s_waitcnt lgkmcnt(0)
	v_mfma_f32_32x32x16_bf16 v[34:49], v[120:123], v[70:73], v[34:49]
	ds_read_b128 v[120:123], v124 offset:4656
	s_waitcnt lgkmcnt(0)
	v_mfma_f32_32x32x16_bf16 v[34:49], v[120:123], v[66:69], v[34:49]
	s_nop 1
	v_max3_f32 v120, v50, s85, v51
	v_max3_f32 v120, v120, v52, v53
	v_max3_f32 v120, v120, v54, v55
	v_max3_f32 v120, v120, v56, v57
	v_max3_f32 v120, v120, v58, v59
	v_max3_f32 v120, v120, v60, v61
	v_max3_f32 v120, v120, v62, v63
	v_max3_f32 v120, v120, v64, v65
	s_nop 1
	v_max3_f32 v120, v120, v34, v35
	v_max3_f32 v120, v120, v36, v37
	v_max3_f32 v120, v120, v38, v39
	v_max3_f32 v120, v120, v40, v41
	v_max3_f32 v120, v120, v42, v43
	v_max3_f32 v120, v120, v44, v45
	v_max3_f32 v120, v120, v46, v47
	v_cndmask_b32_e32 v121, v209, v211, vcc
	v_max3_f32 v120, v120, v48, v49
	v_lshlrev_b32_e32 v121, 2, v121
	ds_bpermute_b32 v121, v121, v120
	s_waitcnt lgkmcnt(0)
	v_max_f32_e32 v121, v121, v121
	v_max_f32_e32 v120, v120, v121
	v_mul_f32_e32 v120, 0x3e38aa3b, v120
	v_cndmask_b32_e64 v120, v220, v120, s[74:75]
	v_add_f32_e32 v121, 0x40c00000, v119
	v_cmp_gt_f32_e32 vcc, v120, v121
	s_cbranch_vccz .LBB0_510
	s_nop 0
	v_cndmask_b32_e32 v121, v119, v120, vcc
	v_sub_f32_e32 v119, v119, v121
	v_exp_f32_e32 v119, v119
	s_nop 0
	v_cndmask_b32_e32 v120, 1.0, v119, vcc
	v_mul_f32_e32 v117, v117, v120
	v_pk_mul_f32 v[32:33], v[32:33], v[120:121] op_sel_hi:[1,0]
	v_pk_mul_f32 v[30:31], v[30:31], v[120:121] op_sel_hi:[1,0]
	v_pk_mul_f32 v[28:29], v[28:29], v[120:121] op_sel_hi:[1,0]
	v_pk_mul_f32 v[26:27], v[26:27], v[120:121] op_sel_hi:[1,0]
	v_pk_mul_f32 v[24:25], v[24:25], v[120:121] op_sel_hi:[1,0]
	v_pk_mul_f32 v[22:23], v[22:23], v[120:121] op_sel_hi:[1,0]
	v_pk_mul_f32 v[20:21], v[20:21], v[120:121] op_sel_hi:[1,0]
	v_pk_mul_f32 v[18:19], v[18:19], v[120:121] op_sel_hi:[1,0]
	v_pk_mul_f32 v[16:17], v[16:17], v[120:121] op_sel_hi:[1,0]
	v_pk_mul_f32 v[14:15], v[14:15], v[120:121] op_sel_hi:[1,0]
	v_pk_mul_f32 v[12:13], v[12:13], v[120:121] op_sel_hi:[1,0]
	v_pk_mul_f32 v[10:11], v[10:11], v[120:121] op_sel_hi:[1,0]
	v_pk_mul_f32 v[8:9], v[8:9], v[120:121] op_sel_hi:[1,0]
	v_pk_mul_f32 v[6:7], v[6:7], v[120:121] op_sel_hi:[1,0]
	v_pk_mul_f32 v[4:5], v[4:5], v[120:121] op_sel_hi:[1,0]
	v_pk_mul_f32 v[2:3], v[2:3], v[120:121] op_sel_hi:[1,0]
	v_mov_b32_e32 v119, v121
.LBB0_510:
	v_cmp_neq_f32_e32 vcc, s85, v119
	s_nop 1
	v_cndmask_b32_e64 v120, 0, -v119, vcc
	v_cndmask_b32_e64 v120, v220, v120, s[74:75]
	v_fmamk_f32 v50, v50, 0x3e38aa3b, v120
	v_exp_f32_e32 v50, v50
	v_fmamk_f32 v51, v51, 0x3e38aa3b, v120
	v_exp_f32_e32 v121, v51
	v_fmamk_f32 v51, v52, 0x3e38aa3b, v120
	v_exp_f32_e32 v51, v51
	v_fmamk_f32 v52, v53, 0x3e38aa3b, v120
	v_exp_f32_e32 v122, v52
	v_fmamk_f32 v53, v54, 0x3e38aa3b, v120
	v_add_f32_e32 v52, 0, v50
	v_exp_f32_e32 v54, v53
	v_fmamk_f32 v53, v55, 0x3e38aa3b, v120
	v_add_f32_e32 v52, v121, v52
	v_exp_f32_e32 v55, v53
	v_fmamk_f32 v53, v56, 0x3e38aa3b, v120
	v_add_f32_e32 v52, v51, v52
	v_exp_f32_e32 v53, v53
	v_fmamk_f32 v56, v57, 0x3e38aa3b, v120
	v_add_f32_e32 v52, v122, v52
	v_exp_f32_e32 v56, v56
	v_fmamk_f32 v57, v58, 0x3e38aa3b, v120
	v_add_f32_e32 v52, v54, v52
	v_exp_f32_e32 v58, v57
	v_fmamk_f32 v57, v59, 0x3e38aa3b, v120
	v_add_f32_e32 v52, v55, v52
	v_exp_f32_e32 v59, v57
	v_fmamk_f32 v57, v60, 0x3e38aa3b, v120
	v_add_f32_e32 v52, v53, v52
	v_exp_f32_e32 v60, v57
	v_fmamk_f32 v57, v61, 0x3e38aa3b, v120
	v_add_f32_e32 v52, v56, v52
	v_exp_f32_e32 v61, v57
	v_fmamk_f32 v57, v62, 0x3e38aa3b, v120
	v_add_f32_e32 v52, v58, v52
	v_exp_f32_e32 v62, v57
	v_fmamk_f32 v57, v63, 0x3e38aa3b, v120
	v_add_f32_e32 v52, v59, v52
	v_exp_f32_e32 v63, v57
	v_fmamk_f32 v57, v64, 0x3e38aa3b, v120
	v_add_f32_e32 v52, v60, v52
	v_exp_f32_e32 v64, v57
	v_fmamk_f32 v57, v65, 0x3e38aa3b, v120
	v_add_f32_e32 v52, v61, v52
	v_exp_f32_e32 v65, v57
	v_fmamk_f32 v34, v34, 0x3e38aa3b, v120
	v_add_f32_e32 v52, v62, v52
	v_exp_f32_e32 v123, v34
	v_fmamk_f32 v34, v35, 0x3e38aa3b, v120
	v_add_f32_e32 v52, v63, v52
	v_exp_f32_e32 v124, v34
	v_fmamk_f32 v34, v36, 0x3e38aa3b, v120
	v_add_f32_e32 v52, v64, v52
	v_exp_f32_e32 v125, v34
	v_fmamk_f32 v34, v37, 0x3e38aa3b, v120
	v_add_f32_e32 v52, v65, v52
	v_exp_f32_e32 v126, v34
	v_add_f32_e32 v34, v123, v52
	v_add_f32_e32 v34, v124, v34
	v_add_f32_e32 v34, v125, v34
	v_add_f32_e32 v127, v126, v34
	v_fmamk_f32 v34, v38, 0x3e38aa3b, v120
	v_lshlrev_b32_e32 v38, 1, v112
	v_exp_f32_e32 v128, v34
	v_fmamk_f32 v34, v39, 0x3e38aa3b, v120
	v_add3_u32 v130, s16, v105, v38
	v_exp_f32_e32 v129, v34
	s_setprio 1
	ds_read_b128 v[34:37], v130 offset:9216
	v_fmamk_f32 v39, v40, 0x3e38aa3b, v120
	v_add3_u32 v132, s16, v113, v38
	v_cvt_pk_bf16_f32 v53, v53, v56
	v_cvt_pk_bf16_f32 v52, v54, v55
	v_cvt_pk_bf16_f32 v51, v51, v122
	v_cvt_pk_bf16_f32 v50, v50, v121
	v_exp_f32_e32 v131, v39
	ds_read_b128 v[54:57], v132 offset:9216
	s_waitcnt lgkmcnt(1)
	v_mfma_f32_32x32x16_bf16 v[18:33], v[34:37], v[50:53], v[18:33]
	v_fmamk_f32 v34, v41, 0x3e38aa3b, v120
	v_exp_f32_e32 v121, v34
	v_add_f32_e32 v34, v128, v127
	v_add_f32_e32 v34, v129, v34
	v_add_f32_e32 v34, v131, v34
	v_add_f32_e32 v122, v121, v34
	ds_read_b128 v[34:37], v130 offset:9248
	v_fmamk_f32 v38, v42, 0x3e38aa3b, v120
	s_waitcnt lgkmcnt(1)
	v_mfma_f32_32x32x16_bf16 v[2:17], v[54:57], v[50:53], v[2:17]
	v_exp_f32_e32 v54, v38
	ds_read_b128 v[38:41], v132 offset:9248
	v_cvt_pk_bf16_f32 v53, v64, v65
	v_cvt_pk_bf16_f32 v52, v62, v63
	v_cvt_pk_bf16_f32 v51, v60, v61
	v_cvt_pk_bf16_f32 v50, v58, v59
	v_fmamk_f32 v58, v45, 0x3e38aa3b, v120
	v_add_f32_e32 v55, v54, v122
	s_waitcnt lgkmcnt(1)
	v_mfma_f32_32x32x16_bf16 v[18:33], v[34:37], v[50:53], v[18:33]
	v_fmamk_f32 v34, v43, 0x3e38aa3b, v120
	v_exp_f32_e32 v56, v34
	v_fmamk_f32 v34, v44, 0x3e38aa3b, v120
	v_exp_f32_e32 v57, v34
	ds_read_b128 v[34:37], v130 offset:9280
	ds_read_b128 v[42:45], v132 offset:9280
	s_waitcnt lgkmcnt(2)
	v_mfma_f32_32x32x16_bf16 v[2:17], v[38:41], v[50:53], v[2:17]
	v_fmamk_f32 v38, v46, 0x3e38aa3b, v120
	v_exp_f32_e32 v46, v38
	v_cvt_pk_bf16_f32 v41, v131, v121
	v_cvt_pk_bf16_f32 v40, v128, v129
	v_cvt_pk_bf16_f32 v39, v125, v126
	v_cvt_pk_bf16_f32 v38, v123, v124
	v_exp_f32_e32 v50, v58
	v_add_f32_e32 v51, v56, v55
	s_waitcnt lgkmcnt(1)
	v_mfma_f32_32x32x16_bf16 v[18:33], v[34:37], v[38:41], v[18:33]
	v_fmamk_f32 v34, v47, 0x3e38aa3b, v120
	v_exp_f32_e32 v47, v34
	v_fmamk_f32 v34, v48, 0x3e38aa3b, v120
	v_exp_f32_e32 v48, v34
	ds_read_b128 v[34:37], v130 offset:9312
	v_fmac_f32_e32 v120, 0x3e38aa3b, v49
	v_exp_f32_e32 v49, v120
	s_waitcnt lgkmcnt(1)
	v_mfma_f32_32x32x16_bf16 v[2:17], v[42:45], v[38:41], v[2:17]
	ds_read_b128 v[42:45], v132 offset:9312
	v_cvt_pk_bf16_f32 v40, v46, v47
	v_cvt_pk_bf16_f32 v41, v48, v49
	v_cvt_pk_bf16_f32 v39, v57, v50
	v_cvt_pk_bf16_f32 v38, v54, v56
	s_waitcnt lgkmcnt(1)
	s_nop 0
	v_mfma_f32_32x32x16_bf16 v[18:33], v[34:37], v[38:41], v[18:33]
	v_add_f32_e32 v34, v57, v51
	v_add_f32_e32 v34, v50, v34
	v_add_f32_e32 v34, v46, v34
	v_add_f32_e32 v34, v47, v34
	v_add_f32_e32 v34, v48, v34
	v_add_f32_e32 v34, v49, v34
	v_add_f32_e32 v117, v117, v34
	s_waitcnt lgkmcnt(0)
	v_mfma_f32_32x32x16_bf16 v[2:17], v[42:45], v[38:41], v[2:17]
.LBB0_511:
	s_andn2_saveexec_b64 s[2:3], s[2:3]
	s_cbranch_execz .LBB0_515
	v_add3_u32 v124, s16, v100, v116
	s_setprio 1
	ds_read_b128 v[34:37], v124
	ds_read_b128 v[50:53], v124 offset:16
	ds_read_b128 v[54:57], v124 offset:32
	ds_read_b128 v[58:61], v124 offset:48
	v_cmp_lt_i32_e32 vcc, -1, v118
	s_waitcnt lgkmcnt(3)
	v_mfma_f32_32x32x16_bf16 v[34:49], v[34:37], v[78:81], 0
	v_cmp_gt_i32_e64 s[38:39], 1, v118
	v_cmp_gt_i32_e64 s[40:41], 32, v118
	v_cmp_gt_i32_e64 s[42:43], 33, v118
	v_cmp_gt_i32_e64 s[44:45], 34, v118
	v_cmp_gt_i32_e64 s[46:47], 35, v118
	v_cmp_gt_i32_e64 s[48:49], 36, v118
	v_cmp_gt_i32_e64 s[50:51], 37, v118
	s_waitcnt lgkmcnt(2)
	v_mfma_f32_32x32x16_bf16 v[34:49], v[50:53], v[74:77], v[34:49]
	ds_read_b128 v[50:53], v124 offset:4608
	ds_read_b128 v[120:123], v124 offset:4624
	v_cmp_gt_i32_e64 s[52:53], 38, v118
	v_cmp_gt_i32_e64 s[56:57], 39, v118
	v_cmp_gt_i32_e64 s[58:59], 48, v118
	v_cmp_gt_i32_e64 s[60:61], 49, v118
	v_cmp_gt_i32_e64 s[62:63], 50, v118
	s_waitcnt lgkmcnt(3)
	v_mfma_f32_32x32x16_bf16 v[34:49], v[54:57], v[70:73], v[34:49]
	v_cmp_gt_i32_e64 s[64:65], 51, v118
	v_cmp_gt_i32_e64 s[66:67], 52, v118
	v_cmp_gt_i32_e64 s[68:69], 53, v118
	v_cmp_gt_i32_e64 s[70:71], 54, v118
	v_cmp_gt_i32_e64 s[54:55], 55, v118
	s_waitcnt lgkmcnt(2)
	v_mfma_f32_32x32x16_bf16 v[34:49], v[58:61], v[66:69], v[34:49]
	s_waitcnt lgkmcnt(1)
	v_mfma_f32_32x32x16_bf16 v[50:65], v[50:53], v[78:81], 0
	s_waitcnt lgkmcnt(0)
	v_mfma_f32_32x32x16_bf16 v[50:65], v[120:123], v[74:77], v[50:65]
	ds_read_b128 v[120:123], v124 offset:4640
	s_waitcnt lgkmcnt(0)
	v_mfma_f32_32x32x16_bf16 v[50:65], v[120:123], v[70:73], v[50:65]
	ds_read_b128 v[120:123], v124 offset:4656
	s_waitcnt lgkmcnt(0)
	v_mfma_f32_32x32x16_bf16 v[50:65], v[120:123], v[66:69], v[50:65]
	s_nop 1
	v_cndmask_b32_e32 v122, v220, v34, vcc
	v_cmp_lt_i32_e32 vcc, 1, v118
	v_cndmask_b32_e64 v120, v35, v220, s[38:39]
	v_max3_f32 v35, v122, s85, v120
	v_cndmask_b32_e32 v36, v220, v36, vcc
	v_cmp_lt_i32_e32 vcc, 2, v118
	s_nop 3
	v_cndmask_b32_e64 v123, v50, v220, s[40:41]
	v_cndmask_b32_e32 v37, v220, v37, vcc
	v_cmp_lt_i32_e32 vcc, 3, v118
	v_max3_f32 v35, v35, v36, v37
	v_cndmask_b32_e64 v124, v51, v220, s[42:43]
	v_cndmask_b32_e32 v121, v220, v38, vcc
	v_cmp_lt_i32_e32 vcc, 4, v118
	v_cndmask_b32_e64 v125, v52, v220, s[44:45]
	v_cndmask_b32_e64 v126, v53, v220, s[46:47]
	v_cndmask_b32_e32 v38, v220, v39, vcc
	v_cmp_lt_i32_e32 vcc, 5, v118
	v_max3_f32 v35, v35, v121, v38
	v_cndmask_b32_e64 v127, v54, v220, s[48:49]
	v_cndmask_b32_e32 v39, v220, v40, vcc
	v_cmp_lt_i32_e32 vcc, 6, v118
	v_cndmask_b32_e64 v128, v55, v220, s[50:51]
	v_cndmask_b32_e64 v130, v56, v220, s[52:53]
	v_cndmask_b32_e32 v40, v220, v41, vcc
	v_cmp_lt_i32_e32 vcc, 15, v118
	v_max3_f32 v35, v35, v39, v40
	v_cndmask_b32_e64 v131, v57, v220, s[56:57]
	v_cndmask_b32_e32 v42, v220, v42, vcc
	v_cmp_lt_i32_e32 vcc, 16, v118
	v_cndmask_b32_e64 v132, v58, v220, s[58:59]
	v_cndmask_b32_e64 v133, v59, v220, s[60:61]
	v_cndmask_b32_e32 v41, v220, v43, vcc
	v_cmp_lt_i32_e32 vcc, 17, v118
	v_max3_f32 v35, v35, v42, v41
	v_cndmask_b32_e64 v134, v60, v220, s[62:63]
	v_cndmask_b32_e32 v43, v220, v44, vcc
	v_cmp_lt_i32_e32 vcc, 18, v118
	v_cndmask_b32_e64 v135, v61, v220, s[64:65]
	v_cndmask_b32_e64 v136, v62, v220, s[66:67]
	v_cndmask_b32_e32 v44, v220, v45, vcc
	v_cmp_lt_i32_e32 vcc, 19, v118
	v_max3_f32 v35, v35, v43, v44
	v_cndmask_b32_e64 v137, v63, v220, s[68:69]
	v_cndmask_b32_e32 v45, v220, v46, vcc
	v_cmp_lt_i32_e32 vcc, 20, v118
	v_cndmask_b32_e64 v129, v64, v220, s[70:71]
	s_nop 0
	v_cndmask_b32_e32 v46, v220, v47, vcc
	v_cmp_lt_i32_e32 vcc, 21, v118
	v_max3_f32 v35, v35, v45, v46
	s_nop 0
	v_cndmask_b32_e32 v47, v220, v48, vcc
	v_cmp_lt_i32_e32 vcc, 22, v118
	s_nop 1
	v_cndmask_b32_e32 v48, v220, v49, vcc
	v_max3_f32 v35, v35, v47, v48
	v_max3_f32 v35, v35, v123, v124
	v_max3_f32 v35, v35, v125, v126
	v_max3_f32 v35, v35, v127, v128
	v_max3_f32 v35, v35, v130, v131
	v_max3_f32 v35, v35, v132, v133
	v_max3_f32 v35, v35, v134, v135
	v_max3_f32 v138, v35, v136, v137
	v_cndmask_b32_e64 v35, v65, v220, s[54:55]
	v_cmp_lt_i32_e32 vcc, v211, v210
	v_max3_f32 v65, v138, v129, v35
	s_nop 0
	v_cndmask_b32_e32 v138, v209, v211, vcc
	v_lshlrev_b32_e32 v138, 2, v138
	ds_bpermute_b32 v138, v138, v65
	s_waitcnt lgkmcnt(0)
	v_max_f32_e32 v138, v138, v138
	v_max_f32_e32 v65, v65, v138
	v_mul_f32_e32 v65, 0x3e38aa3b, v65
	v_add_f32_e32 v138, 0x40c00000, v119
	v_cmp_gt_f32_e32 vcc, v65, v138
	s_cbranch_vccz .LBB0_514
	s_nop 0
	v_cndmask_b32_e32 v65, v119, v65, vcc
	v_sub_f32_e32 v119, v119, v65
	v_exp_f32_e32 v119, v119
	s_nop 0
	v_cndmask_b32_e32 v138, 1.0, v119, vcc
	v_mul_f32_e32 v117, v117, v138
	v_pk_mul_f32 v[32:33], v[32:33], v[138:139] op_sel_hi:[1,0]
	v_pk_mul_f32 v[30:31], v[30:31], v[138:139] op_sel_hi:[1,0]
	v_pk_mul_f32 v[28:29], v[28:29], v[138:139] op_sel_hi:[1,0]
	v_pk_mul_f32 v[26:27], v[26:27], v[138:139] op_sel_hi:[1,0]
	v_pk_mul_f32 v[24:25], v[24:25], v[138:139] op_sel_hi:[1,0]
	v_pk_mul_f32 v[22:23], v[22:23], v[138:139] op_sel_hi:[1,0]
	v_pk_mul_f32 v[20:21], v[20:21], v[138:139] op_sel_hi:[1,0]
	v_pk_mul_f32 v[18:19], v[18:19], v[138:139] op_sel_hi:[1,0]
	v_pk_mul_f32 v[16:17], v[16:17], v[138:139] op_sel_hi:[1,0]
	v_pk_mul_f32 v[14:15], v[14:15], v[138:139] op_sel_hi:[1,0]
	v_pk_mul_f32 v[12:13], v[12:13], v[138:139] op_sel_hi:[1,0]
	v_pk_mul_f32 v[10:11], v[10:11], v[138:139] op_sel_hi:[1,0]
	v_pk_mul_f32 v[8:9], v[8:9], v[138:139] op_sel_hi:[1,0]
	v_pk_mul_f32 v[6:7], v[6:7], v[138:139] op_sel_hi:[1,0]
	v_pk_mul_f32 v[4:5], v[4:5], v[138:139] op_sel_hi:[1,0]
	v_pk_mul_f32 v[2:3], v[2:3], v[138:139] op_sel_hi:[1,0]
	v_mov_b32_e32 v119, v65
.LBB0_514:
	s_and_b64 vcc, s[54:55], s[70:71]
	v_cndmask_b32_e32 v63, v63, v137, vcc
	s_and_b64 vcc, vcc, s[68:69]
	v_cndmask_b32_e32 v62, v62, v136, vcc
	s_and_b64 vcc, vcc, s[66:67]
	v_cndmask_b32_e32 v61, v61, v135, vcc
	s_and_b64 vcc, vcc, s[64:65]
	v_cndmask_b32_e32 v60, v60, v134, vcc
	s_and_b64 vcc, vcc, s[62:63]
	v_cndmask_b32_e32 v59, v59, v133, vcc
	s_and_b64 vcc, vcc, s[60:61]
	v_cndmask_b32_e32 v58, v58, v132, vcc
	s_and_b64 vcc, vcc, s[58:59]
	v_cndmask_b32_e32 v57, v57, v131, vcc
	s_and_b64 vcc, vcc, s[56:57]
	v_cndmask_b32_e64 v34, v34, v122, s[38:39]
	v_cndmask_b32_e32 v56, v56, v130, vcc
	s_and_b64 vcc, vcc, s[52:53]
	v_cmp_neq_f32_e64 s[38:39], s85, v119
	v_cndmask_b32_e32 v55, v55, v128, vcc
	s_and_b64 vcc, vcc, s[50:51]
	v_cndmask_b32_e64 v65, 0, -v119, s[38:39]
	v_cndmask_b32_e32 v54, v54, v127, vcc
	s_and_b64 vcc, vcc, s[48:49]
	v_fmamk_f32 v34, v34, 0x3e38aa3b, v65
	v_cndmask_b32_e32 v53, v53, v126, vcc
	s_and_b64 vcc, vcc, s[46:47]
	v_exp_f32_e32 v34, v34
	v_fmamk_f32 v120, v120, 0x3e38aa3b, v65
	v_cndmask_b32_e32 v52, v52, v125, vcc
	s_and_b64 vcc, vcc, s[44:45]
	v_exp_f32_e32 v120, v120
	v_fmamk_f32 v36, v36, 0x3e38aa3b, v65
	v_cndmask_b32_e32 v51, v51, v124, vcc
	s_and_b64 vcc, vcc, s[42:43]
	v_exp_f32_e32 v122, v36
	v_fmamk_f32 v36, v37, 0x3e38aa3b, v65
	v_cndmask_b32_e32 v50, v50, v123, vcc
	s_and_b64 vcc, vcc, s[40:41]
	v_exp_f32_e32 v123, v36
	v_fmamk_f32 v36, v121, 0x3e38aa3b, v65
	v_cndmask_b32_e32 v48, v49, v48, vcc
	v_add_f32_e32 v49, 0, v34
	v_exp_f32_e32 v121, v36
	v_fmamk_f32 v37, v38, 0x3e38aa3b, v65
	v_add_f32_e32 v36, v120, v49
	v_exp_f32_e32 v49, v37
	v_fmamk_f32 v37, v39, 0x3e38aa3b, v65
	v_add_f32_e32 v36, v122, v36
	v_exp_f32_e32 v124, v37
	v_fmamk_f32 v37, v40, 0x3e38aa3b, v65
	v_add_f32_e32 v36, v123, v36
	v_exp_f32_e32 v40, v37
	v_fmamk_f32 v37, v42, 0x3e38aa3b, v65
	v_add_f32_e32 v36, v121, v36
	v_exp_f32_e32 v125, v37
	v_fmamk_f32 v37, v41, 0x3e38aa3b, v65
	v_add_f32_e32 v36, v49, v36
	v_exp_f32_e32 v126, v37
	v_fmamk_f32 v37, v43, 0x3e38aa3b, v65
	v_add_f32_e32 v36, v124, v36
	v_exp_f32_e32 v127, v37
	v_fmamk_f32 v37, v44, 0x3e38aa3b, v65
	v_add_f32_e32 v36, v40, v36
	v_exp_f32_e32 v128, v37
	v_fmamk_f32 v37, v45, 0x3e38aa3b, v65
	v_cndmask_b32_e64 v64, v64, v129, s[54:55]
	v_add_f32_e32 v36, v125, v36
	v_exp_f32_e32 v129, v37
	v_fmamk_f32 v37, v46, 0x3e38aa3b, v65
	v_add_f32_e32 v36, v126, v36
	v_exp_f32_e32 v130, v37
	v_fmamk_f32 v37, v47, 0x3e38aa3b, v65
	v_add_f32_e32 v36, v127, v36
	v_exp_f32_e32 v131, v37
	v_fmamk_f32 v37, v48, 0x3e38aa3b, v65
	v_add_f32_e32 v36, v128, v36
	v_exp_f32_e32 v132, v37
	v_fmamk_f32 v37, v50, 0x3e38aa3b, v65
	v_add_f32_e32 v36, v129, v36
	v_exp_f32_e32 v133, v37
	v_fmamk_f32 v37, v51, 0x3e38aa3b, v65
	v_add_f32_e32 v36, v130, v36
	v_exp_f32_e32 v134, v37
	v_fmamk_f32 v37, v52, 0x3e38aa3b, v65
	v_add_f32_e32 v36, v131, v36
	v_exp_f32_e32 v52, v37
	v_fmamk_f32 v37, v53, 0x3e38aa3b, v65
	v_add_f32_e32 v36, v132, v36
	v_exp_f32_e32 v53, v37
	v_fmamk_f32 v37, v54, 0x3e38aa3b, v65
	v_add_f32_e32 v36, v133, v36
	v_exp_f32_e32 v54, v37
	v_add_f32_e32 v36, v134, v36
	v_add_f32_e32 v36, v52, v36
	v_lshlrev_b32_e32 v42, 1, v112
	v_add_f32_e32 v36, v53, v36
	v_fmamk_f32 v41, v55, 0x3e38aa3b, v65
	v_add3_u32 v55, s16, v105, v42
	v_add_f32_e32 v135, v54, v36
	s_setprio 1
	ds_read_b128 v[36:39], v55 offset:9216
	v_exp_f32_e32 v136, v41
	v_add3_u32 v137, s16, v113, v42
	v_cvt_pk_bf16_f32 v43, v124, v40
	v_cvt_pk_bf16_f32 v42, v121, v49
	v_cvt_pk_bf16_f32 v41, v122, v123
	v_cvt_pk_bf16_f32 v40, v34, v120
	v_fmamk_f32 v34, v56, 0x3e38aa3b, v65
	ds_read_b128 v[44:47], v55 offset:9248
	ds_read_b128 v[48:51], v137 offset:9216
	s_waitcnt lgkmcnt(2)
	v_mfma_f32_32x32x16_bf16 v[18:33], v[36:39], v[40:43], v[18:33]
	v_exp_f32_e32 v34, v34
	v_fmamk_f32 v37, v57, 0x3e38aa3b, v65
	v_add_f32_e32 v36, v136, v135
	v_exp_f32_e32 v56, v37
	v_add_f32_e32 v57, v34, v36
	ds_read_b128 v[36:39], v137 offset:9248
	v_fmamk_f32 v61, v61, 0x3e38aa3b, v65
	s_waitcnt lgkmcnt(1)
	v_mfma_f32_32x32x16_bf16 v[2:17], v[48:51], v[40:43], v[2:17]
	v_fmamk_f32 v40, v58, 0x3e38aa3b, v65
	v_add_f32_e32 v48, v56, v57
	v_exp_f32_e32 v57, v40
	v_cvt_pk_bf16_f32 v43, v131, v132
	v_cvt_pk_bf16_f32 v42, v129, v130
	v_cvt_pk_bf16_f32 v41, v127, v128
	v_cvt_pk_bf16_f32 v40, v125, v126
	v_add_f32_e32 v58, v57, v48
	v_fmamk_f32 v62, v62, 0x3e38aa3b, v65
	v_mfma_f32_32x32x16_bf16 v[18:33], v[44:47], v[40:43], v[18:33]
	v_fmamk_f32 v44, v59, 0x3e38aa3b, v65
	v_exp_f32_e32 v59, v44
	v_fmamk_f32 v44, v60, 0x3e38aa3b, v65
	v_exp_f32_e32 v60, v44
	ds_read_b128 v[44:47], v55 offset:9280
	s_waitcnt lgkmcnt(1)
	v_mfma_f32_32x32x16_bf16 v[2:17], v[36:39], v[40:43], v[2:17]
	ds_read_b128 v[40:43], v137 offset:9280
	ds_read_b128 v[48:51], v55 offset:9312
	v_cvt_pk_bf16_f32 v39, v34, v56
	v_cvt_pk_bf16_f32 v38, v54, v136
	v_cvt_pk_bf16_f32 v37, v52, v53
	v_cvt_pk_bf16_f32 v36, v133, v134
	v_fmamk_f32 v34, v63, 0x3e38aa3b, v65
	v_exp_f32_e32 v52, v62
	s_waitcnt lgkmcnt(2)
	v_mfma_f32_32x32x16_bf16 v[18:33], v[44:47], v[36:39], v[18:33]
	v_fmamk_f32 v44, v64, 0x3e38aa3b, v65
	v_exp_f32_e32 v53, v44
	ds_read_b128 v[44:47], v137 offset:9312
	v_fmac_f32_e32 v65, 0x3e38aa3b, v35
	v_exp_f32_e32 v54, v65
	s_waitcnt lgkmcnt(2)
	v_mfma_f32_32x32x16_bf16 v[2:17], v[40:43], v[36:39], v[2:17]
	v_exp_f32_e32 v38, v34
	v_exp_f32_e32 v39, v61
	v_cvt_pk_bf16_f32 v37, v53, v54
	v_cvt_pk_bf16_f32 v34, v57, v59
	v_cvt_pk_bf16_f32 v36, v52, v38
	v_cvt_pk_bf16_f32 v35, v60, v39
	v_add_f32_e32 v40, v59, v58
	v_add_f32_e32 v40, v60, v40
	s_waitcnt lgkmcnt(1)
	v_mfma_f32_32x32x16_bf16 v[18:33], v[48:51], v[34:37], v[18:33]
	v_add_f32_e32 v39, v39, v40
	v_add_f32_e32 v39, v52, v39
	v_add_f32_e32 v38, v38, v39
	v_add_f32_e32 v38, v53, v38
	v_add_f32_e32 v38, v54, v38
	v_add_f32_e32 v117, v117, v38
	s_waitcnt lgkmcnt(0)
	v_mfma_f32_32x32x16_bf16 v[2:17], v[44:47], v[34:37], v[2:17]

.LBB0_516:
	s_andn2_saveexec_b64 s[22:23], s[22:23]
	s_cbranch_execz .LBB0_522
	v_cmp_eq_u32_e32 vcc, 1, v34
	s_and_saveexec_b64 s[2:3], vcc
	s_cbranch_execz .LBB0_521
	v_add3_u32 v124, s16, v100, v116
	s_setprio 1
	ds_read_b128 v[34:37], v124
	ds_read_b128 v[38:41], v124 offset:16
	ds_read_b128 v[42:45], v124 offset:32
	ds_read_b128 v[46:49], v124 offset:48
	v_cmp_lt_i32_e32 vcc, v211, v210
	s_waitcnt lgkmcnt(3)
	v_mfma_f32_32x32x16_bf16 v[50:65], v[34:37], v[78:81], 0
	ds_read_b128 v[34:37], v124 offset:4608
	ds_read_b128 v[120:123], v124 offset:4624
	s_waitcnt lgkmcnt(4)
	v_mfma_f32_32x32x16_bf16 v[50:65], v[38:41], v[74:77], v[50:65]
	s_waitcnt lgkmcnt(3)
	v_mfma_f32_32x32x16_bf16 v[50:65], v[42:45], v[70:73], v[50:65]
	s_waitcnt lgkmcnt(2)
	v_mfma_f32_32x32x16_bf16 v[50:65], v[46:49], v[66:69], v[50:65]
	s_waitcnt lgkmcnt(1)
	v_mfma_f32_32x32x16_bf16 v[34:49], v[34:37], v[78:81], 0
	s_waitcnt lgkmcnt(0)
	v_mfma_f32_32x32x16_bf16 v[34:49], v[120:123], v[74:77], v[34:49]
	ds_read_b128 v[120:123], v124 offset:4640
	s_waitcnt lgkmcnt(0)
	v_mfma_f32_32x32x16_bf16 v[34:49], v[120:123], v[70:73], v[34:49]
	ds_read_b128 v[120:123], v124 offset:4656
	s_waitcnt lgkmcnt(0)
	v_mfma_f32_32x32x16_bf16 v[34:49], v[120:123], v[66:69], v[34:49]
	s_nop 1
	v_max3_f32 v120, v50, s85, v51
	v_max3_f32 v120, v120, v52, v53
	v_max3_f32 v120, v120, v54, v55
	v_max3_f32 v120, v120, v56, v57
	v_max3_f32 v120, v120, v58, v59
	v_max3_f32 v120, v120, v60, v61
	v_max3_f32 v120, v120, v62, v63
	v_max3_f32 v120, v120, v64, v65
	s_nop 1
	v_max3_f32 v120, v120, v34, v35
	v_max3_f32 v120, v120, v36, v37
	v_max3_f32 v120, v120, v38, v39
	v_max3_f32 v120, v120, v40, v41
	v_max3_f32 v120, v120, v42, v43
	v_max3_f32 v120, v120, v44, v45
	v_max3_f32 v120, v120, v46, v47
	v_cndmask_b32_e32 v121, v209, v211, vcc
	v_max3_f32 v120, v120, v48, v49
	v_lshlrev_b32_e32 v121, 2, v121
	ds_bpermute_b32 v121, v121, v120
	s_waitcnt lgkmcnt(0)
	v_max_f32_e32 v121, v121, v121
	v_max_f32_e32 v120, v120, v121
	v_mul_f32_e32 v120, 0x3e38aa3b, v120
	v_add_f32_e32 v121, 0x40c00000, v119
	v_cmp_gt_f32_e32 vcc, v120, v121
	s_cbranch_vccz .LBB0_520
	s_nop 0
	v_cndmask_b32_e32 v121, v119, v120, vcc
	v_sub_f32_e32 v119, v119, v121
	v_exp_f32_e32 v119, v119
	s_nop 0
	v_cndmask_b32_e32 v120, 1.0, v119, vcc
	v_mul_f32_e32 v117, v117, v120
	v_pk_mul_f32 v[32:33], v[32:33], v[120:121] op_sel_hi:[1,0]
	v_pk_mul_f32 v[30:31], v[30:31], v[120:121] op_sel_hi:[1,0]
	v_pk_mul_f32 v[28:29], v[28:29], v[120:121] op_sel_hi:[1,0]
	v_pk_mul_f32 v[26:27], v[26:27], v[120:121] op_sel_hi:[1,0]
	v_pk_mul_f32 v[24:25], v[24:25], v[120:121] op_sel_hi:[1,0]
	v_pk_mul_f32 v[22:23], v[22:23], v[120:121] op_sel_hi:[1,0]
	v_pk_mul_f32 v[20:21], v[20:21], v[120:121] op_sel_hi:[1,0]
	v_pk_mul_f32 v[18:19], v[18:19], v[120:121] op_sel_hi:[1,0]
	v_pk_mul_f32 v[16:17], v[16:17], v[120:121] op_sel_hi:[1,0]
	v_pk_mul_f32 v[14:15], v[14:15], v[120:121] op_sel_hi:[1,0]
	v_pk_mul_f32 v[12:13], v[12:13], v[120:121] op_sel_hi:[1,0]
	v_pk_mul_f32 v[10:11], v[10:11], v[120:121] op_sel_hi:[1,0]
	v_pk_mul_f32 v[8:9], v[8:9], v[120:121] op_sel_hi:[1,0]
	v_pk_mul_f32 v[6:7], v[6:7], v[120:121] op_sel_hi:[1,0]
	v_pk_mul_f32 v[4:5], v[4:5], v[120:121] op_sel_hi:[1,0]
	v_pk_mul_f32 v[2:3], v[2:3], v[120:121] op_sel_hi:[1,0]
	v_mov_b32_e32 v119, v121
.LBB0_520:
	v_cmp_neq_f32_e32 vcc, s85, v119
	s_nop 1
	v_cndmask_b32_e64 v120, 0, -v119, vcc
	v_fmamk_f32 v50, v50, 0x3e38aa3b, v120
	v_exp_f32_e32 v50, v50
	v_fmamk_f32 v51, v51, 0x3e38aa3b, v120
	v_exp_f32_e32 v121, v51
	v_fmamk_f32 v51, v52, 0x3e38aa3b, v120
	v_exp_f32_e32 v51, v51
	v_fmamk_f32 v52, v53, 0x3e38aa3b, v120
	v_exp_f32_e32 v122, v52
	v_fmamk_f32 v53, v54, 0x3e38aa3b, v120
	v_add_f32_e32 v52, 0, v50
	v_exp_f32_e32 v54, v53
	v_fmamk_f32 v53, v55, 0x3e38aa3b, v120
	v_add_f32_e32 v52, v121, v52
	v_exp_f32_e32 v55, v53
	v_fmamk_f32 v53, v56, 0x3e38aa3b, v120
	v_add_f32_e32 v52, v51, v52
	v_exp_f32_e32 v53, v53
	v_fmamk_f32 v56, v57, 0x3e38aa3b, v120
	v_add_f32_e32 v52, v122, v52
	v_exp_f32_e32 v56, v56
	v_fmamk_f32 v57, v58, 0x3e38aa3b, v120
	v_add_f32_e32 v52, v54, v52
	v_exp_f32_e32 v58, v57
	v_fmamk_f32 v57, v59, 0x3e38aa3b, v120
	v_add_f32_e32 v52, v55, v52
	v_exp_f32_e32 v59, v57
	v_fmamk_f32 v57, v60, 0x3e38aa3b, v120
	v_add_f32_e32 v52, v53, v52
	v_exp_f32_e32 v60, v57
	v_fmamk_f32 v57, v61, 0x3e38aa3b, v120
	v_add_f32_e32 v52, v56, v52
	v_exp_f32_e32 v61, v57
	v_fmamk_f32 v57, v62, 0x3e38aa3b, v120
	v_add_f32_e32 v52, v58, v52
	v_exp_f32_e32 v62, v57
	v_fmamk_f32 v57, v63, 0x3e38aa3b, v120
	v_add_f32_e32 v52, v59, v52
	v_exp_f32_e32 v63, v57
	v_fmamk_f32 v57, v64, 0x3e38aa3b, v120
	v_add_f32_e32 v52, v60, v52
	v_exp_f32_e32 v64, v57
	v_fmamk_f32 v57, v65, 0x3e38aa3b, v120
	v_add_f32_e32 v52, v61, v52
	v_exp_f32_e32 v65, v57
	v_fmamk_f32 v34, v34, 0x3e38aa3b, v120
	v_add_f32_e32 v52, v62, v52
	v_exp_f32_e32 v123, v34
	v_fmamk_f32 v34, v35, 0x3e38aa3b, v120
	v_add_f32_e32 v52, v63, v52
	v_exp_f32_e32 v124, v34
	v_fmamk_f32 v34, v36, 0x3e38aa3b, v120
	v_add_f32_e32 v52, v64, v52
	v_exp_f32_e32 v125, v34
	v_fmamk_f32 v34, v37, 0x3e38aa3b, v120
	v_add_f32_e32 v52, v65, v52
	v_exp_f32_e32 v126, v34
	v_add_f32_e32 v34, v123, v52
	v_add_f32_e32 v34, v124, v34
	v_add_f32_e32 v34, v125, v34
	v_add_f32_e32 v127, v126, v34
	v_fmamk_f32 v34, v38, 0x3e38aa3b, v120
	v_lshlrev_b32_e32 v38, 1, v112
	v_exp_f32_e32 v128, v34
	v_fmamk_f32 v34, v39, 0x3e38aa3b, v120
	v_add3_u32 v130, s16, v105, v38
	v_exp_f32_e32 v129, v34
	s_setprio 1
	ds_read_b128 v[34:37], v130 offset:9216
	v_fmamk_f32 v39, v40, 0x3e38aa3b, v120
	v_add3_u32 v132, s16, v113, v38
	v_cvt_pk_bf16_f32 v53, v53, v56
	v_cvt_pk_bf16_f32 v52, v54, v55
	v_cvt_pk_bf16_f32 v51, v51, v122
	v_cvt_pk_bf16_f32 v50, v50, v121
	v_exp_f32_e32 v131, v39
	ds_read_b128 v[54:57], v132 offset:9216
	s_waitcnt lgkmcnt(1)
	v_mfma_f32_32x32x16_bf16 v[18:33], v[34:37], v[50:53], v[18:33]
	v_fmamk_f32 v34, v41, 0x3e38aa3b, v120
	v_exp_f32_e32 v121, v34
	v_add_f32_e32 v34, v128, v127
	v_add_f32_e32 v34, v129, v34
	v_add_f32_e32 v34, v131, v34
	v_add_f32_e32 v122, v121, v34
	ds_read_b128 v[34:37], v130 offset:9248
	v_fmamk_f32 v38, v42, 0x3e38aa3b, v120
	s_waitcnt lgkmcnt(1)
	v_mfma_f32_32x32x16_bf16 v[2:17], v[54:57], v[50:53], v[2:17]
	v_exp_f32_e32 v54, v38
	ds_read_b128 v[38:41], v132 offset:9248
	v_cvt_pk_bf16_f32 v53, v64, v65
	v_cvt_pk_bf16_f32 v52, v62, v63
	v_cvt_pk_bf16_f32 v51, v60, v61
	v_cvt_pk_bf16_f32 v50, v58, v59
	v_fmamk_f32 v58, v45, 0x3e38aa3b, v120
	v_add_f32_e32 v55, v54, v122
	s_waitcnt lgkmcnt(1)
	v_mfma_f32_32x32x16_bf16 v[18:33], v[34:37], v[50:53], v[18:33]
	v_fmamk_f32 v34, v43, 0x3e38aa3b, v120
	v_exp_f32_e32 v56, v34
	v_fmamk_f32 v34, v44, 0x3e38aa3b, v120
	v_exp_f32_e32 v57, v34
	ds_read_b128 v[34:37], v130 offset:9280
	ds_read_b128 v[42:45], v132 offset:9280
	s_waitcnt lgkmcnt(2)
	v_mfma_f32_32x32x16_bf16 v[2:17], v[38:41], v[50:53], v[2:17]
	v_fmamk_f32 v38, v46, 0x3e38aa3b, v120
	v_exp_f32_e32 v46, v38
	v_cvt_pk_bf16_f32 v41, v131, v121
	v_cvt_pk_bf16_f32 v40, v128, v129
	v_cvt_pk_bf16_f32 v39, v125, v126
	v_cvt_pk_bf16_f32 v38, v123, v124
	v_exp_f32_e32 v50, v58
	v_add_f32_e32 v51, v56, v55
	s_waitcnt lgkmcnt(1)
	v_mfma_f32_32x32x16_bf16 v[18:33], v[34:37], v[38:41], v[18:33]
	v_fmamk_f32 v34, v47, 0x3e38aa3b, v120
	v_exp_f32_e32 v47, v34
	v_fmamk_f32 v34, v48, 0x3e38aa3b, v120
	v_exp_f32_e32 v48, v34
	ds_read_b128 v[34:37], v130 offset:9312
	v_fmac_f32_e32 v120, 0x3e38aa3b, v49
	v_exp_f32_e32 v49, v120
	s_waitcnt lgkmcnt(1)
	v_mfma_f32_32x32x16_bf16 v[2:17], v[42:45], v[38:41], v[2:17]
	ds_read_b128 v[42:45], v132 offset:9312
	v_cvt_pk_bf16_f32 v40, v46, v47
	v_cvt_pk_bf16_f32 v41, v48, v49
	v_cvt_pk_bf16_f32 v39, v57, v50
	v_cvt_pk_bf16_f32 v38, v54, v56
	s_waitcnt lgkmcnt(1)
	s_nop 0
	v_mfma_f32_32x32x16_bf16 v[18:33], v[34:37], v[38:41], v[18:33]
	v_add_f32_e32 v34, v57, v51
	v_add_f32_e32 v34, v50, v34
	v_add_f32_e32 v34, v46, v34
	v_add_f32_e32 v34, v47, v34
	v_add_f32_e32 v34, v48, v34
	v_add_f32_e32 v34, v49, v34
	v_add_f32_e32 v117, v117, v34
	s_waitcnt lgkmcnt(0)
	v_mfma_f32_32x32x16_bf16 v[2:17], v[42:45], v[38:41], v[2:17]

.LBB0_522:
	s_or_b64 exec, exec, s[22:23]
	s_add_i32 s73, s73, 64
	s_add_i32 s2, s14, 1
	v_subrev_u32_e32 v114, 64, v114
	v_lshl_add_u64 v[106:107], v[106:107], 0, s[28:29]
	s_cmp_lg_u32 s14, s76
	v_lshl_add_u64 v[108:109], v[108:109], 0, s[30:31]
	s_waitcnt lgkmcnt(0)
	s_setprio 0
	s_barrier
	s_cbranch_scc1 .LBB0_498
	v_cmp_lt_i32_e32 vcc, v211, v210
	s_mov_b32 s73, s77
	v_mov_b32_e32 v103, v1
	v_cndmask_b32_e32 v0, v209, v211, vcc
	v_lshlrev_b32_e32 v0, 2, v0
	ds_bpermute_b32 v0, v0, v117
	v_mov_b32_e32 v54, v18
	s_waitcnt lgkmcnt(0)
	v_add_f32_e32 v0, v117, v0
	v_div_scale_f32 v34, s[2:3], v0, v0, 1.0
	v_rcp_f32_e32 v35, v34
	v_cmp_lt_f32_e64 s[38:39], 0, v0
	v_fma_f32 v36, -v34, v35, 1.0
	v_fmac_f32_e32 v35, v36, v35
	v_div_scale_f32 v36, vcc, 1.0, v0, 1.0
	v_mul_f32_e32 v37, v36, v35
	v_fma_f32 v38, -v34, v37, v36
	v_fmac_f32_e32 v37, v38, v35
	v_fma_f32 v34, -v34, v37, v36
	v_div_fmas_f32 v34, v34, v35, v37
	v_lshlrev_b64 v[36:37], 1, v[98:99]
	v_lshl_add_u64 v[38:39], s[18:19], 0, v[36:37]
	v_lshl_add_u64 v[38:39], v[38:39], 0, s[72:73]
	v_lshl_add_u64 v[36:37], s[34:35], 0, v[36:37]
	v_lshl_add_u64 v[48:49], v[36:37], 0, s[72:73]
	v_lshl_add_u64 v[36:37], v[38:39], 0, v[102:103]
	global_load_dwordx2 v[50:51], v[36:37], off
	global_load_dwordx2 v[52:53], v[36:37], off offset:16
	global_load_dwordx2 v[46:47], v[36:37], off offset:32
	global_load_dwordx2 v[44:45], v[36:37], off offset:48
	global_load_dwordx2 v[42:43], v[36:37], off offset:64
	global_load_dwordx2 v[40:41], v[36:37], off offset:80
	global_load_dwordx2 v[38:39], v[36:37], off offset:96
	s_nop 0
	global_load_dwordx2 v[36:37], v[36:37], off offset:112
	v_div_fixup_f32 v0, v34, v0, 1.0
	v_cndmask_b32_e64 v34, 0, v0, s[38:39]
	s_waitcnt vmcnt(7)
	v_lshlrev_b32_e32 v35, 16, v50
	v_mul_f32_e32 v0, 0xbfb8aa3b, v35
	v_exp_f32_e32 v0, v0
	s_nop 0
	v_add_f32_e32 v0, 1.0, v0
	v_rcp_f32_e32 v55, v0
	s_nop 0
	v_pk_mul_f32 v[54:55], v[54:55], v[34:35]
	v_and_b32_e32 v35, 0xffff0000, v50
	v_mul_f32_e32 v18, 0xbfb8aa3b, v35
	v_exp_f32_e32 v18, v18
	v_mul_f32_e32 v0, v54, v55
	v_mov_b32_e32 v54, v19
	v_add_f32_e32 v18, 1.0, v18
	v_rcp_f32_e32 v55, v18
	s_nop 0
	v_pk_mul_f32 v[18:19], v[54:55], v[34:35]
	v_lshlrev_b32_e32 v35, 16, v51
	v_mul_f32_e32 v50, v18, v19
	v_mul_f32_e32 v18, 0xbfb8aa3b, v35
	v_exp_f32_e32 v18, v18
	s_nop 0
	v_add_f32_e32 v18, 1.0, v18
	v_rcp_f32_e32 v19, v18
	v_mov_b32_e32 v18, v20
	v_pk_mul_f32 v[18:19], v[18:19], v[34:35]
	v_and_b32_e32 v35, 0xffff0000, v51
	v_mul_f32_e32 v20, v18, v19
	v_mul_f32_e32 v18, 0xbfb8aa3b, v35
	v_exp_f32_e32 v18, v18
	s_nop 0
	v_add_f32_e32 v18, 1.0, v18
	v_rcp_f32_e32 v19, v18
	v_mov_b32_e32 v18, v21
	v_pk_mul_f32 v[18:19], v[18:19], v[34:35]
	s_nop 0
	v_mul_f32_e32 v21, v18, v19
	s_waitcnt vmcnt(6)
	v_lshlrev_b32_e32 v35, 16, v52
	v_cvt_pk_bf16_f32 v21, v20, v21
	v_cvt_pk_bf16_f32 v20, v0, v50
	v_mul_f32_e32 v0, 0xbfb8aa3b, v35
	v_exp_f32_e32 v0, v0
	v_lshl_add_u64 v[18:19], v[48:49], 0, v[102:103]
	global_store_dwordx2 v[18:19], v[20:21], off
	v_mov_b32_e32 v20, v22
	v_add_f32_e32 v0, 1.0, v0
	v_rcp_f32_e32 v21, v0
	s_nop 0
	v_pk_mul_f32 v[20:21], v[20:21], v[34:35]
	v_and_b32_e32 v35, 0xffff0000, v52
	v_mul_f32_e32 v0, v20, v21
	v_mul_f32_e32 v20, 0xbfb8aa3b, v35
	v_exp_f32_e32 v20, v20
	s_nop 0
	v_add_f32_e32 v20, 1.0, v20
	v_rcp_f32_e32 v21, v20
	v_mov_b32_e32 v20, v23
	v_pk_mul_f32 v[20:21], v[20:21], v[34:35]
	v_lshlrev_b32_e32 v35, 16, v53
	v_mul_f32_e32 v22, v20, v21
	v_mul_f32_e32 v20, 0xbfb8aa3b, v35
	v_exp_f32_e32 v20, v20
	s_nop 0
	v_add_f32_e32 v20, 1.0, v20
	v_rcp_f32_e32 v21, v20
	v_mov_b32_e32 v20, v24
	v_pk_mul_f32 v[20:21], v[20:21], v[34:35]
	v_and_b32_e32 v35, 0xffff0000, v53
	v_mul_f32_e32 v23, v20, v21
	v_mul_f32_e32 v20, 0xbfb8aa3b, v35
	v_exp_f32_e32 v20, v20
	s_nop 0
	v_add_f32_e32 v20, 1.0, v20
	v_rcp_f32_e32 v21, v20
	v_mov_b32_e32 v20, v25
	v_pk_mul_f32 v[20:21], v[20:21], v[34:35]
	s_nop 0
	v_mul_f32_e32 v20, v20, v21
	s_waitcnt vmcnt(6)
	v_lshlrev_b32_e32 v35, 16, v46
	v_cvt_pk_bf16_f32 v21, v23, v20
	v_cvt_pk_bf16_f32 v20, v0, v22
	v_mul_f32_e32 v0, 0xbfb8aa3b, v35
	v_exp_f32_e32 v0, v0
	global_store_dwordx2 v[18:19], v[20:21], off offset:16
	v_mov_b32_e32 v20, v26
	v_add_f32_e32 v0, 1.0, v0
	v_rcp_f32_e32 v21, v0
	s_nop 0
	v_pk_mul_f32 v[20:21], v[20:21], v[34:35]
	v_and_b32_e32 v35, 0xffff0000, v46
	v_mul_f32_e32 v0, v20, v21
	v_mul_f32_e32 v20, 0xbfb8aa3b, v35
	v_exp_f32_e32 v20, v20
	s_nop 0
	v_add_f32_e32 v20, 1.0, v20
	v_rcp_f32_e32 v21, v20
	v_mov_b32_e32 v20, v27
	v_pk_mul_f32 v[20:21], v[20:21], v[34:35]
	v_lshlrev_b32_e32 v35, 16, v47
	v_mul_f32_e32 v22, v20, v21
	v_mul_f32_e32 v20, 0xbfb8aa3b, v35
	v_exp_f32_e32 v20, v20
	s_nop 0
	v_add_f32_e32 v20, 1.0, v20
	v_rcp_f32_e32 v21, v20
	v_mov_b32_e32 v20, v28
	v_pk_mul_f32 v[20:21], v[20:21], v[34:35]
	v_and_b32_e32 v35, 0xffff0000, v47
	v_mul_f32_e32 v23, v20, v21
	v_mul_f32_e32 v20, 0xbfb8aa3b, v35
	v_exp_f32_e32 v20, v20
	s_nop 0
	v_add_f32_e32 v20, 1.0, v20
	v_rcp_f32_e32 v21, v20
	v_mov_b32_e32 v20, v29
	v_pk_mul_f32 v[20:21], v[20:21], v[34:35]
	s_nop 0
	v_mul_f32_e32 v20, v20, v21
	s_waitcnt vmcnt(6)
	v_lshlrev_b32_e32 v35, 16, v44
	v_cvt_pk_bf16_f32 v21, v23, v20
	v_cvt_pk_bf16_f32 v20, v0, v22
	v_mul_f32_e32 v0, 0xbfb8aa3b, v35
	v_exp_f32_e32 v0, v0
	global_store_dwordx2 v[18:19], v[20:21], off offset:32
	v_mov_b32_e32 v20, v30
	v_add_f32_e32 v0, 1.0, v0
	v_rcp_f32_e32 v21, v0
	s_nop 0
	v_pk_mul_f32 v[20:21], v[20:21], v[34:35]
	v_and_b32_e32 v35, 0xffff0000, v44
	v_mul_f32_e32 v0, v20, v21
	v_mul_f32_e32 v20, 0xbfb8aa3b, v35
	v_exp_f32_e32 v20, v20
	s_nop 0
	v_add_f32_e32 v20, 1.0, v20
	v_rcp_f32_e32 v21, v20
	v_mov_b32_e32 v20, v31
	v_pk_mul_f32 v[20:21], v[20:21], v[34:35]
	v_lshlrev_b32_e32 v35, 16, v45
	v_mul_f32_e32 v22, v20, v21
	v_mul_f32_e32 v20, 0xbfb8aa3b, v35
	v_exp_f32_e32 v20, v20
	s_nop 0
	v_add_f32_e32 v20, 1.0, v20
	v_rcp_f32_e32 v21, v20
	v_mov_b32_e32 v20, v32
	v_pk_mul_f32 v[20:21], v[20:21], v[34:35]
	v_and_b32_e32 v35, 0xffff0000, v45
	v_mul_f32_e32 v23, v20, v21
	v_mul_f32_e32 v20, 0xbfb8aa3b, v35
	v_exp_f32_e32 v20, v20
	s_nop 0
	v_add_f32_e32 v20, 1.0, v20
	v_rcp_f32_e32 v21, v20
	v_mov_b32_e32 v20, v33
	v_pk_mul_f32 v[20:21], v[20:21], v[34:35]
	s_nop 0
	v_mul_f32_e32 v20, v20, v21
	s_waitcnt vmcnt(6)
	v_lshlrev_b32_e32 v35, 16, v42
	v_cvt_pk_bf16_f32 v21, v23, v20
	v_cvt_pk_bf16_f32 v20, v0, v22
	v_mul_f32_e32 v0, 0xbfb8aa3b, v35
	v_exp_f32_e32 v0, v0
	global_store_dwordx2 v[18:19], v[20:21], off offset:48
	v_mov_b32_e32 v20, v2
	v_add_f32_e32 v0, 1.0, v0
	v_rcp_f32_e32 v21, v0
	s_nop 0
	v_pk_mul_f32 v[20:21], v[20:21], v[34:35]
	v_and_b32_e32 v35, 0xffff0000, v42
	v_mul_f32_e32 v2, 0xbfb8aa3b, v35
	v_exp_f32_e32 v2, v2
	v_mul_f32_e32 v0, v20, v21
	v_mov_b32_e32 v20, v3
	v_add_f32_e32 v2, 1.0, v2
	v_rcp_f32_e32 v21, v2
	s_nop 0
	v_pk_mul_f32 v[2:3], v[20:21], v[34:35]
	v_lshlrev_b32_e32 v35, 16, v43
	v_mul_f32_e32 v20, v2, v3
	v_mul_f32_e32 v2, 0xbfb8aa3b, v35
	v_exp_f32_e32 v2, v2
	s_nop 0
	v_add_f32_e32 v2, 1.0, v2
	v_rcp_f32_e32 v3, v2
	v_mov_b32_e32 v2, v4
	v_pk_mul_f32 v[2:3], v[2:3], v[34:35]
	v_and_b32_e32 v35, 0xffff0000, v43
	v_mul_f32_e32 v4, v2, v3
	v_mul_f32_e32 v2, 0xbfb8aa3b, v35
	v_exp_f32_e32 v2, v2
	s_nop 0
	v_add_f32_e32 v2, 1.0, v2
	v_rcp_f32_e32 v3, v2
	v_mov_b32_e32 v2, v5
	v_pk_mul_f32 v[2:3], v[2:3], v[34:35]
	s_nop 0
	v_mul_f32_e32 v2, v2, v3
	s_waitcnt vmcnt(6)
	v_lshlrev_b32_e32 v35, 16, v40
	v_cvt_pk_bf16_f32 v3, v4, v2
	v_cvt_pk_bf16_f32 v2, v0, v20
	v_mul_f32_e32 v0, 0xbfb8aa3b, v35
	v_exp_f32_e32 v0, v0
	global_store_dwordx2 v[18:19], v[2:3], off offset:64
	v_mov_b32_e32 v2, v6
	v_add_f32_e32 v0, 1.0, v0
	v_rcp_f32_e32 v3, v0
	s_nop 0
	v_pk_mul_f32 v[2:3], v[2:3], v[34:35]
	v_and_b32_e32 v35, 0xffff0000, v40
	v_mul_f32_e32 v0, v2, v3
	v_mul_f32_e32 v2, 0xbfb8aa3b, v35
	v_exp_f32_e32 v2, v2
	s_nop 0
	v_add_f32_e32 v2, 1.0, v2
	v_rcp_f32_e32 v3, v2
	v_mov_b32_e32 v2, v7
	v_pk_mul_f32 v[2:3], v[2:3], v[34:35]
	v_lshlrev_b32_e32 v35, 16, v41
	v_mul_f32_e32 v4, v2, v3
	v_mul_f32_e32 v2, 0xbfb8aa3b, v35
	v_exp_f32_e32 v2, v2
	s_nop 0
	v_add_f32_e32 v2, 1.0, v2
	v_rcp_f32_e32 v3, v2
	v_mov_b32_e32 v2, v8
	v_pk_mul_f32 v[2:3], v[2:3], v[34:35]
	v_and_b32_e32 v35, 0xffff0000, v41
	v_mul_f32_e32 v5, v2, v3
	v_mul_f32_e32 v2, 0xbfb8aa3b, v35
	v_exp_f32_e32 v2, v2
	s_nop 0
	v_add_f32_e32 v2, 1.0, v2
	v_rcp_f32_e32 v3, v2
	v_mov_b32_e32 v2, v9
	v_pk_mul_f32 v[2:3], v[2:3], v[34:35]
	s_nop 0
	v_mul_f32_e32 v2, v2, v3
	s_waitcnt vmcnt(6)
	v_lshlrev_b32_e32 v35, 16, v38
	v_cvt_pk_bf16_f32 v3, v5, v2
	v_cvt_pk_bf16_f32 v2, v0, v4
	v_mul_f32_e32 v0, 0xbfb8aa3b, v35
	v_exp_f32_e32 v0, v0
	global_store_dwordx2 v[18:19], v[2:3], off offset:80
	v_mov_b32_e32 v2, v10
	v_add_f32_e32 v0, 1.0, v0
	v_rcp_f32_e32 v3, v0
	s_nop 0
	v_pk_mul_f32 v[2:3], v[2:3], v[34:35]
	v_and_b32_e32 v35, 0xffff0000, v38
	v_mul_f32_e32 v0, v2, v3
	v_mul_f32_e32 v2, 0xbfb8aa3b, v35
	v_exp_f32_e32 v2, v2
	s_nop 0
	v_add_f32_e32 v2, 1.0, v2
	v_rcp_f32_e32 v3, v2
	v_mov_b32_e32 v2, v11
	v_pk_mul_f32 v[2:3], v[2:3], v[34:35]
	v_lshlrev_b32_e32 v35, 16, v39
	v_mul_f32_e32 v4, v2, v3
	v_mul_f32_e32 v2, 0xbfb8aa3b, v35
	v_exp_f32_e32 v2, v2
	s_nop 0
	v_add_f32_e32 v2, 1.0, v2
	v_rcp_f32_e32 v3, v2
	v_mov_b32_e32 v2, v12
	v_pk_mul_f32 v[2:3], v[2:3], v[34:35]
	v_and_b32_e32 v35, 0xffff0000, v39
	v_mul_f32_e32 v5, v2, v3
	v_mul_f32_e32 v2, 0xbfb8aa3b, v35
	v_exp_f32_e32 v2, v2
	s_nop 0
	v_add_f32_e32 v2, 1.0, v2
	v_rcp_f32_e32 v3, v2
	v_mov_b32_e32 v2, v13
	v_pk_mul_f32 v[2:3], v[2:3], v[34:35]
	s_nop 0
	v_mul_f32_e32 v2, v2, v3
	s_waitcnt vmcnt(6)
	v_lshlrev_b32_e32 v35, 16, v36
	v_cvt_pk_bf16_f32 v3, v5, v2
	v_cvt_pk_bf16_f32 v2, v0, v4
	v_mul_f32_e32 v0, 0xbfb8aa3b, v35
	v_exp_f32_e32 v0, v0
	global_store_dwordx2 v[18:19], v[2:3], off offset:96
	v_mov_b32_e32 v2, v14
	v_add_f32_e32 v0, 1.0, v0
	v_rcp_f32_e32 v3, v0
	s_nop 0
	v_pk_mul_f32 v[2:3], v[2:3], v[34:35]
	v_and_b32_e32 v35, 0xffff0000, v36
	v_mul_f32_e32 v0, v2, v3
	v_mul_f32_e32 v2, 0xbfb8aa3b, v35
	v_exp_f32_e32 v2, v2
	s_nop 0
	v_add_f32_e32 v2, 1.0, v2
	v_rcp_f32_e32 v3, v2
	v_mov_b32_e32 v2, v15
	v_pk_mul_f32 v[2:3], v[2:3], v[34:35]
	v_lshlrev_b32_e32 v35, 16, v37
	v_mul_f32_e32 v4, v2, v3
	v_mul_f32_e32 v2, 0xbfb8aa3b, v35
	v_exp_f32_e32 v2, v2
	s_nop 0
	v_add_f32_e32 v2, 1.0, v2
	v_rcp_f32_e32 v3, v2
	v_mov_b32_e32 v2, v16
	v_pk_mul_f32 v[2:3], v[2:3], v[34:35]
	v_and_b32_e32 v35, 0xffff0000, v37
	v_mul_f32_e32 v5, v2, v3
	v_mul_f32_e32 v2, 0xbfb8aa3b, v35
	v_exp_f32_e32 v2, v2
	s_nop 0
	v_add_f32_e32 v2, 1.0, v2
	v_rcp_f32_e32 v3, v2
	v_mov_b32_e32 v2, v17
	v_pk_mul_f32 v[2:3], v[2:3], v[34:35]
	s_nop 0
	v_mul_f32_e32 v2, v2, v3
	v_cvt_pk_bf16_f32 v3, v5, v2
	v_cvt_pk_bf16_f32 v2, v0, v4
	global_store_dwordx2 v[18:19], v[2:3], off offset:112
	s_branch .LBB0_477
.LBB0_524:
	s_waitcnt vmcnt(0)
	s_setprio 0
	s_barrier
	s_mov_b64 s[18:19], exec
	v_readlane_b32 s2, v243, 1
	v_readlane_b32 s3, v243, 2
	s_and_b64 s[2:3], s[18:19], s[2:3]
	v_readlane_b32 s12, v242, 16
	s_mov_b64 exec, s[2:3]
	s_cbranch_execz .LBB0_576
	s_waitcnt vmcnt(0) expcnt(0) lgkmcnt(0)
	ds_read_b32 v3, v1 offset:55296
	ds_read_b32 v2, v1 offset:55300
	s_waitcnt lgkmcnt(1)
	v_cmp_ne_u32_e32 vcc, 0, v3
	s_cbranch_vccnz .LBB0_540
	s_mov_b32 s4, 1
	s_branch .LBB0_528

.LBB0_576:
	s_or_b64 exec, exec, s[18:19]
	s_mov_b64 s[2:3], 0
	s_waitcnt lgkmcnt(0)
	s_setprio 0
	s_barrier

.LBB0_582:
	s_cmpk_gt_i32 s10, 0x7f
	s_mov_b64 s[2:3], -1
	s_cbranch_scc0 .LBB0_618
	s_add_i32 s2, s10, 0xffffff80
	v_mov_b32_e32 v7, v206
	v_mov_b32_e32 v0, v206
	s_lshl_b32 s3, s2, 2
	s_lshl_b32 s11, s2, 4
	v_ashrrev_i32_e32 v0, 6, v0
	v_and_b32_e32 v6, 31, v7
	s_lshr_b32 s76, s2, 7
	s_and_b32 s3, s3, 4
	s_and_b32 s12, s11, 0x7e0
	v_add_u32_e32 v0, s3, v0
	v_or_b32_e32 v2, s12, v6
	s_lshl_b64 s[2:3], s[76:77], 11
	v_or_b32_e32 v130, s2, v2
	v_mov_b32_e32 v131, s3
	v_lshlrev_b64 v[2:3], 10, v[130:131]
	v_lshlrev_b32_e32 v134, 6, v0
	s_lshl_b64 s[14:15], s[76:77], 18
	v_lshl_add_u64 v[2:3], s[72:73], 0, v[2:3]
	v_ashrrev_i32_e32 v135, 31, v134
	v_and_b32_e32 v4, 32, v7
	s_add_u32 s2, s37, s14
	v_lshl_add_u64 v[2:3], v[134:135], 1, v[2:3]
	v_lshlrev_b32_e32 v136, 1, v4
	v_mov_b32_e32 v137, v1
	s_addc_u32 s3, s5, s15
	v_lshl_add_u64 v[2:3], v[2:3], 0, v[136:137]
	s_add_u32 s16, s6, s14
	global_load_dwordx4 v[98:101], v[2:3], off
	global_load_dwordx4 v[102:105], v[2:3], off offset:16
	global_load_dwordx4 v[106:109], v[2:3], off offset:32
	global_load_dwordx4 v[110:113], v[2:3], off offset:48
	s_addc_u32 s17, s40, s15
	v_add_u32_e32 v2, s41, v0
	v_readlane_b32 s14, v242, 17
	v_ashrrev_i32_e32 v3, 31, v2
	v_readlane_b32 s15, v242, 18
	v_sub_u32_e64 v0, s12, v221 clamp
	v_and_b32_e32 v5, 0x7c0, v0
	v_lshl_add_u64 v[2:3], v[2:3], 2, s[14:15]
	global_load_dword v9, v[2:3], off
	v_mov_b32_e32 v2, v206
	v_and_b32_e32 v8, 63, v7
	v_ashrrev_i32_e32 v138, 3, v2
	v_lshlrev_b32_e32 v2, 3, v2
	v_and_b32_e32 v4, 56, v2
	v_add_u32_e32 v2, v138, v5
	v_ashrrev_i32_e32 v3, 31, v2
	v_lshlrev_b64 v[2:3], 7, v[2:3]
	v_readfirstlane_b32 s13, v0
	v_lshl_add_u64 v[2:3], s[2:3], 0, v[2:3]
	v_lshlrev_b32_e32 v0, 1, v4
	v_cmp_gt_u32_e32 vcc, 32, v8
	v_lshl_add_u64 v[2:3], v[2:3], 0, v[0:1]
	s_movk_i32 s14, 0x1000
	v_cndmask_b32_e64 v133, 0, 1.0, vcc
	s_setprio 0
	s_barrier
	global_load_dwordx4 v[10:13], v[2:3], off
	v_add_co_u32_e32 v2, vcc, s14, v2
	v_ashrrev_i32_e32 v139, 31, v138
	s_nop 0
	v_addc_co_u32_e32 v3, vcc, 0, v3, vcc
	global_load_dwordx4 v[14:17], v[2:3], off
	v_lshlrev_b64 v[2:3], 12, v[138:139]
	v_lshl_add_u64 v[2:3], s[16:17], 0, v[2:3]
	v_lshlrev_b32_e32 v22, 1, v5
	v_mov_b32_e32 v23, v1
	v_lshl_add_u64 v[4:5], v[2:3], 0, v[22:23]
	v_lshl_add_u64 v[4:5], v[4:5], 0, v[0:1]
	global_load_dwordx4 v[18:21], v[4:5], off
	v_lshl_add_u64 v[4:5], v[2:3], 0, s[30:31]
	v_lshl_add_u64 v[22:23], v[4:5], 0, v[22:23]
	v_lshl_add_u64 v[22:23], v[22:23], 0, v[0:1]
	global_load_dwordx4 v[22:25], v[22:23], off
	s_lshr_b32 s13, s13, 6
	s_bfe_u32 s15, s11, 0x50006
	s_cmp_lt_u32 s13, s15
	s_cselect_b64 s[16:17], -1, 0
	v_mul_lo_u32 v137, v138, s21
	s_cmp_lg_u64 s[16:17], 0
	v_add_u32_e32 v27, v137, v0
	s_addc_u32 s11, s13, 0
	s_lshl_b32 s76, s11, 7
	v_bfe_u32 v26, v7, 5, 1
	s_cmp_gt_u32 s13, s15
	v_lshlrev_b32_e32 v132, 3, v26
	s_waitcnt vmcnt(3)
	ds_write_b128 v27, v[10:13]
	s_waitcnt vmcnt(2)
	ds_write_b128 v27, v[14:17] offset:4608
	s_waitcnt vmcnt(1)
	ds_write_b128 v27, v[18:21] offset:9216
	s_waitcnt vmcnt(0)
	ds_write_b128 v27, v[22:25] offset:13824
	v_lshl_add_u32 v10, s11, 6, v138
	v_ashrrev_i32_e32 v11, 31, v10
	v_lshlrev_b64 v[10:11], 7, v[10:11]
	v_lshl_add_u64 v[10:11], s[2:3], 0, v[10:11]
	v_lshl_add_u64 v[10:11], v[10:11], 0, v[0:1]
	global_load_dwordx4 v[114:117], v[10:11], off
	v_add_co_u32_e32 v10, vcc, s14, v10
	s_nop 1
	v_addc_co_u32_e32 v11, vcc, 0, v11, vcc
	global_load_dwordx4 v[118:121], v[10:11], off
	v_lshl_add_u64 v[10:11], v[2:3], 0, s[76:77]
	v_lshl_add_u64 v[10:11], v[10:11], 0, v[0:1]
	global_load_dwordx4 v[122:125], v[10:11], off
	v_lshl_add_u64 v[10:11], v[4:5], 0, s[76:77]
	v_lshl_add_u64 v[10:11], v[10:11], 0, v[0:1]
	global_load_dwordx4 v[126:129], v[10:11], off
	s_waitcnt lgkmcnt(0)
	s_setprio 0
	s_barrier
	s_cbranch_scc1 .LBB0_616
	v_lshl_add_u64 v[140:141], s[2:3], 0, v[0:1]
	s_and_b32 s2, s7, 0x7e0
	v_lshl_add_u64 v[142:143], v[2:3], 0, v[0:1]
	v_sub_u32_e64 v2, s2, v221 clamp
	v_lshrrev_b32_e32 v3, 1, v7
	v_readfirstlane_b32 s3, v2
	v_lshlrev_b32_e32 v2, 1, v8
	v_lshl_add_u64 v[144:145], v[4:5], 0, v[0:1]
	v_and_b32_e32 v2, 8, v2
	v_and_b32_e32 v3, 4, v3
	v_and_b32_e32 v4, 19, v7
	v_or3_b32 v2, v3, v4, v2
	v_mul_u32_u24_e32 v139, 0x90, v2
	v_lshrrev_b32_e32 v2, 2, v7
	v_and_b32_e32 v147, 8, v2
	v_or_b32_e32 v2, 32, v8
	v_mul_u32_u24_e32 v148, 0x90, v2
	v_or_b32_e32 v2, s2, v6
	s_and_b32 s23, s3, 0x7c0
	v_sub_u32_e32 v2, v2, v132
	v_mov_b32_e32 v16, v1
	v_mov_b32_e32 v17, v1
	v_mul_f32_e32 v152, 0x3fb8aa3b, v9
	v_mul_u32_u24_e32 v146, 0x90, v6
	v_subrev_u32_e32 v149, s23, v2
	v_mov_b32_e32 v2, v1
	v_mov_b32_e32 v3, v1
	v_mov_b32_e32 v4, v1
	v_mov_b32_e32 v5, v1
	v_mov_b32_e32 v6, v1
	v_mov_b32_e32 v7, v1
	v_mov_b32_e32 v8, v1
	v_mov_b32_e32 v9, v1
	v_mov_b32_e32 v10, v1
	v_mov_b32_e32 v11, v1
	v_mov_b32_e32 v12, v1
	v_mov_b32_e32 v13, v1
	v_mov_b32_e32 v14, v1
	v_mov_b32_e32 v15, v1
	v_mov_b64_e32 v[32:33], v[16:17]
	s_mov_b32 s94, s48
	s_mov_b32 s93, s47
	s_mov_b32 s92, s46
	s_mov_b32 s91, s45
	s_mov_b32 s90, s44
	s_mov_b64 s[88:89], s[42:43]
	s_mov_b32 s87, s41
	s_mov_b32 s96, s40
	s_mov_b32 s18, s6
	s_mov_b32 s6, s5
	s_mov_b32 s5, s37
	s_lshr_b32 s22, s3, 6
	s_or_b32 s11, s12, 31
	s_add_i32 s14, s12, 0xffffff80
	s_add_i32 s13, s12, 0xffffff9f
	s_mov_b32 s36, 0
	v_mov_b32_e32 v150, 0
	v_mov_b32_e32 v151, 0
	v_mov_b64_e32 v[30:31], v[14:15]
	v_mov_b64_e32 v[28:29], v[12:13]
	v_mov_b64_e32 v[26:27], v[10:11]
	v_mov_b64_e32 v[24:25], v[8:9]
	v_mov_b64_e32 v[22:23], v[6:7]
	v_mov_b64_e32 v[20:21], v[4:5]
	v_mov_b64_e32 v[18:19], v[2:3]
	s_add_i32 s2, s22, s36
	s_and_b32 s37, s36, 1
	s_cmp_ge_u32 s2, s15
	s_cbranch_scc0 .LBB0_586
	s_branch .LBB0_588

.LBB0_593:
	s_mulk_i32 s37, 0x4800
	s_cmp_lt_i32 s76, 3
	s_mov_b64 s[2:3], -1
	s_cbranch_scc1 .LBB0_603
	s_cmp_gt_i32 s76, 3
	s_cbranch_scc0 .LBB0_598
	v_add3_u32 v70, s37, v136, v139
	s_setprio 1
	ds_read_b128 v[34:37], v70
	ds_read_b128 v[38:41], v70 offset:16
	ds_read_b128 v[42:45], v70 offset:32
	ds_read_b128 v[46:49], v70 offset:48
	v_cmp_lt_i32_e32 vcc, -1, v151
	s_waitcnt lgkmcnt(3)
	v_mfma_f32_32x32x16_bf16 v[50:65], v[34:37], v[98:101], 0
	ds_read_b128 v[34:37], v70 offset:4608
	ds_read_b128 v[66:69], v70 offset:4624
	v_cmp_gt_i32_e64 s[38:39], 0, v150
	s_and_b64 vcc, vcc, s[38:39]
	v_cmp_gt_i32_e64 s[38:39], 1, v150
	v_mov_b32_e32 v153, v152
	s_waitcnt lgkmcnt(4)
	v_mfma_f32_32x32x16_bf16 v[50:65], v[38:41], v[102:105], v[50:65]
	s_waitcnt lgkmcnt(3)
	v_mfma_f32_32x32x16_bf16 v[50:65], v[42:45], v[106:109], v[50:65]
	s_waitcnt lgkmcnt(2)
	v_mfma_f32_32x32x16_bf16 v[50:65], v[46:49], v[110:113], v[50:65]
	s_waitcnt lgkmcnt(1)
	v_mfma_f32_32x32x16_bf16 v[34:49], v[34:37], v[98:101], 0
	s_nop 9
	v_cndmask_b32_e32 v74, v220, v50, vcc
	v_cmp_lt_i32_e32 vcc, 0, v151
	s_and_b64 vcc, vcc, s[38:39]
	v_cmp_gt_i32_e64 s[38:39], 2, v150
	v_cndmask_b32_e32 v77, v220, v51, vcc
	v_cmp_lt_i32_e32 vcc, 1, v151
	s_and_b64 vcc, vcc, s[38:39]
	v_cmp_gt_i32_e64 s[38:39], 3, v150
	v_cndmask_b32_e32 v78, v220, v52, vcc
	v_cmp_lt_i32_e32 vcc, 2, v151
	s_and_b64 vcc, vcc, s[38:39]
	s_waitcnt lgkmcnt(0)
	v_mfma_f32_32x32x16_bf16 v[34:49], v[66:69], v[102:105], v[34:49]
	ds_read_b128 v[66:69], v70 offset:4640
	v_cndmask_b32_e32 v80, v220, v53, vcc
	v_cmp_lt_i32_e32 vcc, 3, v151
	v_cmp_gt_i32_e64 s[38:39], 4, v150
	s_and_b64 vcc, vcc, s[38:39]
	v_cndmask_b32_e32 v81, v220, v54, vcc
	v_cmp_lt_i32_e32 vcc, 4, v151
	v_cmp_gt_i32_e64 s[38:39], 5, v150
	s_and_b64 vcc, vcc, s[38:39]
	v_cndmask_b32_e32 v82, v220, v55, vcc
	v_cmp_lt_i32_e32 vcc, 5, v151
	v_cmp_gt_i32_e64 s[38:39], 6, v150
	s_and_b64 vcc, vcc, s[38:39]
	v_cndmask_b32_e32 v83, v220, v56, vcc
	v_cmp_lt_i32_e32 vcc, 6, v151
	v_cmp_gt_i32_e64 s[38:39], 7, v150
	s_and_b64 vcc, vcc, s[38:39]
	v_cndmask_b32_e32 v92, v220, v57, vcc
	v_cmp_lt_i32_e32 vcc, 15, v151
	v_cmp_gt_i32_e64 s[38:39], 16, v150
	s_waitcnt lgkmcnt(0)
	v_mfma_f32_32x32x16_bf16 v[34:49], v[66:69], v[106:109], v[34:49]
	ds_read_b128 v[66:69], v70 offset:4656
	s_and_b64 vcc, vcc, s[38:39]
	v_cndmask_b32_e32 v95, v220, v58, vcc
	v_cmp_lt_i32_e32 vcc, 16, v151
	v_cmp_gt_i32_e64 s[38:39], 17, v150
	s_and_b64 vcc, vcc, s[38:39]
	v_cndmask_b32_e32 v90, v220, v59, vcc
	v_cmp_lt_i32_e32 vcc, 17, v151
	v_cmp_gt_i32_e64 s[38:39], 18, v150
	s_and_b64 vcc, vcc, s[38:39]
	v_cndmask_b32_e32 v97, v220, v60, vcc
	v_cmp_lt_i32_e32 vcc, 18, v151
	v_cmp_gt_i32_e64 s[38:39], 19, v150
	s_and_b64 vcc, vcc, s[38:39]
	v_cndmask_b32_e32 v154, v220, v61, vcc
	v_cmp_lt_i32_e32 vcc, 19, v151
	v_cmp_gt_i32_e64 s[38:39], 20, v150
	s_and_b64 vcc, vcc, s[38:39]
	s_waitcnt lgkmcnt(0)
	v_mfma_f32_32x32x16_bf16 v[34:49], v[66:69], v[110:113], v[34:49]
	v_cndmask_b32_e32 v96, v220, v62, vcc
	v_cmp_lt_i32_e32 vcc, 20, v151
	v_cmp_gt_i32_e64 s[38:39], 21, v150
	s_and_b64 vcc, vcc, s[38:39]
	v_cndmask_b32_e32 v91, v220, v63, vcc
	v_cmp_lt_i32_e32 vcc, 21, v151
	v_cmp_gt_i32_e64 s[38:39], 22, v150
	s_and_b64 vcc, vcc, s[38:39]
	v_cndmask_b32_e32 v93, v220, v64, vcc
	v_cmp_lt_i32_e32 vcc, 22, v151
	v_cmp_gt_i32_e64 s[38:39], 23, v150
	s_and_b64 vcc, vcc, s[38:39]
	v_cndmask_b32_e32 v94, v220, v65, vcc
	v_cmp_lt_i32_e32 vcc, 31, v151
	v_cmp_gt_i32_e64 s[38:39], 32, v150
	s_and_b64 vcc, vcc, s[38:39]
	v_cndmask_b32_e32 v89, v220, v34, vcc
	v_cmp_lt_i32_e32 vcc, 32, v151
	v_cmp_gt_i32_e64 s[38:39], 33, v150
	s_and_b64 vcc, vcc, s[38:39]
	v_cndmask_b32_e32 v86, v220, v35, vcc
	v_cmp_lt_i32_e32 vcc, 33, v151
	v_cmp_gt_i32_e64 s[38:39], 34, v150
	s_and_b64 vcc, vcc, s[38:39]
	v_cndmask_b32_e32 v87, v220, v36, vcc
	v_cmp_lt_i32_e32 vcc, 34, v151
	v_cmp_gt_i32_e64 s[38:39], 35, v150
	s_and_b64 vcc, vcc, s[38:39]
	v_cndmask_b32_e32 v88, v220, v37, vcc
	v_cmp_lt_i32_e32 vcc, 35, v151
	v_cmp_gt_i32_e64 s[38:39], 36, v150
	s_and_b64 vcc, vcc, s[38:39]
	v_cndmask_b32_e32 v85, v220, v38, vcc
	v_cmp_lt_i32_e32 vcc, 36, v151
	v_cmp_gt_i32_e64 s[38:39], 37, v150
	s_and_b64 vcc, vcc, s[38:39]
	v_cndmask_b32_e32 v84, v220, v39, vcc
	v_cmp_lt_i32_e32 vcc, 37, v151
	v_cmp_gt_i32_e64 s[38:39], 38, v150
	s_and_b64 vcc, vcc, s[38:39]
	v_cndmask_b32_e32 v79, v220, v40, vcc
	v_cmp_lt_i32_e32 vcc, 38, v151
	v_cmp_gt_i32_e64 s[38:39], 39, v150
	s_and_b64 vcc, vcc, s[38:39]
	v_cndmask_b32_e32 v76, v220, v41, vcc
	v_cmp_lt_i32_e32 vcc, 47, v151
	v_cmp_gt_i32_e64 s[38:39], 48, v150
	s_and_b64 vcc, vcc, s[38:39]
	v_cndmask_b32_e32 v75, v220, v42, vcc
	v_cmp_lt_i32_e32 vcc, 48, v151
	v_cmp_gt_i32_e64 s[38:39], 49, v150
	v_max3_f32 v50, v74, s85, v77
	s_and_b64 vcc, vcc, s[38:39]
	v_max3_f32 v50, v50, v78, v80
	v_cndmask_b32_e32 v71, v220, v43, vcc
	v_cmp_lt_i32_e32 vcc, 49, v151
	v_cmp_gt_i32_e64 s[38:39], 50, v150
	v_max3_f32 v50, v50, v81, v82
	s_and_b64 vcc, vcc, s[38:39]
	v_max3_f32 v50, v50, v83, v92
	v_cndmask_b32_e32 v72, v220, v44, vcc
	v_cmp_lt_i32_e32 vcc, 50, v151
	v_cmp_gt_i32_e64 s[38:39], 51, v150
	v_max3_f32 v50, v50, v95, v90
	s_and_b64 vcc, vcc, s[38:39]
	v_max3_f32 v50, v50, v97, v154
	v_cndmask_b32_e32 v73, v220, v45, vcc
	v_cmp_lt_i32_e32 vcc, 51, v151
	v_cmp_gt_i32_e64 s[38:39], 52, v150
	v_max3_f32 v50, v50, v96, v91
	s_and_b64 vcc, vcc, s[38:39]
	v_max3_f32 v50, v50, v93, v94
	v_cndmask_b32_e32 v70, v220, v46, vcc
	v_cmp_lt_i32_e32 vcc, 52, v151
	v_cmp_gt_i32_e64 s[38:39], 53, v150
	v_max3_f32 v34, v50, v89, v86
	s_and_b64 vcc, vcc, s[38:39]
	v_max3_f32 v34, v34, v87, v88
	v_cndmask_b32_e32 v67, v220, v47, vcc
	v_cmp_lt_i32_e32 vcc, 53, v151
	v_cmp_gt_i32_e64 s[38:39], 54, v150
	v_max3_f32 v34, v34, v85, v84
	s_and_b64 vcc, vcc, s[38:39]
	v_max3_f32 v34, v34, v79, v76
	v_cndmask_b32_e32 v68, v220, v48, vcc
	v_cmp_lt_i32_e32 vcc, 54, v151
	v_cmp_gt_i32_e64 s[38:39], 55, v150
	v_max3_f32 v34, v34, v75, v71
	s_and_b64 vcc, vcc, s[38:39]
	v_max3_f32 v34, v34, v72, v73
	v_cndmask_b32_e32 v69, v220, v49, vcc
	v_cmp_lt_i32_e32 vcc, v211, v210
	v_max3_f32 v34, v34, v70, v67
	v_max3_f32 v34, v34, v68, v69
	v_cndmask_b32_e32 v35, v209, v211, vcc
	v_lshlrev_b32_e32 v35, 2, v35
	ds_bpermute_b32 v35, v35, v34
	v_mov_b64_e32 v[64:65], v[16:17]
	v_mov_b32_e32 v66, v133
	v_mov_b64_e32 v[62:63], v[14:15]
	v_mov_b64_e32 v[60:61], v[12:13]
	s_waitcnt lgkmcnt(0)
	v_max_f32_e32 v35, v35, v35
	v_max_f32_e32 v34, v34, v35
	v_mul_f32_e32 v155, 0x3e38aa3b, v34
	v_add_f32_e32 v34, 0x40c00000, v152
	v_cmp_gt_f32_e32 vcc, v155, v34
	v_mov_b64_e32 v[48:49], v[32:33]
	v_mov_b64_e32 v[58:59], v[10:11]
	v_mov_b64_e32 v[56:57], v[8:9]
	v_mov_b64_e32 v[54:55], v[6:7]
	v_mov_b64_e32 v[52:53], v[4:5]
	v_mov_b64_e32 v[50:51], v[2:3]
	v_mov_b64_e32 v[46:47], v[30:31]
	v_mov_b64_e32 v[44:45], v[28:29]
	v_mov_b64_e32 v[42:43], v[26:27]
	v_mov_b64_e32 v[40:41], v[24:25]
	v_mov_b64_e32 v[38:39], v[22:23]
	v_mov_b64_e32 v[36:37], v[20:21]
	v_mov_b64_e32 v[34:35], v[18:19]
	s_cbranch_vccz .LBB0_597
	v_cndmask_b32_e32 v153, v152, v155, vcc
	v_sub_f32_e32 v34, v152, v153
	v_exp_f32_e32 v34, v34
	s_nop 0
	v_cndmask_b32_e32 v34, 1.0, v34, vcc
	v_mul_f32_e32 v66, v133, v34
	v_pk_mul_f32 v[64:65], v[16:17], v[34:35] op_sel_hi:[1,0]
	v_pk_mul_f32 v[62:63], v[14:15], v[34:35] op_sel_hi:[1,0]
	v_pk_mul_f32 v[60:61], v[12:13], v[34:35] op_sel_hi:[1,0]
	v_pk_mul_f32 v[58:59], v[10:11], v[34:35] op_sel_hi:[1,0]
	v_pk_mul_f32 v[56:57], v[8:9], v[34:35] op_sel_hi:[1,0]
	v_pk_mul_f32 v[54:55], v[6:7], v[34:35] op_sel_hi:[1,0]
	v_pk_mul_f32 v[52:53], v[4:5], v[34:35] op_sel_hi:[1,0]
	v_pk_mul_f32 v[50:51], v[2:3], v[34:35] op_sel_hi:[1,0]
	v_pk_mul_f32 v[48:49], v[32:33], v[34:35] op_sel_hi:[1,0]
	v_pk_mul_f32 v[46:47], v[30:31], v[34:35] op_sel_hi:[1,0]
	v_pk_mul_f32 v[44:45], v[28:29], v[34:35] op_sel_hi:[1,0]
	v_pk_mul_f32 v[42:43], v[26:27], v[34:35] op_sel_hi:[1,0]
	v_pk_mul_f32 v[40:41], v[24:25], v[34:35] op_sel_hi:[1,0]
	v_pk_mul_f32 v[38:39], v[22:23], v[34:35] op_sel_hi:[1,0]
	v_pk_mul_f32 v[36:37], v[20:21], v[34:35] op_sel_hi:[1,0]
	v_pk_mul_f32 v[34:35], v[18:19], v[34:35] op_sel_hi:[1,0]
.LBB0_597:
	v_cmp_neq_f32_e32 vcc, s85, v153
	s_mov_b64 s[2:3], 0
	s_nop 0
	v_cndmask_b32_e64 v155, 0, -v153, vcc
	v_fmamk_f32 v74, v74, 0x3e38aa3b, v155
	v_exp_f32_e32 v74, v74
	v_fmamk_f32 v77, v77, 0x3e38aa3b, v155
	v_exp_f32_e32 v77, v77
	v_fmamk_f32 v78, v78, 0x3e38aa3b, v155
	v_exp_f32_e32 v78, v78
	v_fmamk_f32 v80, v80, 0x3e38aa3b, v155
	v_exp_f32_e32 v156, v80
	v_fmamk_f32 v81, v81, 0x3e38aa3b, v155
	v_add_f32_e32 v80, 0, v74
	v_exp_f32_e32 v157, v81
	v_fmamk_f32 v81, v82, 0x3e38aa3b, v155
	v_add_f32_e32 v80, v77, v80
	v_exp_f32_e32 v158, v81
	v_fmamk_f32 v81, v83, 0x3e38aa3b, v155
	v_add_f32_e32 v80, v78, v80
	v_exp_f32_e32 v159, v81
	v_fmamk_f32 v81, v92, 0x3e38aa3b, v155
	v_add_f32_e32 v80, v156, v80
	v_exp_f32_e32 v92, v81
	v_fmamk_f32 v81, v95, 0x3e38aa3b, v155
	v_add_f32_e32 v80, v157, v80
	v_exp_f32_e32 v95, v81
	v_fmamk_f32 v81, v90, 0x3e38aa3b, v155
	v_add_f32_e32 v80, v158, v80
	v_exp_f32_e32 v160, v81
	v_fmamk_f32 v81, v97, 0x3e38aa3b, v155
	v_add_f32_e32 v80, v159, v80
	v_exp_f32_e32 v97, v81
	v_fmamk_f32 v81, v154, 0x3e38aa3b, v155
	v_add_f32_e32 v80, v92, v80
	v_exp_f32_e32 v154, v81
	v_fmamk_f32 v81, v96, 0x3e38aa3b, v155
	v_add_f32_e32 v80, v95, v80
	v_exp_f32_e32 v96, v81
	v_fmamk_f32 v81, v91, 0x3e38aa3b, v155
	v_add_f32_e32 v80, v160, v80
	v_exp_f32_e32 v161, v81
	v_fmamk_f32 v81, v93, 0x3e38aa3b, v155
	v_add_f32_e32 v80, v97, v80
	v_exp_f32_e32 v93, v81
	v_fmamk_f32 v81, v94, 0x3e38aa3b, v155
	v_add_f32_e32 v80, v154, v80
	v_exp_f32_e32 v94, v81
	v_fmamk_f32 v81, v89, 0x3e38aa3b, v155
	v_add_f32_e32 v80, v96, v80
	v_exp_f32_e32 v162, v81
	v_fmamk_f32 v81, v86, 0x3e38aa3b, v155
	v_add_f32_e32 v80, v161, v80
	v_exp_f32_e32 v163, v81
	v_fmamk_f32 v81, v87, 0x3e38aa3b, v155
	v_add_f32_e32 v80, v93, v80
	v_exp_f32_e32 v164, v81
	v_fmamk_f32 v81, v88, 0x3e38aa3b, v155
	v_add_f32_e32 v80, v94, v80
	v_exp_f32_e32 v165, v81
	v_add_f32_e32 v80, v162, v80
	v_add_f32_e32 v80, v163, v80
	v_add_f32_e32 v80, v164, v80
	v_add_f32_e32 v166, v165, v80
	v_fmamk_f32 v80, v85, 0x3e38aa3b, v155
	v_exp_f32_e32 v167, v80
	v_fmamk_f32 v80, v84, 0x3e38aa3b, v155
	v_lshlrev_b32_e32 v84, 1, v147
	v_add3_u32 v169, s37, v146, v84
	v_exp_f32_e32 v168, v80
	s_setprio 1
	ds_read_b128 v[80:83], v169 offset:9216
	v_add3_u32 v171, s37, v148, v84
	ds_read_b128 v[88:91], v171 offset:9216
	v_fmamk_f32 v79, v79, 0x3e38aa3b, v155
	v_cvt_pk_bf16_f32 v87, v159, v92
	v_cvt_pk_bf16_f32 v86, v157, v158
	v_cvt_pk_bf16_f32 v85, v78, v156
	v_cvt_pk_bf16_f32 v84, v74, v77
	v_exp_f32_e32 v170, v79
	v_fmamk_f32 v74, v76, 0x3e38aa3b, v155
	ds_read_b128 v[76:79], v169 offset:9248
	s_waitcnt lgkmcnt(2)
	v_mfma_f32_32x32x16_bf16 v[50:65], v[80:83], v[84:87], v[50:65]
	ds_read_b128 v[80:83], v171 offset:9248
	v_exp_f32_e32 v92, v74
	v_fmamk_f32 v75, v75, 0x3e38aa3b, v155
	v_add_f32_e32 v74, v167, v166
	v_add_f32_e32 v74, v168, v74
	v_add_f32_e32 v74, v170, v74
	v_add_f32_e32 v74, v92, v74
	s_waitcnt lgkmcnt(2)
	v_mfma_f32_32x32x16_bf16 v[34:49], v[88:91], v[84:87], v[34:49]
	v_exp_f32_e32 v88, v75
	v_cvt_pk_bf16_f32 v87, v93, v94
	v_cvt_pk_bf16_f32 v86, v96, v161
	v_cvt_pk_bf16_f32 v85, v97, v154
	v_cvt_pk_bf16_f32 v84, v95, v160
	v_fmamk_f32 v71, v71, 0x3e38aa3b, v155
	v_add_f32_e32 v89, v88, v74
	v_exp_f32_e32 v90, v71
	v_fmamk_f32 v71, v72, 0x3e38aa3b, v155
	v_fmamk_f32 v93, v73, 0x3e38aa3b, v155
	ds_read_b128 v[72:75], v169 offset:9280
	s_waitcnt lgkmcnt(1)
	v_mfma_f32_32x32x16_bf16 v[34:49], v[80:83], v[84:87], v[34:49]
	ds_read_b128 v[80:83], v171 offset:9280
	v_fmamk_f32 v70, v70, 0x3e38aa3b, v155
	v_fmamk_f32 v68, v68, 0x3e38aa3b, v155
	v_exp_f32_e32 v91, v71
	v_fmamk_f32 v67, v67, 0x3e38aa3b, v155
	v_fmac_f32_e32 v155, 0x3e38aa3b, v69
	v_exp_f32_e32 v67, v67
	v_mfma_f32_32x32x16_bf16 v[50:65], v[76:79], v[84:87], v[50:65]
	v_cvt_pk_bf16_f32 v79, v170, v92
	v_cvt_pk_bf16_f32 v78, v167, v168
	v_cvt_pk_bf16_f32 v77, v164, v165
	v_cvt_pk_bf16_f32 v76, v162, v163
	v_exp_f32_e32 v84, v70
	v_exp_f32_e32 v85, v68
	ds_read_b128 v[68:71], v169 offset:9312
	s_waitcnt lgkmcnt(2)
	v_mfma_f32_32x32x16_bf16 v[50:65], v[72:75], v[76:79], v[50:65]
	v_exp_f32_e32 v86, v155
	v_cvt_pk_bf16_f32 v74, v84, v67
	v_cvt_pk_bf16_f32 v72, v88, v90
	v_cvt_pk_bf16_f32 v75, v85, v86
	s_waitcnt lgkmcnt(1)
	v_mfma_f32_32x32x16_bf16 v[34:49], v[80:83], v[76:79], v[34:49]
	ds_read_b128 v[76:79], v171 offset:9312
	v_exp_f32_e32 v80, v93
	v_add_f32_e32 v81, v90, v89
	v_cvt_pk_bf16_f32 v73, v91, v80
	s_waitcnt lgkmcnt(1)
	s_nop 0
	v_mfma_f32_32x32x16_bf16 v[50:65], v[68:71], v[72:75], v[50:65]
	v_add_f32_e32 v68, v91, v81
	v_add_f32_e32 v68, v80, v68
	v_add_f32_e32 v68, v84, v68
	v_add_f32_e32 v67, v67, v68
	v_add_f32_e32 v67, v85, v67
	v_add_f32_e32 v67, v86, v67
	v_add_f32_e32 v66, v66, v67
	s_waitcnt lgkmcnt(0)
	v_mfma_f32_32x32x16_bf16 v[34:49], v[76:79], v[72:75], v[34:49]
.LBB0_598:
	s_and_b64 vcc, exec, s[2:3]
	s_cbranch_vccz .LBB0_602
	s_nop 9
	v_add3_u32 v42, s37, v136, v139
	s_setprio 1
	ds_read_b128 v[34:37], v42
	ds_read_b128 v[38:41], v42 offset:16
	v_cmp_lt_i32_e32 vcc, v211, v210
	v_mov_b64_e32 v[64:65], v[16:17]
	v_mov_b32_e32 v153, v152
	s_waitcnt lgkmcnt(1)
	v_mfma_f32_32x32x16_bf16 v[82:97], v[34:37], v[98:101], 0
	v_mov_b32_e32 v154, v133
	v_mov_b64_e32 v[62:63], v[14:15]
	v_mov_b64_e32 v[60:61], v[12:13]
	v_mov_b64_e32 v[58:59], v[10:11]
	v_mov_b64_e32 v[56:57], v[8:9]
	v_mov_b64_e32 v[54:55], v[6:7]
	v_mov_b64_e32 v[52:53], v[4:5]
	s_waitcnt lgkmcnt(0)
	v_mfma_f32_32x32x16_bf16 v[82:97], v[38:41], v[102:105], v[82:97]
	ds_read_b128 v[34:37], v42 offset:32
	ds_read_b128 v[38:41], v42 offset:48
	v_mov_b64_e32 v[50:51], v[2:3]
	s_waitcnt lgkmcnt(1)
	v_mfma_f32_32x32x16_bf16 v[82:97], v[34:37], v[106:109], v[82:97]
	s_waitcnt lgkmcnt(0)
	v_mfma_f32_32x32x16_bf16 v[82:97], v[38:41], v[110:113], v[82:97]
	ds_read_b128 v[34:37], v42 offset:4608
	ds_read_b128 v[38:41], v42 offset:4624
	s_waitcnt lgkmcnt(1)
	v_mfma_f32_32x32x16_bf16 v[66:81], v[34:37], v[98:101], 0
	s_waitcnt lgkmcnt(0)
	v_mfma_f32_32x32x16_bf16 v[66:81], v[38:41], v[102:105], v[66:81]
	ds_read_b128 v[34:37], v42 offset:4640
	ds_read_b128 v[38:41], v42 offset:4656
	s_nop 3
	v_max3_f32 v42, v82, s85, v83
	s_waitcnt lgkmcnt(1)
	v_mfma_f32_32x32x16_bf16 v[66:81], v[34:37], v[106:109], v[66:81]
	v_max3_f32 v34, v42, v84, v85
	v_max3_f32 v34, v34, v86, v87
	v_max3_f32 v34, v34, v88, v89
	v_max3_f32 v34, v34, v90, v91
	v_max3_f32 v34, v34, v92, v93
	v_max3_f32 v34, v34, v94, v95
	v_max3_f32 v34, v34, v96, v97
	s_waitcnt lgkmcnt(0)
	v_mfma_f32_32x32x16_bf16 v[66:81], v[38:41], v[110:113], v[66:81]
	v_cndmask_b32_e32 v35, v209, v211, vcc
	v_lshlrev_b32_e32 v35, 2, v35
	v_add_f32_e32 v36, 0x40c00000, v152
	s_nop 8
	v_max3_f32 v34, v34, v66, v67
	v_max3_f32 v34, v34, v68, v69
	v_max3_f32 v34, v34, v70, v71
	v_max3_f32 v34, v34, v72, v73
	v_max3_f32 v34, v34, v74, v75
	v_max3_f32 v34, v34, v76, v77
	v_max3_f32 v34, v34, v78, v79
	v_max3_f32 v34, v34, v80, v81
	ds_bpermute_b32 v35, v35, v34
	s_waitcnt lgkmcnt(0)
	v_max_f32_e32 v35, v35, v35
	v_max_f32_e32 v34, v34, v35
	v_mul_f32_e32 v155, 0x3e38aa3b, v34
	v_cmp_gt_f32_e32 vcc, v155, v36
	v_mov_b64_e32 v[48:49], v[32:33]
	v_mov_b64_e32 v[46:47], v[30:31]
	v_mov_b64_e32 v[44:45], v[28:29]
	v_mov_b64_e32 v[42:43], v[26:27]
	v_mov_b64_e32 v[40:41], v[24:25]
	v_mov_b64_e32 v[38:39], v[22:23]
	v_mov_b64_e32 v[36:37], v[20:21]
	v_mov_b64_e32 v[34:35], v[18:19]
	s_cbranch_vccz .LBB0_601
	v_cndmask_b32_e32 v153, v152, v155, vcc
	v_sub_f32_e32 v34, v152, v153
	v_exp_f32_e32 v34, v34
	s_nop 0
	v_cndmask_b32_e32 v34, 1.0, v34, vcc
	v_mul_f32_e32 v154, v133, v34
	v_pk_mul_f32 v[64:65], v[16:17], v[34:35] op_sel_hi:[1,0]
	v_pk_mul_f32 v[62:63], v[14:15], v[34:35] op_sel_hi:[1,0]
	v_pk_mul_f32 v[60:61], v[12:13], v[34:35] op_sel_hi:[1,0]
	v_pk_mul_f32 v[58:59], v[10:11], v[34:35] op_sel_hi:[1,0]
	v_pk_mul_f32 v[56:57], v[8:9], v[34:35] op_sel_hi:[1,0]
	v_pk_mul_f32 v[54:55], v[6:7], v[34:35] op_sel_hi:[1,0]
	v_pk_mul_f32 v[52:53], v[4:5], v[34:35] op_sel_hi:[1,0]
	v_pk_mul_f32 v[50:51], v[2:3], v[34:35] op_sel_hi:[1,0]
	v_pk_mul_f32 v[48:49], v[32:33], v[34:35] op_sel_hi:[1,0]
	v_pk_mul_f32 v[46:47], v[30:31], v[34:35] op_sel_hi:[1,0]
	v_pk_mul_f32 v[44:45], v[28:29], v[34:35] op_sel_hi:[1,0]
	v_pk_mul_f32 v[42:43], v[26:27], v[34:35] op_sel_hi:[1,0]
	v_pk_mul_f32 v[40:41], v[24:25], v[34:35] op_sel_hi:[1,0]
	v_pk_mul_f32 v[38:39], v[22:23], v[34:35] op_sel_hi:[1,0]
	v_pk_mul_f32 v[36:37], v[20:21], v[34:35] op_sel_hi:[1,0]
	v_pk_mul_f32 v[34:35], v[18:19], v[34:35] op_sel_hi:[1,0]
.LBB0_601:
	v_cmp_neq_f32_e32 vcc, s85, v153
	s_nop 1
	v_cndmask_b32_e64 v155, 0, -v153, vcc
	v_fmamk_f32 v82, v82, 0x3e38aa3b, v155
	v_exp_f32_e32 v82, v82
	v_fmamk_f32 v83, v83, 0x3e38aa3b, v155
	v_exp_f32_e32 v156, v83
	v_fmamk_f32 v83, v84, 0x3e38aa3b, v155
	v_exp_f32_e32 v83, v83
	v_fmamk_f32 v84, v85, 0x3e38aa3b, v155
	v_exp_f32_e32 v157, v84
	v_fmamk_f32 v85, v86, 0x3e38aa3b, v155
	v_add_f32_e32 v84, 0, v82
	v_exp_f32_e32 v86, v85
	v_fmamk_f32 v85, v87, 0x3e38aa3b, v155
	v_add_f32_e32 v84, v156, v84
	v_exp_f32_e32 v87, v85
	v_fmamk_f32 v85, v88, 0x3e38aa3b, v155
	v_add_f32_e32 v84, v83, v84
	v_exp_f32_e32 v85, v85
	v_fmamk_f32 v88, v89, 0x3e38aa3b, v155
	v_add_f32_e32 v84, v157, v84
	v_exp_f32_e32 v88, v88
	v_fmamk_f32 v89, v90, 0x3e38aa3b, v155
	v_add_f32_e32 v84, v86, v84
	v_exp_f32_e32 v90, v89
	v_fmamk_f32 v89, v91, 0x3e38aa3b, v155
	v_add_f32_e32 v84, v87, v84
	v_exp_f32_e32 v91, v89
	v_fmamk_f32 v89, v92, 0x3e38aa3b, v155
	v_add_f32_e32 v84, v85, v84
	v_exp_f32_e32 v92, v89
	v_fmamk_f32 v89, v93, 0x3e38aa3b, v155
	v_add_f32_e32 v84, v88, v84
	v_exp_f32_e32 v93, v89
	v_fmamk_f32 v89, v94, 0x3e38aa3b, v155
	v_add_f32_e32 v84, v90, v84
	v_exp_f32_e32 v94, v89
	v_fmamk_f32 v89, v95, 0x3e38aa3b, v155
	v_add_f32_e32 v84, v91, v84
	v_exp_f32_e32 v95, v89
	v_fmamk_f32 v89, v96, 0x3e38aa3b, v155
	v_add_f32_e32 v84, v92, v84
	v_exp_f32_e32 v96, v89
	v_fmamk_f32 v89, v97, 0x3e38aa3b, v155
	v_add_f32_e32 v84, v93, v84
	v_exp_f32_e32 v97, v89
	v_fmamk_f32 v66, v66, 0x3e38aa3b, v155
	v_add_f32_e32 v84, v94, v84
	v_exp_f32_e32 v158, v66
	v_fmamk_f32 v66, v67, 0x3e38aa3b, v155
	v_add_f32_e32 v84, v95, v84
	v_exp_f32_e32 v159, v66
	v_fmamk_f32 v66, v68, 0x3e38aa3b, v155
	v_add_f32_e32 v84, v96, v84
	v_exp_f32_e32 v160, v66
	v_fmamk_f32 v66, v69, 0x3e38aa3b, v155
	v_add_f32_e32 v84, v97, v84
	v_exp_f32_e32 v161, v66
	v_add_f32_e32 v66, v158, v84
	v_add_f32_e32 v66, v159, v66
	v_add_f32_e32 v66, v160, v66
	v_add_f32_e32 v162, v161, v66
	v_fmamk_f32 v66, v70, 0x3e38aa3b, v155
	v_lshlrev_b32_e32 v70, 1, v147
	v_exp_f32_e32 v163, v66
	v_fmamk_f32 v66, v71, 0x3e38aa3b, v155
	v_add3_u32 v165, s37, v146, v70
	v_exp_f32_e32 v164, v66
	s_setprio 1
	ds_read_b128 v[66:69], v165 offset:9216
	v_fmamk_f32 v71, v72, 0x3e38aa3b, v155
	v_add3_u32 v167, s37, v148, v70
	v_cvt_pk_bf16_f32 v85, v85, v88
	v_cvt_pk_bf16_f32 v84, v86, v87
	v_cvt_pk_bf16_f32 v83, v83, v157
	v_cvt_pk_bf16_f32 v82, v82, v156
	v_exp_f32_e32 v166, v71
	ds_read_b128 v[86:89], v167 offset:9216
	s_waitcnt lgkmcnt(1)
	v_mfma_f32_32x32x16_bf16 v[50:65], v[66:69], v[82:85], v[50:65]
	v_fmamk_f32 v66, v73, 0x3e38aa3b, v155
	v_exp_f32_e32 v156, v66
	v_add_f32_e32 v66, v163, v162
	v_add_f32_e32 v66, v164, v66
	v_add_f32_e32 v66, v166, v66
	v_add_f32_e32 v157, v156, v66
	ds_read_b128 v[66:69], v165 offset:9248
	v_fmamk_f32 v70, v74, 0x3e38aa3b, v155
	s_waitcnt lgkmcnt(1)
	v_mfma_f32_32x32x16_bf16 v[34:49], v[86:89], v[82:85], v[34:49]
	v_exp_f32_e32 v86, v70
	ds_read_b128 v[70:73], v167 offset:9248
	v_cvt_pk_bf16_f32 v85, v96, v97
	v_cvt_pk_bf16_f32 v84, v94, v95
	v_cvt_pk_bf16_f32 v83, v92, v93
	v_cvt_pk_bf16_f32 v82, v90, v91
	v_fmamk_f32 v90, v77, 0x3e38aa3b, v155
	v_add_f32_e32 v87, v86, v157
	s_waitcnt lgkmcnt(1)
	v_mfma_f32_32x32x16_bf16 v[50:65], v[66:69], v[82:85], v[50:65]
	v_fmamk_f32 v66, v75, 0x3e38aa3b, v155
	v_exp_f32_e32 v88, v66
	v_fmamk_f32 v66, v76, 0x3e38aa3b, v155
	v_exp_f32_e32 v89, v66
	ds_read_b128 v[66:69], v165 offset:9280
	ds_read_b128 v[74:77], v167 offset:9280
	s_waitcnt lgkmcnt(2)
	v_mfma_f32_32x32x16_bf16 v[34:49], v[70:73], v[82:85], v[34:49]
	v_fmamk_f32 v70, v78, 0x3e38aa3b, v155
	v_exp_f32_e32 v78, v70
	v_cvt_pk_bf16_f32 v73, v166, v156
	v_cvt_pk_bf16_f32 v72, v163, v164
	v_cvt_pk_bf16_f32 v71, v160, v161
	v_cvt_pk_bf16_f32 v70, v158, v159
	v_exp_f32_e32 v82, v90
	v_add_f32_e32 v83, v88, v87
	s_waitcnt lgkmcnt(1)
	v_mfma_f32_32x32x16_bf16 v[50:65], v[66:69], v[70:73], v[50:65]
	v_fmamk_f32 v66, v79, 0x3e38aa3b, v155
	v_exp_f32_e32 v79, v66
	v_fmamk_f32 v66, v80, 0x3e38aa3b, v155
	v_exp_f32_e32 v80, v66
	ds_read_b128 v[66:69], v165 offset:9312
	v_fmac_f32_e32 v155, 0x3e38aa3b, v81
	v_exp_f32_e32 v81, v155
	s_waitcnt lgkmcnt(1)
	v_mfma_f32_32x32x16_bf16 v[34:49], v[74:77], v[70:73], v[34:49]
	ds_read_b128 v[74:77], v167 offset:9312
	v_cvt_pk_bf16_f32 v72, v78, v79
	v_cvt_pk_bf16_f32 v73, v80, v81
	v_cvt_pk_bf16_f32 v71, v89, v82
	v_cvt_pk_bf16_f32 v70, v86, v88
	s_waitcnt lgkmcnt(1)
	s_nop 0
	v_mfma_f32_32x32x16_bf16 v[50:65], v[66:69], v[70:73], v[50:65]
	v_add_f32_e32 v66, v89, v83
	v_add_f32_e32 v66, v82, v66
	v_add_f32_e32 v66, v78, v66
	v_add_f32_e32 v66, v79, v66
	v_add_f32_e32 v66, v80, v66
	v_add_f32_e32 v66, v81, v66
	v_add_f32_e32 v66, v154, v66
	s_waitcnt lgkmcnt(0)
	v_mfma_f32_32x32x16_bf16 v[34:49], v[74:77], v[70:73], v[34:49]

.LBB0_603:
	s_andn2_b64 vcc, exec, s[2:3]
	s_cbranch_vccnz .LBB0_614
	s_cmp_gt_i32 s76, 1
	s_mov_b64 s[2:3], -1
	s_cbranch_scc0 .LBB0_608
	s_nop 5
	v_add3_u32 v46, s37, v136, v139
	s_setprio 1
	ds_read_b128 v[34:37], v46
	ds_read_b128 v[38:41], v46 offset:16
	v_cmp_lt_i32_e32 vcc, -1, v151
	v_cmp_gt_i32_e64 s[38:39], 1, v151
	v_cmp_gt_i32_e64 s[40:41], 32, v151
	s_waitcnt lgkmcnt(1)
	v_mfma_f32_32x32x16_bf16 v[66:81], v[34:37], v[98:101], 0
	v_cmp_gt_i32_e64 s[42:43], 33, v151
	v_cmp_gt_i32_e64 s[44:45], 34, v151
	v_cmp_gt_i32_e64 s[46:47], 35, v151
	v_cmp_gt_i32_e64 s[48:49], 36, v151
	v_cmp_gt_i32_e64 s[50:51], 37, v151
	v_cmp_gt_i32_e64 s[52:53], 38, v151
	v_cmp_gt_i32_e64 s[56:57], 39, v151
	s_waitcnt lgkmcnt(0)
	v_mfma_f32_32x32x16_bf16 v[66:81], v[38:41], v[102:105], v[66:81]
	ds_read_b128 v[34:37], v46 offset:32
	ds_read_b128 v[38:41], v46 offset:48
	v_cmp_gt_i32_e64 s[58:59], 48, v151
	v_cmp_gt_i32_e64 s[60:61], 49, v151
	v_cmp_gt_i32_e64 s[62:63], 50, v151
	v_cmp_gt_i32_e64 s[64:65], 51, v151
	v_cmp_gt_i32_e64 s[66:67], 52, v151
	v_cmp_gt_i32_e64 s[68:69], 53, v151
	s_waitcnt lgkmcnt(1)
	v_mfma_f32_32x32x16_bf16 v[66:81], v[34:37], v[106:109], v[66:81]
	ds_read_b128 v[34:37], v46 offset:4608
	ds_read_b128 v[42:45], v46 offset:4624
	v_cmp_gt_i32_e64 s[70:71], 54, v151
	v_cmp_gt_i32_e64 s[54:55], 55, v151
	v_mov_b64_e32 v[64:65], v[16:17]
	v_mov_b32_e32 v153, v152
	v_mov_b64_e32 v[62:63], v[14:15]
	v_mov_b64_e32 v[60:61], v[12:13]
	s_waitcnt lgkmcnt(1)
	v_mfma_f32_32x32x16_bf16 v[82:97], v[34:37], v[98:101], 0
	ds_read_b128 v[34:37], v46 offset:4640
	ds_read_b128 v[46:49], v46 offset:4656
	v_mov_b64_e32 v[58:59], v[10:11]
	v_mov_b64_e32 v[56:57], v[8:9]
	v_mov_b64_e32 v[54:55], v[6:7]
	v_mov_b64_e32 v[52:53], v[4:5]
	v_mov_b64_e32 v[50:51], v[2:3]
	s_waitcnt lgkmcnt(2)
	v_mfma_f32_32x32x16_bf16 v[82:97], v[42:45], v[102:105], v[82:97]
	v_mfma_f32_32x32x16_bf16 v[66:81], v[38:41], v[110:113], v[66:81]
	s_waitcnt lgkmcnt(1)
	v_mfma_f32_32x32x16_bf16 v[82:97], v[34:37], v[106:109], v[82:97]
	s_nop 9
	v_cndmask_b32_e32 v158, v220, v66, vcc
	v_cmp_lt_i32_e32 vcc, 1, v151
	v_cndmask_b32_e64 v154, v67, v220, s[38:39]
	v_max3_f32 v38, v158, s85, v154
	v_cndmask_b32_e32 v155, v220, v68, vcc
	v_cmp_lt_i32_e32 vcc, 2, v151
	v_mov_b32_e32 v68, v133
	s_waitcnt lgkmcnt(0)
	v_mfma_f32_32x32x16_bf16 v[82:97], v[46:49], v[110:113], v[82:97]
	v_cndmask_b32_e32 v156, v220, v69, vcc
	v_cmp_lt_i32_e32 vcc, 3, v151
	v_max3_f32 v38, v38, v155, v156
	s_nop 0
	v_cndmask_b32_e32 v157, v220, v70, vcc
	v_cmp_lt_i32_e32 vcc, 4, v151
	s_nop 5
	v_cndmask_b32_e64 v159, v83, v220, s[42:43]
	v_cndmask_b32_e32 v69, v220, v71, vcc
	v_cmp_lt_i32_e32 vcc, 5, v151
	v_max3_f32 v38, v38, v157, v69
	v_cndmask_b32_e64 v160, v84, v220, s[44:45]
	v_cndmask_b32_e32 v70, v220, v72, vcc
	v_cmp_lt_i32_e32 vcc, 6, v151
	v_cndmask_b32_e64 v161, v85, v220, s[46:47]
	v_cndmask_b32_e64 v162, v86, v220, s[48:49]
	v_cndmask_b32_e32 v71, v220, v73, vcc
	v_cmp_lt_i32_e32 vcc, 15, v151
	v_max3_f32 v38, v38, v70, v71
	v_cndmask_b32_e64 v163, v87, v220, s[50:51]
	v_cndmask_b32_e32 v73, v220, v74, vcc
	v_cmp_lt_i32_e32 vcc, 16, v151
	v_cndmask_b32_e64 v165, v88, v220, s[52:53]
	v_cndmask_b32_e64 v166, v89, v220, s[56:57]
	v_cndmask_b32_e32 v72, v220, v75, vcc
	v_cmp_lt_i32_e32 vcc, 17, v151
	v_max3_f32 v38, v38, v73, v72
	v_cndmask_b32_e64 v167, v90, v220, s[58:59]
	v_cndmask_b32_e32 v74, v220, v76, vcc
	v_cmp_lt_i32_e32 vcc, 18, v151
	v_cndmask_b32_e64 v168, v91, v220, s[60:61]
	v_cndmask_b32_e64 v169, v92, v220, s[62:63]
	v_cndmask_b32_e32 v75, v220, v77, vcc
	v_cmp_lt_i32_e32 vcc, 19, v151
	v_max3_f32 v38, v38, v74, v75
	v_cndmask_b32_e64 v170, v93, v220, s[64:65]
	v_cndmask_b32_e32 v76, v220, v78, vcc
	v_cmp_lt_i32_e32 vcc, 20, v151
	v_cndmask_b32_e64 v171, v94, v220, s[66:67]
	v_cndmask_b32_e64 v172, v95, v220, s[68:69]
	v_cndmask_b32_e32 v77, v220, v79, vcc
	v_cmp_lt_i32_e32 vcc, 21, v151
	v_max3_f32 v34, v38, v76, v77
	v_cndmask_b32_e64 v164, v96, v220, s[70:71]
	v_cndmask_b32_e32 v78, v220, v80, vcc
	v_cmp_lt_i32_e32 vcc, 22, v151
	v_cndmask_b32_e64 v80, v82, v220, s[40:41]
	v_cndmask_b32_e64 v67, v97, v220, s[54:55]
	v_cndmask_b32_e32 v79, v220, v81, vcc
	v_max3_f32 v34, v34, v78, v79
	v_max3_f32 v34, v34, v80, v159
	v_max3_f32 v34, v34, v160, v161
	v_max3_f32 v34, v34, v162, v163
	v_max3_f32 v34, v34, v165, v166
	v_max3_f32 v34, v34, v167, v168
	v_max3_f32 v34, v34, v169, v170
	v_cmp_lt_i32_e32 vcc, v211, v210
	v_max3_f32 v34, v34, v171, v172
	v_max3_f32 v34, v34, v164, v67
	v_cndmask_b32_e32 v35, v209, v211, vcc
	v_lshlrev_b32_e32 v35, 2, v35
	ds_bpermute_b32 v35, v35, v34
	s_waitcnt lgkmcnt(0)
	v_max_f32_e32 v35, v35, v35
	v_max_f32_e32 v34, v34, v35
	v_mul_f32_e32 v97, 0x3e38aa3b, v34
	v_add_f32_e32 v34, 0x40c00000, v152
	v_cmp_gt_f32_e32 vcc, v97, v34
	v_mov_b64_e32 v[48:49], v[32:33]
	v_mov_b64_e32 v[46:47], v[30:31]
	v_mov_b64_e32 v[44:45], v[28:29]
	v_mov_b64_e32 v[42:43], v[26:27]
	v_mov_b64_e32 v[40:41], v[24:25]
	v_mov_b64_e32 v[38:39], v[22:23]
	v_mov_b64_e32 v[36:37], v[20:21]
	v_mov_b64_e32 v[34:35], v[18:19]
	s_cbranch_vccz .LBB0_607
	v_cndmask_b32_e32 v153, v152, v97, vcc
	v_sub_f32_e32 v34, v152, v153
	v_exp_f32_e32 v34, v34
	s_nop 0
	v_cndmask_b32_e32 v34, 1.0, v34, vcc
	v_mul_f32_e32 v68, v133, v34
	v_pk_mul_f32 v[64:65], v[16:17], v[34:35] op_sel_hi:[1,0]
	v_pk_mul_f32 v[62:63], v[14:15], v[34:35] op_sel_hi:[1,0]
	v_pk_mul_f32 v[60:61], v[12:13], v[34:35] op_sel_hi:[1,0]
	v_pk_mul_f32 v[58:59], v[10:11], v[34:35] op_sel_hi:[1,0]
	v_pk_mul_f32 v[56:57], v[8:9], v[34:35] op_sel_hi:[1,0]
	v_pk_mul_f32 v[54:55], v[6:7], v[34:35] op_sel_hi:[1,0]
	v_pk_mul_f32 v[52:53], v[4:5], v[34:35] op_sel_hi:[1,0]
	v_pk_mul_f32 v[50:51], v[2:3], v[34:35] op_sel_hi:[1,0]
	v_pk_mul_f32 v[48:49], v[32:33], v[34:35] op_sel_hi:[1,0]
	v_pk_mul_f32 v[46:47], v[30:31], v[34:35] op_sel_hi:[1,0]
	v_pk_mul_f32 v[44:45], v[28:29], v[34:35] op_sel_hi:[1,0]
	v_pk_mul_f32 v[42:43], v[26:27], v[34:35] op_sel_hi:[1,0]
	v_pk_mul_f32 v[40:41], v[24:25], v[34:35] op_sel_hi:[1,0]
	v_pk_mul_f32 v[38:39], v[22:23], v[34:35] op_sel_hi:[1,0]
	v_pk_mul_f32 v[36:37], v[20:21], v[34:35] op_sel_hi:[1,0]
	v_pk_mul_f32 v[34:35], v[18:19], v[34:35] op_sel_hi:[1,0]
.LBB0_607:
	s_and_b64 vcc, s[54:55], s[70:71]
	v_cndmask_b32_e32 v95, v95, v172, vcc
	s_and_b64 vcc, vcc, s[68:69]
	v_cndmask_b32_e32 v94, v94, v171, vcc
	s_and_b64 vcc, vcc, s[66:67]
	v_cndmask_b32_e32 v93, v93, v170, vcc
	s_and_b64 vcc, vcc, s[64:65]
	v_cndmask_b32_e32 v92, v92, v169, vcc
	s_and_b64 vcc, vcc, s[62:63]
	v_cndmask_b32_e32 v91, v91, v168, vcc
	s_and_b64 vcc, vcc, s[60:61]
	v_cndmask_b32_e32 v90, v90, v167, vcc
	s_and_b64 vcc, vcc, s[58:59]
	v_cndmask_b32_e32 v89, v89, v166, vcc
	s_and_b64 vcc, vcc, s[56:57]
	v_cndmask_b32_e32 v88, v88, v165, vcc
	s_and_b64 vcc, vcc, s[52:53]
	v_cndmask_b32_e32 v87, v87, v163, vcc
	s_and_b64 vcc, vcc, s[50:51]
	v_cndmask_b32_e32 v86, v86, v162, vcc
	s_and_b64 vcc, vcc, s[48:49]
	v_cndmask_b32_e64 v66, v66, v158, s[38:39]
	v_cndmask_b32_e32 v85, v85, v161, vcc
	s_and_b64 vcc, vcc, s[46:47]
	v_cmp_neq_f32_e64 s[38:39], s85, v153
	v_cndmask_b32_e32 v84, v84, v160, vcc
	s_and_b64 vcc, vcc, s[44:45]
	v_cndmask_b32_e64 v97, 0, -v153, s[38:39]
	v_cndmask_b32_e32 v83, v83, v159, vcc
	s_and_b64 vcc, vcc, s[42:43]
	v_fmamk_f32 v66, v66, 0x3e38aa3b, v97
	v_cndmask_b32_e32 v80, v82, v80, vcc
	v_exp_f32_e32 v66, v66
	v_fmamk_f32 v82, v154, 0x3e38aa3b, v97
	v_exp_f32_e32 v82, v82
	v_fmamk_f32 v154, v155, 0x3e38aa3b, v97
	v_exp_f32_e32 v154, v154
	v_fmamk_f32 v155, v156, 0x3e38aa3b, v97
	s_and_b64 vcc, vcc, s[40:41]
	v_exp_f32_e32 v155, v155
	v_fmamk_f32 v156, v157, 0x3e38aa3b, v97
	v_cndmask_b32_e32 v79, v81, v79, vcc
	v_add_f32_e32 v81, 0, v66
	v_exp_f32_e32 v156, v156
	v_fmamk_f32 v69, v69, 0x3e38aa3b, v97
	v_add_f32_e32 v81, v82, v81
	v_exp_f32_e32 v69, v69
	v_fmamk_f32 v70, v70, 0x3e38aa3b, v97
	v_add_f32_e32 v81, v154, v81
	v_exp_f32_e32 v157, v70
	v_fmamk_f32 v70, v71, 0x3e38aa3b, v97
	v_add_f32_e32 v81, v155, v81
	v_exp_f32_e32 v158, v70
	v_fmamk_f32 v70, v73, 0x3e38aa3b, v97
	v_add_f32_e32 v81, v156, v81
	v_exp_f32_e32 v159, v70
	v_fmamk_f32 v71, v72, 0x3e38aa3b, v97
	v_add_f32_e32 v70, v69, v81
	v_exp_f32_e32 v160, v71
	v_fmamk_f32 v71, v74, 0x3e38aa3b, v97
	v_add_f32_e32 v70, v157, v70
	v_exp_f32_e32 v161, v71
	v_fmamk_f32 v71, v75, 0x3e38aa3b, v97
	v_add_f32_e32 v70, v158, v70
	v_exp_f32_e32 v162, v71
	v_fmamk_f32 v71, v76, 0x3e38aa3b, v97
	v_add_f32_e32 v70, v159, v70
	v_exp_f32_e32 v163, v71
	v_fmamk_f32 v71, v77, 0x3e38aa3b, v97
	v_cndmask_b32_e64 v96, v96, v164, s[54:55]
	v_add_f32_e32 v70, v160, v70
	v_exp_f32_e32 v164, v71
	v_fmamk_f32 v71, v78, 0x3e38aa3b, v97
	v_add_f32_e32 v70, v161, v70
	v_exp_f32_e32 v165, v71
	v_fmamk_f32 v71, v79, 0x3e38aa3b, v97
	v_add_f32_e32 v70, v162, v70
	v_exp_f32_e32 v166, v71
	v_fmamk_f32 v71, v80, 0x3e38aa3b, v97
	v_add_f32_e32 v70, v163, v70
	v_exp_f32_e32 v167, v71
	v_fmamk_f32 v71, v83, 0x3e38aa3b, v97
	v_add_f32_e32 v70, v164, v70
	v_exp_f32_e32 v168, v71
	v_fmamk_f32 v71, v84, 0x3e38aa3b, v97
	v_add_f32_e32 v70, v165, v70
	v_exp_f32_e32 v169, v71
	v_fmamk_f32 v71, v85, 0x3e38aa3b, v97
	v_add_f32_e32 v70, v166, v70
	v_exp_f32_e32 v170, v71
	v_fmamk_f32 v71, v86, 0x3e38aa3b, v97
	v_add_f32_e32 v70, v167, v70
	v_exp_f32_e32 v86, v71
	v_add_f32_e32 v70, v168, v70
	v_add_f32_e32 v70, v169, v70
	v_lshlrev_b32_e32 v75, 1, v147
	v_add_f32_e32 v70, v170, v70
	v_fmamk_f32 v74, v87, 0x3e38aa3b, v97
	v_add3_u32 v87, s37, v146, v75
	v_add_f32_e32 v171, v86, v70
	s_setprio 1
	ds_read_b128 v[70:73], v87 offset:9216
	v_exp_f32_e32 v172, v74
	v_add3_u32 v173, s37, v148, v75
	v_cvt_pk_bf16_f32 v77, v157, v158
	v_cvt_pk_bf16_f32 v76, v156, v69
	v_cvt_pk_bf16_f32 v75, v154, v155
	v_cvt_pk_bf16_f32 v74, v66, v82
	ds_read_b128 v[78:81], v87 offset:9248
	ds_read_b128 v[82:85], v173 offset:9216
	s_waitcnt lgkmcnt(2)
	v_mfma_f32_32x32x16_bf16 v[50:65], v[70:73], v[74:77], v[50:65]
	v_fmamk_f32 v70, v89, 0x3e38aa3b, v97
	v_fmamk_f32 v66, v88, 0x3e38aa3b, v97
	v_exp_f32_e32 v88, v70
	ds_read_b128 v[70:73], v173 offset:9248
	v_exp_f32_e32 v66, v66
	v_add_f32_e32 v69, v172, v171
	s_mov_b64 s[2:3], 0
	s_waitcnt lgkmcnt(1)
	v_mfma_f32_32x32x16_bf16 v[34:49], v[82:85], v[74:77], v[34:49]
	v_fmamk_f32 v74, v90, 0x3e38aa3b, v97
	v_exp_f32_e32 v89, v74
	v_cvt_pk_bf16_f32 v77, v165, v166
	v_cvt_pk_bf16_f32 v76, v163, v164
	v_cvt_pk_bf16_f32 v75, v161, v162
	v_cvt_pk_bf16_f32 v74, v159, v160
	v_add_f32_e32 v69, v66, v69
	v_add_f32_e32 v69, v88, v69
	v_mfma_f32_32x32x16_bf16 v[50:65], v[78:81], v[74:77], v[50:65]
	v_fmamk_f32 v78, v91, 0x3e38aa3b, v97
	v_exp_f32_e32 v90, v78
	v_fmamk_f32 v78, v92, 0x3e38aa3b, v97
	v_exp_f32_e32 v91, v78
	ds_read_b128 v[78:81], v87 offset:9280
	v_fmamk_f32 v92, v93, 0x3e38aa3b, v97
	v_fmamk_f32 v93, v94, 0x3e38aa3b, v97
	s_waitcnt lgkmcnt(1)
	v_mfma_f32_32x32x16_bf16 v[34:49], v[70:73], v[74:77], v[34:49]
	ds_read_b128 v[74:77], v173 offset:9280
	ds_read_b128 v[82:85], v87 offset:9312
	v_cvt_pk_bf16_f32 v73, v66, v88
	v_cvt_pk_bf16_f32 v72, v86, v172
	v_cvt_pk_bf16_f32 v71, v169, v170
	v_cvt_pk_bf16_f32 v70, v167, v168
	v_fmamk_f32 v86, v95, 0x3e38aa3b, v97
	v_exp_f32_e32 v66, v93
	s_waitcnt lgkmcnt(2)
	v_mfma_f32_32x32x16_bf16 v[50:65], v[78:81], v[70:73], v[50:65]
	v_fmamk_f32 v78, v96, 0x3e38aa3b, v97
	v_exp_f32_e32 v87, v78
	ds_read_b128 v[78:81], v173 offset:9312
	v_fmac_f32_e32 v97, 0x3e38aa3b, v67
	v_exp_f32_e32 v67, v97
	v_add_f32_e32 v69, v89, v69
	v_add_f32_e32 v69, v90, v69
	s_waitcnt lgkmcnt(2)
	v_mfma_f32_32x32x16_bf16 v[34:49], v[74:77], v[70:73], v[34:49]
	v_exp_f32_e32 v74, v86
	v_exp_f32_e32 v75, v92
	v_cvt_pk_bf16_f32 v73, v87, v67
	v_cvt_pk_bf16_f32 v70, v89, v90
	v_cvt_pk_bf16_f32 v72, v66, v74
	v_cvt_pk_bf16_f32 v71, v91, v75
	v_add_f32_e32 v69, v91, v69
	v_add_f32_e32 v69, v75, v69
	s_waitcnt lgkmcnt(1)
	v_mfma_f32_32x32x16_bf16 v[50:65], v[82:85], v[70:73], v[50:65]
	v_add_f32_e32 v66, v66, v69
	v_add_f32_e32 v66, v74, v66
	v_add_f32_e32 v66, v87, v66
	v_add_f32_e32 v66, v67, v66
	v_add_f32_e32 v66, v68, v66
	s_waitcnt lgkmcnt(0)
	v_mfma_f32_32x32x16_bf16 v[34:49], v[78:81], v[70:73], v[34:49]
.LBB0_608:
	s_and_b64 vcc, exec, s[2:3]
	s_cbranch_vccz .LBB0_614
	s_cmp_lg_u32 s76, 1
	s_cbranch_scc1 .LBB0_613
	v_add3_u32 v70, s37, v136, v139
	s_nop 6
	s_setprio 1
	ds_read_b128 v[34:37], v70
	ds_read_b128 v[38:41], v70 offset:16
	ds_read_b128 v[42:45], v70 offset:32
	ds_read_b128 v[46:49], v70 offset:48
	v_cmp_lt_i32_e32 vcc, v211, v210
	s_waitcnt lgkmcnt(3)
	v_mfma_f32_32x32x16_bf16 v[50:65], v[34:37], v[98:101], 0
	ds_read_b128 v[34:37], v70 offset:4608
	ds_read_b128 v[66:69], v70 offset:4624
	s_waitcnt lgkmcnt(4)
	v_mfma_f32_32x32x16_bf16 v[50:65], v[38:41], v[102:105], v[50:65]
	s_waitcnt lgkmcnt(3)
	v_mfma_f32_32x32x16_bf16 v[50:65], v[42:45], v[106:109], v[50:65]
	s_waitcnt lgkmcnt(2)
	v_mfma_f32_32x32x16_bf16 v[50:65], v[46:49], v[110:113], v[50:65]
	s_waitcnt lgkmcnt(1)
	v_mfma_f32_32x32x16_bf16 v[34:49], v[34:37], v[98:101], 0
	s_waitcnt lgkmcnt(0)
	v_mfma_f32_32x32x16_bf16 v[34:49], v[66:69], v[102:105], v[34:49]
	ds_read_b128 v[66:69], v70 offset:4640
	s_waitcnt lgkmcnt(0)
	v_mfma_f32_32x32x16_bf16 v[34:49], v[66:69], v[106:109], v[34:49]
	ds_read_b128 v[66:69], v70 offset:4656
	s_waitcnt lgkmcnt(0)
	v_mfma_f32_32x32x16_bf16 v[34:49], v[66:69], v[110:113], v[34:49]
	s_nop 1
	v_max3_f32 v66, v50, s85, v51
	v_max3_f32 v66, v66, v52, v53
	v_max3_f32 v66, v66, v54, v55
	v_max3_f32 v66, v66, v56, v57
	v_max3_f32 v66, v66, v58, v59
	v_max3_f32 v66, v66, v60, v61
	v_max3_f32 v66, v66, v62, v63
	v_max3_f32 v66, v66, v64, v65
	s_nop 1
	v_max3_f32 v66, v66, v34, v35
	v_max3_f32 v66, v66, v36, v37
	v_max3_f32 v66, v66, v38, v39
	v_max3_f32 v66, v66, v40, v41
	v_max3_f32 v66, v66, v42, v43
	v_max3_f32 v66, v66, v44, v45
	v_max3_f32 v66, v66, v46, v47
	v_cndmask_b32_e32 v67, v209, v211, vcc
	v_max3_f32 v66, v66, v48, v49
	v_lshlrev_b32_e32 v67, 2, v67
	ds_bpermute_b32 v67, v67, v66
	s_waitcnt lgkmcnt(0)
	v_max_f32_e32 v67, v67, v67
	v_max_f32_e32 v66, v66, v67
	v_mul_f32_e32 v66, 0x3e38aa3b, v66
	v_add_f32_e32 v67, 0x40c00000, v152
	v_cmp_gt_f32_e32 vcc, v66, v67
	s_cbranch_vccz .LBB0_612
	s_nop 0
	v_cndmask_b32_e32 v67, v152, v66, vcc
	v_sub_f32_e32 v66, v152, v67
	v_exp_f32_e32 v66, v66
	v_mov_b32_e32 v152, v67
	v_cndmask_b32_e32 v66, 1.0, v66, vcc
	v_mul_f32_e32 v133, v133, v66
	v_pk_mul_f32 v[16:17], v[16:17], v[66:67] op_sel_hi:[1,0]
	v_pk_mul_f32 v[14:15], v[14:15], v[66:67] op_sel_hi:[1,0]
	v_pk_mul_f32 v[12:13], v[12:13], v[66:67] op_sel_hi:[1,0]
	v_pk_mul_f32 v[10:11], v[10:11], v[66:67] op_sel_hi:[1,0]
	v_pk_mul_f32 v[8:9], v[8:9], v[66:67] op_sel_hi:[1,0]
	v_pk_mul_f32 v[6:7], v[6:7], v[66:67] op_sel_hi:[1,0]
	v_pk_mul_f32 v[4:5], v[4:5], v[66:67] op_sel_hi:[1,0]
	v_pk_mul_f32 v[2:3], v[2:3], v[66:67] op_sel_hi:[1,0]
	v_pk_mul_f32 v[32:33], v[32:33], v[66:67] op_sel_hi:[1,0]
	v_pk_mul_f32 v[30:31], v[30:31], v[66:67] op_sel_hi:[1,0]
	v_pk_mul_f32 v[28:29], v[28:29], v[66:67] op_sel_hi:[1,0]
	v_pk_mul_f32 v[26:27], v[26:27], v[66:67] op_sel_hi:[1,0]
	v_pk_mul_f32 v[24:25], v[24:25], v[66:67] op_sel_hi:[1,0]
	v_pk_mul_f32 v[22:23], v[22:23], v[66:67] op_sel_hi:[1,0]
	v_pk_mul_f32 v[20:21], v[20:21], v[66:67] op_sel_hi:[1,0]
	v_pk_mul_f32 v[18:19], v[18:19], v[66:67] op_sel_hi:[1,0]
.LBB0_612:
	v_cmp_neq_f32_e32 vcc, s85, v152
	s_nop 1
	v_cndmask_b32_e64 v66, 0, -v152, vcc
	v_fmamk_f32 v50, v50, 0x3e38aa3b, v66
	v_exp_f32_e32 v50, v50
	v_fmamk_f32 v51, v51, 0x3e38aa3b, v66
	v_exp_f32_e32 v67, v51
	v_fmamk_f32 v51, v52, 0x3e38aa3b, v66
	v_exp_f32_e32 v51, v51
	v_fmamk_f32 v52, v53, 0x3e38aa3b, v66
	v_exp_f32_e32 v68, v52
	v_fmamk_f32 v53, v54, 0x3e38aa3b, v66
	v_add_f32_e32 v52, 0, v50
	v_exp_f32_e32 v54, v53
	v_fmamk_f32 v53, v55, 0x3e38aa3b, v66
	v_add_f32_e32 v52, v67, v52
	v_exp_f32_e32 v55, v53
	v_fmamk_f32 v53, v56, 0x3e38aa3b, v66
	v_add_f32_e32 v52, v51, v52
	v_exp_f32_e32 v53, v53
	v_fmamk_f32 v56, v57, 0x3e38aa3b, v66
	v_add_f32_e32 v52, v68, v52
	v_exp_f32_e32 v56, v56
	v_fmamk_f32 v57, v58, 0x3e38aa3b, v66
	v_add_f32_e32 v52, v54, v52
	v_exp_f32_e32 v58, v57
	v_fmamk_f32 v57, v59, 0x3e38aa3b, v66
	v_add_f32_e32 v52, v55, v52
	v_exp_f32_e32 v59, v57
	v_fmamk_f32 v57, v60, 0x3e38aa3b, v66
	v_add_f32_e32 v52, v53, v52
	v_exp_f32_e32 v60, v57
	v_fmamk_f32 v57, v61, 0x3e38aa3b, v66
	v_add_f32_e32 v52, v56, v52
	v_exp_f32_e32 v61, v57
	v_fmamk_f32 v57, v62, 0x3e38aa3b, v66
	v_add_f32_e32 v52, v58, v52
	v_exp_f32_e32 v62, v57
	v_fmamk_f32 v57, v63, 0x3e38aa3b, v66
	v_add_f32_e32 v52, v59, v52
	v_exp_f32_e32 v63, v57
	v_fmamk_f32 v57, v64, 0x3e38aa3b, v66
	v_add_f32_e32 v52, v60, v52
	v_exp_f32_e32 v64, v57
	v_fmamk_f32 v57, v65, 0x3e38aa3b, v66
	v_add_f32_e32 v52, v61, v52
	v_exp_f32_e32 v65, v57
	v_fmamk_f32 v34, v34, 0x3e38aa3b, v66
	v_add_f32_e32 v52, v62, v52
	v_exp_f32_e32 v69, v34
	v_fmamk_f32 v34, v35, 0x3e38aa3b, v66
	v_add_f32_e32 v52, v63, v52
	v_exp_f32_e32 v70, v34
	v_fmamk_f32 v34, v36, 0x3e38aa3b, v66
	v_add_f32_e32 v52, v64, v52
	v_exp_f32_e32 v71, v34
	v_fmamk_f32 v34, v37, 0x3e38aa3b, v66
	v_add_f32_e32 v52, v65, v52
	v_exp_f32_e32 v72, v34
	v_add_f32_e32 v34, v69, v52
	v_add_f32_e32 v34, v70, v34
	v_add_f32_e32 v34, v71, v34
	v_add_f32_e32 v73, v72, v34
	v_fmamk_f32 v34, v38, 0x3e38aa3b, v66
	v_lshlrev_b32_e32 v38, 1, v147
	v_exp_f32_e32 v74, v34
	v_fmamk_f32 v34, v39, 0x3e38aa3b, v66
	v_add3_u32 v76, s37, v146, v38
	v_exp_f32_e32 v75, v34
	s_setprio 1
	ds_read_b128 v[34:37], v76 offset:9216
	v_fmamk_f32 v39, v40, 0x3e38aa3b, v66
	v_add3_u32 v78, s37, v148, v38
	v_cvt_pk_bf16_f32 v53, v53, v56
	v_cvt_pk_bf16_f32 v52, v54, v55
	v_cvt_pk_bf16_f32 v51, v51, v68
	v_cvt_pk_bf16_f32 v50, v50, v67
	v_exp_f32_e32 v77, v39
	ds_read_b128 v[54:57], v78 offset:9216
	s_waitcnt lgkmcnt(1)
	v_mfma_f32_32x32x16_bf16 v[2:17], v[34:37], v[50:53], v[2:17]
	v_fmamk_f32 v34, v41, 0x3e38aa3b, v66
	v_exp_f32_e32 v67, v34
	v_add_f32_e32 v34, v74, v73
	v_add_f32_e32 v34, v75, v34
	v_add_f32_e32 v34, v77, v34
	v_add_f32_e32 v68, v67, v34
	ds_read_b128 v[34:37], v76 offset:9248
	v_fmamk_f32 v38, v42, 0x3e38aa3b, v66
	s_waitcnt lgkmcnt(1)
	v_mfma_f32_32x32x16_bf16 v[18:33], v[54:57], v[50:53], v[18:33]
	v_exp_f32_e32 v54, v38
	ds_read_b128 v[38:41], v78 offset:9248
	v_cvt_pk_bf16_f32 v53, v64, v65
	v_cvt_pk_bf16_f32 v52, v62, v63
	v_cvt_pk_bf16_f32 v51, v60, v61
	v_cvt_pk_bf16_f32 v50, v58, v59
	v_fmamk_f32 v58, v45, 0x3e38aa3b, v66
	v_add_f32_e32 v55, v54, v68
	s_waitcnt lgkmcnt(1)
	v_mfma_f32_32x32x16_bf16 v[2:17], v[34:37], v[50:53], v[2:17]
	v_fmamk_f32 v34, v43, 0x3e38aa3b, v66
	v_exp_f32_e32 v56, v34
	v_fmamk_f32 v34, v44, 0x3e38aa3b, v66
	v_exp_f32_e32 v57, v34
	ds_read_b128 v[34:37], v76 offset:9280
	ds_read_b128 v[42:45], v78 offset:9280
	s_waitcnt lgkmcnt(2)
	v_mfma_f32_32x32x16_bf16 v[18:33], v[38:41], v[50:53], v[18:33]
	v_fmamk_f32 v38, v46, 0x3e38aa3b, v66
	v_exp_f32_e32 v46, v38
	v_cvt_pk_bf16_f32 v41, v77, v67
	v_cvt_pk_bf16_f32 v40, v74, v75
	v_cvt_pk_bf16_f32 v39, v71, v72
	v_cvt_pk_bf16_f32 v38, v69, v70
	v_exp_f32_e32 v50, v58
	v_add_f32_e32 v51, v56, v55
	s_waitcnt lgkmcnt(1)
	v_mfma_f32_32x32x16_bf16 v[2:17], v[34:37], v[38:41], v[2:17]
	v_fmamk_f32 v34, v47, 0x3e38aa3b, v66
	v_exp_f32_e32 v47, v34
	v_fmamk_f32 v34, v48, 0x3e38aa3b, v66
	v_exp_f32_e32 v48, v34
	ds_read_b128 v[34:37], v76 offset:9312
	v_fmac_f32_e32 v66, 0x3e38aa3b, v49
	v_exp_f32_e32 v49, v66
	s_waitcnt lgkmcnt(1)
	v_mfma_f32_32x32x16_bf16 v[18:33], v[42:45], v[38:41], v[18:33]
	ds_read_b128 v[42:45], v78 offset:9312
	v_cvt_pk_bf16_f32 v40, v46, v47
	v_cvt_pk_bf16_f32 v41, v48, v49
	v_cvt_pk_bf16_f32 v39, v57, v50
	v_cvt_pk_bf16_f32 v38, v54, v56
	s_waitcnt lgkmcnt(1)
	s_nop 0
	v_mfma_f32_32x32x16_bf16 v[2:17], v[34:37], v[38:41], v[2:17]
	v_add_f32_e32 v34, v57, v51
	v_add_f32_e32 v34, v50, v34
	v_add_f32_e32 v34, v46, v34
	v_add_f32_e32 v34, v47, v34
	v_add_f32_e32 v34, v48, v34
	v_add_f32_e32 v34, v49, v34
	v_add_f32_e32 v133, v133, v34
	s_waitcnt lgkmcnt(0)
	v_mfma_f32_32x32x16_bf16 v[18:33], v[42:45], v[38:41], v[18:33]

.LBB0_614:
	s_add_i32 s36, s36, 1
	s_add_i32 s2, s22, s36
	s_add_i32 s23, s23, 64
	s_add_i32 s2, s2, -1
	s_cmp_lt_u32 s2, s15
	v_subrev_u32_e32 v149, 64, v149
	s_waitcnt lgkmcnt(0)
	s_setprio 0
	s_barrier
	s_cbranch_scc1 .LBB0_585
	v_mov_b32_e32 v133, v66
	s_mov_b32 s37, s5
	s_mov_b32 s5, s6
	s_mov_b32 s6, s18
	s_mov_b32 s40, s96
	s_movk_i32 s96, 0x1bff
	s_mov_b32 s41, s87
	s_mov_b32 s87, 0xc400000
	s_mov_b64 s[42:43], s[88:89]
	s_mov_b32 s88, 0xc420000
	s_mov_b32 s89, 0xc440000
	s_mov_b32 s44, s90
	s_mov_b32 s90, 0xc460000
	s_mov_b32 s45, s91
	s_mov_b32 s91, 0xc480000
	s_mov_b32 s46, s92
	s_mov_b32 s92, 0xc4a0000
	s_mov_b32 s47, s93
	s_mov_b32 s93, 0xc4c0000
	s_mov_b32 s48, s94
	s_mov_b32 s94, 0xc4e0000
	s_branch .LBB0_617

.LBB0_620:
	s_setprio 0
	s_barrier
	s_waitcnt vmcnt(3)
	ds_write_b128 v182, v[166:169]
	s_waitcnt vmcnt(2)
	ds_write_b128 v182, v[162:165] offset:4608
	s_waitcnt vmcnt(1)
	ds_write_b128 v182, v[174:177] offset:9216
	s_waitcnt vmcnt(0)
	ds_write_b128 v182, v[170:173] offset:13824
	ds_write_b128 v182, v[130:133] offset:18432
	ds_write_b128 v182, v[134:137] offset:23040
	ds_write_b128 v182, v[138:141] offset:27648
	ds_write_b128 v182, v[142:145] offset:32256
	ds_write_b128 v182, v[146:149] offset:36864
	ds_write_b128 v182, v[150:153] offset:41472
	ds_write_b128 v182, v[154:157] offset:46080
	ds_write_b128 v182, v[158:161] offset:50688
	s_waitcnt lgkmcnt(0)
	s_setprio 0
	s_barrier
	s_setprio 1
	ds_read_b128 v[130:133], v0 offset:18432
	ds_read_b128 v[134:137], v194
	ds_read_b128 v[138:141], v194 offset:32
	ds_read_b128 v[142:145], v0 offset:18464
	ds_read_b128 v[146:149], v194 offset:4608
	ds_read_b128 v[150:153], v194 offset:4640
	s_waitcnt lgkmcnt(4)
	v_mfma_f32_32x32x16_bf16 v[114:129], v[130:133], v[134:137], v[114:129]
	s_waitcnt lgkmcnt(1)
	v_mfma_f32_32x32x16_bf16 v[82:97], v[130:133], v[146:149], v[82:97]
	ds_read_b128 v[130:133], v0 offset:23040
	ds_read_b128 v[154:157], v0 offset:23072
	s_waitcnt lgkmcnt(1)
	v_mfma_f32_32x32x16_bf16 v[98:113], v[130:133], v[134:137], v[98:113]
	v_mfma_f32_32x32x16_bf16 v[66:81], v[130:133], v[146:149], v[66:81]
	ds_read_b128 v[130:133], v0 offset:27648
	ds_read_b128 v[158:161], v0 offset:27680
	s_waitcnt lgkmcnt(1)
	v_mfma_f32_32x32x16_bf16 v[50:65], v[130:133], v[134:137], v[50:65]
	v_mfma_f32_32x32x16_bf16 v[18:33], v[130:133], v[146:149], v[18:33]
	ds_read_b128 v[130:133], v0 offset:32256
	ds_read_b128 v[162:165], v0 offset:32288
	s_waitcnt lgkmcnt(1)
	v_mfma_f32_32x32x16_bf16 v[34:49], v[130:133], v[134:137], v[34:49]
	v_mfma_f32_32x32x16_bf16 v[114:129], v[142:145], v[138:141], v[114:129]
	v_mfma_f32_32x32x16_bf16 v[82:97], v[142:145], v[150:153], v[82:97]
	v_mfma_f32_32x32x16_bf16 v[2:17], v[130:133], v[146:149], v[2:17]
	v_mfma_f32_32x32x16_bf16 v[98:113], v[154:157], v[138:141], v[98:113]
	v_mfma_f32_32x32x16_bf16 v[66:81], v[154:157], v[150:153], v[66:81]
	v_mfma_f32_32x32x16_bf16 v[50:65], v[158:161], v[138:141], v[50:65]
	v_mfma_f32_32x32x16_bf16 v[18:33], v[158:161], v[150:153], v[18:33]
	s_waitcnt lgkmcnt(0)
	v_mfma_f32_32x32x16_bf16 v[34:49], v[162:165], v[138:141], v[34:49]
	ds_read_b128 v[130:133], v0 offset:18496
	ds_read_b128 v[134:137], v194 offset:64
	ds_read_b128 v[158:161], v194 offset:96
	ds_read_b128 v[138:141], v0 offset:18528
	ds_read_b128 v[142:145], v194 offset:4672
	ds_read_b128 v[196:199], v194 offset:4704
	s_waitcnt lgkmcnt(4)
	v_mfma_f32_32x32x16_bf16 v[114:129], v[130:133], v[134:137], v[114:129]
	s_waitcnt lgkmcnt(1)
	v_mfma_f32_32x32x16_bf16 v[82:97], v[130:133], v[142:145], v[82:97]
	ds_read_b128 v[130:133], v0 offset:23104
	ds_read_b128 v[146:149], v0 offset:23136
	v_mfma_f32_32x32x16_bf16 v[2:17], v[162:165], v[150:153], v[2:17]
	s_waitcnt lgkmcnt(1)
	v_mfma_f32_32x32x16_bf16 v[98:113], v[130:133], v[134:137], v[98:113]
	v_mfma_f32_32x32x16_bf16 v[66:81], v[130:133], v[142:145], v[66:81]
	ds_read_b128 v[130:133], v0 offset:27712
	ds_read_b128 v[150:153], v0 offset:27744
	s_waitcnt lgkmcnt(1)
	v_mfma_f32_32x32x16_bf16 v[50:65], v[130:133], v[134:137], v[50:65]
	v_mfma_f32_32x32x16_bf16 v[18:33], v[130:133], v[142:145], v[18:33]
	ds_read_b128 v[130:133], v0 offset:32320
	ds_read_b128 v[200:203], v0 offset:32352
	s_waitcnt lgkmcnt(1)
	v_mfma_f32_32x32x16_bf16 v[34:49], v[130:133], v[134:137], v[34:49]
	v_lshl_add_u64 v[134:135], v[188:189], 0, s[22:23]
	v_lshl_add_u64 v[136:137], v[186:187], 0, s[22:23]
	v_mfma_f32_32x32x16_bf16 v[2:17], v[130:133], v[142:145], v[2:17]
	v_lshl_add_u64 v[130:131], v[192:193], 0, s[22:23]
	v_lshl_add_u64 v[142:143], v[184:185], 0, s[22:23]
	v_lshl_add_u64 v[132:133], v[190:191], 0, s[22:23]
	global_load_dwordx4 v[166:169], v[130:131], off
	global_load_dwordx4 v[162:165], v[132:133], off
	global_load_dwordx4 v[174:177], v[134:135], off
	global_load_dwordx4 v[170:173], v[136:137], off
	v_add_co_u32_e32 v130, vcc, s87, v142
	s_add_u32 s22, s22, 0x80
	s_nop 0
	v_addc_co_u32_e32 v131, vcc, 0, v143, vcc
	v_add_co_u32_e32 v134, vcc, s88, v142
	v_mfma_f32_32x32x16_bf16 v[114:129], v[138:141], v[158:161], v[114:129]
	s_nop 0
	v_addc_co_u32_e32 v135, vcc, 0, v143, vcc
	s_addc_u32 s23, s23, 0
	s_cmpk_lg_i32 s22, 0x380
	v_mfma_f32_32x32x16_bf16 v[82:97], v[138:141], v[196:199], v[82:97]
	v_add_co_u32_e32 v138, vcc, s89, v142
	s_nop 1
	v_addc_co_u32_e32 v139, vcc, 0, v143, vcc
	v_add_co_u32_e32 v144, vcc, s90, v142
	v_mfma_f32_32x32x16_bf16 v[98:113], v[146:149], v[158:161], v[98:113]
	s_nop 0
	v_addc_co_u32_e32 v145, vcc, 0, v143, vcc
	v_mfma_f32_32x32x16_bf16 v[66:81], v[146:149], v[196:199], v[66:81]
	v_add_co_u32_e32 v146, vcc, s91, v142
	s_nop 1
	v_addc_co_u32_e32 v147, vcc, 0, v143, vcc
	v_add_co_u32_e32 v154, vcc, s92, v142
	v_mfma_f32_32x32x16_bf16 v[50:65], v[150:153], v[158:161], v[50:65]
	s_nop 0
	v_addc_co_u32_e32 v155, vcc, 0, v143, vcc
	v_add_co_u32_e32 v156, vcc, s93, v142
	s_nop 1
	v_addc_co_u32_e32 v157, vcc, 0, v143, vcc
	v_add_co_u32_e32 v204, vcc, s94, v142
	v_mfma_f32_32x32x16_bf16 v[18:33], v[150:153], v[196:199], v[18:33]
	s_nop 0
	v_addc_co_u32_e32 v205, vcc, 0, v143, vcc
	global_load_dwordx4 v[130:133], v[130:131], off offset:128
	s_nop 0
	global_load_dwordx4 v[134:137], v[134:135], off offset:128
	s_nop 0
	global_load_dwordx4 v[138:141], v[138:139], off offset:128
	s_nop 0
	global_load_dwordx4 v[142:145], v[144:145], off offset:128
	s_nop 0
	global_load_dwordx4 v[146:149], v[146:147], off offset:128
	s_nop 0
	global_load_dwordx4 v[150:153], v[154:155], off offset:128
	s_nop 0
	global_load_dwordx4 v[154:157], v[156:157], off offset:128
	s_waitcnt lgkmcnt(0)
	v_mfma_f32_32x32x16_bf16 v[34:49], v[200:203], v[158:161], v[34:49]
	global_load_dwordx4 v[158:161], v[204:205], off offset:128
	v_mfma_f32_32x32x16_bf16 v[2:17], v[200:203], v[196:199], v[2:17]
	s_cbranch_scc1 .LBB0_620
	s_setprio 0
	s_barrier
	s_waitcnt vmcnt(11)
	ds_write_b128 v182, v[166:169]
	s_waitcnt vmcnt(10)
	ds_write_b128 v182, v[162:165] offset:4608
	s_waitcnt vmcnt(9)
	ds_write_b128 v182, v[174:177] offset:9216
	s_waitcnt vmcnt(8)
	ds_write_b128 v182, v[170:173] offset:13824
	s_waitcnt vmcnt(7)
	ds_write_b128 v182, v[130:133] offset:18432
	s_waitcnt vmcnt(6)
	ds_write_b128 v182, v[134:137] offset:23040
	s_waitcnt vmcnt(5)
	ds_write_b128 v182, v[138:141] offset:27648
	s_waitcnt vmcnt(4)
	ds_write_b128 v182, v[142:145] offset:32256
	s_waitcnt vmcnt(3)
	ds_write_b128 v182, v[146:149] offset:36864
	s_waitcnt vmcnt(2)
	ds_write_b128 v182, v[150:153] offset:41472
	s_waitcnt vmcnt(1)
	ds_write_b128 v182, v[154:157] offset:46080
	s_waitcnt vmcnt(0)
	ds_write_b128 v182, v[158:161] offset:50688
	s_waitcnt lgkmcnt(0)
	s_setprio 0
	s_barrier
	s_setprio 1
	ds_read_b128 v[130:133], v0 offset:18432
	ds_read_b128 v[134:137], v194
	ds_read_b128 v[138:141], v194 offset:32
	ds_read_b128 v[142:145], v0 offset:18464
	ds_read_b128 v[146:149], v194 offset:4608
	ds_read_b128 v[150:153], v194 offset:4640
	s_waitcnt lgkmcnt(4)
	v_mfma_f32_32x32x16_bf16 v[114:129], v[130:133], v[134:137], v[114:129]
	s_lshl_b32 s2, s11, 1
	s_add_i32 s2, s2, s12
	s_ashr_i32 s3, s2, 31
	s_lshl_b64 s[2:3], s[2:3], 21
	s_add_u32 s2, s47, s2
	s_addc_u32 s3, s48, s3
	v_readlane_b32 s12, v242, 16
	s_waitcnt lgkmcnt(1)
	v_mfma_f32_32x32x16_bf16 v[82:97], v[130:133], v[146:149], v[82:97]
	ds_read_b128 v[130:133], v0 offset:23040
	ds_read_b128 v[154:157], v0 offset:23072
	s_waitcnt lgkmcnt(1)
	v_mfma_f32_32x32x16_bf16 v[98:113], v[130:133], v[134:137], v[98:113]
	v_mfma_f32_32x32x16_bf16 v[66:81], v[130:133], v[146:149], v[66:81]
	ds_read_b128 v[130:133], v0 offset:27648
	ds_read_b128 v[158:161], v0 offset:27680
	s_waitcnt lgkmcnt(1)
	v_mfma_f32_32x32x16_bf16 v[50:65], v[130:133], v[134:137], v[50:65]
	v_mfma_f32_32x32x16_bf16 v[18:33], v[130:133], v[146:149], v[18:33]
	ds_read_b128 v[130:133], v0 offset:32256
	ds_read_b128 v[162:165], v0 offset:32288
	s_waitcnt lgkmcnt(1)
	v_mfma_f32_32x32x16_bf16 v[34:49], v[130:133], v[134:137], v[34:49]
	v_mfma_f32_32x32x16_bf16 v[2:17], v[130:133], v[146:149], v[2:17]
	v_mfma_f32_32x32x16_bf16 v[114:129], v[142:145], v[138:141], v[114:129]
	v_mfma_f32_32x32x16_bf16 v[82:97], v[142:145], v[150:153], v[82:97]
	v_mfma_f32_32x32x16_bf16 v[98:113], v[154:157], v[138:141], v[98:113]
	v_mfma_f32_32x32x16_bf16 v[66:81], v[154:157], v[150:153], v[66:81]
	v_mfma_f32_32x32x16_bf16 v[50:65], v[158:161], v[138:141], v[50:65]
	v_mfma_f32_32x32x16_bf16 v[18:33], v[158:161], v[150:153], v[18:33]
	s_waitcnt lgkmcnt(0)
	v_mfma_f32_32x32x16_bf16 v[34:49], v[162:165], v[138:141], v[34:49]
	ds_read_b128 v[130:133], v0 offset:18496
	ds_read_b128 v[134:137], v194 offset:64
	ds_read_b128 v[138:141], v194 offset:96
	ds_read_b128 v[142:145], v0 offset:18528
	v_mfma_f32_32x32x16_bf16 v[2:17], v[162:165], v[150:153], v[2:17]
	ds_read_b128 v[146:149], v194 offset:4672
	ds_read_b128 v[150:153], v194 offset:4704
	s_waitcnt lgkmcnt(4)
	v_mfma_f32_32x32x16_bf16 v[114:129], v[130:133], v[134:137], v[114:129]
	s_waitcnt lgkmcnt(1)
	v_mfma_f32_32x32x16_bf16 v[82:97], v[130:133], v[146:149], v[82:97]
	ds_read_b128 v[130:133], v0 offset:23104
	ds_read_b128 v[154:157], v0 offset:23136
	s_waitcnt lgkmcnt(1)
	v_mfma_f32_32x32x16_bf16 v[98:113], v[130:133], v[134:137], v[98:113]
	v_mfma_f32_32x32x16_bf16 v[66:81], v[130:133], v[146:149], v[66:81]
	ds_read_b128 v[130:133], v0 offset:27712
	ds_read_b128 v[158:161], v0 offset:27744
	s_waitcnt lgkmcnt(1)
	v_mfma_f32_32x32x16_bf16 v[50:65], v[130:133], v[134:137], v[50:65]
	v_mfma_f32_32x32x16_bf16 v[18:33], v[130:133], v[146:149], v[18:33]
	ds_read_b128 v[130:133], v0 offset:32320
	ds_read_b128 v[162:165], v0 offset:32352
	v_lshlrev_b32_e32 v0, 2, v181
	v_mov_b32_e32 v181, v1
	s_waitcnt lgkmcnt(0)
	s_setprio 0
	s_barrier
	v_mfma_f32_32x32x16_bf16 v[34:49], v[130:133], v[134:137], v[34:49]
	v_mfma_f32_32x32x16_bf16 v[2:17], v[130:133], v[146:149], v[2:17]
	v_add_u32_e32 v130, s13, v183
	v_ashrrev_i32_e32 v131, 31, v130
	v_lshlrev_b64 v[132:133], 10, v[130:131]
	v_lshl_add_u64 v[132:133], s[2:3], 0, v[132:133]
	v_lshl_add_u64 v[132:133], v[132:133], 0, v[0:1]
	v_lshl_add_u64 v[132:133], v[132:133], 0, v[180:181]
	v_mfma_f32_32x32x16_bf16 v[114:129], v[142:145], v[138:141], v[114:129]
	v_mfma_f32_32x32x16_bf16 v[98:113], v[154:157], v[138:141], v[98:113]
	s_nop 10
	global_store_dwordx4 v[132:133], v[114:117], off
	global_store_dwordx4 v[132:133], v[118:121], off offset:32
	global_store_dwordx4 v[132:133], v[122:125], off offset:64
	global_store_dwordx4 v[132:133], v[126:129], off offset:96
	global_store_dwordx4 v[132:133], v[98:101], off offset:128
	global_store_dwordx4 v[132:133], v[102:105], off offset:160
	s_nop 0
	v_or_b32_e32 v98, 32, v130
	v_ashrrev_i32_e32 v99, 31, v98
	v_lshlrev_b64 v[98:99], 10, v[98:99]
	v_mfma_f32_32x32x16_bf16 v[82:97], v[142:145], v[150:153], v[82:97]
	v_lshl_add_u64 v[98:99], s[2:3], 0, v[98:99]
	v_lshl_add_u64 v[98:99], v[98:99], 0, v[0:1]
	v_lshl_add_u64 v[98:99], v[98:99], 0, v[180:181]
	global_store_dwordx4 v[132:133], v[106:109], off offset:192
	global_store_dwordx4 v[132:133], v[110:113], off offset:224
	v_mfma_f32_32x32x16_bf16 v[66:81], v[154:157], v[150:153], v[66:81]
	s_nop 5
	global_store_dwordx4 v[98:99], v[82:85], off
	global_store_dwordx4 v[98:99], v[86:89], off offset:32
	global_store_dwordx4 v[98:99], v[90:93], off offset:64
	global_store_dwordx4 v[98:99], v[94:97], off offset:96
	s_nop 1
	global_store_dwordx4 v[98:99], v[66:69], off offset:128
	global_store_dwordx4 v[98:99], v[70:73], off offset:160
	v_mfma_f32_32x32x16_bf16 v[34:49], v[162:165], v[138:141], v[34:49]
	v_mfma_f32_32x32x16_bf16 v[2:17], v[162:165], v[150:153], v[2:17]
	v_mfma_f32_32x32x16_bf16 v[50:65], v[158:161], v[138:141], v[50:65]
	global_store_dwordx4 v[98:99], v[74:77], off offset:192
	global_store_dwordx4 v[98:99], v[78:81], off offset:224
	s_nop 9
	global_store_dwordx4 v[132:133], v[50:53], off offset:256
	global_store_dwordx4 v[132:133], v[54:57], off offset:288
	global_store_dwordx4 v[132:133], v[58:61], off offset:320
	global_store_dwordx4 v[132:133], v[62:65], off offset:352
	global_store_dwordx4 v[132:133], v[34:37], off offset:384
	v_mfma_f32_32x32x16_bf16 v[18:33], v[158:161], v[150:153], v[18:33]
	global_store_dwordx4 v[132:133], v[38:41], off offset:416
	global_store_dwordx4 v[132:133], v[42:45], off offset:448
	global_store_dwordx4 v[132:133], v[46:49], off offset:480
	s_nop 8
	global_store_dwordx4 v[98:99], v[18:21], off offset:256
	global_store_dwordx4 v[98:99], v[22:25], off offset:288
	global_store_dwordx4 v[98:99], v[26:29], off offset:320
	global_store_dwordx4 v[98:99], v[30:33], off offset:352
	global_store_dwordx4 v[98:99], v[2:5], off offset:384
	global_store_dwordx4 v[98:99], v[6:9], off offset:416
	global_store_dwordx4 v[98:99], v[10:13], off offset:448
	global_store_dwordx4 v[98:99], v[14:17], off offset:480
	s_branch .LBB0_581

.LBB0_629:
	v_mov_b32_e32 v7, v206
	v_mov_b32_e32 v0, v206
	s_lshl_b32 s2, s5, 2
	s_lshl_b32 s22, s5, 4
	v_ashrrev_i32_e32 v0, 6, v0
	v_and_b32_e32 v6, 31, v7
	s_lshr_b32 s76, s5, 7
	s_and_b32 s2, s2, 4
	s_and_b32 s13, s22, 0x7e0
	v_add_u32_e32 v0, s2, v0
	v_or_b32_e32 v2, s13, v6
	s_lshl_b64 s[2:3], s[76:77], 11
	v_or_b32_e32 v130, s2, v2
	v_mov_b32_e32 v131, s3
	v_lshlrev_b64 v[2:3], 10, v[130:131]
	v_lshlrev_b32_e32 v134, 6, v0
	s_lshl_b64 s[14:15], s[76:77], 18
	v_lshl_add_u64 v[2:3], s[18:19], 0, v[2:3]
	v_ashrrev_i32_e32 v135, 31, v134
	v_and_b32_e32 v4, 32, v7
	s_add_u32 s2, s6, s14
	v_lshl_add_u64 v[2:3], v[134:135], 1, v[2:3]
	v_lshlrev_b32_e32 v136, 1, v4
	v_mov_b32_e32 v137, v1
	s_addc_u32 s3, s7, s15
	v_lshl_add_u64 v[2:3], v[2:3], 0, v[136:137]
	s_add_u32 s16, s8, s14
	global_load_dwordx4 v[98:101], v[2:3], off
	global_load_dwordx4 v[102:105], v[2:3], off offset:16
	global_load_dwordx4 v[106:109], v[2:3], off offset:32
	global_load_dwordx4 v[110:113], v[2:3], off offset:48
	s_addc_u32 s17, s9, s15
	v_add_u32_e32 v2, s10, v0
	v_readlane_b32 s14, v242, 17
	v_ashrrev_i32_e32 v3, 31, v2
	v_readlane_b32 s15, v242, 18
	v_sub_u32_e64 v0, s13, v221 clamp
	v_and_b32_e32 v5, 0x7c0, v0
	v_lshl_add_u64 v[2:3], v[2:3], 2, s[14:15]
	global_load_dword v9, v[2:3], off
	v_mov_b32_e32 v2, v206
	v_and_b32_e32 v8, 63, v7
	v_ashrrev_i32_e32 v138, 3, v2
	v_lshlrev_b32_e32 v2, 3, v2
	v_and_b32_e32 v4, 56, v2
	v_add_u32_e32 v2, v138, v5
	v_ashrrev_i32_e32 v3, 31, v2
	v_lshlrev_b64 v[2:3], 7, v[2:3]
	v_readfirstlane_b32 s14, v0
	v_lshl_add_u64 v[2:3], s[2:3], 0, v[2:3]
	v_lshlrev_b32_e32 v0, 1, v4
	v_cmp_gt_u32_e32 vcc, 32, v8
	s_lshr_b32 s15, s14, 6
	s_bfe_u32 s14, s22, 0x50006
	v_lshl_add_u64 v[2:3], v[2:3], 0, v[0:1]
	s_movk_i32 s22, 0x1000
	v_cndmask_b32_e64 v133, 0, 1.0, vcc
	s_setprio 0
	s_barrier
	global_load_dwordx4 v[10:13], v[2:3], off
	v_add_co_u32_e32 v2, vcc, s22, v2
	v_ashrrev_i32_e32 v139, 31, v138
	s_nop 0
	v_addc_co_u32_e32 v3, vcc, 0, v3, vcc
	global_load_dwordx4 v[14:17], v[2:3], off
	v_lshlrev_b64 v[2:3], 12, v[138:139]
	v_lshl_add_u64 v[2:3], s[16:17], 0, v[2:3]
	v_lshlrev_b32_e32 v22, 1, v5
	v_mov_b32_e32 v23, v1
	v_lshl_add_u64 v[4:5], v[2:3], 0, v[22:23]
	v_lshl_add_u64 v[4:5], v[4:5], 0, v[0:1]
	global_load_dwordx4 v[18:21], v[4:5], off
	v_lshl_add_u64 v[4:5], v[2:3], 0, s[30:31]
	v_lshl_add_u64 v[22:23], v[4:5], 0, v[22:23]
	v_lshl_add_u64 v[22:23], v[22:23], 0, v[0:1]
	global_load_dwordx4 v[22:25], v[22:23], off
	s_cmp_lt_u32 s15, s14
	s_cselect_b64 s[16:17], -1, 0
	v_mul_lo_u32 v137, v138, s21
	s_cmp_lg_u64 s[16:17], 0
	v_add_u32_e32 v27, v137, v0
	s_addc_u32 s16, s15, 0
	s_lshl_b32 s76, s16, 7
	v_bfe_u32 v26, v7, 5, 1
	s_cmp_gt_u32 s15, s14
	v_lshlrev_b32_e32 v132, 3, v26
	s_waitcnt vmcnt(3)
	ds_write_b128 v27, v[10:13]
	s_waitcnt vmcnt(2)
	ds_write_b128 v27, v[14:17] offset:4608
	s_waitcnt vmcnt(1)
	ds_write_b128 v27, v[18:21] offset:9216
	s_waitcnt vmcnt(0)
	ds_write_b128 v27, v[22:25] offset:13824
	v_lshl_add_u32 v10, s16, 6, v138
	v_ashrrev_i32_e32 v11, 31, v10
	v_lshlrev_b64 v[10:11], 7, v[10:11]
	v_lshl_add_u64 v[10:11], s[2:3], 0, v[10:11]
	v_lshl_add_u64 v[10:11], v[10:11], 0, v[0:1]
	global_load_dwordx4 v[114:117], v[10:11], off
	v_add_co_u32_e32 v10, vcc, s22, v10
	s_nop 1
	v_addc_co_u32_e32 v11, vcc, 0, v11, vcc
	global_load_dwordx4 v[118:121], v[10:11], off
	v_lshl_add_u64 v[10:11], v[2:3], 0, s[76:77]
	v_lshl_add_u64 v[10:11], v[10:11], 0, v[0:1]
	global_load_dwordx4 v[122:125], v[10:11], off
	v_lshl_add_u64 v[10:11], v[4:5], 0, s[76:77]
	v_lshl_add_u64 v[10:11], v[10:11], 0, v[0:1]
	global_load_dwordx4 v[126:129], v[10:11], off
	s_waitcnt lgkmcnt(0)
	s_setprio 0
	s_barrier
	s_cbranch_scc1 .LBB0_627
	v_lshl_add_u64 v[142:143], v[2:3], 0, v[0:1]
	v_lshlrev_b32_e32 v2, 1, v8
	v_lshrrev_b32_e32 v3, 1, v7
	v_lshl_add_u64 v[144:145], v[4:5], 0, v[0:1]
	v_and_b32_e32 v2, 8, v2
	v_and_b32_e32 v3, 4, v3
	v_and_b32_e32 v4, 19, v7
	v_or3_b32 v2, v3, v4, v2
	s_and_b32 s16, s12, 0x7e0
	v_mul_u32_u24_e32 v139, 0x90, v2
	v_lshrrev_b32_e32 v2, 2, v7
	s_min_u32 s15, s16, 0x80
	v_and_b32_e32 v147, 8, v2
	v_or_b32_e32 v2, 32, v8
	s_sub_i32 s17, s16, s15
	v_mul_u32_u24_e32 v148, 0x90, v2
	v_add_u32_e32 v2, s16, v6
	s_and_b32 s22, s17, 0xffffffc0
	v_sub_u32_e32 v2, v2, v132
	v_mov_b32_e32 v16, v1
	v_mov_b32_e32 v17, v1
	v_mul_f32_e32 v152, 0x3fb8aa3b, v9
	v_mul_u32_u24_e32 v146, 0x90, v6
	v_subrev_u32_e32 v149, s22, v2
	v_mov_b32_e32 v2, v1
	v_mov_b32_e32 v3, v1
	v_mov_b32_e32 v4, v1
	v_mov_b32_e32 v5, v1
	v_mov_b32_e32 v6, v1
	v_mov_b32_e32 v7, v1
	v_mov_b32_e32 v8, v1
	v_mov_b32_e32 v9, v1
	v_mov_b32_e32 v10, v1
	v_mov_b32_e32 v11, v1
	v_mov_b32_e32 v12, v1
	v_mov_b32_e32 v13, v1
	v_mov_b32_e32 v14, v1
	v_mov_b32_e32 v15, v1
	v_mov_b64_e32 v[32:33], v[16:17]
	s_lshr_b32 s15, s17, 6
	v_lshl_add_u64 v[140:141], s[2:3], 0, v[0:1]
	s_or_b32 s23, s13, 31
	s_add_i32 s74, s13, 0xffffff80
	s_add_i32 s75, s13, 0xffffff9f
	s_mov_b32 s36, 0
	v_mov_b32_e32 v150, 0
	v_mov_b32_e32 v151, 0
	v_mov_b64_e32 v[30:31], v[14:15]
	v_mov_b64_e32 v[28:29], v[12:13]
	v_mov_b64_e32 v[26:27], v[10:11]
	v_mov_b64_e32 v[24:25], v[8:9]
	v_mov_b64_e32 v[22:23], v[6:7]
	v_mov_b64_e32 v[20:21], v[4:5]
	v_mov_b64_e32 v[18:19], v[2:3]
	s_add_i32 s2, s15, s36
	s_and_b32 s37, s36, 1
	s_cmp_ge_u32 s2, s14
	s_cbranch_scc0 .LBB0_632
	s_branch .LBB0_634

.LBB0_660:
	s_add_i32 s36, s36, 1
	s_add_i32 s2, s15, s36
	s_add_i32 s22, s22, 64
	s_add_i32 s2, s2, -1
	s_cmp_lt_u32 s2, s14
	v_subrev_u32_e32 v149, 64, v149
	s_waitcnt lgkmcnt(0)
	s_setprio 0
	s_barrier
	s_cbranch_scc1 .LBB0_631
	v_mov_b32_e32 v133, v66
	s_branch .LBB0_628

.LBB0_665:
	s_setprio 0
	s_barrier
	s_waitcnt vmcnt(3)
	ds_write_b128 v182, v[166:169]
	s_waitcnt vmcnt(2)
	ds_write_b128 v182, v[162:165] offset:4608
	s_waitcnt vmcnt(1)
	ds_write_b128 v182, v[174:177] offset:9216
	s_waitcnt vmcnt(0)
	ds_write_b128 v182, v[170:173] offset:13824
	ds_write_b128 v182, v[130:133] offset:18432
	ds_write_b128 v182, v[134:137] offset:23040
	ds_write_b128 v182, v[138:141] offset:27648
	ds_write_b128 v182, v[142:145] offset:32256
	ds_write_b128 v182, v[146:149] offset:36864
	ds_write_b128 v182, v[150:153] offset:41472
	ds_write_b128 v182, v[154:157] offset:46080
	ds_write_b128 v182, v[158:161] offset:50688
	s_waitcnt lgkmcnt(0)
	s_setprio 0
	s_barrier
	s_setprio 1
	ds_read_b128 v[130:133], v0 offset:18432
	ds_read_b128 v[134:137], v194
	ds_read_b128 v[138:141], v194 offset:32
	ds_read_b128 v[142:145], v0 offset:18464
	ds_read_b128 v[146:149], v194 offset:4608
	ds_read_b128 v[150:153], v194 offset:4640
	s_waitcnt lgkmcnt(4)
	v_mfma_f32_32x32x16_bf16 v[114:129], v[130:133], v[134:137], v[114:129]
	s_waitcnt lgkmcnt(1)
	v_mfma_f32_32x32x16_bf16 v[82:97], v[130:133], v[146:149], v[82:97]
	ds_read_b128 v[130:133], v0 offset:23040
	ds_read_b128 v[154:157], v0 offset:23072
	s_waitcnt lgkmcnt(1)
	v_mfma_f32_32x32x16_bf16 v[98:113], v[130:133], v[134:137], v[98:113]
	v_mfma_f32_32x32x16_bf16 v[66:81], v[130:133], v[146:149], v[66:81]
	ds_read_b128 v[130:133], v0 offset:27648
	ds_read_b128 v[158:161], v0 offset:27680
	s_waitcnt lgkmcnt(1)
	v_mfma_f32_32x32x16_bf16 v[50:65], v[130:133], v[134:137], v[50:65]
	v_mfma_f32_32x32x16_bf16 v[18:33], v[130:133], v[146:149], v[18:33]
	ds_read_b128 v[130:133], v0 offset:32256
	ds_read_b128 v[162:165], v0 offset:32288
	s_waitcnt lgkmcnt(1)
	v_mfma_f32_32x32x16_bf16 v[34:49], v[130:133], v[134:137], v[34:49]
	v_mfma_f32_32x32x16_bf16 v[114:129], v[142:145], v[138:141], v[114:129]
	v_mfma_f32_32x32x16_bf16 v[82:97], v[142:145], v[150:153], v[82:97]
	v_mfma_f32_32x32x16_bf16 v[2:17], v[130:133], v[146:149], v[2:17]
	v_mfma_f32_32x32x16_bf16 v[98:113], v[154:157], v[138:141], v[98:113]
	v_mfma_f32_32x32x16_bf16 v[66:81], v[154:157], v[150:153], v[66:81]
	v_mfma_f32_32x32x16_bf16 v[50:65], v[158:161], v[138:141], v[50:65]
	v_mfma_f32_32x32x16_bf16 v[18:33], v[158:161], v[150:153], v[18:33]
	s_waitcnt lgkmcnt(0)
	v_mfma_f32_32x32x16_bf16 v[34:49], v[162:165], v[138:141], v[34:49]
	ds_read_b128 v[130:133], v0 offset:18496
	ds_read_b128 v[134:137], v194 offset:64
	ds_read_b128 v[158:161], v194 offset:96
	ds_read_b128 v[138:141], v0 offset:18528
	ds_read_b128 v[142:145], v194 offset:4672
	ds_read_b128 v[196:199], v194 offset:4704
	s_waitcnt lgkmcnt(4)
	v_mfma_f32_32x32x16_bf16 v[114:129], v[130:133], v[134:137], v[114:129]
	s_waitcnt lgkmcnt(1)
	v_mfma_f32_32x32x16_bf16 v[82:97], v[130:133], v[142:145], v[82:97]
	ds_read_b128 v[130:133], v0 offset:23104
	ds_read_b128 v[146:149], v0 offset:23136
	v_mfma_f32_32x32x16_bf16 v[2:17], v[162:165], v[150:153], v[2:17]
	s_waitcnt lgkmcnt(1)
	v_mfma_f32_32x32x16_bf16 v[98:113], v[130:133], v[134:137], v[98:113]
	v_mfma_f32_32x32x16_bf16 v[66:81], v[130:133], v[142:145], v[66:81]
	ds_read_b128 v[130:133], v0 offset:27712
	ds_read_b128 v[150:153], v0 offset:27744
	s_waitcnt lgkmcnt(1)
	v_mfma_f32_32x32x16_bf16 v[50:65], v[130:133], v[134:137], v[50:65]
	v_mfma_f32_32x32x16_bf16 v[18:33], v[130:133], v[142:145], v[18:33]
	ds_read_b128 v[130:133], v0 offset:32320
	ds_read_b128 v[200:203], v0 offset:32352
	s_waitcnt lgkmcnt(1)
	v_mfma_f32_32x32x16_bf16 v[34:49], v[130:133], v[134:137], v[34:49]
	v_lshl_add_u64 v[134:135], v[188:189], 0, s[18:19]
	v_lshl_add_u64 v[136:137], v[186:187], 0, s[18:19]
	v_mfma_f32_32x32x16_bf16 v[2:17], v[130:133], v[142:145], v[2:17]
	v_lshl_add_u64 v[130:131], v[192:193], 0, s[18:19]
	v_lshl_add_u64 v[142:143], v[184:185], 0, s[18:19]
	v_lshl_add_u64 v[132:133], v[190:191], 0, s[18:19]
	global_load_dwordx4 v[166:169], v[130:131], off
	global_load_dwordx4 v[162:165], v[132:133], off
	global_load_dwordx4 v[174:177], v[134:135], off
	global_load_dwordx4 v[170:173], v[136:137], off
	v_add_co_u32_e32 v130, vcc, s87, v142
	s_add_u32 s18, s18, 0x80
	s_nop 0
	v_addc_co_u32_e32 v131, vcc, 0, v143, vcc
	v_add_co_u32_e32 v134, vcc, s88, v142
	v_mfma_f32_32x32x16_bf16 v[114:129], v[138:141], v[158:161], v[114:129]
	s_nop 0
	v_addc_co_u32_e32 v135, vcc, 0, v143, vcc
	s_addc_u32 s19, s19, 0
	s_cmpk_lg_i32 s18, 0x380
	v_mfma_f32_32x32x16_bf16 v[82:97], v[138:141], v[196:199], v[82:97]
	v_add_co_u32_e32 v138, vcc, s89, v142
	s_nop 1
	v_addc_co_u32_e32 v139, vcc, 0, v143, vcc
	v_add_co_u32_e32 v144, vcc, s90, v142
	v_mfma_f32_32x32x16_bf16 v[98:113], v[146:149], v[158:161], v[98:113]
	s_nop 0
	v_addc_co_u32_e32 v145, vcc, 0, v143, vcc
	v_mfma_f32_32x32x16_bf16 v[66:81], v[146:149], v[196:199], v[66:81]
	v_add_co_u32_e32 v146, vcc, s91, v142
	s_nop 1
	v_addc_co_u32_e32 v147, vcc, 0, v143, vcc
	v_add_co_u32_e32 v154, vcc, s92, v142
	v_mfma_f32_32x32x16_bf16 v[50:65], v[150:153], v[158:161], v[50:65]
	s_nop 0
	v_addc_co_u32_e32 v155, vcc, 0, v143, vcc
	v_add_co_u32_e32 v156, vcc, s93, v142
	s_nop 1
	v_addc_co_u32_e32 v157, vcc, 0, v143, vcc
	v_add_co_u32_e32 v204, vcc, s94, v142
	v_mfma_f32_32x32x16_bf16 v[18:33], v[150:153], v[196:199], v[18:33]
	s_nop 0
	v_addc_co_u32_e32 v205, vcc, 0, v143, vcc
	global_load_dwordx4 v[130:133], v[130:131], off offset:128
	s_nop 0
	global_load_dwordx4 v[134:137], v[134:135], off offset:128
	s_nop 0
	global_load_dwordx4 v[138:141], v[138:139], off offset:128
	s_nop 0
	global_load_dwordx4 v[142:145], v[144:145], off offset:128
	s_nop 0
	global_load_dwordx4 v[146:149], v[146:147], off offset:128
	s_nop 0
	global_load_dwordx4 v[150:153], v[154:155], off offset:128
	s_nop 0
	global_load_dwordx4 v[154:157], v[156:157], off offset:128
	s_waitcnt lgkmcnt(0)
	v_mfma_f32_32x32x16_bf16 v[34:49], v[200:203], v[158:161], v[34:49]
	global_load_dwordx4 v[158:161], v[204:205], off offset:128
	v_mfma_f32_32x32x16_bf16 v[2:17], v[200:203], v[196:199], v[2:17]
	s_cbranch_scc1 .LBB0_665
	s_setprio 0
	s_barrier
	s_waitcnt vmcnt(11)
	ds_write_b128 v182, v[166:169]
	s_waitcnt vmcnt(10)
	ds_write_b128 v182, v[162:165] offset:4608
	s_waitcnt vmcnt(9)
	ds_write_b128 v182, v[174:177] offset:9216
	s_waitcnt vmcnt(8)
	ds_write_b128 v182, v[170:173] offset:13824
	s_waitcnt vmcnt(7)
	ds_write_b128 v182, v[130:133] offset:18432
	s_waitcnt vmcnt(6)
	ds_write_b128 v182, v[134:137] offset:23040
	s_waitcnt vmcnt(5)
	ds_write_b128 v182, v[138:141] offset:27648
	s_waitcnt vmcnt(4)
	ds_write_b128 v182, v[142:145] offset:32256
	s_waitcnt vmcnt(3)
	ds_write_b128 v182, v[146:149] offset:36864
	s_waitcnt vmcnt(2)
	ds_write_b128 v182, v[150:153] offset:41472
	s_waitcnt vmcnt(1)
	ds_write_b128 v182, v[154:157] offset:46080
	s_waitcnt vmcnt(0)
	ds_write_b128 v182, v[158:161] offset:50688
	s_waitcnt lgkmcnt(0)
	s_setprio 0
	s_barrier
	s_setprio 1
	ds_read_b128 v[130:133], v0 offset:18432
	ds_read_b128 v[134:137], v194
	ds_read_b128 v[138:141], v194 offset:32
	ds_read_b128 v[142:145], v0 offset:18464
	ds_read_b128 v[146:149], v194 offset:4608
	ds_read_b128 v[150:153], v194 offset:4640
	s_waitcnt lgkmcnt(4)
	v_mfma_f32_32x32x16_bf16 v[114:129], v[130:133], v[134:137], v[114:129]
	s_lshl_b32 s2, s4, 1
	s_add_i32 s2, s2, s5
	s_ashr_i32 s3, s2, 31
	s_lshl_b64 s[2:3], s[2:3], 21
	s_add_u32 s2, s34, s2
	s_addc_u32 s3, s35, s3
	s_add_u32 s2, s2, 0x8000000
	s_waitcnt lgkmcnt(1)
	v_mfma_f32_32x32x16_bf16 v[82:97], v[130:133], v[146:149], v[82:97]
	ds_read_b128 v[130:133], v0 offset:23040
	ds_read_b128 v[154:157], v0 offset:23072
	s_addc_u32 s3, s3, 0
	s_waitcnt lgkmcnt(1)
	v_mfma_f32_32x32x16_bf16 v[98:113], v[130:133], v[134:137], v[98:113]
	v_mfma_f32_32x32x16_bf16 v[66:81], v[130:133], v[146:149], v[66:81]
	ds_read_b128 v[130:133], v0 offset:27648
	ds_read_b128 v[158:161], v0 offset:27680
	s_waitcnt lgkmcnt(1)
	v_mfma_f32_32x32x16_bf16 v[50:65], v[130:133], v[134:137], v[50:65]
	v_mfma_f32_32x32x16_bf16 v[18:33], v[130:133], v[146:149], v[18:33]
	ds_read_b128 v[130:133], v0 offset:32256
	ds_read_b128 v[162:165], v0 offset:32288
	s_waitcnt lgkmcnt(1)
	v_mfma_f32_32x32x16_bf16 v[34:49], v[130:133], v[134:137], v[34:49]
	v_mfma_f32_32x32x16_bf16 v[2:17], v[130:133], v[146:149], v[2:17]
	v_mfma_f32_32x32x16_bf16 v[114:129], v[142:145], v[138:141], v[114:129]
	v_mfma_f32_32x32x16_bf16 v[82:97], v[142:145], v[150:153], v[82:97]
	v_mfma_f32_32x32x16_bf16 v[98:113], v[154:157], v[138:141], v[98:113]
	v_mfma_f32_32x32x16_bf16 v[66:81], v[154:157], v[150:153], v[66:81]
	v_mfma_f32_32x32x16_bf16 v[50:65], v[158:161], v[138:141], v[50:65]
	v_mfma_f32_32x32x16_bf16 v[18:33], v[158:161], v[150:153], v[18:33]
	s_waitcnt lgkmcnt(0)
	v_mfma_f32_32x32x16_bf16 v[34:49], v[162:165], v[138:141], v[34:49]
	ds_read_b128 v[130:133], v0 offset:18496
	ds_read_b128 v[134:137], v194 offset:64
	ds_read_b128 v[138:141], v194 offset:96
	ds_read_b128 v[142:145], v0 offset:18528
	v_mfma_f32_32x32x16_bf16 v[2:17], v[162:165], v[150:153], v[2:17]
	ds_read_b128 v[146:149], v194 offset:4672
	ds_read_b128 v[150:153], v194 offset:4704
	s_waitcnt lgkmcnt(4)
	v_mfma_f32_32x32x16_bf16 v[114:129], v[130:133], v[134:137], v[114:129]
	s_waitcnt lgkmcnt(1)
	v_mfma_f32_32x32x16_bf16 v[82:97], v[130:133], v[146:149], v[82:97]
	ds_read_b128 v[130:133], v0 offset:23104
	ds_read_b128 v[154:157], v0 offset:23136
	s_waitcnt lgkmcnt(1)
	v_mfma_f32_32x32x16_bf16 v[98:113], v[130:133], v[134:137], v[98:113]
	v_mfma_f32_32x32x16_bf16 v[66:81], v[130:133], v[146:149], v[66:81]
	ds_read_b128 v[130:133], v0 offset:27712
	ds_read_b128 v[158:161], v0 offset:27744
	s_waitcnt lgkmcnt(1)
	v_mfma_f32_32x32x16_bf16 v[50:65], v[130:133], v[134:137], v[50:65]
	v_mfma_f32_32x32x16_bf16 v[18:33], v[130:133], v[146:149], v[18:33]
	ds_read_b128 v[130:133], v0 offset:32320
	ds_read_b128 v[162:165], v0 offset:32352
	v_lshlrev_b32_e32 v0, 2, v181
	v_mov_b32_e32 v181, v1
	s_waitcnt lgkmcnt(0)
	s_setprio 0
	s_barrier
	v_mfma_f32_32x32x16_bf16 v[34:49], v[130:133], v[134:137], v[34:49]
	v_mfma_f32_32x32x16_bf16 v[2:17], v[130:133], v[146:149], v[2:17]
	v_add_u32_e32 v130, s6, v183
	v_ashrrev_i32_e32 v131, 31, v130
	v_lshlrev_b64 v[132:133], 10, v[130:131]
	v_lshl_add_u64 v[132:133], s[2:3], 0, v[132:133]
	v_lshl_add_u64 v[132:133], v[132:133], 0, v[0:1]
	v_lshl_add_u64 v[132:133], v[132:133], 0, v[180:181]
	v_mfma_f32_32x32x16_bf16 v[114:129], v[142:145], v[138:141], v[114:129]
	v_mfma_f32_32x32x16_bf16 v[98:113], v[154:157], v[138:141], v[98:113]
	s_nop 10
	global_store_dwordx4 v[132:133], v[114:117], off
	global_store_dwordx4 v[132:133], v[118:121], off offset:32
	global_store_dwordx4 v[132:133], v[122:125], off offset:64
	global_store_dwordx4 v[132:133], v[126:129], off offset:96
	global_store_dwordx4 v[132:133], v[98:101], off offset:128
	global_store_dwordx4 v[132:133], v[102:105], off offset:160
	s_nop 0
	v_or_b32_e32 v98, 32, v130
	v_ashrrev_i32_e32 v99, 31, v98
	v_lshlrev_b64 v[98:99], 10, v[98:99]
	v_mfma_f32_32x32x16_bf16 v[82:97], v[142:145], v[150:153], v[82:97]
	v_lshl_add_u64 v[98:99], s[2:3], 0, v[98:99]
	v_lshl_add_u64 v[98:99], v[98:99], 0, v[0:1]
	v_lshl_add_u64 v[98:99], v[98:99], 0, v[180:181]
	global_store_dwordx4 v[132:133], v[106:109], off offset:192
	global_store_dwordx4 v[132:133], v[110:113], off offset:224
	v_mfma_f32_32x32x16_bf16 v[66:81], v[154:157], v[150:153], v[66:81]
	s_nop 5
	global_store_dwordx4 v[98:99], v[82:85], off
	global_store_dwordx4 v[98:99], v[86:89], off offset:32
	global_store_dwordx4 v[98:99], v[90:93], off offset:64
	global_store_dwordx4 v[98:99], v[94:97], off offset:96
	s_nop 1
	global_store_dwordx4 v[98:99], v[66:69], off offset:128
	global_store_dwordx4 v[98:99], v[70:73], off offset:160
	v_mfma_f32_32x32x16_bf16 v[34:49], v[162:165], v[138:141], v[34:49]
	v_mfma_f32_32x32x16_bf16 v[2:17], v[162:165], v[150:153], v[2:17]
	v_mfma_f32_32x32x16_bf16 v[50:65], v[158:161], v[138:141], v[50:65]
	global_store_dwordx4 v[98:99], v[74:77], off offset:192
	global_store_dwordx4 v[98:99], v[78:81], off offset:224
	s_nop 9
	global_store_dwordx4 v[132:133], v[50:53], off offset:256
	global_store_dwordx4 v[132:133], v[54:57], off offset:288
	global_store_dwordx4 v[132:133], v[58:61], off offset:320
	global_store_dwordx4 v[132:133], v[62:65], off offset:352
	global_store_dwordx4 v[132:133], v[34:37], off offset:384
	v_mfma_f32_32x32x16_bf16 v[18:33], v[158:161], v[150:153], v[18:33]
	global_store_dwordx4 v[132:133], v[38:41], off offset:416
	global_store_dwordx4 v[132:133], v[42:45], off offset:448
	global_store_dwordx4 v[132:133], v[46:49], off offset:480
	s_nop 8
	global_store_dwordx4 v[98:99], v[18:21], off offset:256
	global_store_dwordx4 v[98:99], v[22:25], off offset:288
	global_store_dwordx4 v[98:99], v[26:29], off offset:320
	global_store_dwordx4 v[98:99], v[30:33], off offset:352
	global_store_dwordx4 v[98:99], v[2:5], off offset:384
	global_store_dwordx4 v[98:99], v[6:9], off offset:416
	global_store_dwordx4 v[98:99], v[10:13], off offset:448
	global_store_dwordx4 v[98:99], v[14:17], off offset:480

.LBB0_719:
	s_or_b64 exec, exec, s[18:19]
	v_readlane_b32 s6, v243, 3
	v_readlane_b32 s7, v243, 4
	s_waitcnt lgkmcnt(0)
	s_setprio 0
	s_barrier
	s_load_dwordx2 s[4:5], s[6:7], 0x98
	s_waitcnt lgkmcnt(0)
	v_readlane_b32 s5, v243, 0
	s_mov_b64 s[2:3], s[6:7]
	s_mov_b32 s56, s5
	s_mov_b32 s19, s12
	s_load_dwordx2 s[34:35], s[2:3], 0x90
	s_ashr_i32 s2, s19, 1
	s_cmp_lt_i32 s56, 32
	v_writelane_b32 v242, s2, 17
	s_cselect_b64 s[2:3], -1, 0
	s_cmp_gt_i32 s56, 31
	s_cselect_b64 s[6:7], -1, 0
	s_cmp_gt_i32 s4, 64
	s_mov_b64 s[22:23], -1
	s_cbranch_scc1 .LBB0_770
	v_writelane_b32 v242, s6, 21
	s_andn2_b64 vcc, exec, s[2:3]
	s_nop 0
	v_writelane_b32 v242, s7, 22
	s_cbranch_vccnz .LBB0_733
	s_and_b32 s5, s19, -2
	s_waitcnt lgkmcnt(0)
	s_add_u32 s36, s34, 0x8000000
	s_addc_u32 s37, s35, 0
	s_add_u32 s40, s34, 0xce00000
	s_addc_u32 s41, s35, 0
	s_add_u32 s6, s34, 0xcd80000
	v_readlane_b32 s2, v242, 17
	s_addc_u32 s7, s35, 0
	s_lshl_b32 s8, s2, 9
	s_add_u32 s9, s34, 0xc800000
	s_addc_u32 s10, s35, 0
	s_add_u32 s42, s34, 0xd000000
	s_addc_u32 s43, s35, 0
	s_add_u32 s44, s34, 0xd080000
	s_addc_u32 s45, s35, 0
	s_lshl_b32 s11, s56, 7
	s_lshl_b32 s12, s4, 7
	s_mov_b32 s13, s56
	s_branch .LBB0_725

.LBB0_728:
	s_or_b64 exec, exec, s[46:47]
	s_lshl_b32 s3, s13, 7
	s_ashr_i32 s23, s22, 31
	s_add_i32 s2, s22, s5
	s_and_b32 s14, s3, 0x780
	s_lshl_b64 s[16:17], s[22:23], 20
	s_add_u32 s16, s40, s16
	s_addc_u32 s17, s41, s17
	s_ashr_i32 s3, s2, 31
	v_mov_b32_e32 v95, v206
	s_waitcnt vmcnt(0)
	s_setprio 0
	s_barrier
	s_lshl_b64 s[2:3], s[2:3], 17
	s_add_u32 s2, s9, s2
	v_ashrrev_i32_e32 v50, 3, v95
	v_ashrrev_i32_e32 v51, 31, v50
	s_addc_u32 s3, s10, s3
	v_lshlrev_b32_e32 v0, 4, v95
	v_lshlrev_b64 v[2:3], 9, v[50:51]
	v_and_b32_e32 v0, 0x70, v0
	v_lshl_add_u64 v[2:3], s[2:3], 0, v[2:3]
	v_lshl_add_u64 v[66:67], v[2:3], 0, v[0:1]
	s_movk_i32 s2, 0x4000
	v_add_co_u32_e32 v68, vcc, s2, v66
	s_mov_b32 s2, 0x8000
	s_nop 0
	v_addc_co_u32_e32 v69, vcc, 0, v67, vcc
	v_add_co_u32_e32 v70, vcc, s2, v66
	s_mov_b32 s2, 0xc000
	s_nop 0
	v_addc_co_u32_e32 v71, vcc, 0, v67, vcc
	v_add_co_u32_e32 v72, vcc, s2, v66
	s_mov_b32 s2, 0x14000
	s_nop 0
	v_addc_co_u32_e32 v73, vcc, 0, v67, vcc
	v_add_co_u32_e32 v74, vcc, s26, v66
	v_add_u32_e32 v28, s14, v50
	s_nop 0
	v_addc_co_u32_e32 v75, vcc, 0, v67, vcc
	v_add_co_u32_e32 v76, vcc, s2, v66
	s_or_b32 s2, s14, 32
	v_ashrrev_i32_e32 v29, 31, v28
	s_sub_u32 s2, s2, s14
	v_lshl_add_u64 v[26:27], s[16:17], 0, v[0:1]
	v_lshlrev_b64 v[28:29], 9, v[28:29]
	s_subb_u32 s3, 0, 0
	v_lshl_add_u64 v[80:81], v[26:27], 0, v[28:29]
	s_lshl_b64 s[2:3], s[2:3], 9
	v_lshl_add_u64 v[90:91], v[80:81], 0, s[2:3]
	v_lshl_add_u64 v[88:89], v[90:91], 0, s[2:3]
	v_addc_co_u32_e32 v77, vcc, 0, v67, vcc
	v_lshl_add_u64 v[92:93], v[88:89], 0, s[2:3]
	s_mov_b32 s2, 0x18000
	v_add_co_u32_e32 v84, vcc, s2, v66
	s_mov_b32 s2, 0x1c000
	s_nop 0
	v_addc_co_u32_e32 v85, vcc, 0, v67, vcc
	v_add_co_u32_e32 v86, vcc, s2, v66
	global_load_dwordx4 v[2:5], v[66:67], off
	global_load_dwordx4 v[6:9], v[68:69], off
	global_load_dwordx4 v[10:13], v[70:71], off
	global_load_dwordx4 v[14:17], v[72:73], off
	global_load_dwordx4 v[18:21], v[74:75], off
	global_load_dwordx4 v[22:25], v[76:77], off
	global_load_dwordx4 v[26:29], v[80:81], off
	global_load_dwordx4 v[30:33], v[90:91], off
	global_load_dwordx4 v[34:37], v[88:89], off
	global_load_dwordx4 v[38:41], v[92:93], off
	v_addc_co_u32_e32 v87, vcc, 0, v67, vcc
	global_load_dwordx4 v[42:45], v[84:85], off
	global_load_dwordx4 v[46:49], v[86:87], off
	v_ashrrev_i32_e32 v97, 6, v95
	v_and_b32_e32 v94, 31, v95
	v_lshrrev_b32_e32 v51, 1, v95
	v_and_b32_e32 v99, 1, v97
	s_movk_i32 s15, 0x90
	v_and_b32_e32 v52, 16, v51
	v_mad_u64_u32 v[82:83], s[2:3], v50, s15, v[0:1]
	v_lshl_or_b32 v0, v99, 7, v94
	v_mad_u32_u24 v0, v0, s15, v52
	s_setprio 0
	s_barrier
	v_ashrrev_i32_e32 v98, 1, v95
	v_and_b32_e32 v96, 0xffffffc0, v98
	s_movk_i32 s21, 0x90
	v_cmp_eq_u32_e32 vcc, 0, v99
	s_waitcnt vmcnt(5)
	ds_write_b128 v82, v[26:29]
	ds_write_b128 v82, v[2:5] offset:18432
	s_waitcnt vmcnt(4)
	ds_write_b128 v82, v[30:33] offset:4608
	s_waitcnt vmcnt(3)
	ds_write_b128 v82, v[34:37] offset:9216
	s_waitcnt vmcnt(2)
	ds_write_b128 v82, v[38:41] offset:13824
	ds_write_b128 v82, v[6:9] offset:23040
	ds_write_b128 v82, v[10:13] offset:27648
	ds_write_b128 v82, v[14:17] offset:32256
	ds_write_b128 v82, v[18:21] offset:36864
	ds_write_b128 v82, v[22:25] offset:41472
	s_waitcnt vmcnt(1)
	ds_write_b128 v82, v[42:45] offset:46080
	s_waitcnt vmcnt(0)
	ds_write_b128 v82, v[46:49] offset:50688
	s_waitcnt lgkmcnt(0)
	s_setprio 0
	s_barrier
	s_setprio 1
	ds_read_b128 v[2:5], v0 offset:18432
	v_or_b32_e32 v6, v96, v94
	v_mad_u64_u32 v[78:79], s[2:3], v6, s15, v[52:53]
	ds_read_b128 v[6:9], v78
	ds_read_b128 v[100:103], v78 offset:32
	ds_read_b128 v[104:107], v0 offset:18464
	ds_read_b128 v[34:37], v78 offset:4608
	ds_read_b128 v[108:111], v78 offset:4640
	s_waitcnt lgkmcnt(4)
	v_mfma_f32_32x32x16_bf16 v[18:33], v[2:5], v[6:9], 0
	ds_read_b128 v[38:41], v0 offset:23040
	ds_read_b128 v[112:115], v0 offset:23072
	s_waitcnt lgkmcnt(3)
	v_mfma_f32_32x32x16_bf16 v[50:65], v[2:5], v[34:37], 0
	s_waitcnt lgkmcnt(1)
	v_mfma_f32_32x32x16_bf16 v[2:17], v[38:41], v[6:9], 0
	v_mfma_f32_32x32x16_bf16 v[34:49], v[38:41], v[34:37], 0
	v_mfma_f32_32x32x16_bf16 v[18:33], v[104:107], v[100:103], v[18:33]
	v_mfma_f32_32x32x16_bf16 v[50:65], v[104:107], v[108:111], v[50:65]
	s_waitcnt lgkmcnt(0)
	v_mfma_f32_32x32x16_bf16 v[2:17], v[112:115], v[100:103], v[2:17]
	v_mfma_f32_32x32x16_bf16 v[34:49], v[112:115], v[108:111], v[34:49]
	ds_read_b128 v[100:103], v0 offset:18496
	ds_read_b128 v[104:107], v78 offset:64
	ds_read_b128 v[108:111], v78 offset:96
	ds_read_b128 v[112:115], v0 offset:18528
	ds_read_b128 v[116:119], v78 offset:4672
	ds_read_b128 v[120:123], v78 offset:4704
	s_waitcnt lgkmcnt(4)
	v_mfma_f32_32x32x16_bf16 v[18:33], v[100:103], v[104:107], v[18:33]
	s_waitcnt lgkmcnt(1)
	v_mfma_f32_32x32x16_bf16 v[50:65], v[100:103], v[116:119], v[50:65]
	ds_read_b128 v[100:103], v0 offset:23104
	ds_read_b128 v[124:127], v0 offset:23136
	s_waitcnt lgkmcnt(1)
	v_mfma_f32_32x32x16_bf16 v[2:17], v[100:103], v[104:107], v[2:17]
	v_mfma_f32_32x32x16_bf16 v[34:49], v[100:103], v[116:119], v[34:49]
	global_load_dwordx4 v[100:103], v[90:91], off offset:128
	global_load_dwordx4 v[104:107], v[80:81], off offset:128
	v_mfma_f32_32x32x16_bf16 v[18:33], v[112:115], v[108:111], v[18:33]
	v_mfma_f32_32x32x16_bf16 v[50:65], v[112:115], v[120:123], v[50:65]
	global_load_dwordx4 v[112:115], v[92:93], off offset:128
	global_load_dwordx4 v[116:119], v[88:89], off offset:128
	global_load_dwordx4 v[128:131], v[68:69], off offset:128
	global_load_dwordx4 v[132:135], v[66:67], off offset:128
	global_load_dwordx4 v[136:139], v[72:73], off offset:128
	global_load_dwordx4 v[140:143], v[70:71], off offset:128
	global_load_dwordx4 v[144:147], v[76:77], off offset:128
	global_load_dwordx4 v[148:151], v[74:75], off offset:128
	s_waitcnt lgkmcnt(0)
	v_mfma_f32_32x32x16_bf16 v[2:17], v[124:127], v[108:111], v[2:17]
	global_load_dwordx4 v[108:111], v[84:85], off offset:128
	global_load_dwordx4 v[152:155], v[86:87], off offset:128
	s_setprio 0
	s_barrier
	s_waitcnt vmcnt(10)
	ds_write_b128 v82, v[104:107]
	ds_write_b128 v82, v[100:103] offset:4608
	s_waitcnt vmcnt(8)
	ds_write_b128 v82, v[116:119] offset:9216
	ds_write_b128 v82, v[112:115] offset:13824
	s_waitcnt vmcnt(6)
	ds_write_b128 v82, v[132:135] offset:18432
	ds_write_b128 v82, v[128:131] offset:23040
	s_waitcnt vmcnt(4)
	ds_write_b128 v82, v[140:143] offset:27648
	ds_write_b128 v82, v[136:139] offset:32256
	s_waitcnt vmcnt(2)
	ds_write_b128 v82, v[148:151] offset:36864
	ds_write_b128 v82, v[144:147] offset:41472
	s_waitcnt vmcnt(1)
	ds_write_b128 v82, v[108:111] offset:46080
	s_waitcnt vmcnt(0)
	ds_write_b128 v82, v[152:155] offset:50688
	v_mfma_f32_32x32x16_bf16 v[34:49], v[124:127], v[120:123], v[34:49]
	s_waitcnt lgkmcnt(0)
	s_setprio 0
	s_barrier
	ds_read_b128 v[100:103], v0 offset:18432
	ds_read_b128 v[104:107], v78
	ds_read_b128 v[108:111], v78 offset:32
	ds_read_b128 v[112:115], v0 offset:18464
	ds_read_b128 v[116:119], v78 offset:4608
	ds_read_b128 v[120:123], v78 offset:4640
	s_waitcnt lgkmcnt(4)
	v_mfma_f32_32x32x16_bf16 v[18:33], v[100:103], v[104:107], v[18:33]
	s_waitcnt lgkmcnt(1)
	v_mfma_f32_32x32x16_bf16 v[50:65], v[100:103], v[116:119], v[50:65]
	ds_read_b128 v[100:103], v0 offset:23040
	ds_read_b128 v[124:127], v0 offset:23072
	s_waitcnt lgkmcnt(1)
	v_mfma_f32_32x32x16_bf16 v[2:17], v[100:103], v[104:107], v[2:17]
	v_mfma_f32_32x32x16_bf16 v[34:49], v[100:103], v[116:119], v[34:49]
	v_mfma_f32_32x32x16_bf16 v[18:33], v[112:115], v[108:111], v[18:33]
	v_mfma_f32_32x32x16_bf16 v[50:65], v[112:115], v[120:123], v[50:65]
	s_waitcnt lgkmcnt(0)
	v_mfma_f32_32x32x16_bf16 v[2:17], v[124:127], v[108:111], v[2:17]
	ds_read_b128 v[100:103], v0 offset:18496
	ds_read_b128 v[104:107], v78 offset:64
	ds_read_b128 v[108:111], v78 offset:96
	ds_read_b128 v[112:115], v0 offset:18528
	v_mfma_f32_32x32x16_bf16 v[34:49], v[124:127], v[120:123], v[34:49]
	ds_read_b128 v[116:119], v78 offset:4672
	ds_read_b128 v[120:123], v78 offset:4704
	s_waitcnt lgkmcnt(4)
	v_mfma_f32_32x32x16_bf16 v[18:33], v[100:103], v[104:107], v[18:33]
	s_waitcnt lgkmcnt(1)
	v_mfma_f32_32x32x16_bf16 v[50:65], v[100:103], v[116:119], v[50:65]
	ds_read_b128 v[100:103], v0 offset:23104
	ds_read_b128 v[124:127], v0 offset:23136
	s_waitcnt lgkmcnt(1)
	v_mfma_f32_32x32x16_bf16 v[2:17], v[100:103], v[104:107], v[2:17]
	v_mfma_f32_32x32x16_bf16 v[34:49], v[100:103], v[116:119], v[34:49]
	global_load_dwordx4 v[100:103], v[90:91], off offset:256
	global_load_dwordx4 v[104:107], v[80:81], off offset:256
	v_mfma_f32_32x32x16_bf16 v[18:33], v[112:115], v[108:111], v[18:33]
	v_mfma_f32_32x32x16_bf16 v[50:65], v[112:115], v[120:123], v[50:65]
	global_load_dwordx4 v[112:115], v[92:93], off offset:256
	global_load_dwordx4 v[116:119], v[88:89], off offset:256
	global_load_dwordx4 v[128:131], v[68:69], off offset:256
	global_load_dwordx4 v[132:135], v[66:67], off offset:256
	global_load_dwordx4 v[136:139], v[72:73], off offset:256
	global_load_dwordx4 v[140:143], v[70:71], off offset:256
	global_load_dwordx4 v[144:147], v[76:77], off offset:256
	global_load_dwordx4 v[148:151], v[74:75], off offset:256
	s_waitcnt lgkmcnt(0)
	v_mfma_f32_32x32x16_bf16 v[2:17], v[124:127], v[108:111], v[2:17]
	global_load_dwordx4 v[108:111], v[84:85], off offset:256
	global_load_dwordx4 v[152:155], v[86:87], off offset:256
	s_setprio 0
	s_barrier
	s_waitcnt vmcnt(10)
	ds_write_b128 v82, v[104:107]
	ds_write_b128 v82, v[100:103] offset:4608
	s_waitcnt vmcnt(8)
	ds_write_b128 v82, v[116:119] offset:9216
	ds_write_b128 v82, v[112:115] offset:13824
	s_waitcnt vmcnt(6)
	ds_write_b128 v82, v[132:135] offset:18432
	ds_write_b128 v82, v[128:131] offset:23040
	s_waitcnt vmcnt(4)
	ds_write_b128 v82, v[140:143] offset:27648
	ds_write_b128 v82, v[136:139] offset:32256
	s_waitcnt vmcnt(2)
	ds_write_b128 v82, v[148:151] offset:36864
	ds_write_b128 v82, v[144:147] offset:41472
	s_waitcnt vmcnt(1)
	ds_write_b128 v82, v[108:111] offset:46080
	s_waitcnt vmcnt(0)
	ds_write_b128 v82, v[152:155] offset:50688
	v_mfma_f32_32x32x16_bf16 v[34:49], v[124:127], v[120:123], v[34:49]
	s_waitcnt lgkmcnt(0)
	s_setprio 0
	s_barrier
	ds_read_b128 v[100:103], v0 offset:18432
	ds_read_b128 v[104:107], v78
	ds_read_b128 v[108:111], v78 offset:32
	ds_read_b128 v[112:115], v0 offset:18464
	ds_read_b128 v[116:119], v78 offset:4608
	ds_read_b128 v[120:123], v78 offset:4640
	s_waitcnt lgkmcnt(4)
	v_mfma_f32_32x32x16_bf16 v[18:33], v[100:103], v[104:107], v[18:33]
	s_waitcnt lgkmcnt(1)
	v_mfma_f32_32x32x16_bf16 v[50:65], v[100:103], v[116:119], v[50:65]
	ds_read_b128 v[100:103], v0 offset:23040
	ds_read_b128 v[124:127], v0 offset:23072
	s_waitcnt lgkmcnt(1)
	v_mfma_f32_32x32x16_bf16 v[2:17], v[100:103], v[104:107], v[2:17]
	v_mfma_f32_32x32x16_bf16 v[34:49], v[100:103], v[116:119], v[34:49]
	v_mfma_f32_32x32x16_bf16 v[18:33], v[112:115], v[108:111], v[18:33]
	v_mfma_f32_32x32x16_bf16 v[50:65], v[112:115], v[120:123], v[50:65]
	s_waitcnt lgkmcnt(0)
	v_mfma_f32_32x32x16_bf16 v[2:17], v[124:127], v[108:111], v[2:17]
	ds_read_b128 v[100:103], v0 offset:18496
	ds_read_b128 v[104:107], v78 offset:64
	ds_read_b128 v[108:111], v78 offset:96
	ds_read_b128 v[112:115], v0 offset:18528
	v_mfma_f32_32x32x16_bf16 v[34:49], v[124:127], v[120:123], v[34:49]
	ds_read_b128 v[116:119], v78 offset:4672
	ds_read_b128 v[120:123], v78 offset:4704
	s_waitcnt lgkmcnt(4)
	v_mfma_f32_32x32x16_bf16 v[18:33], v[100:103], v[104:107], v[18:33]
	s_waitcnt lgkmcnt(1)
	v_mfma_f32_32x32x16_bf16 v[50:65], v[100:103], v[116:119], v[50:65]
	ds_read_b128 v[100:103], v0 offset:23104
	ds_read_b128 v[124:127], v0 offset:23136
	s_waitcnt lgkmcnt(1)
	v_mfma_f32_32x32x16_bf16 v[2:17], v[100:103], v[104:107], v[2:17]
	v_mfma_f32_32x32x16_bf16 v[34:49], v[100:103], v[116:119], v[34:49]
	global_load_dwordx4 v[100:103], v[90:91], off offset:384
	global_load_dwordx4 v[104:107], v[80:81], off offset:384
	v_mfma_f32_32x32x16_bf16 v[18:33], v[112:115], v[108:111], v[18:33]
	v_mfma_f32_32x32x16_bf16 v[50:65], v[112:115], v[120:123], v[50:65]
	global_load_dwordx4 v[90:93], v[92:93], off offset:384
	s_nop 0
	global_load_dwordx4 v[112:115], v[88:89], off offset:384
	global_load_dwordx4 v[116:119], v[68:69], off offset:384
	s_nop 0
	global_load_dwordx4 v[66:69], v[66:67], off offset:384
	s_nop 0
	global_load_dwordx4 v[128:131], v[72:73], off offset:384
	s_nop 0
	global_load_dwordx4 v[70:73], v[70:71], off offset:384
	s_nop 0
	global_load_dwordx4 v[132:135], v[76:77], off offset:384
	s_nop 0
	global_load_dwordx4 v[74:77], v[74:75], off offset:384
	s_waitcnt lgkmcnt(0)
	v_mfma_f32_32x32x16_bf16 v[2:17], v[124:127], v[108:111], v[2:17]
	global_load_dwordx4 v[108:111], v[84:85], off offset:384
	s_nop 0
	global_load_dwordx4 v[84:87], v[86:87], off offset:384
	s_setprio 0
	s_barrier
	s_waitcnt vmcnt(10)
	ds_write_b128 v82, v[104:107]
	ds_write_b128 v82, v[100:103] offset:4608
	s_waitcnt vmcnt(8)
	ds_write_b128 v82, v[112:115] offset:9216
	ds_write_b128 v82, v[90:93] offset:13824
	s_waitcnt vmcnt(6)
	ds_write_b128 v82, v[66:69] offset:18432
	ds_write_b128 v82, v[116:119] offset:23040
	s_waitcnt vmcnt(4)
	ds_write_b128 v82, v[70:73] offset:27648
	ds_write_b128 v82, v[128:131] offset:32256
	s_waitcnt vmcnt(2)
	ds_write_b128 v82, v[74:77] offset:36864
	ds_write_b128 v82, v[132:135] offset:41472
	s_waitcnt vmcnt(1)
	ds_write_b128 v82, v[108:111] offset:46080
	s_waitcnt vmcnt(0)
	ds_write_b128 v82, v[84:87] offset:50688
	v_mfma_f32_32x32x16_bf16 v[34:49], v[124:127], v[120:123], v[34:49]
	s_waitcnt lgkmcnt(0)
	s_setprio 0
	s_barrier
	ds_read_b128 v[66:69], v0 offset:18432
	ds_read_b128 v[70:73], v78
	ds_read_b128 v[74:77], v78 offset:32
	ds_read_b128 v[80:83], v0 offset:18464
	ds_read_b128 v[84:87], v78 offset:4608
	ds_read_b128 v[88:91], v78 offset:4640
	s_waitcnt lgkmcnt(4)
	v_mfma_f32_32x32x16_bf16 v[18:33], v[66:69], v[70:73], v[18:33]
	s_waitcnt lgkmcnt(1)
	v_mfma_f32_32x32x16_bf16 v[50:65], v[66:69], v[84:87], v[50:65]
	ds_read_b128 v[66:69], v0 offset:23040
	ds_read_b128 v[100:103], v0 offset:23072
	s_waitcnt lgkmcnt(1)
	v_mfma_f32_32x32x16_bf16 v[2:17], v[66:69], v[70:73], v[2:17]
	v_mfma_f32_32x32x16_bf16 v[34:49], v[66:69], v[84:87], v[34:49]
	v_mfma_f32_32x32x16_bf16 v[18:33], v[80:83], v[74:77], v[18:33]
	v_mfma_f32_32x32x16_bf16 v[50:65], v[80:83], v[88:91], v[50:65]
	s_waitcnt lgkmcnt(0)
	v_mfma_f32_32x32x16_bf16 v[2:17], v[100:103], v[74:77], v[2:17]
	ds_read_b128 v[66:69], v0 offset:18496
	ds_read_b128 v[70:73], v78 offset:64
	ds_read_b128 v[74:77], v78 offset:96
	ds_read_b128 v[80:83], v0 offset:18528
	v_mfma_f32_32x32x16_bf16 v[34:49], v[100:103], v[88:91], v[34:49]
	ds_read_b128 v[84:87], v78 offset:4672
	ds_read_b128 v[88:91], v78 offset:4704
	s_waitcnt lgkmcnt(4)
	v_mfma_f32_32x32x16_bf16 v[18:33], v[66:69], v[70:73], v[18:33]
	s_waitcnt lgkmcnt(1)
	v_mfma_f32_32x32x16_bf16 v[50:65], v[66:69], v[84:87], v[50:65]
	ds_read_b128 v[66:69], v0 offset:23104
	ds_read_b128 v[100:103], v0 offset:23136
	s_waitcnt lgkmcnt(0)
	s_setprio 0
	s_barrier
	v_mfma_f32_32x32x16_bf16 v[2:17], v[66:69], v[70:73], v[2:17]
	v_mfma_f32_32x32x16_bf16 v[34:49], v[66:69], v[84:87], v[34:49]
	v_mfma_f32_32x32x16_bf16 v[18:33], v[80:83], v[74:77], v[18:33]
	v_mfma_f32_32x32x16_bf16 v[50:65], v[80:83], v[88:91], v[50:65]
	v_mfma_f32_32x32x16_bf16 v[2:17], v[100:103], v[74:77], v[2:17]
	v_mfma_f32_32x32x16_bf16 v[34:49], v[100:103], v[88:91], v[34:49]
	s_and_saveexec_b64 s[2:3], vcc
	s_cbranch_execz .LBB0_724
	v_bfe_u32 v71, v95, 3, 3
	s_movk_i32 s15, 0x2400
	v_and_b32_e32 v70, 63, v95
	v_and_b32_e32 v67, 4, v71
	v_mul_lo_u32 v72, v97, s15
	v_and_b32_e32 v73, 64, v98
	v_add_u32_e32 v66, s14, v96
	s_cmp_gt_u32 s13, 15
	s_mov_b64 s[22:23], -1
	s_cbranch_scc0 .LBB0_731
	v_mul_u32_u24_e32 v0, 0x90, v67
	v_lshlrev_b32_e32 v68, 1, v94
	v_add3_u32 v74, v72, v0, v68
	v_ashrrev_i32_e32 v68, 7, v66
	s_movk_i32 s14, 0x5f
	v_ashrrev_i32_e32 v69, 31, v68
	v_bitop3_b32 v0, v96, s14, v70 bitop3:0xc8
	v_lshlrev_b64 v[68:69], 14, v[68:69]
	v_cmp_eq_u32_e32 vcc, s14, v0
	v_lshl_add_u64 v[68:69], s[44:45], 0, v[68:69]
	v_lshlrev_b32_e32 v0, 1, v73
	v_lshl_add_u64 v[68:69], v[68:69], 0, v[0:1]
	v_cvt_pk_bf16_f32 v0, v18, s0
	ds_write_b16 v74, v0
	v_cvt_pk_bf16_f32 v0, v19, s0
	ds_write_b16 v74, v0 offset:144
	v_cvt_pk_bf16_f32 v0, v20, s0
	ds_write_b16 v74, v0 offset:288
	v_cvt_pk_bf16_f32 v0, v21, s0
	ds_write_b16 v74, v0 offset:432
	v_cvt_pk_bf16_f32 v0, v22, s0
	ds_write_b16 v74, v0 offset:1152
	v_cvt_pk_bf16_f32 v0, v23, s0
	ds_write_b16 v74, v0 offset:1296
	v_cvt_pk_bf16_f32 v0, v24, s0
	ds_write_b16 v74, v0 offset:1440
	v_cvt_pk_bf16_f32 v0, v25, s0
	ds_write_b16 v74, v0 offset:1584
	v_cvt_pk_bf16_f32 v0, v26, s0
	ds_write_b16 v74, v0 offset:2304
	v_cvt_pk_bf16_f32 v0, v27, s0
	ds_write_b16 v74, v0 offset:2448
	v_cvt_pk_bf16_f32 v0, v28, s0
	ds_write_b16 v74, v0 offset:2592
	v_cvt_pk_bf16_f32 v0, v29, s0
	ds_write_b16 v74, v0 offset:2736
	v_cvt_pk_bf16_f32 v0, v30, s0
	ds_write_b16 v74, v0 offset:3456
	v_cvt_pk_bf16_f32 v0, v31, s0
	ds_write_b16 v74, v0 offset:3600
	v_cvt_pk_bf16_f32 v0, v32, s0
	ds_write_b16 v74, v0 offset:3744
	v_cvt_pk_bf16_f32 v0, v33, s0
	ds_write_b16 v74, v0 offset:3888
	v_cvt_pk_bf16_f32 v0, v2, s0
	ds_write_b16 v74, v0 offset:4608
	v_cvt_pk_bf16_f32 v0, v3, s0
	ds_write_b16 v74, v0 offset:4752
	v_cvt_pk_bf16_f32 v0, v4, s0
	ds_write_b16 v74, v0 offset:4896
	v_cvt_pk_bf16_f32 v0, v5, s0
	ds_write_b16 v74, v0 offset:5040
	v_cvt_pk_bf16_f32 v0, v6, s0
	ds_write_b16 v74, v0 offset:5760
	v_cvt_pk_bf16_f32 v0, v7, s0
	ds_write_b16 v74, v0 offset:5904
	v_cvt_pk_bf16_f32 v0, v8, s0
	ds_write_b16 v74, v0 offset:6048
	v_cvt_pk_bf16_f32 v0, v9, s0
	ds_write_b16 v74, v0 offset:6192
	v_cvt_pk_bf16_f32 v0, v10, s0
	ds_write_b16 v74, v0 offset:6912
	v_cvt_pk_bf16_f32 v0, v11, s0
	ds_write_b16 v74, v0 offset:7056
	v_cvt_pk_bf16_f32 v0, v12, s0
	ds_write_b16 v74, v0 offset:7200
	v_cvt_pk_bf16_f32 v0, v13, s0
	ds_write_b16 v74, v0 offset:7344
	v_cvt_pk_bf16_f32 v0, v14, s0
	ds_write_b16 v74, v0 offset:8064
	v_cvt_pk_bf16_f32 v0, v15, s0
	ds_write_b16 v74, v0 offset:8208
	v_cvt_pk_bf16_f32 v0, v16, s0
	ds_write_b16 v74, v0 offset:8352
	v_cvt_pk_bf16_f32 v0, v17, s0
	ds_write_b16 v74, v0 offset:8496
	v_cvt_pk_bf16_f32 v0, v50, s0
	v_cndmask_b32_e64 v0, v0, 0, vcc
	ds_write_b16 v74, v0 offset:64
	v_cvt_pk_bf16_f32 v0, v51, s0
	v_cndmask_b32_e64 v0, v0, 0, vcc
	ds_write_b16 v74, v0 offset:208
	v_cvt_pk_bf16_f32 v0, v52, s0
	v_cndmask_b32_e64 v0, v0, 0, vcc
	ds_write_b16 v74, v0 offset:352
	v_cvt_pk_bf16_f32 v0, v53, s0
	v_cndmask_b32_e64 v0, v0, 0, vcc
	ds_write_b16 v74, v0 offset:496
	v_cvt_pk_bf16_f32 v0, v54, s0
	v_cndmask_b32_e64 v0, v0, 0, vcc
	ds_write_b16 v74, v0 offset:1216
	v_cvt_pk_bf16_f32 v0, v55, s0
	v_cndmask_b32_e64 v0, v0, 0, vcc
	ds_write_b16 v74, v0 offset:1360
	v_cvt_pk_bf16_f32 v0, v56, s0
	v_cndmask_b32_e64 v0, v0, 0, vcc
	ds_write_b16 v74, v0 offset:1504
	v_cvt_pk_bf16_f32 v0, v57, s0
	v_cndmask_b32_e64 v0, v0, 0, vcc
	ds_write_b16 v74, v0 offset:1648
	v_cvt_pk_bf16_f32 v0, v58, s0
	v_cndmask_b32_e64 v0, v0, 0, vcc
	ds_write_b16 v74, v0 offset:2368
	v_cvt_pk_bf16_f32 v0, v59, s0
	v_cndmask_b32_e64 v0, v0, 0, vcc
	ds_write_b16 v74, v0 offset:2512
	v_cvt_pk_bf16_f32 v0, v60, s0
	v_cndmask_b32_e64 v0, v0, 0, vcc
	ds_write_b16 v74, v0 offset:2656
	v_cvt_pk_bf16_f32 v0, v61, s0
	v_cndmask_b32_e64 v0, v0, 0, vcc
	ds_write_b16 v74, v0 offset:2800
	v_cvt_pk_bf16_f32 v0, v62, s0
	v_cndmask_b32_e64 v0, v0, 0, vcc
	ds_write_b16 v74, v0 offset:3520
	v_cvt_pk_bf16_f32 v0, v63, s0
	v_cndmask_b32_e64 v0, v0, 0, vcc
	ds_write_b16 v74, v0 offset:3664
	v_cvt_pk_bf16_f32 v0, v64, s0
	v_cndmask_b32_e64 v0, v0, 0, vcc
	ds_write_b16 v74, v0 offset:3808
	v_cvt_pk_bf16_f32 v0, v65, s0
	v_cndmask_b32_e64 v0, v0, 0, vcc
	ds_write_b16 v74, v0 offset:3952
	v_cvt_pk_bf16_f32 v0, v34, s0
	v_cndmask_b32_e64 v0, v0, 0, vcc
	ds_write_b16 v74, v0 offset:4672
	v_cvt_pk_bf16_f32 v0, v35, s0
	v_cndmask_b32_e64 v0, v0, 0, vcc
	ds_write_b16 v74, v0 offset:4816
	v_cvt_pk_bf16_f32 v0, v36, s0
	v_cndmask_b32_e64 v0, v0, 0, vcc
	ds_write_b16 v74, v0 offset:4960
	v_cvt_pk_bf16_f32 v0, v37, s0
	v_cndmask_b32_e64 v0, v0, 0, vcc
	ds_write_b16 v74, v0 offset:5104
	v_cvt_pk_bf16_f32 v0, v38, s0
	v_cndmask_b32_e64 v0, v0, 0, vcc
	ds_write_b16 v74, v0 offset:5824
	v_cvt_pk_bf16_f32 v0, v39, s0
	v_cndmask_b32_e64 v0, v0, 0, vcc
	ds_write_b16 v74, v0 offset:5968
	v_cvt_pk_bf16_f32 v0, v40, s0
	v_cndmask_b32_e64 v0, v0, 0, vcc
	ds_write_b16 v74, v0 offset:6112
	v_cvt_pk_bf16_f32 v0, v41, s0
	v_cndmask_b32_e64 v0, v0, 0, vcc
	ds_write_b16 v74, v0 offset:6256
	v_cvt_pk_bf16_f32 v0, v42, s0
	v_cndmask_b32_e64 v0, v0, 0, vcc
	ds_write_b16 v74, v0 offset:6976
	v_cvt_pk_bf16_f32 v0, v43, s0
	v_cndmask_b32_e64 v0, v0, 0, vcc
	ds_write_b16 v74, v0 offset:7120
	v_cvt_pk_bf16_f32 v0, v44, s0
	v_cndmask_b32_e64 v0, v0, 0, vcc
	ds_write_b16 v74, v0 offset:7264
	v_cvt_pk_bf16_f32 v0, v45, s0
	v_cndmask_b32_e64 v0, v0, 0, vcc
	ds_write_b16 v74, v0 offset:7408
	v_cvt_pk_bf16_f32 v0, v46, s0
	v_cndmask_b32_e64 v0, v0, 0, vcc
	ds_write_b16 v74, v0 offset:8128
	v_cvt_pk_bf16_f32 v0, v47, s0
	v_cndmask_b32_e64 v0, v0, 0, vcc
	ds_write_b16 v74, v0 offset:8272
	v_cvt_pk_bf16_f32 v0, v48, s0
	v_cndmask_b32_e64 v0, v0, 0, vcc
	ds_write_b16 v74, v0 offset:8416
	v_cvt_pk_bf16_f32 v0, v49, s0
	v_cndmask_b32_e64 v0, v0, 0, vcc
	ds_write_b16 v74, v0 offset:8560
	v_lshlrev_b32_e32 v0, 8, v71
	v_lshl_add_u64 v[68:69], v[68:69], 0, v[0:1]
	s_mov_b64 s[22:23], 0

.LBB0_737:
	s_lshl_b32 s2, s9, 6
	s_ashr_i32 s3, s9, 4
	s_and_b32 s2, s2, 0x3c0
	s_sub_i32 s3, 63, s3
	s_or_b32 s11, s2, s3
	v_mov_b32_e32 v7, v206
	s_lshl_b32 s16, s3, 5
	s_and_b32 s10, s16, 0x7e0
	v_and_b32_e32 v6, 31, v7
	s_lshl_b32 s2, s11, 4
	v_ashrrev_i32_e32 v0, 6, v7
	s_bfe_u32 s12, s11, 0x10006
	v_or_b32_e32 v2, s10, v6
	s_and_b32 s76, s2, 0xfffff800
	v_lshl_add_u32 v4, s12, 2, v0
	v_or_b32_e32 v0, s76, v2
	v_lshlrev_b64 v[2:3], 10, v[0:1]
	v_lshlrev_b32_e32 v130, 6, v4
	v_lshl_add_u64 v[2:3], s[36:37], 0, v[2:3]
	v_ashrrev_i32_e32 v131, 31, v130
	v_and_b32_e32 v5, 32, v7
	v_lshl_add_u64 v[2:3], v[130:131], 1, v[2:3]
	v_lshlrev_b32_e32 v132, 1, v5
	v_mov_b32_e32 v133, v1
	v_lshl_add_u64 v[2:3], v[2:3], 0, v[132:133]
	global_load_dwordx4 v[98:101], v[2:3], off
	global_load_dwordx4 v[102:105], v[2:3], off offset:16
	global_load_dwordx4 v[106:109], v[2:3], off offset:32
	global_load_dwordx4 v[110:113], v[2:3], off offset:48
	v_lshl_add_u32 v2, v4, 1, v4
	v_mov_b64_e32 v[4:5], s[72:73]
	s_movk_i32 s2, 0x60
	v_mad_u64_u32 v[4:5], s[2:3], v0, s2, v[4:5]
	s_lshl_b64 s[2:3], s[76:77], 8
	v_ashrrev_i32_e32 v3, 31, v2
	s_add_u32 s2, s5, s2
	v_lshl_add_u64 v[2:3], v[2:3], 2, v[4:5]
	s_addc_u32 s3, s6, s3
	s_lshl_b32 s13, s12, 6
	s_lshl_b32 s12, s12, 7
	global_load_dword v133, v[2:3], off
	s_add_u32 s2, s2, s12
	v_sub_u32_e64 v2, s10, v222 clamp
	v_mov_b32_e32 v3, v206
	s_addc_u32 s3, s3, 0
	s_and_b32 s11, s11, 0xfffff80
	v_and_b32_e32 v5, 0x7c0, v2
	v_ashrrev_i32_e32 v136, 3, v3
	s_or_b32 s76, s13, s11
	v_readfirstlane_b32 s11, v2
	v_lshlrev_b32_e32 v3, 3, v3
	v_add_u32_e32 v2, v136, v5
	v_and_b32_e32 v4, 56, v3
	v_ashrrev_i32_e32 v3, 31, v2
	s_lshl_b64 s[12:13], s[76:77], 12
	v_lshlrev_b64 v[2:3], 8, v[2:3]
	s_add_u32 s14, s7, s12
	v_lshl_add_u64 v[2:3], s[2:3], 0, v[2:3]
	v_lshlrev_b32_e32 v138, 1, v4
	v_mov_b32_e32 v139, v1
	s_addc_u32 s15, s8, s13
	s_bfe_u32 s12, s16, 0x50006
	v_lshl_add_u64 v[2:3], v[2:3], 0, v[138:139]
	s_movk_i32 s16, 0x2000
	s_setprio 0
	s_barrier
	global_load_dwordx4 v[8:11], v[2:3], off
	v_add_co_u32_e32 v2, vcc, s16, v2
	v_ashrrev_i32_e32 v137, 31, v136
	s_nop 0
	v_addc_co_u32_e32 v3, vcc, 0, v3, vcc
	global_load_dwordx4 v[12:15], v[2:3], off
	v_lshlrev_b64 v[2:3], 12, v[136:137]
	v_lshl_add_u64 v[2:3], s[14:15], 0, v[2:3]
	s_waitcnt vmcnt(11)
	v_lshlrev_b32_e32 v20, 1, v5
	v_mov_b32_e32 v21, v1
	v_lshl_add_u64 v[4:5], v[2:3], 0, v[20:21]
	v_lshl_add_u64 v[4:5], v[4:5], 0, v[138:139]
	global_load_dwordx4 v[16:19], v[4:5], off
	v_lshl_add_u64 v[4:5], v[2:3], 0, s[30:31]
	v_lshl_add_u64 v[20:21], v[4:5], 0, v[20:21]
	v_lshl_add_u64 v[20:21], v[20:21], 0, v[138:139]
	global_load_dwordx4 v[20:23], v[20:21], off
	s_lshr_b32 s11, s11, 6
	s_cmp_lt_u32 s11, s12
	s_cselect_b64 s[14:15], -1, 0
	v_mul_lo_u32 v135, v136, s21
	s_cmp_lg_u64 s[14:15], 0
	v_add_u32_e32 v25, v135, v138
	s_addc_u32 s13, s11, 0
	s_lshl_b32 s76, s13, 7
	v_bfe_u32 v24, v7, 5, 1
	s_cmp_gt_u32 s11, s12
	v_lshlrev_b32_e32 v134, 3, v24
	s_waitcnt vmcnt(3)
	ds_write_b128 v25, v[8:11]
	s_waitcnt vmcnt(2)
	ds_write_b128 v25, v[12:15] offset:4608
	s_waitcnt vmcnt(1)
	ds_write_b128 v25, v[16:19] offset:9216
	s_waitcnt vmcnt(0)
	ds_write_b128 v25, v[20:23] offset:13824
	v_lshl_add_u32 v8, s13, 6, v136
	v_ashrrev_i32_e32 v9, 31, v8
	v_lshlrev_b64 v[8:9], 8, v[8:9]
	v_lshl_add_u64 v[8:9], s[2:3], 0, v[8:9]
	v_lshl_add_u64 v[8:9], v[8:9], 0, v[138:139]
	global_load_dwordx4 v[114:117], v[8:9], off
	v_add_co_u32_e32 v8, vcc, s16, v8
	s_nop 1
	v_addc_co_u32_e32 v9, vcc, 0, v9, vcc
	global_load_dwordx4 v[118:121], v[8:9], off
	v_lshl_add_u64 v[8:9], v[2:3], 0, s[76:77]
	v_lshl_add_u64 v[8:9], v[8:9], 0, v[138:139]
	global_load_dwordx4 v[122:125], v[8:9], off
	v_lshl_add_u64 v[8:9], v[4:5], 0, s[76:77]
	v_lshl_add_u64 v[8:9], v[8:9], 0, v[138:139]
	global_load_dwordx4 v[126:129], v[8:9], off
	s_waitcnt lgkmcnt(0)
	s_setprio 0
	s_barrier
	s_cbranch_scc1 .LBB0_735
	v_and_b32_e32 v8, 63, v7
	v_lshl_add_u64 v[142:143], v[2:3], 0, v[138:139]
	v_lshlrev_b32_e32 v2, 1, v8
	v_lshrrev_b32_e32 v3, 1, v7
	v_lshl_add_u64 v[144:145], v[4:5], 0, v[138:139]
	v_and_b32_e32 v2, 8, v2
	v_and_b32_e32 v3, 4, v3
	v_and_b32_e32 v4, 19, v7
	v_or3_b32 v2, v3, v4, v2
	v_mul_u32_u24_e32 v137, 0x90, v2
	v_lshrrev_b32_e32 v2, 2, v7
	v_and_b32_e32 v146, 8, v2
	v_or_b32_e32 v2, 32, v8
	v_mul_u32_u24_e32 v147, 0x90, v2
	v_add_u32_e32 v2, s10, v6
	s_lshl_b32 s22, s11, 6
	v_sub_u32_e32 v2, v2, v134
	v_mov_b32_e32 v16, v1
	v_mov_b32_e32 v17, v1
	v_lshl_add_u64 v[140:141], s[2:3], 0, v[138:139]
	v_mul_u32_u24_e32 v139, 0x90, v6
	v_subrev_u32_e32 v148, s22, v2
	v_mov_b32_e32 v2, v1
	v_mov_b32_e32 v3, v1
	v_mov_b32_e32 v4, v1
	v_mov_b32_e32 v5, v1
	v_mov_b32_e32 v6, v1
	v_mov_b32_e32 v7, v1
	v_mov_b32_e32 v8, v1
	v_mov_b32_e32 v9, v1
	v_mov_b32_e32 v10, v1
	v_mov_b32_e32 v11, v1
	v_mov_b32_e32 v12, v1
	v_mov_b32_e32 v13, v1
	v_mov_b32_e32 v14, v1
	v_mov_b32_e32 v15, v1
	v_mov_b64_e32 v[32:33], v[16:17]
	s_or_b32 s13, s10, 31
	s_add_i32 s14, s10, 0xfffffe00
	s_add_i32 s15, s10, 0xfffffe1f
	s_mov_b32 s23, 0
	v_mov_b32_e32 v151, 0
	v_mov_b32_e32 v152, 0xff800000
	v_mov_b32_e32 v149, 0
	v_mov_b32_e32 v150, 0
	v_mov_b64_e32 v[30:31], v[14:15]
	v_mov_b64_e32 v[28:29], v[12:13]
	v_mov_b64_e32 v[26:27], v[10:11]
	v_mov_b64_e32 v[24:25], v[8:9]
	v_mov_b64_e32 v[22:23], v[6:7]
	v_mov_b64_e32 v[20:21], v[4:5]
	v_mov_b64_e32 v[18:19], v[2:3]
	s_add_i32 s2, s11, s23
	s_and_b32 s17, s23, 1
	s_cmp_ge_u32 s2, s12
	s_cbranch_scc0 .LBB0_740
	s_branch .LBB0_742

.LBB0_747:
	s_mul_i32 s76, s17, 0x4800
	s_cmp_lt_i32 s16, 3
	s_mov_b64 s[2:3], -1
	s_cbranch_scc1 .LBB0_757
	s_cmp_gt_i32 s16, 3
	s_cbranch_scc0 .LBB0_752
	v_add3_u32 v70, s76, v132, v137
	s_setprio 1
	ds_read_b128 v[34:37], v70
	ds_read_b128 v[38:41], v70 offset:16
	ds_read_b128 v[42:45], v70 offset:32
	ds_read_b128 v[46:49], v70 offset:48
	v_cmp_lt_i32_e32 vcc, -1, v150
	s_waitcnt lgkmcnt(3)
	v_mfma_f32_32x32x16_bf16 v[50:65], v[34:37], v[98:101], 0
	ds_read_b128 v[34:37], v70 offset:4608
	ds_read_b128 v[66:69], v70 offset:4624
	v_cmp_gt_i32_e64 s[38:39], 0, v149
	s_and_b64 vcc, vcc, s[38:39]
	v_cmp_gt_i32_e64 s[38:39], 1, v149
	v_mov_b32_e32 v153, v152
	s_waitcnt lgkmcnt(4)
	v_mfma_f32_32x32x16_bf16 v[50:65], v[38:41], v[102:105], v[50:65]
	s_waitcnt lgkmcnt(3)
	v_mfma_f32_32x32x16_bf16 v[50:65], v[42:45], v[106:109], v[50:65]
	s_waitcnt lgkmcnt(2)
	v_mfma_f32_32x32x16_bf16 v[50:65], v[46:49], v[110:113], v[50:65]
	s_waitcnt lgkmcnt(1)
	v_mfma_f32_32x32x16_bf16 v[34:49], v[34:37], v[98:101], 0
	s_nop 9
	v_cndmask_b32_e32 v74, v220, v50, vcc
	v_cmp_lt_i32_e32 vcc, 0, v150
	s_and_b64 vcc, vcc, s[38:39]
	v_cmp_gt_i32_e64 s[38:39], 2, v149
	v_cndmask_b32_e32 v77, v220, v51, vcc
	v_cmp_lt_i32_e32 vcc, 1, v150
	s_and_b64 vcc, vcc, s[38:39]
	v_cmp_gt_i32_e64 s[38:39], 3, v149
	v_cndmask_b32_e32 v78, v220, v52, vcc
	v_cmp_lt_i32_e32 vcc, 2, v150
	s_and_b64 vcc, vcc, s[38:39]
	s_waitcnt lgkmcnt(0)
	v_mfma_f32_32x32x16_bf16 v[34:49], v[66:69], v[102:105], v[34:49]
	ds_read_b128 v[66:69], v70 offset:4640
	v_cndmask_b32_e32 v80, v220, v53, vcc
	v_cmp_lt_i32_e32 vcc, 3, v150
	v_cmp_gt_i32_e64 s[38:39], 4, v149
	s_and_b64 vcc, vcc, s[38:39]
	v_cndmask_b32_e32 v81, v220, v54, vcc
	v_cmp_lt_i32_e32 vcc, 4, v150
	v_cmp_gt_i32_e64 s[38:39], 5, v149
	s_and_b64 vcc, vcc, s[38:39]
	v_cndmask_b32_e32 v82, v220, v55, vcc
	v_cmp_lt_i32_e32 vcc, 5, v150
	v_cmp_gt_i32_e64 s[38:39], 6, v149
	s_and_b64 vcc, vcc, s[38:39]
	v_cndmask_b32_e32 v83, v220, v56, vcc
	v_cmp_lt_i32_e32 vcc, 6, v150
	v_cmp_gt_i32_e64 s[38:39], 7, v149
	s_and_b64 vcc, vcc, s[38:39]
	v_cndmask_b32_e32 v92, v220, v57, vcc
	v_cmp_lt_i32_e32 vcc, 15, v150
	v_cmp_gt_i32_e64 s[38:39], 16, v149
	s_waitcnt lgkmcnt(0)
	v_mfma_f32_32x32x16_bf16 v[34:49], v[66:69], v[106:109], v[34:49]
	ds_read_b128 v[66:69], v70 offset:4656
	s_and_b64 vcc, vcc, s[38:39]
	v_cndmask_b32_e32 v95, v220, v58, vcc
	v_cmp_lt_i32_e32 vcc, 16, v150
	v_cmp_gt_i32_e64 s[38:39], 17, v149
	s_and_b64 vcc, vcc, s[38:39]
	v_cndmask_b32_e32 v90, v220, v59, vcc
	v_cmp_lt_i32_e32 vcc, 17, v150
	v_cmp_gt_i32_e64 s[38:39], 18, v149
	s_and_b64 vcc, vcc, s[38:39]
	v_cndmask_b32_e32 v97, v220, v60, vcc
	v_cmp_lt_i32_e32 vcc, 18, v150
	v_cmp_gt_i32_e64 s[38:39], 19, v149
	s_and_b64 vcc, vcc, s[38:39]
	v_cndmask_b32_e32 v154, v220, v61, vcc
	v_cmp_lt_i32_e32 vcc, 19, v150
	v_cmp_gt_i32_e64 s[38:39], 20, v149
	s_and_b64 vcc, vcc, s[38:39]
	s_waitcnt lgkmcnt(0)
	v_mfma_f32_32x32x16_bf16 v[34:49], v[66:69], v[110:113], v[34:49]
	v_cndmask_b32_e32 v96, v220, v62, vcc
	v_cmp_lt_i32_e32 vcc, 20, v150
	v_cmp_gt_i32_e64 s[38:39], 21, v149
	s_and_b64 vcc, vcc, s[38:39]
	v_cndmask_b32_e32 v91, v220, v63, vcc
	v_cmp_lt_i32_e32 vcc, 21, v150
	v_cmp_gt_i32_e64 s[38:39], 22, v149
	s_and_b64 vcc, vcc, s[38:39]
	v_cndmask_b32_e32 v93, v220, v64, vcc
	v_cmp_lt_i32_e32 vcc, 22, v150
	v_cmp_gt_i32_e64 s[38:39], 23, v149
	s_and_b64 vcc, vcc, s[38:39]
	v_cndmask_b32_e32 v94, v220, v65, vcc
	v_cmp_lt_i32_e32 vcc, 31, v150
	v_cmp_gt_i32_e64 s[38:39], 32, v149
	s_and_b64 vcc, vcc, s[38:39]
	v_cndmask_b32_e32 v89, v220, v34, vcc
	v_cmp_lt_i32_e32 vcc, 32, v150
	v_cmp_gt_i32_e64 s[38:39], 33, v149
	s_and_b64 vcc, vcc, s[38:39]
	v_cndmask_b32_e32 v86, v220, v35, vcc
	v_cmp_lt_i32_e32 vcc, 33, v150
	v_cmp_gt_i32_e64 s[38:39], 34, v149
	s_and_b64 vcc, vcc, s[38:39]
	v_cndmask_b32_e32 v87, v220, v36, vcc
	v_cmp_lt_i32_e32 vcc, 34, v150
	v_cmp_gt_i32_e64 s[38:39], 35, v149
	s_and_b64 vcc, vcc, s[38:39]
	v_cndmask_b32_e32 v88, v220, v37, vcc
	v_cmp_lt_i32_e32 vcc, 35, v150
	v_cmp_gt_i32_e64 s[38:39], 36, v149
	s_and_b64 vcc, vcc, s[38:39]
	v_cndmask_b32_e32 v85, v220, v38, vcc
	v_cmp_lt_i32_e32 vcc, 36, v150
	v_cmp_gt_i32_e64 s[38:39], 37, v149
	s_and_b64 vcc, vcc, s[38:39]
	v_cndmask_b32_e32 v84, v220, v39, vcc
	v_cmp_lt_i32_e32 vcc, 37, v150
	v_cmp_gt_i32_e64 s[38:39], 38, v149
	s_and_b64 vcc, vcc, s[38:39]
	v_cndmask_b32_e32 v79, v220, v40, vcc
	v_cmp_lt_i32_e32 vcc, 38, v150
	v_cmp_gt_i32_e64 s[38:39], 39, v149
	s_and_b64 vcc, vcc, s[38:39]
	v_cndmask_b32_e32 v76, v220, v41, vcc
	v_cmp_lt_i32_e32 vcc, 47, v150
	v_cmp_gt_i32_e64 s[38:39], 48, v149
	s_and_b64 vcc, vcc, s[38:39]
	v_cndmask_b32_e32 v75, v220, v42, vcc
	v_cmp_lt_i32_e32 vcc, 48, v150
	v_cmp_gt_i32_e64 s[38:39], 49, v149
	v_max3_f32 v50, v74, s85, v77
	s_and_b64 vcc, vcc, s[38:39]
	v_max3_f32 v50, v50, v78, v80
	v_cndmask_b32_e32 v71, v220, v43, vcc
	v_cmp_lt_i32_e32 vcc, 49, v150
	v_cmp_gt_i32_e64 s[38:39], 50, v149
	v_max3_f32 v50, v50, v81, v82
	s_and_b64 vcc, vcc, s[38:39]
	v_max3_f32 v50, v50, v83, v92
	v_cndmask_b32_e32 v72, v220, v44, vcc
	v_cmp_lt_i32_e32 vcc, 50, v150
	v_cmp_gt_i32_e64 s[38:39], 51, v149
	v_max3_f32 v50, v50, v95, v90
	s_and_b64 vcc, vcc, s[38:39]
	v_max3_f32 v50, v50, v97, v154
	v_cndmask_b32_e32 v73, v220, v45, vcc
	v_cmp_lt_i32_e32 vcc, 51, v150
	v_cmp_gt_i32_e64 s[38:39], 52, v149
	v_max3_f32 v50, v50, v96, v91
	s_and_b64 vcc, vcc, s[38:39]
	v_max3_f32 v50, v50, v93, v94
	v_cndmask_b32_e32 v70, v220, v46, vcc
	v_cmp_lt_i32_e32 vcc, 52, v150
	v_cmp_gt_i32_e64 s[38:39], 53, v149
	v_max3_f32 v34, v50, v89, v86
	s_and_b64 vcc, vcc, s[38:39]
	v_max3_f32 v34, v34, v87, v88
	v_cndmask_b32_e32 v67, v220, v47, vcc
	v_cmp_lt_i32_e32 vcc, 53, v150
	v_cmp_gt_i32_e64 s[38:39], 54, v149
	v_max3_f32 v34, v34, v85, v84
	s_and_b64 vcc, vcc, s[38:39]
	v_max3_f32 v34, v34, v79, v76
	v_cndmask_b32_e32 v68, v220, v48, vcc
	v_cmp_lt_i32_e32 vcc, 54, v150
	v_cmp_gt_i32_e64 s[38:39], 55, v149
	v_max3_f32 v34, v34, v75, v71
	s_and_b64 vcc, vcc, s[38:39]
	v_max3_f32 v34, v34, v72, v73
	v_cndmask_b32_e32 v69, v220, v49, vcc
	v_cmp_lt_i32_e32 vcc, v211, v210
	v_max3_f32 v34, v34, v70, v67
	v_max3_f32 v34, v34, v68, v69
	v_cndmask_b32_e32 v35, v209, v211, vcc
	v_lshlrev_b32_e32 v35, 2, v35
	ds_bpermute_b32 v35, v35, v34
	v_mov_b64_e32 v[64:65], v[32:33]
	v_mov_b32_e32 v66, v151
	v_mov_b64_e32 v[62:63], v[30:31]
	v_mov_b64_e32 v[60:61], v[28:29]
	s_waitcnt lgkmcnt(0)
	v_max_f32_e32 v35, v35, v35
	v_max_f32_e32 v34, v34, v35
	v_mul_f32_e32 v155, 0x3e38aa3b, v34
	v_add_f32_e32 v34, 0x40c00000, v152
	v_cmp_gt_f32_e32 vcc, v155, v34
	v_mov_b64_e32 v[48:49], v[16:17]
	v_mov_b64_e32 v[46:47], v[14:15]
	v_mov_b64_e32 v[44:45], v[12:13]
	v_mov_b64_e32 v[42:43], v[10:11]
	v_mov_b64_e32 v[40:41], v[8:9]
	v_mov_b64_e32 v[38:39], v[6:7]
	v_mov_b64_e32 v[36:37], v[4:5]
	v_mov_b64_e32 v[34:35], v[2:3]
	v_mov_b64_e32 v[58:59], v[26:27]
	v_mov_b64_e32 v[56:57], v[24:25]
	v_mov_b64_e32 v[54:55], v[22:23]
	v_mov_b64_e32 v[52:53], v[20:21]
	v_mov_b64_e32 v[50:51], v[18:19]
	s_cbranch_vccz .LBB0_751
	v_cndmask_b32_e32 v153, v152, v155, vcc
	v_sub_f32_e32 v34, v152, v153
	v_exp_f32_e32 v34, v34
	s_nop 0
	v_cndmask_b32_e32 v50, 1.0, v34, vcc
	v_mul_f32_e32 v66, v151, v50
	v_pk_mul_f32 v[48:49], v[16:17], v[50:51] op_sel_hi:[1,0]
	v_pk_mul_f32 v[46:47], v[14:15], v[50:51] op_sel_hi:[1,0]
	v_pk_mul_f32 v[44:45], v[12:13], v[50:51] op_sel_hi:[1,0]
	v_pk_mul_f32 v[42:43], v[10:11], v[50:51] op_sel_hi:[1,0]
	v_pk_mul_f32 v[40:41], v[8:9], v[50:51] op_sel_hi:[1,0]
	v_pk_mul_f32 v[38:39], v[6:7], v[50:51] op_sel_hi:[1,0]
	v_pk_mul_f32 v[36:37], v[4:5], v[50:51] op_sel_hi:[1,0]
	v_pk_mul_f32 v[34:35], v[2:3], v[50:51] op_sel_hi:[1,0]
	v_pk_mul_f32 v[64:65], v[32:33], v[50:51] op_sel_hi:[1,0]
	v_pk_mul_f32 v[62:63], v[30:31], v[50:51] op_sel_hi:[1,0]
	v_pk_mul_f32 v[60:61], v[28:29], v[50:51] op_sel_hi:[1,0]
	v_pk_mul_f32 v[58:59], v[26:27], v[50:51] op_sel_hi:[1,0]
	v_pk_mul_f32 v[56:57], v[24:25], v[50:51] op_sel_hi:[1,0]
	v_pk_mul_f32 v[54:55], v[22:23], v[50:51] op_sel_hi:[1,0]
	v_pk_mul_f32 v[52:53], v[20:21], v[50:51] op_sel_hi:[1,0]
	v_pk_mul_f32 v[50:51], v[18:19], v[50:51] op_sel_hi:[1,0]
.LBB0_751:
	v_cmp_neq_f32_e32 vcc, s85, v153
	s_mov_b64 s[2:3], 0
	s_nop 0
	v_cndmask_b32_e64 v155, 0, -v153, vcc
	v_fmamk_f32 v74, v74, 0x3e38aa3b, v155
	v_exp_f32_e32 v74, v74
	v_fmamk_f32 v77, v77, 0x3e38aa3b, v155
	v_exp_f32_e32 v77, v77
	v_fmamk_f32 v78, v78, 0x3e38aa3b, v155
	v_exp_f32_e32 v78, v78
	v_fmamk_f32 v80, v80, 0x3e38aa3b, v155
	v_exp_f32_e32 v156, v80
	v_fmamk_f32 v81, v81, 0x3e38aa3b, v155
	v_add_f32_e32 v80, 0, v74
	v_exp_f32_e32 v157, v81
	v_fmamk_f32 v81, v82, 0x3e38aa3b, v155
	v_add_f32_e32 v80, v77, v80
	v_exp_f32_e32 v158, v81
	v_fmamk_f32 v81, v83, 0x3e38aa3b, v155
	v_add_f32_e32 v80, v78, v80
	v_exp_f32_e32 v159, v81
	v_fmamk_f32 v81, v92, 0x3e38aa3b, v155
	v_add_f32_e32 v80, v156, v80
	v_exp_f32_e32 v92, v81
	v_fmamk_f32 v81, v95, 0x3e38aa3b, v155
	v_add_f32_e32 v80, v157, v80
	v_exp_f32_e32 v95, v81
	v_fmamk_f32 v81, v90, 0x3e38aa3b, v155
	v_add_f32_e32 v80, v158, v80
	v_exp_f32_e32 v160, v81
	v_fmamk_f32 v81, v97, 0x3e38aa3b, v155
	v_add_f32_e32 v80, v159, v80
	v_exp_f32_e32 v97, v81
	v_fmamk_f32 v81, v154, 0x3e38aa3b, v155
	v_add_f32_e32 v80, v92, v80
	v_exp_f32_e32 v154, v81
	v_fmamk_f32 v81, v96, 0x3e38aa3b, v155
	v_add_f32_e32 v80, v95, v80
	v_exp_f32_e32 v96, v81
	v_fmamk_f32 v81, v91, 0x3e38aa3b, v155
	v_add_f32_e32 v80, v160, v80
	v_exp_f32_e32 v161, v81
	v_fmamk_f32 v81, v93, 0x3e38aa3b, v155
	v_add_f32_e32 v80, v97, v80
	v_exp_f32_e32 v93, v81
	v_fmamk_f32 v81, v94, 0x3e38aa3b, v155
	v_add_f32_e32 v80, v154, v80
	v_exp_f32_e32 v94, v81
	v_fmamk_f32 v81, v89, 0x3e38aa3b, v155
	v_add_f32_e32 v80, v96, v80
	v_exp_f32_e32 v162, v81
	v_fmamk_f32 v81, v86, 0x3e38aa3b, v155
	v_add_f32_e32 v80, v161, v80
	v_exp_f32_e32 v163, v81
	v_fmamk_f32 v81, v87, 0x3e38aa3b, v155
	v_add_f32_e32 v80, v93, v80
	v_exp_f32_e32 v164, v81
	v_fmamk_f32 v81, v88, 0x3e38aa3b, v155
	v_add_f32_e32 v80, v94, v80
	v_exp_f32_e32 v165, v81
	v_add_f32_e32 v80, v162, v80
	v_add_f32_e32 v80, v163, v80
	v_add_f32_e32 v80, v164, v80
	v_add_f32_e32 v166, v165, v80
	v_fmamk_f32 v80, v85, 0x3e38aa3b, v155
	v_exp_f32_e32 v167, v80
	v_fmamk_f32 v80, v84, 0x3e38aa3b, v155
	v_lshlrev_b32_e32 v84, 1, v146
	v_add3_u32 v169, s76, v139, v84
	v_exp_f32_e32 v168, v80
	s_setprio 1
	ds_read_b128 v[80:83], v169 offset:9216
	v_add3_u32 v171, s76, v147, v84
	ds_read_b128 v[88:91], v171 offset:9216
	v_fmamk_f32 v79, v79, 0x3e38aa3b, v155
	v_cvt_pk_bf16_f32 v87, v159, v92
	v_cvt_pk_bf16_f32 v86, v157, v158
	v_cvt_pk_bf16_f32 v85, v78, v156
	v_cvt_pk_bf16_f32 v84, v74, v77
	v_exp_f32_e32 v170, v79
	v_fmamk_f32 v74, v76, 0x3e38aa3b, v155
	ds_read_b128 v[76:79], v169 offset:9248
	s_waitcnt lgkmcnt(2)
	v_mfma_f32_32x32x16_bf16 v[34:49], v[80:83], v[84:87], v[34:49]
	ds_read_b128 v[80:83], v171 offset:9248
	v_exp_f32_e32 v92, v74
	v_fmamk_f32 v75, v75, 0x3e38aa3b, v155
	v_add_f32_e32 v74, v167, v166
	v_add_f32_e32 v74, v168, v74
	v_add_f32_e32 v74, v170, v74
	v_add_f32_e32 v74, v92, v74
	s_waitcnt lgkmcnt(2)
	v_mfma_f32_32x32x16_bf16 v[50:65], v[88:91], v[84:87], v[50:65]
	v_exp_f32_e32 v88, v75
	v_cvt_pk_bf16_f32 v87, v93, v94
	v_cvt_pk_bf16_f32 v86, v96, v161
	v_cvt_pk_bf16_f32 v85, v97, v154
	v_cvt_pk_bf16_f32 v84, v95, v160
	v_fmamk_f32 v71, v71, 0x3e38aa3b, v155
	v_add_f32_e32 v89, v88, v74
	v_exp_f32_e32 v90, v71
	v_fmamk_f32 v71, v72, 0x3e38aa3b, v155
	v_fmamk_f32 v93, v73, 0x3e38aa3b, v155
	ds_read_b128 v[72:75], v169 offset:9280
	s_waitcnt lgkmcnt(1)
	v_mfma_f32_32x32x16_bf16 v[50:65], v[80:83], v[84:87], v[50:65]
	ds_read_b128 v[80:83], v171 offset:9280
	v_fmamk_f32 v70, v70, 0x3e38aa3b, v155
	v_fmamk_f32 v68, v68, 0x3e38aa3b, v155
	v_exp_f32_e32 v91, v71
	v_fmamk_f32 v67, v67, 0x3e38aa3b, v155
	v_fmac_f32_e32 v155, 0x3e38aa3b, v69
	v_exp_f32_e32 v67, v67
	v_mfma_f32_32x32x16_bf16 v[34:49], v[76:79], v[84:87], v[34:49]
	v_cvt_pk_bf16_f32 v79, v170, v92
	v_cvt_pk_bf16_f32 v78, v167, v168
	v_cvt_pk_bf16_f32 v77, v164, v165
	v_cvt_pk_bf16_f32 v76, v162, v163
	v_exp_f32_e32 v84, v70
	v_exp_f32_e32 v85, v68
	ds_read_b128 v[68:71], v169 offset:9312
	s_waitcnt lgkmcnt(2)
	v_mfma_f32_32x32x16_bf16 v[34:49], v[72:75], v[76:79], v[34:49]
	v_exp_f32_e32 v86, v155
	v_cvt_pk_bf16_f32 v74, v84, v67
	v_cvt_pk_bf16_f32 v72, v88, v90
	v_cvt_pk_bf16_f32 v75, v85, v86
	s_waitcnt lgkmcnt(1)
	v_mfma_f32_32x32x16_bf16 v[50:65], v[80:83], v[76:79], v[50:65]
	ds_read_b128 v[76:79], v171 offset:9312
	v_exp_f32_e32 v80, v93
	v_add_f32_e32 v81, v90, v89
	v_cvt_pk_bf16_f32 v73, v91, v80
	s_waitcnt lgkmcnt(1)
	s_nop 0
	v_mfma_f32_32x32x16_bf16 v[34:49], v[68:71], v[72:75], v[34:49]
	v_add_f32_e32 v68, v91, v81
	v_add_f32_e32 v68, v80, v68
	v_add_f32_e32 v68, v84, v68
	v_add_f32_e32 v67, v67, v68
	v_add_f32_e32 v67, v85, v67
	v_add_f32_e32 v67, v86, v67
	v_add_f32_e32 v66, v66, v67
	s_waitcnt lgkmcnt(0)
	v_mfma_f32_32x32x16_bf16 v[50:65], v[76:79], v[72:75], v[50:65]
.LBB0_752:
	s_and_b64 vcc, exec, s[2:3]
	s_cbranch_vccz .LBB0_756
	s_nop 0
	v_add3_u32 v42, s76, v132, v137
	s_setprio 1
	ds_read_b128 v[34:37], v42
	ds_read_b128 v[38:41], v42 offset:16
	v_cmp_lt_i32_e32 vcc, v211, v210
	s_nop 4
	v_add_f32_e32 v52, 0x40c00000, v152
	v_mov_b32_e32 v153, v152
	s_waitcnt lgkmcnt(1)
	v_mfma_f32_32x32x16_bf16 v[82:97], v[34:37], v[98:101], 0
	v_mov_b32_e32 v154, v151
	s_waitcnt lgkmcnt(0)
	v_mfma_f32_32x32x16_bf16 v[82:97], v[38:41], v[102:105], v[82:97]
	ds_read_b128 v[34:37], v42 offset:32
	ds_read_b128 v[38:41], v42 offset:48
	s_waitcnt lgkmcnt(1)
	v_mfma_f32_32x32x16_bf16 v[82:97], v[34:37], v[106:109], v[82:97]
	s_waitcnt lgkmcnt(0)
	v_mfma_f32_32x32x16_bf16 v[82:97], v[38:41], v[110:113], v[82:97]
	ds_read_b128 v[34:37], v42 offset:4608
	ds_read_b128 v[38:41], v42 offset:4624
	s_waitcnt lgkmcnt(1)
	v_mfma_f32_32x32x16_bf16 v[66:81], v[34:37], v[98:101], 0
	s_waitcnt lgkmcnt(0)
	v_mfma_f32_32x32x16_bf16 v[66:81], v[38:41], v[102:105], v[66:81]
	ds_read_b128 v[34:37], v42 offset:4640
	ds_read_b128 v[38:41], v42 offset:4656
	s_nop 3
	v_max3_f32 v42, v82, s85, v83
	s_waitcnt lgkmcnt(1)
	v_mfma_f32_32x32x16_bf16 v[66:81], v[34:37], v[106:109], v[66:81]
	v_max3_f32 v34, v42, v84, v85
	v_max3_f32 v34, v34, v86, v87
	v_max3_f32 v34, v34, v88, v89
	v_max3_f32 v34, v34, v90, v91
	v_max3_f32 v34, v34, v92, v93
	v_max3_f32 v34, v34, v94, v95
	v_max3_f32 v34, v34, v96, v97
	s_waitcnt lgkmcnt(0)
	v_mfma_f32_32x32x16_bf16 v[66:81], v[38:41], v[110:113], v[66:81]
	s_nop 11
	v_max3_f32 v34, v34, v66, v67
	v_max3_f32 v34, v34, v68, v69
	v_max3_f32 v34, v34, v70, v71
	v_max3_f32 v34, v34, v72, v73
	v_max3_f32 v34, v34, v74, v75
	v_max3_f32 v34, v34, v76, v77
	v_max3_f32 v34, v34, v78, v79
	v_max3_f32 v50, v34, v80, v81
	v_cndmask_b32_e32 v34, v209, v211, vcc
	v_lshlrev_b32_e32 v34, 2, v34
	ds_bpermute_b32 v51, v34, v50
	v_mov_b64_e32 v[48:49], v[16:17]
	v_mov_b64_e32 v[46:47], v[14:15]
	v_mov_b64_e32 v[44:45], v[12:13]
	v_mov_b64_e32 v[42:43], v[10:11]
	s_waitcnt lgkmcnt(0)
	v_max_f32_e32 v51, v51, v51
	v_max_f32_e32 v50, v50, v51
	v_mul_f32_e32 v155, 0x3e38aa3b, v50
	v_cmp_gt_f32_e32 vcc, v155, v52
	v_mov_b64_e32 v[64:65], v[32:33]
	v_mov_b64_e32 v[40:41], v[8:9]
	v_mov_b64_e32 v[38:39], v[6:7]
	v_mov_b64_e32 v[36:37], v[4:5]
	v_mov_b64_e32 v[34:35], v[2:3]
	v_mov_b64_e32 v[62:63], v[30:31]
	v_mov_b64_e32 v[60:61], v[28:29]
	v_mov_b64_e32 v[58:59], v[26:27]
	v_mov_b64_e32 v[56:57], v[24:25]
	v_mov_b64_e32 v[54:55], v[22:23]
	v_mov_b64_e32 v[52:53], v[20:21]
	v_mov_b64_e32 v[50:51], v[18:19]
	s_cbranch_vccz .LBB0_755
	v_cndmask_b32_e32 v153, v152, v155, vcc
	v_sub_f32_e32 v34, v152, v153
	v_exp_f32_e32 v34, v34
	s_nop 0
	v_cndmask_b32_e32 v50, 1.0, v34, vcc
	v_mul_f32_e32 v154, v151, v50
	v_pk_mul_f32 v[48:49], v[16:17], v[50:51] op_sel_hi:[1,0]
	v_pk_mul_f32 v[46:47], v[14:15], v[50:51] op_sel_hi:[1,0]
	v_pk_mul_f32 v[44:45], v[12:13], v[50:51] op_sel_hi:[1,0]
	v_pk_mul_f32 v[42:43], v[10:11], v[50:51] op_sel_hi:[1,0]
	v_pk_mul_f32 v[40:41], v[8:9], v[50:51] op_sel_hi:[1,0]
	v_pk_mul_f32 v[38:39], v[6:7], v[50:51] op_sel_hi:[1,0]
	v_pk_mul_f32 v[36:37], v[4:5], v[50:51] op_sel_hi:[1,0]
	v_pk_mul_f32 v[34:35], v[2:3], v[50:51] op_sel_hi:[1,0]
	v_pk_mul_f32 v[64:65], v[32:33], v[50:51] op_sel_hi:[1,0]
	v_pk_mul_f32 v[62:63], v[30:31], v[50:51] op_sel_hi:[1,0]
	v_pk_mul_f32 v[60:61], v[28:29], v[50:51] op_sel_hi:[1,0]
	v_pk_mul_f32 v[58:59], v[26:27], v[50:51] op_sel_hi:[1,0]
	v_pk_mul_f32 v[56:57], v[24:25], v[50:51] op_sel_hi:[1,0]
	v_pk_mul_f32 v[54:55], v[22:23], v[50:51] op_sel_hi:[1,0]
	v_pk_mul_f32 v[52:53], v[20:21], v[50:51] op_sel_hi:[1,0]
	v_pk_mul_f32 v[50:51], v[18:19], v[50:51] op_sel_hi:[1,0]
.LBB0_755:
	v_cmp_neq_f32_e32 vcc, s85, v153
	s_nop 1
	v_cndmask_b32_e64 v155, 0, -v153, vcc
	v_fmamk_f32 v82, v82, 0x3e38aa3b, v155
	v_exp_f32_e32 v82, v82
	v_fmamk_f32 v83, v83, 0x3e38aa3b, v155
	v_exp_f32_e32 v156, v83
	v_fmamk_f32 v83, v84, 0x3e38aa3b, v155
	v_exp_f32_e32 v83, v83
	v_fmamk_f32 v84, v85, 0x3e38aa3b, v155
	v_exp_f32_e32 v157, v84
	v_fmamk_f32 v85, v86, 0x3e38aa3b, v155
	v_add_f32_e32 v84, 0, v82
	v_exp_f32_e32 v86, v85
	v_fmamk_f32 v85, v87, 0x3e38aa3b, v155
	v_add_f32_e32 v84, v156, v84
	v_exp_f32_e32 v87, v85
	v_fmamk_f32 v85, v88, 0x3e38aa3b, v155
	v_add_f32_e32 v84, v83, v84
	v_exp_f32_e32 v85, v85
	v_fmamk_f32 v88, v89, 0x3e38aa3b, v155
	v_add_f32_e32 v84, v157, v84
	v_exp_f32_e32 v88, v88
	v_fmamk_f32 v89, v90, 0x3e38aa3b, v155
	v_add_f32_e32 v84, v86, v84
	v_exp_f32_e32 v90, v89
	v_fmamk_f32 v89, v91, 0x3e38aa3b, v155
	v_add_f32_e32 v84, v87, v84
	v_exp_f32_e32 v91, v89
	v_fmamk_f32 v89, v92, 0x3e38aa3b, v155
	v_add_f32_e32 v84, v85, v84
	v_exp_f32_e32 v92, v89
	v_fmamk_f32 v89, v93, 0x3e38aa3b, v155
	v_add_f32_e32 v84, v88, v84
	v_exp_f32_e32 v93, v89
	v_fmamk_f32 v89, v94, 0x3e38aa3b, v155
	v_add_f32_e32 v84, v90, v84
	v_exp_f32_e32 v94, v89
	v_fmamk_f32 v89, v95, 0x3e38aa3b, v155
	v_add_f32_e32 v84, v91, v84
	v_exp_f32_e32 v95, v89
	v_fmamk_f32 v89, v96, 0x3e38aa3b, v155
	v_add_f32_e32 v84, v92, v84
	v_exp_f32_e32 v96, v89
	v_fmamk_f32 v89, v97, 0x3e38aa3b, v155
	v_add_f32_e32 v84, v93, v84
	v_exp_f32_e32 v97, v89
	v_fmamk_f32 v66, v66, 0x3e38aa3b, v155
	v_add_f32_e32 v84, v94, v84
	v_exp_f32_e32 v158, v66
	v_fmamk_f32 v66, v67, 0x3e38aa3b, v155
	v_add_f32_e32 v84, v95, v84
	v_exp_f32_e32 v159, v66
	v_fmamk_f32 v66, v68, 0x3e38aa3b, v155
	v_add_f32_e32 v84, v96, v84
	v_exp_f32_e32 v160, v66
	v_fmamk_f32 v66, v69, 0x3e38aa3b, v155
	v_add_f32_e32 v84, v97, v84
	v_exp_f32_e32 v161, v66
	v_add_f32_e32 v66, v158, v84
	v_add_f32_e32 v66, v159, v66
	v_add_f32_e32 v66, v160, v66
	v_add_f32_e32 v162, v161, v66
	v_fmamk_f32 v66, v70, 0x3e38aa3b, v155
	v_lshlrev_b32_e32 v70, 1, v146
	v_exp_f32_e32 v163, v66
	v_fmamk_f32 v66, v71, 0x3e38aa3b, v155
	v_add3_u32 v165, s76, v139, v70
	v_exp_f32_e32 v164, v66
	s_setprio 1
	ds_read_b128 v[66:69], v165 offset:9216
	v_fmamk_f32 v71, v72, 0x3e38aa3b, v155
	v_add3_u32 v167, s76, v147, v70
	v_cvt_pk_bf16_f32 v85, v85, v88
	v_cvt_pk_bf16_f32 v84, v86, v87
	v_cvt_pk_bf16_f32 v83, v83, v157
	v_cvt_pk_bf16_f32 v82, v82, v156
	v_exp_f32_e32 v166, v71
	ds_read_b128 v[86:89], v167 offset:9216
	s_waitcnt lgkmcnt(1)
	v_mfma_f32_32x32x16_bf16 v[34:49], v[66:69], v[82:85], v[34:49]
	v_fmamk_f32 v66, v73, 0x3e38aa3b, v155
	v_exp_f32_e32 v156, v66
	v_add_f32_e32 v66, v163, v162
	v_add_f32_e32 v66, v164, v66
	v_add_f32_e32 v66, v166, v66
	v_add_f32_e32 v157, v156, v66
	ds_read_b128 v[66:69], v165 offset:9248
	v_fmamk_f32 v70, v74, 0x3e38aa3b, v155
	s_waitcnt lgkmcnt(1)
	v_mfma_f32_32x32x16_bf16 v[50:65], v[86:89], v[82:85], v[50:65]
	v_exp_f32_e32 v86, v70
	ds_read_b128 v[70:73], v167 offset:9248
	v_cvt_pk_bf16_f32 v85, v96, v97
	v_cvt_pk_bf16_f32 v84, v94, v95
	v_cvt_pk_bf16_f32 v83, v92, v93
	v_cvt_pk_bf16_f32 v82, v90, v91
	v_fmamk_f32 v90, v77, 0x3e38aa3b, v155
	v_add_f32_e32 v87, v86, v157
	s_waitcnt lgkmcnt(1)
	v_mfma_f32_32x32x16_bf16 v[34:49], v[66:69], v[82:85], v[34:49]
	v_fmamk_f32 v66, v75, 0x3e38aa3b, v155
	v_exp_f32_e32 v88, v66
	v_fmamk_f32 v66, v76, 0x3e38aa3b, v155
	v_exp_f32_e32 v89, v66
	ds_read_b128 v[66:69], v165 offset:9280
	ds_read_b128 v[74:77], v167 offset:9280
	s_waitcnt lgkmcnt(2)
	v_mfma_f32_32x32x16_bf16 v[50:65], v[70:73], v[82:85], v[50:65]
	v_fmamk_f32 v70, v78, 0x3e38aa3b, v155
	v_exp_f32_e32 v78, v70
	v_cvt_pk_bf16_f32 v73, v166, v156
	v_cvt_pk_bf16_f32 v72, v163, v164
	v_cvt_pk_bf16_f32 v71, v160, v161
	v_cvt_pk_bf16_f32 v70, v158, v159
	v_exp_f32_e32 v82, v90
	v_add_f32_e32 v83, v88, v87
	s_waitcnt lgkmcnt(1)
	v_mfma_f32_32x32x16_bf16 v[34:49], v[66:69], v[70:73], v[34:49]
	v_fmamk_f32 v66, v79, 0x3e38aa3b, v155
	v_exp_f32_e32 v79, v66
	v_fmamk_f32 v66, v80, 0x3e38aa3b, v155
	v_exp_f32_e32 v80, v66
	ds_read_b128 v[66:69], v165 offset:9312
	v_fmac_f32_e32 v155, 0x3e38aa3b, v81
	v_exp_f32_e32 v81, v155
	s_waitcnt lgkmcnt(1)
	v_mfma_f32_32x32x16_bf16 v[50:65], v[74:77], v[70:73], v[50:65]
	ds_read_b128 v[74:77], v167 offset:9312
	v_cvt_pk_bf16_f32 v72, v78, v79
	v_cvt_pk_bf16_f32 v73, v80, v81
	v_cvt_pk_bf16_f32 v71, v89, v82
	v_cvt_pk_bf16_f32 v70, v86, v88
	s_waitcnt lgkmcnt(1)
	s_nop 0
	v_mfma_f32_32x32x16_bf16 v[34:49], v[66:69], v[70:73], v[34:49]
	v_add_f32_e32 v66, v89, v83
	v_add_f32_e32 v66, v82, v66
	v_add_f32_e32 v66, v78, v66
	v_add_f32_e32 v66, v79, v66
	v_add_f32_e32 v66, v80, v66
	v_add_f32_e32 v66, v81, v66
	v_add_f32_e32 v66, v154, v66
	s_waitcnt lgkmcnt(0)
	v_mfma_f32_32x32x16_bf16 v[50:65], v[74:77], v[70:73], v[50:65]

.LBB0_757:
	s_andn2_b64 vcc, exec, s[2:3]
	s_cbranch_vccnz .LBB0_768
	s_cmp_gt_i32 s16, 1
	s_mov_b64 s[2:3], -1
	s_cbranch_scc0 .LBB0_762
	v_add3_u32 v46, s76, v132, v137
	s_setprio 1
	ds_read_b128 v[34:37], v46
	ds_read_b128 v[38:41], v46 offset:16
	v_cmp_lt_i32_e32 vcc, -1, v150
	v_cmp_gt_i32_e64 s[38:39], 1, v150
	v_cmp_gt_i32_e64 s[40:41], 32, v150
	s_waitcnt lgkmcnt(1)
	v_mfma_f32_32x32x16_bf16 v[66:81], v[34:37], v[98:101], 0
	v_cmp_gt_i32_e64 s[42:43], 33, v150
	v_cmp_gt_i32_e64 s[44:45], 34, v150
	v_cmp_gt_i32_e64 s[46:47], 35, v150
	v_cmp_gt_i32_e64 s[48:49], 36, v150
	v_cmp_gt_i32_e64 s[50:51], 37, v150
	v_cmp_gt_i32_e64 s[52:53], 38, v150
	v_cmp_gt_i32_e64 s[56:57], 39, v150
	s_waitcnt lgkmcnt(0)
	v_mfma_f32_32x32x16_bf16 v[66:81], v[38:41], v[102:105], v[66:81]
	ds_read_b128 v[34:37], v46 offset:32
	ds_read_b128 v[38:41], v46 offset:48
	v_cmp_gt_i32_e64 s[58:59], 48, v150
	v_cmp_gt_i32_e64 s[60:61], 49, v150
	v_cmp_gt_i32_e64 s[62:63], 50, v150
	v_cmp_gt_i32_e64 s[64:65], 51, v150
	v_cmp_gt_i32_e64 s[66:67], 52, v150
	v_cmp_gt_i32_e64 s[68:69], 53, v150
	s_waitcnt lgkmcnt(1)
	v_mfma_f32_32x32x16_bf16 v[66:81], v[34:37], v[106:109], v[66:81]
	ds_read_b128 v[34:37], v46 offset:4608
	ds_read_b128 v[42:45], v46 offset:4624
	v_cmp_gt_i32_e64 s[70:71], 54, v150
	v_cmp_gt_i32_e64 s[54:55], 55, v150
	v_mov_b64_e32 v[64:65], v[32:33]
	v_mov_b32_e32 v153, v152
	v_mov_b64_e32 v[62:63], v[30:31]
	v_mov_b64_e32 v[60:61], v[28:29]
	s_waitcnt lgkmcnt(1)
	v_mfma_f32_32x32x16_bf16 v[82:97], v[34:37], v[98:101], 0
	ds_read_b128 v[34:37], v46 offset:4640
	ds_read_b128 v[46:49], v46 offset:4656
	v_mov_b64_e32 v[58:59], v[26:27]
	v_mov_b64_e32 v[56:57], v[24:25]
	v_mov_b64_e32 v[54:55], v[22:23]
	v_mov_b64_e32 v[52:53], v[20:21]
	v_mov_b64_e32 v[50:51], v[18:19]
	s_waitcnt lgkmcnt(2)
	v_mfma_f32_32x32x16_bf16 v[82:97], v[42:45], v[102:105], v[82:97]
	v_mfma_f32_32x32x16_bf16 v[66:81], v[38:41], v[110:113], v[66:81]
	s_waitcnt lgkmcnt(1)
	v_mfma_f32_32x32x16_bf16 v[82:97], v[34:37], v[106:109], v[82:97]
	s_nop 9
	v_cndmask_b32_e32 v158, v220, v66, vcc
	v_cmp_lt_i32_e32 vcc, 1, v150
	v_cndmask_b32_e64 v154, v67, v220, s[38:39]
	v_max3_f32 v38, v158, s85, v154
	v_cndmask_b32_e32 v155, v220, v68, vcc
	v_cmp_lt_i32_e32 vcc, 2, v150
	v_mov_b32_e32 v68, v151
	s_waitcnt lgkmcnt(0)
	v_mfma_f32_32x32x16_bf16 v[82:97], v[46:49], v[110:113], v[82:97]
	v_cndmask_b32_e32 v156, v220, v69, vcc
	v_cmp_lt_i32_e32 vcc, 3, v150
	v_max3_f32 v38, v38, v155, v156
	s_nop 0
	v_cndmask_b32_e32 v157, v220, v70, vcc
	v_cmp_lt_i32_e32 vcc, 4, v150
	s_nop 5
	v_cndmask_b32_e64 v159, v83, v220, s[42:43]
	v_cndmask_b32_e32 v69, v220, v71, vcc
	v_cmp_lt_i32_e32 vcc, 5, v150
	v_max3_f32 v38, v38, v157, v69
	v_cndmask_b32_e64 v160, v84, v220, s[44:45]
	v_cndmask_b32_e32 v70, v220, v72, vcc
	v_cmp_lt_i32_e32 vcc, 6, v150
	v_cndmask_b32_e64 v161, v85, v220, s[46:47]
	v_cndmask_b32_e64 v162, v86, v220, s[48:49]
	v_cndmask_b32_e32 v71, v220, v73, vcc
	v_cmp_lt_i32_e32 vcc, 15, v150
	v_max3_f32 v38, v38, v70, v71
	v_cndmask_b32_e64 v163, v87, v220, s[50:51]
	v_cndmask_b32_e32 v73, v220, v74, vcc
	v_cmp_lt_i32_e32 vcc, 16, v150
	v_cndmask_b32_e64 v165, v88, v220, s[52:53]
	v_cndmask_b32_e64 v166, v89, v220, s[56:57]
	v_cndmask_b32_e32 v72, v220, v75, vcc
	v_cmp_lt_i32_e32 vcc, 17, v150
	v_max3_f32 v38, v38, v73, v72
	v_cndmask_b32_e64 v167, v90, v220, s[58:59]
	v_cndmask_b32_e32 v74, v220, v76, vcc
	v_cmp_lt_i32_e32 vcc, 18, v150
	v_cndmask_b32_e64 v168, v91, v220, s[60:61]
	v_cndmask_b32_e64 v169, v92, v220, s[62:63]
	v_cndmask_b32_e32 v75, v220, v77, vcc
	v_cmp_lt_i32_e32 vcc, 19, v150
	v_max3_f32 v38, v38, v74, v75
	v_cndmask_b32_e64 v170, v93, v220, s[64:65]
	v_cndmask_b32_e32 v76, v220, v78, vcc
	v_cmp_lt_i32_e32 vcc, 20, v150
	v_cndmask_b32_e64 v171, v94, v220, s[66:67]
	v_cndmask_b32_e64 v172, v95, v220, s[68:69]
	v_cndmask_b32_e32 v77, v220, v79, vcc
	v_cmp_lt_i32_e32 vcc, 21, v150
	v_max3_f32 v34, v38, v76, v77
	v_cndmask_b32_e64 v164, v96, v220, s[70:71]
	v_cndmask_b32_e32 v78, v220, v80, vcc
	v_cmp_lt_i32_e32 vcc, 22, v150
	v_cndmask_b32_e64 v80, v82, v220, s[40:41]
	v_cndmask_b32_e64 v67, v97, v220, s[54:55]
	v_cndmask_b32_e32 v79, v220, v81, vcc
	v_max3_f32 v34, v34, v78, v79
	v_max3_f32 v34, v34, v80, v159
	v_max3_f32 v34, v34, v160, v161
	v_max3_f32 v34, v34, v162, v163
	v_max3_f32 v34, v34, v165, v166
	v_max3_f32 v34, v34, v167, v168
	v_max3_f32 v34, v34, v169, v170
	v_cmp_lt_i32_e32 vcc, v211, v210
	v_max3_f32 v34, v34, v171, v172
	v_max3_f32 v34, v34, v164, v67
	v_cndmask_b32_e32 v35, v209, v211, vcc
	v_lshlrev_b32_e32 v35, 2, v35
	ds_bpermute_b32 v35, v35, v34
	s_waitcnt lgkmcnt(0)
	v_max_f32_e32 v35, v35, v35
	v_max_f32_e32 v34, v34, v35
	v_mul_f32_e32 v97, 0x3e38aa3b, v34
	v_add_f32_e32 v34, 0x40c00000, v152
	v_cmp_gt_f32_e32 vcc, v97, v34
	v_mov_b64_e32 v[48:49], v[16:17]
	v_mov_b64_e32 v[46:47], v[14:15]
	v_mov_b64_e32 v[44:45], v[12:13]
	v_mov_b64_e32 v[42:43], v[10:11]
	v_mov_b64_e32 v[40:41], v[8:9]
	v_mov_b64_e32 v[38:39], v[6:7]
	v_mov_b64_e32 v[36:37], v[4:5]
	v_mov_b64_e32 v[34:35], v[2:3]
	s_cbranch_vccz .LBB0_761
	v_cndmask_b32_e32 v153, v152, v97, vcc
	v_sub_f32_e32 v34, v152, v153
	v_exp_f32_e32 v34, v34
	s_nop 0
	v_cndmask_b32_e32 v50, 1.0, v34, vcc
	v_mul_f32_e32 v68, v151, v50
	v_pk_mul_f32 v[48:49], v[16:17], v[50:51] op_sel_hi:[1,0]
	v_pk_mul_f32 v[46:47], v[14:15], v[50:51] op_sel_hi:[1,0]
	v_pk_mul_f32 v[44:45], v[12:13], v[50:51] op_sel_hi:[1,0]
	v_pk_mul_f32 v[42:43], v[10:11], v[50:51] op_sel_hi:[1,0]
	v_pk_mul_f32 v[40:41], v[8:9], v[50:51] op_sel_hi:[1,0]
	v_pk_mul_f32 v[38:39], v[6:7], v[50:51] op_sel_hi:[1,0]
	v_pk_mul_f32 v[36:37], v[4:5], v[50:51] op_sel_hi:[1,0]
	v_pk_mul_f32 v[34:35], v[2:3], v[50:51] op_sel_hi:[1,0]
	v_pk_mul_f32 v[64:65], v[32:33], v[50:51] op_sel_hi:[1,0]
	v_pk_mul_f32 v[62:63], v[30:31], v[50:51] op_sel_hi:[1,0]
	v_pk_mul_f32 v[60:61], v[28:29], v[50:51] op_sel_hi:[1,0]
	v_pk_mul_f32 v[58:59], v[26:27], v[50:51] op_sel_hi:[1,0]
	v_pk_mul_f32 v[56:57], v[24:25], v[50:51] op_sel_hi:[1,0]
	v_pk_mul_f32 v[54:55], v[22:23], v[50:51] op_sel_hi:[1,0]
	v_pk_mul_f32 v[52:53], v[20:21], v[50:51] op_sel_hi:[1,0]
	v_pk_mul_f32 v[50:51], v[18:19], v[50:51] op_sel_hi:[1,0]
.LBB0_761:
	s_and_b64 vcc, s[54:55], s[70:71]
	v_cndmask_b32_e32 v95, v95, v172, vcc
	s_and_b64 vcc, vcc, s[68:69]
	v_cndmask_b32_e32 v94, v94, v171, vcc
	s_and_b64 vcc, vcc, s[66:67]
	v_cndmask_b32_e32 v93, v93, v170, vcc
	s_and_b64 vcc, vcc, s[64:65]
	v_cndmask_b32_e32 v92, v92, v169, vcc
	s_and_b64 vcc, vcc, s[62:63]
	v_cndmask_b32_e32 v91, v91, v168, vcc
	s_and_b64 vcc, vcc, s[60:61]
	v_cndmask_b32_e32 v90, v90, v167, vcc
	s_and_b64 vcc, vcc, s[58:59]
	v_cndmask_b32_e32 v89, v89, v166, vcc
	s_and_b64 vcc, vcc, s[56:57]
	v_cndmask_b32_e32 v88, v88, v165, vcc
	s_and_b64 vcc, vcc, s[52:53]
	v_cndmask_b32_e32 v87, v87, v163, vcc
	s_and_b64 vcc, vcc, s[50:51]
	v_cndmask_b32_e32 v86, v86, v162, vcc
	s_and_b64 vcc, vcc, s[48:49]
	v_cndmask_b32_e64 v66, v66, v158, s[38:39]
	v_cndmask_b32_e32 v85, v85, v161, vcc
	s_and_b64 vcc, vcc, s[46:47]
	v_cmp_neq_f32_e64 s[38:39], s85, v153
	v_cndmask_b32_e32 v84, v84, v160, vcc
	s_and_b64 vcc, vcc, s[44:45]
	v_cndmask_b32_e64 v97, 0, -v153, s[38:39]
	v_cndmask_b32_e32 v83, v83, v159, vcc
	s_and_b64 vcc, vcc, s[42:43]
	v_fmamk_f32 v66, v66, 0x3e38aa3b, v97
	v_cndmask_b32_e32 v80, v82, v80, vcc
	v_exp_f32_e32 v66, v66
	v_fmamk_f32 v82, v154, 0x3e38aa3b, v97
	v_exp_f32_e32 v82, v82
	v_fmamk_f32 v154, v155, 0x3e38aa3b, v97
	v_exp_f32_e32 v154, v154
	v_fmamk_f32 v155, v156, 0x3e38aa3b, v97
	s_and_b64 vcc, vcc, s[40:41]
	v_exp_f32_e32 v155, v155
	v_fmamk_f32 v156, v157, 0x3e38aa3b, v97
	v_cndmask_b32_e32 v79, v81, v79, vcc
	v_add_f32_e32 v81, 0, v66
	v_exp_f32_e32 v156, v156
	v_fmamk_f32 v69, v69, 0x3e38aa3b, v97
	v_add_f32_e32 v81, v82, v81
	v_exp_f32_e32 v69, v69
	v_fmamk_f32 v70, v70, 0x3e38aa3b, v97
	v_add_f32_e32 v81, v154, v81
	v_exp_f32_e32 v157, v70
	v_fmamk_f32 v70, v71, 0x3e38aa3b, v97
	v_add_f32_e32 v81, v155, v81
	v_exp_f32_e32 v158, v70
	v_fmamk_f32 v70, v73, 0x3e38aa3b, v97
	v_add_f32_e32 v81, v156, v81
	v_exp_f32_e32 v159, v70
	v_fmamk_f32 v71, v72, 0x3e38aa3b, v97
	v_add_f32_e32 v70, v69, v81
	v_exp_f32_e32 v160, v71
	v_fmamk_f32 v71, v74, 0x3e38aa3b, v97
	v_add_f32_e32 v70, v157, v70
	v_exp_f32_e32 v161, v71
	v_fmamk_f32 v71, v75, 0x3e38aa3b, v97
	v_add_f32_e32 v70, v158, v70
	v_exp_f32_e32 v162, v71
	v_fmamk_f32 v71, v76, 0x3e38aa3b, v97
	v_add_f32_e32 v70, v159, v70
	v_exp_f32_e32 v163, v71
	v_fmamk_f32 v71, v77, 0x3e38aa3b, v97
	v_cndmask_b32_e64 v96, v96, v164, s[54:55]
	v_add_f32_e32 v70, v160, v70
	v_exp_f32_e32 v164, v71
	v_fmamk_f32 v71, v78, 0x3e38aa3b, v97
	v_add_f32_e32 v70, v161, v70
	v_exp_f32_e32 v165, v71
	v_fmamk_f32 v71, v79, 0x3e38aa3b, v97
	v_add_f32_e32 v70, v162, v70
	v_exp_f32_e32 v166, v71
	v_fmamk_f32 v71, v80, 0x3e38aa3b, v97
	v_add_f32_e32 v70, v163, v70
	v_exp_f32_e32 v167, v71
	v_fmamk_f32 v71, v83, 0x3e38aa3b, v97
	v_add_f32_e32 v70, v164, v70
	v_exp_f32_e32 v168, v71
	v_fmamk_f32 v71, v84, 0x3e38aa3b, v97
	v_add_f32_e32 v70, v165, v70
	v_exp_f32_e32 v169, v71
	v_fmamk_f32 v71, v85, 0x3e38aa3b, v97
	v_add_f32_e32 v70, v166, v70
	v_exp_f32_e32 v170, v71
	v_fmamk_f32 v71, v86, 0x3e38aa3b, v97
	v_add_f32_e32 v70, v167, v70
	v_exp_f32_e32 v86, v71
	v_add_f32_e32 v70, v168, v70
	v_add_f32_e32 v70, v169, v70
	v_lshlrev_b32_e32 v75, 1, v146
	v_add_f32_e32 v70, v170, v70
	v_fmamk_f32 v74, v87, 0x3e38aa3b, v97
	v_add3_u32 v87, s76, v139, v75
	v_add_f32_e32 v171, v86, v70
	s_setprio 1
	ds_read_b128 v[70:73], v87 offset:9216
	v_exp_f32_e32 v172, v74
	v_add3_u32 v173, s76, v147, v75
	v_cvt_pk_bf16_f32 v77, v157, v158
	v_cvt_pk_bf16_f32 v76, v156, v69
	v_cvt_pk_bf16_f32 v75, v154, v155
	v_cvt_pk_bf16_f32 v74, v66, v82
	ds_read_b128 v[78:81], v87 offset:9248
	ds_read_b128 v[82:85], v173 offset:9216
	s_waitcnt lgkmcnt(2)
	v_mfma_f32_32x32x16_bf16 v[34:49], v[70:73], v[74:77], v[34:49]
	v_fmamk_f32 v70, v89, 0x3e38aa3b, v97
	v_fmamk_f32 v66, v88, 0x3e38aa3b, v97
	v_exp_f32_e32 v88, v70
	ds_read_b128 v[70:73], v173 offset:9248
	v_exp_f32_e32 v66, v66
	v_add_f32_e32 v69, v172, v171
	s_mov_b64 s[2:3], 0
	s_waitcnt lgkmcnt(1)
	v_mfma_f32_32x32x16_bf16 v[50:65], v[82:85], v[74:77], v[50:65]
	v_fmamk_f32 v74, v90, 0x3e38aa3b, v97
	v_exp_f32_e32 v89, v74
	v_cvt_pk_bf16_f32 v77, v165, v166
	v_cvt_pk_bf16_f32 v76, v163, v164
	v_cvt_pk_bf16_f32 v75, v161, v162
	v_cvt_pk_bf16_f32 v74, v159, v160
	v_add_f32_e32 v69, v66, v69
	v_add_f32_e32 v69, v88, v69
	v_mfma_f32_32x32x16_bf16 v[34:49], v[78:81], v[74:77], v[34:49]
	v_fmamk_f32 v78, v91, 0x3e38aa3b, v97
	v_exp_f32_e32 v90, v78
	v_fmamk_f32 v78, v92, 0x3e38aa3b, v97
	v_exp_f32_e32 v91, v78
	ds_read_b128 v[78:81], v87 offset:9280
	v_fmamk_f32 v92, v93, 0x3e38aa3b, v97
	v_fmamk_f32 v93, v94, 0x3e38aa3b, v97
	s_waitcnt lgkmcnt(1)
	v_mfma_f32_32x32x16_bf16 v[50:65], v[70:73], v[74:77], v[50:65]
	ds_read_b128 v[74:77], v173 offset:9280
	ds_read_b128 v[82:85], v87 offset:9312
	v_cvt_pk_bf16_f32 v73, v66, v88
	v_cvt_pk_bf16_f32 v72, v86, v172
	v_cvt_pk_bf16_f32 v71, v169, v170
	v_cvt_pk_bf16_f32 v70, v167, v168
	v_fmamk_f32 v86, v95, 0x3e38aa3b, v97
	v_exp_f32_e32 v66, v93
	s_waitcnt lgkmcnt(2)
	v_mfma_f32_32x32x16_bf16 v[34:49], v[78:81], v[70:73], v[34:49]
	v_fmamk_f32 v78, v96, 0x3e38aa3b, v97
	v_exp_f32_e32 v87, v78
	ds_read_b128 v[78:81], v173 offset:9312
	v_fmac_f32_e32 v97, 0x3e38aa3b, v67
	v_exp_f32_e32 v67, v97
	v_add_f32_e32 v69, v89, v69
	v_add_f32_e32 v69, v90, v69
	s_waitcnt lgkmcnt(2)
	v_mfma_f32_32x32x16_bf16 v[50:65], v[74:77], v[70:73], v[50:65]
	v_exp_f32_e32 v74, v86
	v_exp_f32_e32 v75, v92
	v_cvt_pk_bf16_f32 v73, v87, v67
	v_cvt_pk_bf16_f32 v70, v89, v90
	v_cvt_pk_bf16_f32 v72, v66, v74
	v_cvt_pk_bf16_f32 v71, v91, v75
	v_add_f32_e32 v69, v91, v69
	v_add_f32_e32 v69, v75, v69
	s_waitcnt lgkmcnt(1)
	v_mfma_f32_32x32x16_bf16 v[34:49], v[82:85], v[70:73], v[34:49]
	v_add_f32_e32 v66, v66, v69
	v_add_f32_e32 v66, v74, v66
	v_add_f32_e32 v66, v87, v66
	v_add_f32_e32 v66, v67, v66
	v_add_f32_e32 v66, v68, v66
	s_waitcnt lgkmcnt(0)
	v_mfma_f32_32x32x16_bf16 v[50:65], v[78:81], v[70:73], v[50:65]
.LBB0_762:
	s_and_b64 vcc, exec, s[2:3]
	s_cbranch_vccz .LBB0_768
	s_cmp_lg_u32 s16, 1
	s_cbranch_scc1 .LBB0_767
	v_add3_u32 v70, s76, v132, v137
	s_setprio 1
	ds_read_b128 v[34:37], v70
	ds_read_b128 v[38:41], v70 offset:16
	ds_read_b128 v[42:45], v70 offset:32
	ds_read_b128 v[46:49], v70 offset:48
	v_cmp_lt_i32_e32 vcc, v211, v210
	s_waitcnt lgkmcnt(3)
	v_mfma_f32_32x32x16_bf16 v[50:65], v[34:37], v[98:101], 0
	ds_read_b128 v[34:37], v70 offset:4608
	ds_read_b128 v[66:69], v70 offset:4624
	s_waitcnt lgkmcnt(4)
	v_mfma_f32_32x32x16_bf16 v[50:65], v[38:41], v[102:105], v[50:65]
	s_waitcnt lgkmcnt(3)
	v_mfma_f32_32x32x16_bf16 v[50:65], v[42:45], v[106:109], v[50:65]
	s_waitcnt lgkmcnt(2)
	v_mfma_f32_32x32x16_bf16 v[50:65], v[46:49], v[110:113], v[50:65]
	s_waitcnt lgkmcnt(1)
	v_mfma_f32_32x32x16_bf16 v[34:49], v[34:37], v[98:101], 0
	s_waitcnt lgkmcnt(0)
	v_mfma_f32_32x32x16_bf16 v[34:49], v[66:69], v[102:105], v[34:49]
	ds_read_b128 v[66:69], v70 offset:4640
	s_waitcnt lgkmcnt(0)
	v_mfma_f32_32x32x16_bf16 v[34:49], v[66:69], v[106:109], v[34:49]
	ds_read_b128 v[66:69], v70 offset:4656
	s_waitcnt lgkmcnt(0)
	v_mfma_f32_32x32x16_bf16 v[34:49], v[66:69], v[110:113], v[34:49]
	s_nop 1
	v_max3_f32 v66, v50, s85, v51
	v_max3_f32 v66, v66, v52, v53
	v_max3_f32 v66, v66, v54, v55
	v_max3_f32 v66, v66, v56, v57
	v_max3_f32 v66, v66, v58, v59
	v_max3_f32 v66, v66, v60, v61
	v_max3_f32 v66, v66, v62, v63
	v_max3_f32 v66, v66, v64, v65
	s_nop 1
	v_max3_f32 v66, v66, v34, v35
	v_max3_f32 v66, v66, v36, v37
	v_max3_f32 v66, v66, v38, v39
	v_max3_f32 v66, v66, v40, v41
	v_max3_f32 v66, v66, v42, v43
	v_max3_f32 v66, v66, v44, v45
	v_max3_f32 v66, v66, v46, v47
	v_cndmask_b32_e32 v67, v209, v211, vcc
	v_max3_f32 v66, v66, v48, v49
	v_lshlrev_b32_e32 v67, 2, v67
	ds_bpermute_b32 v67, v67, v66
	s_waitcnt lgkmcnt(0)
	v_max_f32_e32 v67, v67, v67
	v_max_f32_e32 v66, v66, v67
	v_mul_f32_e32 v66, 0x3e38aa3b, v66
	v_add_f32_e32 v67, 0x40c00000, v152
	v_cmp_gt_f32_e32 vcc, v66, v67
	s_cbranch_vccz .LBB0_766
	s_nop 0
	v_cndmask_b32_e32 v67, v152, v66, vcc
	v_sub_f32_e32 v66, v152, v67
	v_exp_f32_e32 v66, v66
	v_mov_b32_e32 v152, v67
	v_cndmask_b32_e32 v66, 1.0, v66, vcc
	v_mul_f32_e32 v151, v151, v66
	v_pk_mul_f32 v[16:17], v[16:17], v[66:67] op_sel_hi:[1,0]
	v_pk_mul_f32 v[14:15], v[14:15], v[66:67] op_sel_hi:[1,0]
	v_pk_mul_f32 v[12:13], v[12:13], v[66:67] op_sel_hi:[1,0]
	v_pk_mul_f32 v[10:11], v[10:11], v[66:67] op_sel_hi:[1,0]
	v_pk_mul_f32 v[8:9], v[8:9], v[66:67] op_sel_hi:[1,0]
	v_pk_mul_f32 v[6:7], v[6:7], v[66:67] op_sel_hi:[1,0]
	v_pk_mul_f32 v[4:5], v[4:5], v[66:67] op_sel_hi:[1,0]
	v_pk_mul_f32 v[2:3], v[2:3], v[66:67] op_sel_hi:[1,0]
	v_pk_mul_f32 v[32:33], v[32:33], v[66:67] op_sel_hi:[1,0]
	v_pk_mul_f32 v[30:31], v[30:31], v[66:67] op_sel_hi:[1,0]
	v_pk_mul_f32 v[28:29], v[28:29], v[66:67] op_sel_hi:[1,0]
	v_pk_mul_f32 v[26:27], v[26:27], v[66:67] op_sel_hi:[1,0]
	v_pk_mul_f32 v[24:25], v[24:25], v[66:67] op_sel_hi:[1,0]
	v_pk_mul_f32 v[22:23], v[22:23], v[66:67] op_sel_hi:[1,0]
	v_pk_mul_f32 v[20:21], v[20:21], v[66:67] op_sel_hi:[1,0]
	v_pk_mul_f32 v[18:19], v[18:19], v[66:67] op_sel_hi:[1,0]
.LBB0_766:
	v_cmp_neq_f32_e32 vcc, s85, v152
	s_nop 1
	v_cndmask_b32_e64 v66, 0, -v152, vcc
	v_fmamk_f32 v50, v50, 0x3e38aa3b, v66
	v_exp_f32_e32 v50, v50
	v_fmamk_f32 v51, v51, 0x3e38aa3b, v66
	v_exp_f32_e32 v67, v51
	v_fmamk_f32 v51, v52, 0x3e38aa3b, v66
	v_exp_f32_e32 v51, v51
	v_fmamk_f32 v52, v53, 0x3e38aa3b, v66
	v_exp_f32_e32 v68, v52
	v_fmamk_f32 v53, v54, 0x3e38aa3b, v66
	v_add_f32_e32 v52, 0, v50
	v_exp_f32_e32 v54, v53
	v_fmamk_f32 v53, v55, 0x3e38aa3b, v66
	v_add_f32_e32 v52, v67, v52
	v_exp_f32_e32 v55, v53
	v_fmamk_f32 v53, v56, 0x3e38aa3b, v66
	v_add_f32_e32 v52, v51, v52
	v_exp_f32_e32 v53, v53
	v_fmamk_f32 v56, v57, 0x3e38aa3b, v66
	v_add_f32_e32 v52, v68, v52
	v_exp_f32_e32 v56, v56
	v_fmamk_f32 v57, v58, 0x3e38aa3b, v66
	v_add_f32_e32 v52, v54, v52
	v_exp_f32_e32 v58, v57
	v_fmamk_f32 v57, v59, 0x3e38aa3b, v66
	v_add_f32_e32 v52, v55, v52
	v_exp_f32_e32 v59, v57
	v_fmamk_f32 v57, v60, 0x3e38aa3b, v66
	v_add_f32_e32 v52, v53, v52
	v_exp_f32_e32 v60, v57
	v_fmamk_f32 v57, v61, 0x3e38aa3b, v66
	v_add_f32_e32 v52, v56, v52
	v_exp_f32_e32 v61, v57
	v_fmamk_f32 v57, v62, 0x3e38aa3b, v66
	v_add_f32_e32 v52, v58, v52
	v_exp_f32_e32 v62, v57
	v_fmamk_f32 v57, v63, 0x3e38aa3b, v66
	v_add_f32_e32 v52, v59, v52
	v_exp_f32_e32 v63, v57
	v_fmamk_f32 v57, v64, 0x3e38aa3b, v66
	v_add_f32_e32 v52, v60, v52
	v_exp_f32_e32 v64, v57
	v_fmamk_f32 v57, v65, 0x3e38aa3b, v66
	v_add_f32_e32 v52, v61, v52
	v_exp_f32_e32 v65, v57
	v_fmamk_f32 v34, v34, 0x3e38aa3b, v66
	v_add_f32_e32 v52, v62, v52
	v_exp_f32_e32 v69, v34
	v_fmamk_f32 v34, v35, 0x3e38aa3b, v66
	v_add_f32_e32 v52, v63, v52
	v_exp_f32_e32 v70, v34
	v_fmamk_f32 v34, v36, 0x3e38aa3b, v66
	v_add_f32_e32 v52, v64, v52
	v_exp_f32_e32 v71, v34
	v_fmamk_f32 v34, v37, 0x3e38aa3b, v66
	v_add_f32_e32 v52, v65, v52
	v_exp_f32_e32 v72, v34
	v_add_f32_e32 v34, v69, v52
	v_add_f32_e32 v34, v70, v34
	v_add_f32_e32 v34, v71, v34
	v_add_f32_e32 v73, v72, v34
	v_fmamk_f32 v34, v38, 0x3e38aa3b, v66
	v_lshlrev_b32_e32 v38, 1, v146
	v_exp_f32_e32 v74, v34
	v_fmamk_f32 v34, v39, 0x3e38aa3b, v66
	v_add3_u32 v76, s76, v139, v38
	v_exp_f32_e32 v75, v34
	s_setprio 1
	ds_read_b128 v[34:37], v76 offset:9216
	v_fmamk_f32 v39, v40, 0x3e38aa3b, v66
	v_add3_u32 v78, s76, v147, v38
	v_cvt_pk_bf16_f32 v53, v53, v56
	v_cvt_pk_bf16_f32 v52, v54, v55
	v_cvt_pk_bf16_f32 v51, v51, v68
	v_cvt_pk_bf16_f32 v50, v50, v67
	v_exp_f32_e32 v77, v39
	ds_read_b128 v[54:57], v78 offset:9216
	s_waitcnt lgkmcnt(1)
	v_mfma_f32_32x32x16_bf16 v[2:17], v[34:37], v[50:53], v[2:17]
	v_fmamk_f32 v34, v41, 0x3e38aa3b, v66
	v_exp_f32_e32 v67, v34
	v_add_f32_e32 v34, v74, v73
	v_add_f32_e32 v34, v75, v34
	v_add_f32_e32 v34, v77, v34
	v_add_f32_e32 v68, v67, v34
	ds_read_b128 v[34:37], v76 offset:9248
	v_fmamk_f32 v38, v42, 0x3e38aa3b, v66
	s_waitcnt lgkmcnt(1)
	v_mfma_f32_32x32x16_bf16 v[18:33], v[54:57], v[50:53], v[18:33]
	v_exp_f32_e32 v54, v38
	ds_read_b128 v[38:41], v78 offset:9248
	v_cvt_pk_bf16_f32 v53, v64, v65
	v_cvt_pk_bf16_f32 v52, v62, v63
	v_cvt_pk_bf16_f32 v51, v60, v61
	v_cvt_pk_bf16_f32 v50, v58, v59
	v_fmamk_f32 v58, v45, 0x3e38aa3b, v66
	v_add_f32_e32 v55, v54, v68
	s_waitcnt lgkmcnt(1)
	v_mfma_f32_32x32x16_bf16 v[2:17], v[34:37], v[50:53], v[2:17]
	v_fmamk_f32 v34, v43, 0x3e38aa3b, v66
	v_exp_f32_e32 v56, v34
	v_fmamk_f32 v34, v44, 0x3e38aa3b, v66
	v_exp_f32_e32 v57, v34
	ds_read_b128 v[34:37], v76 offset:9280
	ds_read_b128 v[42:45], v78 offset:9280
	s_waitcnt lgkmcnt(2)
	v_mfma_f32_32x32x16_bf16 v[18:33], v[38:41], v[50:53], v[18:33]
	v_fmamk_f32 v38, v46, 0x3e38aa3b, v66
	v_exp_f32_e32 v46, v38
	v_cvt_pk_bf16_f32 v41, v77, v67
	v_cvt_pk_bf16_f32 v40, v74, v75
	v_cvt_pk_bf16_f32 v39, v71, v72
	v_cvt_pk_bf16_f32 v38, v69, v70
	v_exp_f32_e32 v50, v58
	v_add_f32_e32 v51, v56, v55
	s_waitcnt lgkmcnt(1)
	v_mfma_f32_32x32x16_bf16 v[2:17], v[34:37], v[38:41], v[2:17]
	v_fmamk_f32 v34, v47, 0x3e38aa3b, v66
	v_exp_f32_e32 v47, v34
	v_fmamk_f32 v34, v48, 0x3e38aa3b, v66
	v_exp_f32_e32 v48, v34
	ds_read_b128 v[34:37], v76 offset:9312
	v_fmac_f32_e32 v66, 0x3e38aa3b, v49
	v_exp_f32_e32 v49, v66
	s_waitcnt lgkmcnt(1)
	v_mfma_f32_32x32x16_bf16 v[18:33], v[42:45], v[38:41], v[18:33]
	ds_read_b128 v[42:45], v78 offset:9312
	v_cvt_pk_bf16_f32 v40, v46, v47
	v_cvt_pk_bf16_f32 v41, v48, v49
	v_cvt_pk_bf16_f32 v39, v57, v50
	v_cvt_pk_bf16_f32 v38, v54, v56
	s_waitcnt lgkmcnt(1)
	s_nop 0
	v_mfma_f32_32x32x16_bf16 v[2:17], v[34:37], v[38:41], v[2:17]
	v_add_f32_e32 v34, v57, v51
	v_add_f32_e32 v34, v50, v34
	v_add_f32_e32 v34, v46, v34
	v_add_f32_e32 v34, v47, v34
	v_add_f32_e32 v34, v48, v34
	v_add_f32_e32 v34, v49, v34
	v_add_f32_e32 v151, v151, v34
	s_waitcnt lgkmcnt(0)
	v_mfma_f32_32x32x16_bf16 v[18:33], v[42:45], v[38:41], v[18:33]

.LBB0_768:
	s_add_i32 s23, s23, 1
	s_add_i32 s2, s11, s23
	s_add_i32 s22, s22, 64
	s_add_i32 s2, s2, -1
	s_cmp_lt_u32 s2, s12
	v_subrev_u32_e32 v148, 64, v148
	s_waitcnt lgkmcnt(0)
	s_setprio 0
	s_barrier
	s_cbranch_scc1 .LBB0_739
	s_branch .LBB0_736

.LBB0_776:
	s_bitcmp0_b32 s11, 0
	s_cselect_b32 s3, s6, s4
	s_add_i32 s2, s3, s2
	s_cmpk_gt_i32 s2, 0x3ff
	s_cbranch_scc1 .LBB0_775
	s_lshl_b32 s3, s2, 6
	s_ashr_i32 s2, s2, 4
	s_and_b32 s3, s3, 0x3c0
	s_sub_i32 s2, 63, s2
	s_or_b32 s13, s3, s2
	v_mov_b32_e32 v7, v206
	s_lshl_b32 s22, s2, 5
	s_and_b32 s12, s22, 0x7e0
	v_and_b32_e32 v6, 31, v7
	s_lshl_b32 s2, s13, 4
	v_ashrrev_i32_e32 v0, 6, v7
	s_bfe_u32 s14, s13, 0x10006
	v_or_b32_e32 v2, s12, v6
	s_and_b32 s76, s2, 0xfffff800
	v_lshl_add_u32 v4, s14, 2, v0
	v_or_b32_e32 v0, s76, v2
	v_lshlrev_b64 v[2:3], 10, v[0:1]
	v_lshlrev_b32_e32 v130, 6, v4
	v_lshl_add_u64 v[2:3], s[18:19], 0, v[2:3]
	v_ashrrev_i32_e32 v131, 31, v130
	v_and_b32_e32 v5, 32, v7
	v_lshl_add_u64 v[2:3], v[130:131], 1, v[2:3]
	v_lshlrev_b32_e32 v132, 1, v5
	v_mov_b32_e32 v133, v1
	v_lshl_add_u64 v[2:3], v[2:3], 0, v[132:133]
	global_load_dwordx4 v[98:101], v[2:3], off
	global_load_dwordx4 v[102:105], v[2:3], off offset:16
	global_load_dwordx4 v[106:109], v[2:3], off offset:32
	global_load_dwordx4 v[110:113], v[2:3], off offset:48
	v_lshl_add_u32 v2, v4, 1, v4
	v_mov_b64_e32 v[4:5], s[36:37]
	s_movk_i32 s2, 0x60
	v_mad_u64_u32 v[4:5], s[2:3], v0, s2, v[4:5]
	s_lshl_b64 s[2:3], s[76:77], 8
	v_ashrrev_i32_e32 v3, 31, v2
	s_add_u32 s2, s7, s2
	v_lshl_add_u64 v[2:3], v[2:3], 2, v[4:5]
	s_addc_u32 s3, s8, s3
	s_lshl_b32 s15, s14, 6
	s_lshl_b32 s14, s14, 7
	global_load_dword v133, v[2:3], off
	s_add_u32 s2, s2, s14
	v_sub_u32_e64 v2, s12, v222 clamp
	v_mov_b32_e32 v3, v206
	s_addc_u32 s3, s3, 0
	s_and_b32 s13, s13, 0xfffff80
	v_and_b32_e32 v5, 0x7c0, v2
	v_ashrrev_i32_e32 v136, 3, v3
	s_or_b32 s76, s15, s13
	v_readfirstlane_b32 s13, v2
	v_lshlrev_b32_e32 v3, 3, v3
	v_add_u32_e32 v2, v136, v5
	v_and_b32_e32 v4, 56, v3
	v_ashrrev_i32_e32 v3, 31, v2
	s_lshl_b64 s[14:15], s[76:77], 12
	v_lshlrev_b64 v[2:3], 8, v[2:3]
	s_add_u32 s16, s9, s14
	v_lshl_add_u64 v[2:3], s[2:3], 0, v[2:3]
	v_lshlrev_b32_e32 v138, 1, v4
	v_mov_b32_e32 v139, v1
	s_addc_u32 s17, s10, s15
	s_bfe_u32 s14, s22, 0x50006
	v_lshl_add_u64 v[2:3], v[2:3], 0, v[138:139]
	s_movk_i32 s22, 0x2000
	s_setprio 0
	s_barrier
	global_load_dwordx4 v[8:11], v[2:3], off
	v_add_co_u32_e32 v2, vcc, s22, v2
	v_ashrrev_i32_e32 v137, 31, v136
	s_nop 0
	v_addc_co_u32_e32 v3, vcc, 0, v3, vcc
	global_load_dwordx4 v[12:15], v[2:3], off
	v_lshlrev_b64 v[2:3], 12, v[136:137]
	v_lshl_add_u64 v[2:3], s[16:17], 0, v[2:3]
	s_waitcnt vmcnt(11)
	v_lshlrev_b32_e32 v20, 1, v5
	v_mov_b32_e32 v21, v1
	v_lshl_add_u64 v[4:5], v[2:3], 0, v[20:21]
	v_lshl_add_u64 v[4:5], v[4:5], 0, v[138:139]
	global_load_dwordx4 v[16:19], v[4:5], off
	v_lshl_add_u64 v[4:5], v[2:3], 0, s[30:31]
	v_lshl_add_u64 v[20:21], v[4:5], 0, v[20:21]
	v_lshl_add_u64 v[20:21], v[20:21], 0, v[138:139]
	global_load_dwordx4 v[20:23], v[20:21], off
	s_lshr_b32 s13, s13, 6
	s_cmp_lt_u32 s13, s14
	s_cselect_b64 s[16:17], -1, 0
	v_mul_lo_u32 v135, v136, s21
	s_cmp_lg_u64 s[16:17], 0
	v_add_u32_e32 v25, v135, v138
	s_addc_u32 s15, s13, 0
	s_lshl_b32 s76, s15, 7
	v_bfe_u32 v24, v7, 5, 1
	s_cmp_gt_u32 s13, s14
	v_lshlrev_b32_e32 v134, 3, v24
	s_waitcnt vmcnt(3)
	ds_write_b128 v25, v[8:11]
	s_waitcnt vmcnt(2)
	ds_write_b128 v25, v[12:15] offset:4608
	s_waitcnt vmcnt(1)
	ds_write_b128 v25, v[16:19] offset:9216
	s_waitcnt vmcnt(0)
	ds_write_b128 v25, v[20:23] offset:13824
	v_lshl_add_u32 v8, s15, 6, v136
	v_ashrrev_i32_e32 v9, 31, v8
	v_lshlrev_b64 v[8:9], 8, v[8:9]
	v_lshl_add_u64 v[8:9], s[2:3], 0, v[8:9]
	v_lshl_add_u64 v[8:9], v[8:9], 0, v[138:139]
	global_load_dwordx4 v[114:117], v[8:9], off
	v_add_co_u32_e32 v8, vcc, s22, v8
	s_nop 1
	v_addc_co_u32_e32 v9, vcc, 0, v9, vcc
	global_load_dwordx4 v[118:121], v[8:9], off
	v_lshl_add_u64 v[8:9], v[2:3], 0, s[76:77]
	v_lshl_add_u64 v[8:9], v[8:9], 0, v[138:139]
	global_load_dwordx4 v[122:125], v[8:9], off
	v_lshl_add_u64 v[8:9], v[4:5], 0, s[76:77]
	v_lshl_add_u64 v[8:9], v[8:9], 0, v[138:139]
	global_load_dwordx4 v[126:129], v[8:9], off
	s_waitcnt lgkmcnt(0)
	s_setprio 0
	s_barrier
	s_cbranch_scc1 .LBB0_773
	v_and_b32_e32 v8, 63, v7
	v_lshl_add_u64 v[142:143], v[2:3], 0, v[138:139]
	v_lshlrev_b32_e32 v2, 1, v8
	v_lshrrev_b32_e32 v3, 1, v7
	v_lshl_add_u64 v[144:145], v[4:5], 0, v[138:139]
	v_and_b32_e32 v2, 8, v2
	v_and_b32_e32 v3, 4, v3
	v_and_b32_e32 v4, 19, v7
	v_or3_b32 v2, v3, v4, v2
	v_mul_u32_u24_e32 v137, 0x90, v2
	v_lshrrev_b32_e32 v2, 2, v7
	v_and_b32_e32 v146, 8, v2
	v_or_b32_e32 v2, 32, v8
	v_mul_u32_u24_e32 v147, 0x90, v2
	v_add_u32_e32 v2, s12, v6
	s_lshl_b32 s74, s13, 6
	v_sub_u32_e32 v2, v2, v134
	v_mov_b32_e32 v16, v1
	v_mov_b32_e32 v17, v1
	v_lshl_add_u64 v[140:141], s[2:3], 0, v[138:139]
	v_mul_u32_u24_e32 v139, 0x90, v6
	v_subrev_u32_e32 v148, s74, v2
	v_mov_b32_e32 v2, v1
	v_mov_b32_e32 v3, v1
	v_mov_b32_e32 v4, v1
	v_mov_b32_e32 v5, v1
	v_mov_b32_e32 v6, v1
	v_mov_b32_e32 v7, v1
	v_mov_b32_e32 v8, v1
	v_mov_b32_e32 v9, v1
	v_mov_b32_e32 v10, v1
	v_mov_b32_e32 v11, v1
	v_mov_b32_e32 v12, v1
	v_mov_b32_e32 v13, v1
	v_mov_b32_e32 v14, v1
	v_mov_b32_e32 v15, v1
	v_mov_b64_e32 v[32:33], v[16:17]
	s_or_b32 s15, s12, 31
	s_add_i32 s22, s12, 0xfffffe00
	s_add_i32 s23, s12, 0xfffffe1f
	s_mov_b32 s75, 0
	v_mov_b32_e32 v151, 0
	v_mov_b32_e32 v152, 0xff800000
	v_mov_b32_e32 v149, 0
	v_mov_b32_e32 v150, 0
	v_mov_b64_e32 v[30:31], v[14:15]
	v_mov_b64_e32 v[28:29], v[12:13]
	v_mov_b64_e32 v[26:27], v[10:11]
	v_mov_b64_e32 v[24:25], v[8:9]
	v_mov_b64_e32 v[22:23], v[6:7]
	v_mov_b64_e32 v[20:21], v[4:5]
	v_mov_b64_e32 v[18:19], v[2:3]
	s_add_i32 s2, s13, s75
	s_and_b32 s17, s75, 1
	s_cmp_ge_u32 s2, s14
	s_cbranch_scc0 .LBB0_780
	s_branch .LBB0_782

.LBB0_808:
	s_add_i32 s75, s75, 1
	s_add_i32 s2, s13, s75
	s_add_i32 s74, s74, 64
	s_add_i32 s2, s2, -1
	s_cmp_lt_u32 s2, s14
	v_subrev_u32_e32 v148, 64, v148
	s_waitcnt lgkmcnt(0)
	s_setprio 0
	s_barrier
	s_cbranch_scc1 .LBB0_779
	s_branch .LBB0_774

.LBB0_814:
	s_or_b64 exec, exec, s[36:37]
	s_and_b32 s2, s19, -2
	s_ashr_i32 s19, s18, 31
	s_add_i32 s2, s18, s2
	s_lshl_b64 s[6:7], s[18:19], 20
	s_add_u32 s6, s22, s6
	s_addc_u32 s7, s23, s7
	s_ashr_i32 s3, s2, 31
	v_mov_b32_e32 v93, v206
	s_waitcnt vmcnt(0)
	s_setprio 0
	s_barrier
	s_lshl_b64 s[2:3], s[2:3], 17
	s_add_u32 s2, s34, s2
	v_ashrrev_i32_e32 v50, 3, v93
	v_ashrrev_i32_e32 v51, 31, v50
	s_addc_u32 s3, s35, s3
	v_lshlrev_b32_e32 v0, 4, v93
	v_lshlrev_b64 v[2:3], 9, v[50:51]
	v_and_b32_e32 v0, 0x70, v0
	v_lshl_add_u64 v[2:3], s[2:3], 0, v[2:3]
	s_waitcnt vmcnt(9)
	v_lshl_add_u64 v[124:125], v[2:3], 0, v[0:1]
	s_mov_b32 s2, 0xc800000
	v_add_co_u32_e32 v2, vcc, s2, v124
	s_mov_b32 s2, 0xc804000
	s_nop 0
	v_addc_co_u32_e32 v3, vcc, 0, v125, vcc
	v_add_co_u32_e32 v66, vcc, s2, v124
	s_mov_b32 s2, 0xc808000
	s_nop 0
	v_addc_co_u32_e32 v67, vcc, 0, v125, vcc
	v_add_co_u32_e32 v68, vcc, s2, v124
	s_mov_b32 s2, 0xc80c000
	s_nop 0
	v_addc_co_u32_e32 v69, vcc, 0, v125, vcc
	v_add_co_u32_e32 v70, vcc, s2, v124
	s_mov_b32 s2, 0xc810000
	s_nop 0
	v_addc_co_u32_e32 v71, vcc, 0, v125, vcc
	v_add_co_u32_e32 v72, vcc, s2, v124
	s_mov_b32 s2, 0xc814000
	s_nop 0
	v_addc_co_u32_e32 v73, vcc, 0, v125, vcc
	v_add_co_u32_e32 v74, vcc, s2, v124
	v_add_u32_e32 v28, s4, v50
	s_or_b32 s2, s4, 32
	v_ashrrev_i32_e32 v29, 31, v28
	s_sub_u32 s2, s2, s4
	v_lshl_add_u64 v[26:27], s[6:7], 0, v[0:1]
	v_lshlrev_b64 v[28:29], 9, v[28:29]
	s_subb_u32 s3, 0, 0
	v_lshl_add_u64 v[80:81], v[26:27], 0, v[28:29]
	s_lshl_b64 s[2:3], s[2:3], 9
	v_lshl_add_u64 v[88:89], v[80:81], 0, s[2:3]
	v_lshl_add_u64 v[86:87], v[88:89], 0, s[2:3]
	v_addc_co_u32_e32 v75, vcc, 0, v125, vcc
	v_lshl_add_u64 v[90:91], v[86:87], 0, s[2:3]
	s_mov_b32 s2, 0xc818000
	v_add_co_u32_e32 v82, vcc, s2, v124
	s_mov_b32 s2, 0xc81c000
	s_nop 0
	v_addc_co_u32_e32 v83, vcc, 0, v125, vcc
	v_add_co_u32_e32 v84, vcc, s2, v124
	global_load_dwordx4 v[2:5], v[2:3], off
	s_nop 0
	global_load_dwordx4 v[6:9], v[66:67], off
	global_load_dwordx4 v[10:13], v[68:69], off
	global_load_dwordx4 v[14:17], v[70:71], off
	global_load_dwordx4 v[18:21], v[72:73], off
	global_load_dwordx4 v[22:25], v[74:75], off
	global_load_dwordx4 v[26:29], v[80:81], off
	global_load_dwordx4 v[30:33], v[88:89], off
	global_load_dwordx4 v[34:37], v[86:87], off
	global_load_dwordx4 v[38:41], v[90:91], off
	v_addc_co_u32_e32 v85, vcc, 0, v125, vcc
	global_load_dwordx4 v[42:45], v[82:83], off
	global_load_dwordx4 v[46:49], v[84:85], off
	v_ashrrev_i32_e32 v94, 6, v93
	s_movk_i32 s5, 0x90
	v_and_b32_e32 v95, 1, v94
	v_and_b32_e32 v92, 31, v93
	v_mad_u64_u32 v[78:79], s[2:3], v50, s5, v[0:1]
	v_lshrrev_b32_e32 v50, 1, v93
	v_and_b32_e32 v50, 16, v50
	v_lshl_or_b32 v51, v95, 7, v92
	v_mad_u32_u24 v154, v51, s5, v50
	s_setprio 0
	s_barrier
	v_ashrrev_i32_e32 v79, 1, v93
	v_and_b32_e32 v0, 0xffffffc0, v79
	s_movk_i32 s21, 0x90
	v_cmp_eq_u32_e32 vcc, 0, v95
	s_waitcnt vmcnt(5)
	ds_write_b128 v78, v[26:29]
	s_waitcnt vmcnt(4)
	ds_write_b128 v78, v[30:33] offset:4608
	s_waitcnt vmcnt(3)
	ds_write_b128 v78, v[34:37] offset:9216
	s_waitcnt vmcnt(2)
	ds_write_b128 v78, v[38:41] offset:13824
	ds_write_b128 v78, v[2:5] offset:18432
	ds_write_b128 v78, v[6:9] offset:23040
	ds_write_b128 v78, v[10:13] offset:27648
	ds_write_b128 v78, v[14:17] offset:32256
	ds_write_b128 v78, v[18:21] offset:36864
	ds_write_b128 v78, v[22:25] offset:41472
	s_waitcnt vmcnt(1)
	ds_write_b128 v78, v[42:45] offset:46080
	s_waitcnt vmcnt(0)
	ds_write_b128 v78, v[46:49] offset:50688
	s_waitcnt lgkmcnt(0)
	s_setprio 0
	s_barrier
	s_setprio 1
	ds_read_b128 v[2:5], v154 offset:18432
	v_or_b32_e32 v6, v0, v92
	v_mad_u64_u32 v[76:77], s[2:3], v6, s5, v[50:51]
	ds_read_b128 v[6:9], v76
	ds_read_b128 v[96:99], v76 offset:32
	ds_read_b128 v[100:103], v154 offset:18464
	ds_read_b128 v[34:37], v76 offset:4608
	ds_read_b128 v[104:107], v76 offset:4640
	s_waitcnt lgkmcnt(4)
	v_mfma_f32_32x32x16_bf16 v[18:33], v[2:5], v[6:9], 0
	ds_read_b128 v[38:41], v154 offset:23040
	ds_read_b128 v[108:111], v154 offset:23072
	s_mov_b64 s[2:3], 0xc800000
	v_lshl_add_u64 v[152:153], v[124:125], 0, s[2:3]
	s_waitcnt lgkmcnt(3)
	v_mfma_f32_32x32x16_bf16 v[50:65], v[2:5], v[34:37], 0
	s_waitcnt lgkmcnt(1)
	v_mfma_f32_32x32x16_bf16 v[2:17], v[38:41], v[6:9], 0
	v_mfma_f32_32x32x16_bf16 v[34:49], v[38:41], v[34:37], 0
	v_mfma_f32_32x32x16_bf16 v[18:33], v[100:103], v[96:99], v[18:33]
	v_mfma_f32_32x32x16_bf16 v[50:65], v[100:103], v[104:107], v[50:65]
	s_waitcnt lgkmcnt(0)
	v_mfma_f32_32x32x16_bf16 v[2:17], v[108:111], v[96:99], v[2:17]
	v_mfma_f32_32x32x16_bf16 v[34:49], v[108:111], v[104:107], v[34:49]
	ds_read_b128 v[96:99], v154 offset:18496
	ds_read_b128 v[100:103], v76 offset:64
	ds_read_b128 v[104:107], v76 offset:96
	ds_read_b128 v[108:111], v154 offset:18528
	ds_read_b128 v[112:115], v76 offset:4672
	ds_read_b128 v[116:119], v76 offset:4704
	s_waitcnt lgkmcnt(4)
	v_mfma_f32_32x32x16_bf16 v[18:33], v[96:99], v[100:103], v[18:33]
	s_waitcnt lgkmcnt(1)
	v_mfma_f32_32x32x16_bf16 v[50:65], v[96:99], v[112:115], v[50:65]
	ds_read_b128 v[96:99], v154 offset:23104
	ds_read_b128 v[120:123], v154 offset:23136
	s_waitcnt lgkmcnt(1)
	v_mfma_f32_32x32x16_bf16 v[2:17], v[96:99], v[100:103], v[2:17]
	v_mfma_f32_32x32x16_bf16 v[34:49], v[96:99], v[112:115], v[34:49]
	global_load_dwordx4 v[96:99], v[88:89], off offset:128
	global_load_dwordx4 v[100:103], v[80:81], off offset:128
	v_mfma_f32_32x32x16_bf16 v[18:33], v[108:111], v[104:107], v[18:33]
	v_mfma_f32_32x32x16_bf16 v[50:65], v[108:111], v[116:119], v[50:65]
	global_load_dwordx4 v[108:111], v[90:91], off offset:128
	global_load_dwordx4 v[112:115], v[86:87], off offset:128
	global_load_dwordx4 v[124:127], v[66:67], off offset:128
	global_load_dwordx4 v[128:131], v[152:153], off offset:128
	global_load_dwordx4 v[132:135], v[70:71], off offset:128
	global_load_dwordx4 v[136:139], v[68:69], off offset:128
	global_load_dwordx4 v[140:143], v[74:75], off offset:128
	global_load_dwordx4 v[144:147], v[72:73], off offset:128
	s_waitcnt lgkmcnt(0)
	v_mfma_f32_32x32x16_bf16 v[2:17], v[120:123], v[104:107], v[2:17]
	global_load_dwordx4 v[104:107], v[82:83], off offset:128
	global_load_dwordx4 v[148:151], v[84:85], off offset:128
	s_setprio 0
	s_barrier
	s_waitcnt vmcnt(10)
	ds_write_b128 v78, v[100:103]
	ds_write_b128 v78, v[96:99] offset:4608
	s_waitcnt vmcnt(8)
	ds_write_b128 v78, v[112:115] offset:9216
	ds_write_b128 v78, v[108:111] offset:13824
	s_waitcnt vmcnt(6)
	ds_write_b128 v78, v[128:131] offset:18432
	ds_write_b128 v78, v[124:127] offset:23040
	s_waitcnt vmcnt(4)
	ds_write_b128 v78, v[136:139] offset:27648
	ds_write_b128 v78, v[132:135] offset:32256
	s_waitcnt vmcnt(2)
	ds_write_b128 v78, v[144:147] offset:36864
	ds_write_b128 v78, v[140:143] offset:41472
	s_waitcnt vmcnt(1)
	ds_write_b128 v78, v[104:107] offset:46080
	s_waitcnt vmcnt(0)
	ds_write_b128 v78, v[148:151] offset:50688
	v_mfma_f32_32x32x16_bf16 v[34:49], v[120:123], v[116:119], v[34:49]
	s_waitcnt lgkmcnt(0)
	s_setprio 0
	s_barrier
	ds_read_b128 v[96:99], v154 offset:18432
	ds_read_b128 v[100:103], v76
	ds_read_b128 v[104:107], v76 offset:32
	ds_read_b128 v[108:111], v154 offset:18464
	ds_read_b128 v[112:115], v76 offset:4608
	ds_read_b128 v[116:119], v76 offset:4640
	s_waitcnt lgkmcnt(4)
	v_mfma_f32_32x32x16_bf16 v[18:33], v[96:99], v[100:103], v[18:33]
	s_waitcnt lgkmcnt(1)
	v_mfma_f32_32x32x16_bf16 v[50:65], v[96:99], v[112:115], v[50:65]
	ds_read_b128 v[96:99], v154 offset:23040
	ds_read_b128 v[120:123], v154 offset:23072
	s_waitcnt lgkmcnt(1)
	v_mfma_f32_32x32x16_bf16 v[2:17], v[96:99], v[100:103], v[2:17]
	v_mfma_f32_32x32x16_bf16 v[34:49], v[96:99], v[112:115], v[34:49]
	v_mfma_f32_32x32x16_bf16 v[18:33], v[108:111], v[104:107], v[18:33]
	v_mfma_f32_32x32x16_bf16 v[50:65], v[108:111], v[116:119], v[50:65]
	s_waitcnt lgkmcnt(0)
	v_mfma_f32_32x32x16_bf16 v[2:17], v[120:123], v[104:107], v[2:17]
	ds_read_b128 v[96:99], v154 offset:18496
	ds_read_b128 v[100:103], v76 offset:64
	ds_read_b128 v[104:107], v76 offset:96
	ds_read_b128 v[108:111], v154 offset:18528
	v_mfma_f32_32x32x16_bf16 v[34:49], v[120:123], v[116:119], v[34:49]
	ds_read_b128 v[112:115], v76 offset:4672
	ds_read_b128 v[116:119], v76 offset:4704
	s_waitcnt lgkmcnt(4)
	v_mfma_f32_32x32x16_bf16 v[18:33], v[96:99], v[100:103], v[18:33]
	s_waitcnt lgkmcnt(1)
	v_mfma_f32_32x32x16_bf16 v[50:65], v[96:99], v[112:115], v[50:65]
	ds_read_b128 v[96:99], v154 offset:23104
	ds_read_b128 v[120:123], v154 offset:23136
	s_waitcnt lgkmcnt(1)
	v_mfma_f32_32x32x16_bf16 v[2:17], v[96:99], v[100:103], v[2:17]
	v_mfma_f32_32x32x16_bf16 v[34:49], v[96:99], v[112:115], v[34:49]
	global_load_dwordx4 v[96:99], v[88:89], off offset:256
	global_load_dwordx4 v[100:103], v[80:81], off offset:256
	v_mfma_f32_32x32x16_bf16 v[18:33], v[108:111], v[104:107], v[18:33]
	v_mfma_f32_32x32x16_bf16 v[50:65], v[108:111], v[116:119], v[50:65]
	global_load_dwordx4 v[108:111], v[90:91], off offset:256
	global_load_dwordx4 v[112:115], v[86:87], off offset:256
	global_load_dwordx4 v[124:127], v[66:67], off offset:256
	global_load_dwordx4 v[128:131], v[152:153], off offset:256
	global_load_dwordx4 v[132:135], v[70:71], off offset:256
	global_load_dwordx4 v[136:139], v[68:69], off offset:256
	global_load_dwordx4 v[140:143], v[74:75], off offset:256
	global_load_dwordx4 v[144:147], v[72:73], off offset:256
	s_waitcnt lgkmcnt(0)
	v_mfma_f32_32x32x16_bf16 v[2:17], v[120:123], v[104:107], v[2:17]
	global_load_dwordx4 v[104:107], v[82:83], off offset:256
	global_load_dwordx4 v[148:151], v[84:85], off offset:256
	s_setprio 0
	s_barrier
	s_waitcnt vmcnt(10)
	ds_write_b128 v78, v[100:103]
	ds_write_b128 v78, v[96:99] offset:4608
	s_waitcnt vmcnt(8)
	ds_write_b128 v78, v[112:115] offset:9216
	ds_write_b128 v78, v[108:111] offset:13824
	s_waitcnt vmcnt(6)
	ds_write_b128 v78, v[128:131] offset:18432
	ds_write_b128 v78, v[124:127] offset:23040
	s_waitcnt vmcnt(4)
	ds_write_b128 v78, v[136:139] offset:27648
	ds_write_b128 v78, v[132:135] offset:32256
	s_waitcnt vmcnt(2)
	ds_write_b128 v78, v[144:147] offset:36864
	ds_write_b128 v78, v[140:143] offset:41472
	s_waitcnt vmcnt(1)
	ds_write_b128 v78, v[104:107] offset:46080
	s_waitcnt vmcnt(0)
	ds_write_b128 v78, v[148:151] offset:50688
	v_mfma_f32_32x32x16_bf16 v[34:49], v[120:123], v[116:119], v[34:49]
	s_waitcnt lgkmcnt(0)
	s_setprio 0
	s_barrier
	ds_read_b128 v[96:99], v154 offset:18432
	ds_read_b128 v[100:103], v76
	ds_read_b128 v[104:107], v76 offset:32
	ds_read_b128 v[108:111], v154 offset:18464
	ds_read_b128 v[112:115], v76 offset:4608
	ds_read_b128 v[116:119], v76 offset:4640
	s_waitcnt lgkmcnt(4)
	v_mfma_f32_32x32x16_bf16 v[18:33], v[96:99], v[100:103], v[18:33]
	s_waitcnt lgkmcnt(1)
	v_mfma_f32_32x32x16_bf16 v[50:65], v[96:99], v[112:115], v[50:65]
	ds_read_b128 v[96:99], v154 offset:23040
	ds_read_b128 v[120:123], v154 offset:23072
	s_waitcnt lgkmcnt(1)
	v_mfma_f32_32x32x16_bf16 v[2:17], v[96:99], v[100:103], v[2:17]
	v_mfma_f32_32x32x16_bf16 v[34:49], v[96:99], v[112:115], v[34:49]
	v_mfma_f32_32x32x16_bf16 v[18:33], v[108:111], v[104:107], v[18:33]
	v_mfma_f32_32x32x16_bf16 v[50:65], v[108:111], v[116:119], v[50:65]
	s_waitcnt lgkmcnt(0)
	v_mfma_f32_32x32x16_bf16 v[2:17], v[120:123], v[104:107], v[2:17]
	ds_read_b128 v[96:99], v154 offset:18496
	ds_read_b128 v[100:103], v76 offset:64
	ds_read_b128 v[104:107], v76 offset:96
	ds_read_b128 v[108:111], v154 offset:18528
	v_mfma_f32_32x32x16_bf16 v[34:49], v[120:123], v[116:119], v[34:49]
	ds_read_b128 v[112:115], v76 offset:4672
	ds_read_b128 v[116:119], v76 offset:4704
	s_waitcnt lgkmcnt(4)
	v_mfma_f32_32x32x16_bf16 v[18:33], v[96:99], v[100:103], v[18:33]
	s_waitcnt lgkmcnt(1)
	v_mfma_f32_32x32x16_bf16 v[50:65], v[96:99], v[112:115], v[50:65]
	ds_read_b128 v[96:99], v154 offset:23104
	ds_read_b128 v[120:123], v154 offset:23136
	s_waitcnt lgkmcnt(1)
	v_mfma_f32_32x32x16_bf16 v[2:17], v[96:99], v[100:103], v[2:17]
	v_mfma_f32_32x32x16_bf16 v[34:49], v[96:99], v[112:115], v[34:49]
	global_load_dwordx4 v[96:99], v[88:89], off offset:384
	global_load_dwordx4 v[100:103], v[80:81], off offset:384
	v_mfma_f32_32x32x16_bf16 v[18:33], v[108:111], v[104:107], v[18:33]
	v_mfma_f32_32x32x16_bf16 v[50:65], v[108:111], v[116:119], v[50:65]
	global_load_dwordx4 v[88:91], v[90:91], off offset:384
	s_nop 0
	global_load_dwordx4 v[108:111], v[86:87], off offset:384
	global_load_dwordx4 v[112:115], v[66:67], off offset:384
	global_load_dwordx4 v[124:127], v[152:153], off offset:384
	global_load_dwordx4 v[128:131], v[70:71], off offset:384
	s_nop 0
	global_load_dwordx4 v[66:69], v[68:69], off offset:384
	s_nop 0
	global_load_dwordx4 v[132:135], v[74:75], off offset:384
	s_nop 0
	global_load_dwordx4 v[70:73], v[72:73], off offset:384
	s_nop 0
	global_load_dwordx4 v[80:83], v[82:83], off offset:384
	s_nop 0
	global_load_dwordx4 v[84:87], v[84:85], off offset:384
	s_waitcnt lgkmcnt(0)
	s_setprio 0
	s_barrier
	s_waitcnt vmcnt(10)
	ds_write_b128 v78, v[100:103]
	ds_write_b128 v78, v[96:99] offset:4608
	s_waitcnt vmcnt(8)
	ds_write_b128 v78, v[108:111] offset:9216
	ds_write_b128 v78, v[88:91] offset:13824
	s_waitcnt vmcnt(6)
	ds_write_b128 v78, v[124:127] offset:18432
	ds_write_b128 v78, v[112:115] offset:23040
	s_waitcnt vmcnt(4)
	ds_write_b128 v78, v[66:69] offset:27648
	ds_write_b128 v78, v[128:131] offset:32256
	s_waitcnt vmcnt(2)
	ds_write_b128 v78, v[70:73] offset:36864
	ds_write_b128 v78, v[132:135] offset:41472
	s_waitcnt vmcnt(1)
	ds_write_b128 v78, v[80:83] offset:46080
	s_waitcnt vmcnt(0)
	ds_write_b128 v78, v[84:87] offset:50688
	v_mfma_f32_32x32x16_bf16 v[2:17], v[120:123], v[104:107], v[2:17]
	s_waitcnt lgkmcnt(0)
	s_setprio 0
	s_barrier
	ds_read_b128 v[66:69], v154 offset:18432
	ds_read_b128 v[70:73], v76
	ds_read_b128 v[80:83], v76 offset:32
	ds_read_b128 v[84:87], v154 offset:18464
	ds_read_b128 v[88:91], v76 offset:4608
	ds_read_b128 v[96:99], v76 offset:4640
	v_mfma_f32_32x32x16_bf16 v[34:49], v[120:123], v[116:119], v[34:49]
	s_waitcnt lgkmcnt(4)
	v_mfma_f32_32x32x16_bf16 v[18:33], v[66:69], v[70:73], v[18:33]
	s_waitcnt lgkmcnt(1)
	v_mfma_f32_32x32x16_bf16 v[50:65], v[66:69], v[88:91], v[50:65]
	ds_read_b128 v[66:69], v154 offset:23040
	ds_read_b128 v[100:103], v154 offset:23072
	s_waitcnt lgkmcnt(1)
	v_mfma_f32_32x32x16_bf16 v[2:17], v[66:69], v[70:73], v[2:17]
	v_mfma_f32_32x32x16_bf16 v[34:49], v[66:69], v[88:91], v[34:49]
	v_mfma_f32_32x32x16_bf16 v[18:33], v[84:87], v[80:83], v[18:33]
	v_mfma_f32_32x32x16_bf16 v[50:65], v[84:87], v[96:99], v[50:65]
	s_waitcnt lgkmcnt(0)
	v_mfma_f32_32x32x16_bf16 v[2:17], v[100:103], v[80:83], v[2:17]
	ds_read_b128 v[66:69], v154 offset:18496
	ds_read_b128 v[70:73], v76 offset:64
	ds_read_b128 v[80:83], v76 offset:96
	ds_read_b128 v[84:87], v154 offset:18528
	ds_read_b128 v[88:91], v76 offset:4672
	ds_read_b128 v[74:77], v76 offset:4704
	v_mfma_f32_32x32x16_bf16 v[34:49], v[100:103], v[96:99], v[34:49]
	s_waitcnt lgkmcnt(4)
	v_mfma_f32_32x32x16_bf16 v[18:33], v[66:69], v[70:73], v[18:33]
	s_waitcnt lgkmcnt(1)
	v_mfma_f32_32x32x16_bf16 v[50:65], v[66:69], v[88:91], v[50:65]
	ds_read_b128 v[66:69], v154 offset:23104
	ds_read_b128 v[96:99], v154 offset:23136
	s_waitcnt lgkmcnt(0)
	s_setprio 0
	s_barrier
	v_mfma_f32_32x32x16_bf16 v[2:17], v[66:69], v[70:73], v[2:17]
	v_mfma_f32_32x32x16_bf16 v[34:49], v[66:69], v[88:91], v[34:49]
	v_mfma_f32_32x32x16_bf16 v[18:33], v[84:87], v[80:83], v[18:33]
	v_mfma_f32_32x32x16_bf16 v[50:65], v[84:87], v[74:77], v[50:65]
	v_mfma_f32_32x32x16_bf16 v[2:17], v[96:99], v[80:83], v[2:17]
	v_mfma_f32_32x32x16_bf16 v[34:49], v[96:99], v[74:77], v[34:49]
	s_and_saveexec_b64 s[2:3], vcc
	s_cbranch_execz .LBB0_821
	v_bfe_u32 v71, v93, 3, 3
	s_movk_i32 s5, 0x2400
	v_and_b32_e32 v70, 63, v93
	v_and_b32_e32 v67, 4, v71
	v_mul_lo_u32 v72, v94, s5
	v_and_b32_e32 v73, 64, v79
	v_add_u32_e32 v66, s4, v0
	s_cmp_gt_u32 s56, 15
	s_mov_b64 s[18:19], -1
	s_cbranch_scc0 .LBB0_817
	v_mul_u32_u24_e32 v68, 0x90, v67
	v_lshlrev_b32_e32 v69, 1, v92
	v_add3_u32 v74, v72, v68, v69
	v_ashrrev_i32_e32 v68, 7, v66
	s_movk_i32 s4, 0x5f
	v_ashrrev_i32_e32 v69, 31, v68
	v_bitop3_b32 v0, v0, s4, v70 bitop3:0xc8
	v_lshlrev_b64 v[68:69], 14, v[68:69]
	v_cmp_eq_u32_e32 vcc, s4, v0
	v_lshl_add_u64 v[68:69], s[34:35], 0, v[68:69]
	v_lshlrev_b32_e32 v0, 1, v73
	v_lshl_add_u64 v[68:69], v[68:69], 0, v[0:1]
	v_cvt_pk_bf16_f32 v0, v18, s0
	ds_write_b16 v74, v0
	v_cvt_pk_bf16_f32 v0, v19, s0
	ds_write_b16 v74, v0 offset:144
	v_cvt_pk_bf16_f32 v0, v20, s0
	ds_write_b16 v74, v0 offset:288
	v_cvt_pk_bf16_f32 v0, v21, s0
	ds_write_b16 v74, v0 offset:432
	v_cvt_pk_bf16_f32 v0, v22, s0
	ds_write_b16 v74, v0 offset:1152
	v_cvt_pk_bf16_f32 v0, v23, s0
	ds_write_b16 v74, v0 offset:1296
	v_cvt_pk_bf16_f32 v0, v24, s0
	ds_write_b16 v74, v0 offset:1440
	v_cvt_pk_bf16_f32 v0, v25, s0
	ds_write_b16 v74, v0 offset:1584
	v_cvt_pk_bf16_f32 v0, v26, s0
	ds_write_b16 v74, v0 offset:2304
	v_cvt_pk_bf16_f32 v0, v27, s0
	ds_write_b16 v74, v0 offset:2448
	v_cvt_pk_bf16_f32 v0, v28, s0
	ds_write_b16 v74, v0 offset:2592
	v_cvt_pk_bf16_f32 v0, v29, s0
	ds_write_b16 v74, v0 offset:2736
	v_cvt_pk_bf16_f32 v0, v30, s0
	ds_write_b16 v74, v0 offset:3456
	v_cvt_pk_bf16_f32 v0, v31, s0
	ds_write_b16 v74, v0 offset:3600
	v_cvt_pk_bf16_f32 v0, v32, s0
	ds_write_b16 v74, v0 offset:3744
	v_cvt_pk_bf16_f32 v0, v33, s0
	ds_write_b16 v74, v0 offset:3888
	v_cvt_pk_bf16_f32 v0, v2, s0
	ds_write_b16 v74, v0 offset:4608
	v_cvt_pk_bf16_f32 v0, v3, s0
	ds_write_b16 v74, v0 offset:4752
	v_cvt_pk_bf16_f32 v0, v4, s0
	ds_write_b16 v74, v0 offset:4896
	v_cvt_pk_bf16_f32 v0, v5, s0
	ds_write_b16 v74, v0 offset:5040
	v_cvt_pk_bf16_f32 v0, v6, s0
	ds_write_b16 v74, v0 offset:5760
	v_cvt_pk_bf16_f32 v0, v7, s0
	ds_write_b16 v74, v0 offset:5904
	v_cvt_pk_bf16_f32 v0, v8, s0
	ds_write_b16 v74, v0 offset:6048
	v_cvt_pk_bf16_f32 v0, v9, s0
	ds_write_b16 v74, v0 offset:6192
	v_cvt_pk_bf16_f32 v0, v10, s0
	ds_write_b16 v74, v0 offset:6912
	v_cvt_pk_bf16_f32 v0, v11, s0
	ds_write_b16 v74, v0 offset:7056
	v_cvt_pk_bf16_f32 v0, v12, s0
	ds_write_b16 v74, v0 offset:7200
	v_cvt_pk_bf16_f32 v0, v13, s0
	ds_write_b16 v74, v0 offset:7344
	v_cvt_pk_bf16_f32 v0, v14, s0
	ds_write_b16 v74, v0 offset:8064
	v_cvt_pk_bf16_f32 v0, v15, s0
	ds_write_b16 v74, v0 offset:8208
	v_cvt_pk_bf16_f32 v0, v16, s0
	ds_write_b16 v74, v0 offset:8352
	v_cvt_pk_bf16_f32 v0, v17, s0
	ds_write_b16 v74, v0 offset:8496
	v_cvt_pk_bf16_f32 v0, v50, s0
	v_cndmask_b32_e64 v0, v0, 0, vcc
	ds_write_b16 v74, v0 offset:64
	v_cvt_pk_bf16_f32 v0, v51, s0
	v_cndmask_b32_e64 v0, v0, 0, vcc
	ds_write_b16 v74, v0 offset:208
	v_cvt_pk_bf16_f32 v0, v52, s0
	v_cndmask_b32_e64 v0, v0, 0, vcc
	ds_write_b16 v74, v0 offset:352
	v_cvt_pk_bf16_f32 v0, v53, s0
	v_cndmask_b32_e64 v0, v0, 0, vcc
	ds_write_b16 v74, v0 offset:496
	v_cvt_pk_bf16_f32 v0, v54, s0
	v_cndmask_b32_e64 v0, v0, 0, vcc
	ds_write_b16 v74, v0 offset:1216
	v_cvt_pk_bf16_f32 v0, v55, s0
	v_cndmask_b32_e64 v0, v0, 0, vcc
	ds_write_b16 v74, v0 offset:1360
	v_cvt_pk_bf16_f32 v0, v56, s0
	v_cndmask_b32_e64 v0, v0, 0, vcc
	ds_write_b16 v74, v0 offset:1504
	v_cvt_pk_bf16_f32 v0, v57, s0
	v_cndmask_b32_e64 v0, v0, 0, vcc
	ds_write_b16 v74, v0 offset:1648
	v_cvt_pk_bf16_f32 v0, v58, s0
	v_cndmask_b32_e64 v0, v0, 0, vcc
	ds_write_b16 v74, v0 offset:2368
	v_cvt_pk_bf16_f32 v0, v59, s0
	v_cndmask_b32_e64 v0, v0, 0, vcc
	ds_write_b16 v74, v0 offset:2512
	v_cvt_pk_bf16_f32 v0, v60, s0
	v_cndmask_b32_e64 v0, v0, 0, vcc
	ds_write_b16 v74, v0 offset:2656
	v_cvt_pk_bf16_f32 v0, v61, s0
	v_cndmask_b32_e64 v0, v0, 0, vcc
	ds_write_b16 v74, v0 offset:2800
	v_cvt_pk_bf16_f32 v0, v62, s0
	v_cndmask_b32_e64 v0, v0, 0, vcc
	ds_write_b16 v74, v0 offset:3520
	v_cvt_pk_bf16_f32 v0, v63, s0
	v_cndmask_b32_e64 v0, v0, 0, vcc
	ds_write_b16 v74, v0 offset:3664
	v_cvt_pk_bf16_f32 v0, v64, s0
	v_cndmask_b32_e64 v0, v0, 0, vcc
	ds_write_b16 v74, v0 offset:3808
	v_cvt_pk_bf16_f32 v0, v65, s0
	v_cndmask_b32_e64 v0, v0, 0, vcc
	ds_write_b16 v74, v0 offset:3952
	v_cvt_pk_bf16_f32 v0, v34, s0
	v_cndmask_b32_e64 v0, v0, 0, vcc
	ds_write_b16 v74, v0 offset:4672
	v_cvt_pk_bf16_f32 v0, v35, s0
	v_cndmask_b32_e64 v0, v0, 0, vcc
	ds_write_b16 v74, v0 offset:4816
	v_cvt_pk_bf16_f32 v0, v36, s0
	v_cndmask_b32_e64 v0, v0, 0, vcc
	ds_write_b16 v74, v0 offset:4960
	v_cvt_pk_bf16_f32 v0, v37, s0
	v_cndmask_b32_e64 v0, v0, 0, vcc
	ds_write_b16 v74, v0 offset:5104
	v_cvt_pk_bf16_f32 v0, v38, s0
	v_cndmask_b32_e64 v0, v0, 0, vcc
	ds_write_b16 v74, v0 offset:5824
	v_cvt_pk_bf16_f32 v0, v39, s0
	v_cndmask_b32_e64 v0, v0, 0, vcc
	ds_write_b16 v74, v0 offset:5968
	v_cvt_pk_bf16_f32 v0, v40, s0
	v_cndmask_b32_e64 v0, v0, 0, vcc
	ds_write_b16 v74, v0 offset:6112
	v_cvt_pk_bf16_f32 v0, v41, s0
	v_cndmask_b32_e64 v0, v0, 0, vcc
	ds_write_b16 v74, v0 offset:6256
	v_cvt_pk_bf16_f32 v0, v42, s0
	v_cndmask_b32_e64 v0, v0, 0, vcc
	ds_write_b16 v74, v0 offset:6976
	v_cvt_pk_bf16_f32 v0, v43, s0
	v_cndmask_b32_e64 v0, v0, 0, vcc
	ds_write_b16 v74, v0 offset:7120
	v_cvt_pk_bf16_f32 v0, v44, s0
	v_cndmask_b32_e64 v0, v0, 0, vcc
	ds_write_b16 v74, v0 offset:7264
	v_cvt_pk_bf16_f32 v0, v45, s0
	v_cndmask_b32_e64 v0, v0, 0, vcc
	ds_write_b16 v74, v0 offset:7408
	v_cvt_pk_bf16_f32 v0, v46, s0
	v_cndmask_b32_e64 v0, v0, 0, vcc
	ds_write_b16 v74, v0 offset:8128
	v_cvt_pk_bf16_f32 v0, v47, s0
	v_cndmask_b32_e64 v0, v0, 0, vcc
	ds_write_b16 v74, v0 offset:8272
	v_cvt_pk_bf16_f32 v0, v48, s0
	v_cndmask_b32_e64 v0, v0, 0, vcc
	ds_write_b16 v74, v0 offset:8416
	v_cvt_pk_bf16_f32 v0, v49, s0
	v_cndmask_b32_e64 v0, v0, 0, vcc
	ds_write_b16 v74, v0 offset:8560
	v_lshlrev_b32_e32 v0, 8, v71
	v_lshl_add_u64 v[68:69], v[68:69], 0, v[0:1]
	s_mov_b64 s[4:5], 0xd080000
	v_lshl_add_u64 v[68:69], v[68:69], 0, s[4:5]
	s_mov_b64 s[18:19], 0

.LBB0_874:
	s_or_b64 exec, exec, s[18:19]
	v_readlane_b32 s10, v243, 3
	v_readlane_b32 s11, v243, 4
	s_waitcnt lgkmcnt(0)
	s_setprio 0
	s_barrier
	s_load_dwordx2 s[8:9], s[10:11], 0x98
	v_readlane_b32 s4, v243, 0
	s_mov_b32 s6, s12
	s_mov_b64 s[2:3], s[10:11]
	s_mov_b32 s13, 0
	s_waitcnt lgkmcnt(0)
	s_mov_b32 s5, s8
	s_load_dwordx2 s[18:19], s[2:3], 0x90
	s_not_b32 s2, s4
	s_add_i32 s6, s5, s2
	s_mov_b32 s2, 0
	s_waitcnt lgkmcnt(0)
	s_add_u32 s34, s18, 0x4000000
	s_addc_u32 s35, s19, 0
	s_add_u32 s36, s18, 0x7c00000
	s_addc_u32 s37, s19, 0
	s_add_u32 s7, s18, 0xd000000
	s_addc_u32 s8, s19, 0
	s_add_u32 s9, s18, 0x6c00000
	s_addc_u32 s10, s19, 0
	s_add_u32 s11, s18, 0x7000000
	s_addc_u32 s12, s19, 0
	s_add_u32 s72, s18, 0x9000000
	s_addc_u32 s73, s19, 0
	s_add_u32 s74, s18, 0x5000000
	s_addc_u32 s75, s19, 0
	s_branch .LBB0_876

.LBB0_876:
	s_bitcmp0_b32 s13, 0
	s_cselect_b32 s14, s4, s6
	s_add_i32 s14, s14, s2
	s_cmpk_gt_i32 s14, 0x3ff
	s_cbranch_scc1 .LBB0_875
	v_mov_b32_e32 v90, v206
	s_movk_i32 s2, 0x1000
	s_nop 0
	v_cmp_gt_i32_e32 vcc, s2, v90
	s_setprio 0
	s_barrier
	s_and_saveexec_b64 s[2:3], vcc
	s_cbranch_execz .LBB0_880
	v_add_u32_e32 v0, 0xffffff00, v90
	v_lshlrev_b32_e32 v2, 2, v90
	s_mov_b64 s[22:23], 0

.LBB0_880:
	s_or_b64 exec, exec, s[2:3]
	v_cmp_eq_u32_e32 vcc, 0, v90
	s_and_saveexec_b64 s[2:3], vcc
	ds_write_b32 v1, v1 offset:20736
	s_or_b64 exec, exec, s[2:3]
	s_ashr_i32 s2, s14, 4
	s_lshl_b32 s3, s14, 6
	s_sub_i32 s2, 63, s2
	s_and_b32 s3, s3, 0x3c0
	s_or_b32 s16, s3, s2
	s_lshl_b32 s41, s2, 5
	v_and_b32_e32 v91, 31, v90
	s_lshr_b32 s3, s16, 7
	s_and_b32 s14, s41, 0x7e0
	s_waitcnt vmcnt(4)
	v_ashrrev_i32_e32 v18, 6, v90
	s_bfe_u32 s17, s16, 0x10006
	v_or_b32_e32 v94, s14, v91
	s_lshl_b32 s40, s3, 11
	v_lshl_add_u32 v4, s17, 2, v18
	v_or_b32_e32 v0, s40, v94
	v_lshlrev_b64 v[2:3], 10, v[0:1]
	v_lshlrev_b32_e32 v162, 6, v4
	v_lshl_add_u64 v[2:3], s[34:35], 0, v[2:3]
	v_ashrrev_i32_e32 v163, 31, v162
	v_and_b32_e32 v5, 32, v90
	v_lshl_add_u64 v[2:3], v[162:163], 1, v[2:3]
	v_lshlrev_b32_e32 v170, 1, v5
	v_mov_b32_e32 v171, v1
	s_lshl_b32 s2, s3, 1
	v_lshl_add_u64 v[2:3], v[2:3], 0, v[170:171]
	s_or_b32 s76, s2, s17
	s_waitcnt lgkmcnt(0)
	s_setprio 0
	s_barrier
	global_load_dwordx4 v[130:133], v[2:3], off
	global_load_dwordx4 v[134:137], v[2:3], off offset:16
	global_load_dwordx4 v[138:141], v[2:3], off offset:32
	global_load_dwordx4 v[142:145], v[2:3], off offset:48
	v_mov_b64_e32 v[2:3], s[36:37]
	s_movk_i32 s2, 0x60
	v_lshl_add_u32 v4, v4, 1, v4
	v_mad_u64_u32 v[2:3], s[2:3], v0, s2, v[2:3]
	v_ashrrev_i32_e32 v5, 31, v4
	v_lshl_add_u64 v[2:3], v[4:5], 2, v[2:3]
	v_lshlrev_b32_e32 v4, 1, v90
	v_lshrrev_b32_e32 v19, 1, v90
	s_lshl_b64 s[22:23], s[76:77], 14
	v_and_b32_e32 v6, 8, v4
	v_and_b32_e32 v7, 4, v19
	v_and_b32_e32 v8, 19, v90
	s_add_u32 s38, s7, s22
	v_or3_b32 v95, v8, v6, v7
	s_addc_u32 s39, s8, s23
	v_lshlrev_b32_e32 v4, 7, v95
	v_mov_b32_e32 v5, v1
	v_lshl_add_u64 v[4:5], s[38:39], 0, v[4:5]
	v_lshl_add_u64 v[4:5], v[4:5], 0, v[170:171]
	global_load_dwordx2 v[168:169], v[2:3], off
	global_load_dwordx4 v[50:53], v[4:5], off
	global_load_dwordx4 v[54:57], v[4:5], off offset:16
	global_load_dwordx4 v[58:61], v[4:5], off offset:32
	global_load_dwordx4 v[62:65], v[4:5], off offset:48
	v_cmp_lt_i32_e32 vcc, v211, v210
	v_bfe_u32 v21, v90, 5, 1
	v_lshl_add_u64 v[82:83], s[38:39], 0, v[170:171]
	v_cndmask_b32_e32 v2, v209, v211, vcc
	s_and_b32 s38, s41, 0x600
	v_and_b32_e32 v92, 63, v90
	v_lshlrev_b64 v[164:165], 9, v[0:1]
	s_mov_b32 s2, 32
	s_bfe_u32 s15, s41, 0x20009
	v_subrev_u32_e32 v22, 31, v94
	s_mov_b32 s3, 0
	v_lshlrev_b32_e32 v167, 2, v2
	v_lshlrev_b32_e32 v20, 7, v21
	v_or3_b32 v93, v7, v8, v6
	s_addk_i32 s38, 0x200
	v_mov_b32_e32 v2, 0
	v_mov_b32_e32 v23, 0xff800000
	s_mov_b32 s41, 0
.LBB0_883:
	s_add_i32 s39, s41, 1
	v_mov_b32_e32 v36, v2
	s_waitcnt vmcnt(3)
	v_mov_b64_e32 v[2:3], v[50:51]
	s_cmp_lt_u32 s41, s15
	v_mov_b64_e32 v[4:5], v[52:53]
	s_cselect_b32 s41, s2, 0
	v_or_b32_e32 v6, s41, v93
	v_ashrrev_i32_e32 v7, 31, v6
	v_lshlrev_b64 v[6:7], 7, v[6:7]
	s_waitcnt vmcnt(0)
	v_mov_b64_e32 v[24:25], v[62:63]
	v_mov_b64_e32 v[28:29], v[58:59]
	v_mov_b64_e32 v[32:33], v[54:55]
	v_lshl_add_u64 v[6:7], v[82:83], 0, v[6:7]
	v_mov_b64_e32 v[26:27], v[64:65]
	v_mov_b64_e32 v[30:31], v[60:61]
	v_mov_b64_e32 v[34:35], v[56:57]
	global_load_dwordx4 v[50:53], v[6:7], off
	global_load_dwordx4 v[54:57], v[6:7], off offset:16
	global_load_dwordx4 v[58:61], v[6:7], off offset:32
	global_load_dwordx4 v[62:65], v[6:7], off offset:48
	s_setprio 1
	v_mfma_f32_32x32x16_bf16 v[2:17], v[2:5], v[130:133], 0
	s_add_i32 s2, s2, 32
	s_mov_b32 s41, s39
	v_mfma_f32_32x32x16_bf16 v[2:17], v[32:35], v[134:137], v[2:17]
	v_mfma_f32_32x32x16_bf16 v[2:17], v[28:31], v[138:141], v[2:17]
	v_mfma_f32_32x32x16_bf16 v[2:17], v[24:27], v[142:145], v[2:17]
	v_add_u32_e32 v24, s3, v20
	v_cmp_le_i32_e32 vcc, v24, v22
	v_add_u32_e32 v25, 16, v24
	v_add_u32_e32 v26, 32, v24
	s_addk_i32 s3, 0x200
	s_cmp_eq_u32 s38, s3
	s_nop 5
	v_mul_f32_e32 v2, 0x3e38aa3b, v2
	v_cndmask_b32_e32 v2, v220, v2, vcc
	v_mul_f32_e32 v3, 0x3e38aa3b, v3
	v_cmp_le_i32_e32 vcc, v25, v22
	v_mul_f32_e32 v4, 0x3e38aa3b, v4
	v_mul_f32_e32 v5, 0x3e38aa3b, v5
	v_cndmask_b32_e32 v3, v220, v3, vcc
	v_cmp_le_i32_e32 vcc, v26, v22
	v_add_u32_e32 v26, 48, v24
	v_mul_f32_e32 v6, 0x3e38aa3b, v6
	v_cndmask_b32_e32 v4, v220, v4, vcc
	v_cmp_le_i32_e32 vcc, v26, v22
	v_add_u32_e32 v26, 64, v24
	v_mul_f32_e32 v7, 0x3e38aa3b, v7
	v_cndmask_b32_e32 v5, v220, v5, vcc
	v_cmp_le_i32_e32 vcc, v26, v22
	v_add_u32_e32 v26, 0x50, v24
	v_mul_f32_e32 v8, 0x3e38aa3b, v8
	v_cndmask_b32_e32 v6, v220, v6, vcc
	v_cmp_le_i32_e32 vcc, v26, v22
	v_add_u32_e32 v26, 0x60, v24
	v_mul_f32_e32 v9, 0x3e38aa3b, v9
	v_cndmask_b32_e32 v7, v220, v7, vcc
	v_cmp_le_i32_e32 vcc, v26, v22
	v_add_u32_e32 v26, 0x70, v24
	v_mul_f32_e32 v10, 0x3e38aa3b, v10
	v_cndmask_b32_e32 v8, v220, v8, vcc
	v_cmp_le_i32_e32 vcc, v26, v22
	v_add_u32_e32 v26, 0x100, v24
	v_mul_f32_e32 v11, 0x3e38aa3b, v11
	v_cndmask_b32_e32 v9, v220, v9, vcc
	v_cmp_le_i32_e32 vcc, v26, v22
	v_add_u32_e32 v26, 0x110, v24
	v_max3_f32 v25, v2, s85, v3
	v_cndmask_b32_e32 v10, v220, v10, vcc
	v_cmp_le_i32_e32 vcc, v26, v22
	v_add_u32_e32 v26, 0x120, v24
	v_mul_f32_e32 v12, 0x3e38aa3b, v12
	v_cndmask_b32_e32 v11, v220, v11, vcc
	v_cmp_le_i32_e32 vcc, v26, v22
	v_add_u32_e32 v26, 0x130, v24
	v_max3_f32 v25, v25, v4, v5
	v_cndmask_b32_e32 v12, v220, v12, vcc
	v_mul_f32_e32 v13, 0x3e38aa3b, v13
	v_cmp_le_i32_e32 vcc, v26, v22
	v_add_u32_e32 v26, 0x140, v24
	v_max3_f32 v25, v25, v6, v7
	v_cndmask_b32_e32 v13, v220, v13, vcc
	v_mul_f32_e32 v14, 0x3e38aa3b, v14
	v_cmp_le_i32_e32 vcc, v26, v22
	v_add_u32_e32 v26, 0x150, v24
	v_max3_f32 v25, v25, v8, v9
	v_cndmask_b32_e32 v14, v220, v14, vcc
	v_mul_f32_e32 v15, 0x3e38aa3b, v15
	v_cmp_le_i32_e32 vcc, v26, v22
	v_add_u32_e32 v26, 0x160, v24
	v_max3_f32 v25, v25, v10, v11
	v_cndmask_b32_e32 v15, v220, v15, vcc
	v_mul_f32_e32 v16, 0x3e38aa3b, v16
	v_cmp_le_i32_e32 vcc, v26, v22
	v_add_u32_e32 v24, 0x170, v24
	v_max3_f32 v25, v25, v12, v13
	v_cndmask_b32_e32 v16, v220, v16, vcc
	v_mul_f32_e32 v17, 0x3e38aa3b, v17
	v_cmp_le_i32_e32 vcc, v24, v22
	v_max3_f32 v25, v25, v14, v15
	s_nop 0
	v_cndmask_b32_e32 v17, v220, v17, vcc
	v_max3_f32 v24, v25, v16, v17
	ds_bpermute_b32 v25, v167, v24
	s_waitcnt lgkmcnt(0)
	v_max3_f32 v24, v23, v24, v25
	v_cmp_neq_f32_e32 vcc, s85, v24
	s_nop 1
	v_cndmask_b32_e32 v96, 0, v24, vcc
	v_sub_f32_e32 v2, v2, v96
	v_exp_f32_e32 v2, v2
	v_sub_f32_e32 v3, v3, v96
	v_exp_f32_e32 v3, v3
	v_sub_f32_e32 v23, v23, v96
	v_add_f32_e32 v2, 0, v2
	v_add_f32_e32 v2, v3, v2
	v_sub_f32_e32 v3, v4, v96
	v_exp_f32_e32 v3, v3
	s_nop 0
	v_add_f32_e32 v2, v3, v2
	v_sub_f32_e32 v3, v5, v96
	v_exp_f32_e32 v3, v3
	s_nop 0
	v_add_f32_e32 v2, v3, v2
	v_sub_f32_e32 v3, v6, v96
	v_exp_f32_e32 v3, v3
	s_nop 0
	v_add_f32_e32 v2, v3, v2
	v_sub_f32_e32 v3, v7, v96
	v_exp_f32_e32 v3, v3
	s_nop 0
	v_add_f32_e32 v2, v3, v2
	v_sub_f32_e32 v3, v8, v96
	v_exp_f32_e32 v3, v3
	s_nop 0
	v_add_f32_e32 v2, v3, v2
	v_sub_f32_e32 v3, v9, v96
	v_exp_f32_e32 v3, v3
	s_nop 0
	v_add_f32_e32 v2, v3, v2
	v_sub_f32_e32 v3, v10, v96
	v_exp_f32_e32 v3, v3
	s_nop 0
	v_add_f32_e32 v2, v3, v2
	v_sub_f32_e32 v3, v11, v96
	v_exp_f32_e32 v3, v3
	s_nop 0
	v_add_f32_e32 v2, v3, v2
	v_sub_f32_e32 v3, v12, v96
	v_exp_f32_e32 v3, v3
	s_nop 0
	v_add_f32_e32 v2, v3, v2
	v_sub_f32_e32 v3, v13, v96
	v_exp_f32_e32 v3, v3
	s_nop 0
	v_add_f32_e32 v2, v3, v2
	v_sub_f32_e32 v3, v14, v96
	v_exp_f32_e32 v3, v3
	s_nop 0
	v_add_f32_e32 v2, v3, v2
	v_sub_f32_e32 v3, v15, v96
	v_exp_f32_e32 v3, v3
	s_nop 0
	v_add_f32_e32 v2, v3, v2
	v_sub_f32_e32 v3, v16, v96
	v_exp_f32_e32 v3, v3
	s_nop 0
	v_add_f32_e32 v2, v3, v2
	v_sub_f32_e32 v3, v17, v96
	v_exp_f32_e32 v3, v3
	s_nop 0
	v_add_f32_e32 v2, v3, v2
	v_exp_f32_e32 v3, v23
	v_mov_b32_e32 v23, v24
	v_fmac_f32_e32 v2, v36, v3
	s_cbranch_scc0 .LBB0_883
	ds_bpermute_b32 v3, v167, v2
	v_lshlrev_b32_e32 v166, 3, v21
	v_add_u32_e32 v98, 0x18f, v20
	v_lshl_or_b32 v84, v92, 8, v223
	v_mov_b32_e32 v85, v1
	s_waitcnt lgkmcnt(0)
	v_add_f32_e32 v3, v2, v3
	v_div_scale_f32 v4, s[2:3], v3, v3, 1.0
	v_rcp_f32_e32 v5, v4
	v_div_scale_f32 v6, vcc, 1.0, v3, 1.0
	s_add_u32 s2, s18, s22
	v_fma_f32 v7, -v4, v5, 1.0
	v_fmac_f32_e32 v5, v7, v5
	v_mul_f32_e32 v7, v6, v5
	v_fma_f32 v8, -v4, v7, v6
	v_fmac_f32_e32 v7, v8, v5
	v_fma_f32 v4, -v4, v7, v6
	v_div_fmas_f32 v4, v4, v5, v7
	v_div_fixup_f32 v4, v4, v3, 1.0
	v_cmp_lt_f32_e32 vcc, 0, v3
	v_lshlrev_b32_e32 v3, 12, v18
	v_mov_b32_e32 v2, 0
	v_cndmask_b32_e32 v97, 0, v4, vcc
	v_lshlrev_b32_e32 v4, 7, v91
	v_or3_b32 v99, v3, v4, v166
	v_and_b32_e32 v4, 16, v19
	v_mov_b32_e32 v5, v1
	s_addc_u32 s3, s19, s23
	v_lshl_add_u64 v[86:87], s[2:3], 0, v[4:5]
	v_lshlrev_b32_e32 v88, 8, v91
	v_mov_b32_e32 v89, v1
	s_mov_b32 s22, 0
	v_mov_b32_e32 v3, v2
	v_mov_b32_e32 v4, v2
	v_mov_b32_e32 v5, v2
	v_mov_b32_e32 v6, v2
	v_mov_b32_e32 v7, v2
	v_mov_b32_e32 v8, v2
	v_mov_b32_e32 v9, v2
	v_mov_b32_e32 v10, v2
	v_mov_b32_e32 v11, v2
	v_mov_b32_e32 v12, v2
	v_mov_b32_e32 v13, v2
	v_mov_b32_e32 v14, v2
	v_mov_b32_e32 v15, v2
	v_mov_b32_e32 v16, v2
	v_mov_b32_e32 v17, v2
	v_mov_b32_e32 v18, v2
	v_mov_b32_e32 v19, v2
	v_mov_b32_e32 v20, v2
	v_mov_b32_e32 v21, v2
	v_mov_b32_e32 v22, v2
	v_mov_b32_e32 v23, v2
	v_mov_b32_e32 v24, v2
	v_mov_b32_e32 v25, v2
	v_mov_b32_e32 v26, v2
	v_mov_b32_e32 v27, v2
	v_mov_b32_e32 v28, v2
	v_mov_b32_e32 v29, v2
	v_mov_b32_e32 v30, v2
	v_mov_b32_e32 v31, v2
	v_mov_b32_e32 v32, v2
	v_mov_b32_e32 v33, v2
	s_branch .LBB0_886
.LBB0_885:
	s_or_b64 exec, exec, s[2:3]
	v_cvt_pk_bf16_f32 v103, v40, v42
	v_cvt_pk_bf16_f32 v102, v38, v39
	v_cvt_pk_bf16_f32 v101, v36, v37
	v_cvt_pk_bf16_f32 v100, v34, v35
	v_cvt_pk_bf16_f32 v37, v48, v49
	v_cvt_pk_bf16_f32 v36, v46, v47
	s_waitcnt vmcnt(5)
	s_setprio 1
	v_mfma_f32_32x32x16_bf16 v[2:17], v[74:77], v[100:103], v[2:17]
	v_cvt_pk_bf16_f32 v35, v44, v45
	v_cvt_pk_bf16_f32 v34, v41, v43
	v_add_u32_e32 v98, 0x200, v98
	v_add_u32_e32 v99, 32, v99
	v_lshl_add_u64 v[86:87], v[86:87], 0, 64
	s_cmp_eq_u32 s22, s15
	s_mov_b32 s22, s23
	s_waitcnt vmcnt(3)
	v_mfma_f32_32x32x16_bf16 v[18:33], v[78:81], v[100:103], v[18:33]
	v_mfma_f32_32x32x16_bf16 v[2:17], v[70:73], v[34:37], v[2:17]
	s_waitcnt vmcnt(2)
	v_mfma_f32_32x32x16_bf16 v[18:33], v[66:69], v[34:37], v[18:33]
	s_cbranch_scc1 .LBB0_888
.LBB0_886:
	s_waitcnt vmcnt(3)
	s_setprio 1
	v_mfma_f32_32x32x16_bf16 v[34:49], v[50:53], v[130:133], 0
	s_waitcnt vmcnt(2)
	v_mov_b64_e32 v[68:69], v[56:57]
	v_mov_b64_e32 v[66:67], v[54:55]
	s_add_i32 s23, s22, 1
	s_cmp_lt_u32 s22, s15
	s_cselect_b32 s2, s23, s22
	v_lshl_or_b32 v50, s2, 5, v95
	v_ashrrev_i32_e32 v51, 31, v50
	v_mfma_f32_32x32x16_bf16 v[34:49], v[66:69], v[134:137], v[34:49]
	v_lshl_add_u64 v[70:71], v[86:87], 0, v[88:89]
	v_lshlrev_b64 v[50:51], 7, v[50:51]
	v_add_co_u32_e32 v66, vcc, s97, v70
	v_lshl_add_u64 v[100:101], v[82:83], 0, v[50:51]
	s_nop 0
	v_addc_co_u32_e32 v67, vcc, 0, v71, vcc
	s_waitcnt vmcnt(1)
	v_mfma_f32_32x32x16_bf16 v[34:49], v[58:61], v[138:141], v[34:49]
	global_load_dwordx4 v[50:53], v[100:101], off
	global_load_dwordx4 v[54:57], v[100:101], off offset:16
	global_load_dwordx4 v[74:77], v[66:67], off
	global_load_dwordx4 v[70:73], v[66:67], off offset:32
	v_lshl_add_u64 v[66:67], v[86:87], 0, v[84:85]
	v_add_co_u32_e32 v58, vcc, s97, v66
	v_add_u32_e32 v102, 0xfffffe90, v98
	s_nop 0
	v_addc_co_u32_e32 v59, vcc, 0, v67, vcc
	global_load_dwordx4 v[78:81], v[58:59], off
	global_load_dwordx4 v[66:69], v[58:59], off offset:32
	s_waitcnt vmcnt(6)
	v_mfma_f32_32x32x16_bf16 v[34:49], v[62:65], v[142:145], v[34:49]
	global_load_dwordx4 v[58:61], v[100:101], off offset:32
	global_load_dwordx4 v[62:65], v[100:101], off offset:48
	v_add_u32_e32 v103, 0xfffffea0, v98
	v_cmp_le_u32_e32 vcc, v102, v94
	v_add_u32_e32 v100, 0xfffffeb0, v98
	s_movk_i32 s2, 0x80f
	s_nop 5
	v_fma_f32 v34, v34, s86, -v96
	v_fma_f32 v35, v35, s86, -v96
	v_exp_f32_e32 v34, v34
	v_exp_f32_e32 v35, v35
	v_fma_f32 v36, v36, s86, -v96
	v_exp_f32_e32 v36, v36
	v_fma_f32 v37, v37, s86, -v96
	v_exp_f32_e32 v37, v37
	v_fma_f32 v38, v38, s86, -v96
	v_mul_f32_e32 v34, v97, v34
	v_exp_f32_e32 v38, v38
	v_fma_f32 v39, v39, s86, -v96
	v_mul_f32_e32 v35, v97, v35
	v_cndmask_b32_e32 v34, 0, v34, vcc
	v_cmp_le_u32_e32 vcc, v103, v94
	v_exp_f32_e32 v39, v39
	v_fma_f32 v40, v40, s86, -v96
	v_cndmask_b32_e32 v35, 0, v35, vcc
	v_mul_f32_e32 v36, v97, v36
	v_cmp_le_u32_e32 vcc, v100, v94
	v_add_u32_e32 v100, 0xfffffec0, v98
	v_exp_f32_e32 v40, v40
	v_fma_f32 v41, v41, s86, -v96
	v_cndmask_b32_e32 v36, 0, v36, vcc
	v_mul_f32_e32 v37, v97, v37
	v_cmp_le_u32_e32 vcc, v100, v94
	v_add_u32_e32 v100, 0xfffffed0, v98
	v_exp_f32_e32 v41, v41
	v_cndmask_b32_e32 v37, 0, v37, vcc
	v_mul_f32_e32 v38, v97, v38
	v_cmp_le_u32_e32 vcc, v100, v94
	v_add_u32_e32 v100, 0xfffffee0, v98
	v_fma_f32 v42, v42, s86, -v96
	v_cndmask_b32_e32 v38, 0, v38, vcc
	v_mul_f32_e32 v39, v97, v39
	v_cmp_le_u32_e32 vcc, v100, v94
	v_add_u32_e32 v100, 0xfffffef0, v98
	v_exp_f32_e32 v101, v42
	v_cndmask_b32_e32 v39, 0, v39, vcc
	v_mul_f32_e32 v40, v97, v40
	v_cmp_le_u32_e32 vcc, v100, v94
	v_add_u32_e32 v100, 0xffffff00, v98
	v_fma_f32 v43, v43, s86, -v96
	v_cndmask_b32_e32 v40, 0, v40, vcc
	v_mul_f32_e32 v41, v97, v41
	v_cmp_le_u32_e32 vcc, v100, v94
	v_exp_f32_e32 v43, v43
	v_fma_f32 v44, v44, s86, -v96
	v_cndmask_b32_e32 v42, 0, v41, vcc
	v_add_u32_e32 v41, 0xffffff90, v98
	v_exp_f32_e32 v44, v44
	v_fma_f32 v45, v45, s86, -v96
	v_mul_f32_e32 v100, v97, v101
	v_cmp_le_u32_e32 vcc, v41, v94
	v_exp_f32_e32 v45, v45
	v_fma_f32 v46, v46, s86, -v96
	v_cndmask_b32_e32 v41, 0, v100, vcc
	v_add_u32_e32 v100, 0xffffffa0, v98
	v_exp_f32_e32 v46, v46
	v_fma_f32 v47, v47, s86, -v96
	v_mul_f32_e32 v43, v97, v43
	v_cmp_le_u32_e32 vcc, v100, v94
	v_add_u32_e32 v100, 0xffffffb0, v98
	v_exp_f32_e32 v47, v47
	v_cndmask_b32_e32 v43, 0, v43, vcc
	v_mul_f32_e32 v44, v97, v44
	v_cmp_le_u32_e32 vcc, v100, v94
	v_subrev_u32_e32 v100, 64, v98
	v_mul_f32_e32 v45, v97, v45
	v_cndmask_b32_e32 v44, 0, v44, vcc
	v_cmp_le_u32_e32 vcc, v100, v94
	v_subrev_u32_e32 v100, 48, v98
	v_mul_f32_e32 v46, v97, v46
	v_cndmask_b32_e32 v45, 0, v45, vcc
	v_cmp_le_u32_e32 vcc, v100, v94
	v_subrev_u32_e32 v100, 32, v98
	v_fma_f32 v48, v48, s86, -v96
	v_cndmask_b32_e32 v46, 0, v46, vcc
	v_mul_f32_e32 v47, v97, v47
	v_cmp_le_u32_e32 vcc, v100, v94
	v_exp_f32_e32 v48, v48
	v_add_u32_e32 v100, -16, v98
	v_fma_f32 v49, v49, s86, -v96
	v_add_f32_e32 v101, v37, v38
	v_cndmask_b32_e32 v47, 0, v47, vcc
	v_exp_f32_e32 v49, v49
	v_cmp_le_u32_e32 vcc, v100, v94
	v_add_f32_e32 v100, v34, v35
	v_add_f32_e32 v101, v39, v101
	v_add_f32_e32 v100, v36, v100
	v_add_f32_e32 v101, v40, v101
	v_add_f32_e32 v100, v37, v100
	v_add_f32_e32 v101, v42, v101
	v_mul_f32_e32 v48, v97, v48
	ds_add_f32 v99, v100
	ds_add_f32 v99, v101 offset:4
	ds_add_f32 v99, v42 offset:8
	v_add_f32_e32 v100, v41, v43
	v_add_f32_e32 v101, v45, v46
	v_cndmask_b32_e32 v48, 0, v48, vcc
	v_mul_f32_e32 v49, v97, v49
	v_cmp_le_u32_e32 vcc, v98, v94
	v_add_f32_e32 v100, v44, v100
	v_add_f32_e32 v101, v47, v101
	v_cndmask_b32_e32 v49, 0, v49, vcc
	v_add_f32_e32 v100, v45, v100
	v_add_f32_e32 v101, v48, v101
	v_add_f32_e32 v101, v49, v101
	ds_add_f32 v99, v100 offset:16
	ds_add_f32 v99, v101 offset:20
	v_cmp_ne_u32_e32 vcc, s2, v98
	s_and_saveexec_b64 s[2:3], vcc
	s_cbranch_execz .LBB0_885
	ds_add_f32 v99, v49 offset:24
	s_branch .LBB0_885
.LBB0_888:
	v_ashrrev_i32_e32 v34, 3, v90
	v_and_b32_e32 v35, 7, v90
	s_lshr_b32 s15, s14, 6
	v_lshlrev_b32_e32 v36, 2, v35
	v_lshlrev_b32_e32 v38, 7, v34
	s_add_i32 s22, s15, -1
	v_cmp_ge_u32_e32 vcc, s15, v36
	v_mov_b32_e32 v37, 0xff800000
	v_lshl_add_u32 v44, v36, 2, v38
	v_mov_b32_e32 v38, 0xff800000
	s_waitcnt lgkmcnt(0)
	s_setprio 0
	s_barrier
	s_and_saveexec_b64 s[2:3], vcc
	s_cbranch_execz .LBB0_890
	ds_read2st64_b32 v[38:39], v44 offset1:16
	v_cmp_eq_u32_e32 vcc, 0, v35
	v_cmp_eq_u32_e64 s[38:39], s15, v36
	s_or_b64 s[38:39], vcc, s[38:39]
	v_cmp_eq_u32_e32 vcc, s22, v36
	s_waitcnt lgkmcnt(0)
	v_add_f32_e32 v40, v38, v39
	ds_read2st64_b32 v[38:39], v44 offset0:32 offset1:48
	s_or_b64 vcc, vcc, s[38:39]
	s_waitcnt lgkmcnt(0)
	v_add_f32_e32 v38, v40, v38
	v_add_f32_e32 v38, v38, v39
	v_cndmask_b32_e32 v38, v38, v224, vcc

.LBB0_912:
	v_cmp_eq_u32_e32 vcc, 0, v35
	s_and_saveexec_b64 s[2:3], vcc
	v_lshlrev_b32_e32 v34, 2, v34
	ds_write_b32 v34, v44 offset:20608
	s_or_b64 exec, exec, s[2:3]
	s_mov_b32 s41, s77
	s_lshl_b64 s[2:3], s[40:41], 8
	s_add_u32 s22, s9, s2
	s_addc_u32 s23, s10, s3
	s_lshl_b32 s17, s17, 7
	s_add_u32 s22, s22, s17
	s_addc_u32 s23, s23, 0
	s_lshl_b64 s[38:39], s[76:77], 18
	s_add_u32 s40, s11, s38
	s_addc_u32 s41, s12, s39
	v_lshlrev_b32_e32 v34, 2, v91
	s_waitcnt vmcnt(0)
	v_mov_b32_e32 v64, v206
	s_cmp_lt_u32 s14, 64
	s_waitcnt lgkmcnt(0)
	s_setprio 0
	s_barrier
	ds_read_b32 v171, v34 offset:20608
	s_cselect_b32 s17, 0, 64
	v_ashrrev_i32_e32 v50, 3, v64
	v_lshlrev_b32_e32 v34, 3, v64
	v_add_u32_e32 v42, 32, v50
	v_add_u32_e32 v60, s17, v50
	v_and_b32_e32 v36, 56, v34
	v_ashrrev_i32_e32 v51, 31, v50
	v_ashrrev_i32_e32 v43, 31, v42
	v_ashrrev_i32_e32 v61, 31, v60
	v_lshlrev_b64 v[52:53], 8, v[50:51]
	v_lshlrev_b32_e32 v172, 1, v36
	v_lshlrev_b64 v[36:37], 8, v[42:43]
	v_lshlrev_b64 v[54:55], 12, v[50:51]
	v_lshlrev_b64 v[42:43], 12, v[42:43]
	v_lshlrev_b64 v[60:61], 8, v[60:61]
	v_lshl_add_u64 v[34:35], s[22:23], 0, v[52:53]
	v_mov_b32_e32 v173, v1
	v_lshl_add_u64 v[36:37], s[22:23], 0, v[36:37]
	v_lshl_add_u64 v[56:57], s[40:41], 0, v[54:55]
	v_lshl_add_u64 v[58:59], s[40:41], 0, v[42:43]
	v_lshl_add_u64 v[60:61], s[22:23], 0, v[60:61]
	s_lshl_b32 s76, s17, 1
	v_lshl_add_u64 v[34:35], v[34:35], 0, v[172:173]
	v_lshl_add_u64 v[38:39], v[36:37], 0, v[172:173]
	v_lshl_add_u64 v[44:45], v[56:57], 0, v[172:173]
	v_lshl_add_u64 v[46:47], v[58:59], 0, v[172:173]
	v_lshl_add_u64 v[60:61], v[60:61], 0, v[172:173]
	s_movk_i32 s22, 0x2000
	v_lshl_add_u64 v[56:57], v[56:57], 0, s[76:77]
	s_waitcnt lgkmcnt(0)
	s_setprio 0
	s_barrier
	global_load_dwordx4 v[34:37], v[34:35], off
	s_nop 0
	global_load_dwordx4 v[38:41], v[38:39], off
	s_nop 0
	global_load_dwordx4 v[42:45], v[44:45], off
	s_nop 0
	global_load_dwordx4 v[46:49], v[46:47], off
	v_add_co_u32_e32 v62, vcc, s22, v60
	v_lshl_add_u64 v[56:57], v[56:57], 0, v[172:173]
	v_lshl_add_u64 v[58:59], v[58:59], 0, s[76:77]
	v_addc_co_u32_e32 v63, vcc, 0, v61, vcc
	v_lshl_add_u64 v[58:59], v[58:59], 0, v[172:173]
	global_load_dwordx4 v[154:157], v[56:57], off
	global_load_dwordx4 v[158:161], v[58:59], off
	global_load_dwordx4 v[146:149], v[60:61], off
	global_load_dwordx4 v[150:153], v[62:63], off
	s_or_b32 s17, s14, 31
	s_add_u32 s22, s18, s38
	s_addc_u32 s23, s19, s39
	s_lshl_b32 s16, s16, 1
	s_and_b32 s16, s16, 0x80
	s_add_u32 s16, s18, s16
	v_mul_lo_u32 v186, v50, s21
	v_lshl_add_u64 v[176:177], s[22:23], 0, v[54:55]
	s_addc_u32 s22, s19, 0
	v_lshrrev_b32_e32 v51, 2, v90
	v_add_u32_e32 v50, v186, v172
	s_add_u32 s2, s16, s2
	v_or_b32_e32 v56, 32, v92
	v_add_u32_e32 v57, s14, v91
	v_and_b32_e32 v183, 8, v51
	v_and_b32_e32 v51, 7, v64
	s_addc_u32 s3, s22, s3
	v_mul_u32_u24_e32 v184, 0x90, v56
	v_sub_u32_e32 v185, v57, v166
	v_lshlrev_b32_e32 v174, 4, v51
	v_lshl_add_u64 v[180:181], s[2:3], 0, v[52:53]
	v_mul_u32_u24_e32 v173, 0x90, v93
	v_mul_u32_u24_e32 v182, 0x90, v91
	v_mov_b32_e32 v175, v1
	v_mov_b32_e32 v187, 0
	v_mov_b32_e32 v188, 0
	v_mov_b32_e32 v189, 0xff800000
	s_mov_b32 s16, 63
	s_mov_b32 s22, 0
	s_waitcnt vmcnt(7)
	ds_write_b128 v50, v[34:37]
	s_waitcnt vmcnt(6)
	ds_write_b128 v50, v[38:41] offset:4608
	s_waitcnt vmcnt(5)
	ds_write_b128 v50, v[42:45] offset:9216
	s_waitcnt vmcnt(4)
	ds_write_b128 v50, v[46:49] offset:13824
	v_mov_b32_e32 v48, v1
	v_mov_b32_e32 v49, v1
	v_mov_b32_e32 v34, v1
	v_mov_b32_e32 v35, v1
	v_mov_b32_e32 v36, v1
	v_mov_b32_e32 v37, v1
	v_mov_b32_e32 v38, v1
	v_mov_b32_e32 v39, v1
	v_mov_b32_e32 v40, v1
	v_mov_b32_e32 v41, v1
	v_mov_b32_e32 v42, v1
	v_mov_b32_e32 v43, v1
	v_mov_b32_e32 v44, v1
	v_mov_b32_e32 v45, v1
	v_mov_b32_e32 v46, v1
	v_mov_b32_e32 v47, v1
	v_mov_b64_e32 v[64:65], v[48:49]
	v_mov_b64_e32 v[62:63], v[46:47]
	v_mov_b64_e32 v[60:61], v[44:45]
	v_mov_b64_e32 v[58:59], v[42:43]
	v_mov_b64_e32 v[56:57], v[40:41]
	v_mov_b64_e32 v[54:55], v[38:39]
	v_mov_b64_e32 v[52:53], v[36:37]
	v_mov_b64_e32 v[50:51], v[34:35]
	s_waitcnt lgkmcnt(0)
	s_setprio 0
	s_barrier
	s_and_b32 s23, s22, 1
	s_cmp_ge_u32 s22, s15
	s_cbranch_scc1 .LBB0_917
	s_branch .LBB0_916

.LBB0_924:
	s_mulk_i32 s23, 0x4800
	s_cmp_lt_i32 s76, 2
	s_mov_b64 s[2:3], -1
	s_cbranch_scc1 .LBB0_934
	s_cmp_gt_i32 s76, 2
	s_cbranch_scc0 .LBB0_929
	v_add3_u32 v74, s23, v170, v173
	s_setprio 1
	ds_read_b128 v[66:69], v74
	ds_read_b128 v[70:73], v74 offset:16
	v_add_f32_e32 v84, 0x40c00000, v189
	v_mov_b32_e32 v190, v189
	v_mov_b32_e32 v191, v188
	s_waitcnt lgkmcnt(1)
	v_mfma_f32_32x32x16_bf16 v[114:129], v[66:69], v[130:133], 0
	s_waitcnt lgkmcnt(0)
	v_mfma_f32_32x32x16_bf16 v[114:129], v[70:73], v[134:137], v[114:129]
	ds_read_b128 v[66:69], v74 offset:32
	ds_read_b128 v[70:73], v74 offset:48
	s_waitcnt lgkmcnt(1)
	v_mfma_f32_32x32x16_bf16 v[114:129], v[66:69], v[138:141], v[114:129]
	s_waitcnt lgkmcnt(0)
	v_mfma_f32_32x32x16_bf16 v[114:129], v[70:73], v[142:145], v[114:129]
	ds_read_b128 v[66:69], v74 offset:4608
	ds_read_b128 v[70:73], v74 offset:4624
	s_waitcnt lgkmcnt(1)
	v_mfma_f32_32x32x16_bf16 v[98:113], v[66:69], v[130:133], 0
	s_waitcnt lgkmcnt(0)
	v_mfma_f32_32x32x16_bf16 v[98:113], v[70:73], v[134:137], v[98:113]
	ds_read_b128 v[66:69], v74 offset:4640
	ds_read_b128 v[70:73], v74 offset:4656
	s_nop 3
	v_max3_f32 v74, v114, s85, v115
	s_waitcnt lgkmcnt(1)
	v_mfma_f32_32x32x16_bf16 v[98:113], v[66:69], v[138:141], v[98:113]
	v_max3_f32 v66, v74, v116, v117
	v_max3_f32 v66, v66, v118, v119
	v_max3_f32 v66, v66, v120, v121
	v_max3_f32 v66, v66, v122, v123
	v_max3_f32 v66, v66, v124, v125
	v_max3_f32 v66, v66, v126, v127
	v_max3_f32 v66, v66, v128, v129
	s_waitcnt lgkmcnt(0)
	v_mfma_f32_32x32x16_bf16 v[98:113], v[70:73], v[142:145], v[98:113]
	s_nop 11
	v_max3_f32 v66, v66, v98, v99
	v_max3_f32 v66, v66, v100, v101
	v_max3_f32 v66, v66, v102, v103
	v_max3_f32 v66, v66, v104, v105
	v_max3_f32 v66, v66, v106, v107
	v_max3_f32 v66, v66, v108, v109
	v_max3_f32 v66, v66, v110, v111
	v_max3_f32 v82, v66, v112, v113
	ds_bpermute_b32 v83, v167, v82
	v_mov_b64_e32 v[80:81], v[48:49]
	v_mov_b64_e32 v[78:79], v[46:47]
	v_mov_b64_e32 v[76:77], v[44:45]
	v_mov_b64_e32 v[74:75], v[42:43]
	s_waitcnt lgkmcnt(0)
	v_max_f32_e32 v83, v83, v83
	v_max_f32_e32 v82, v82, v83
	v_mul_f32_e32 v82, 0x3e38aa3b, v82
	v_cndmask_b32_e64 v192, v220, v82, s[38:39]
	v_cmp_gt_f32_e32 vcc, v192, v84
	v_mov_b64_e32 v[96:97], v[64:65]
	v_mov_b64_e32 v[72:73], v[40:41]
	v_mov_b64_e32 v[70:71], v[38:39]
	v_mov_b64_e32 v[68:69], v[36:37]
	v_mov_b64_e32 v[66:67], v[34:35]
	v_mov_b64_e32 v[94:95], v[62:63]
	v_mov_b64_e32 v[92:93], v[60:61]
	v_mov_b64_e32 v[90:91], v[58:59]
	v_mov_b64_e32 v[88:89], v[56:57]
	v_mov_b64_e32 v[86:87], v[54:55]
	v_mov_b64_e32 v[84:85], v[52:53]
	v_mov_b64_e32 v[82:83], v[50:51]
	s_cbranch_vccz .LBB0_928
	v_cndmask_b32_e32 v190, v189, v192, vcc
	v_sub_f32_e32 v66, v189, v190
	v_exp_f32_e32 v66, v66
	s_nop 0
	v_cndmask_b32_e32 v82, 1.0, v66, vcc
	v_mul_f32_e32 v191, v188, v82
	v_pk_mul_f32 v[80:81], v[48:49], v[82:83] op_sel_hi:[1,0]
	v_pk_mul_f32 v[78:79], v[46:47], v[82:83] op_sel_hi:[1,0]
	v_pk_mul_f32 v[76:77], v[44:45], v[82:83] op_sel_hi:[1,0]
	v_pk_mul_f32 v[74:75], v[42:43], v[82:83] op_sel_hi:[1,0]
	v_pk_mul_f32 v[72:73], v[40:41], v[82:83] op_sel_hi:[1,0]
	v_pk_mul_f32 v[70:71], v[38:39], v[82:83] op_sel_hi:[1,0]
	v_pk_mul_f32 v[68:69], v[36:37], v[82:83] op_sel_hi:[1,0]
	v_pk_mul_f32 v[66:67], v[34:35], v[82:83] op_sel_hi:[1,0]
	v_pk_mul_f32 v[96:97], v[64:65], v[82:83] op_sel_hi:[1,0]
	v_pk_mul_f32 v[94:95], v[62:63], v[82:83] op_sel_hi:[1,0]
	v_pk_mul_f32 v[92:93], v[60:61], v[82:83] op_sel_hi:[1,0]
	v_pk_mul_f32 v[90:91], v[58:59], v[82:83] op_sel_hi:[1,0]
	v_pk_mul_f32 v[88:89], v[56:57], v[82:83] op_sel_hi:[1,0]
	v_pk_mul_f32 v[86:87], v[54:55], v[82:83] op_sel_hi:[1,0]
	v_pk_mul_f32 v[84:85], v[52:53], v[82:83] op_sel_hi:[1,0]
	v_pk_mul_f32 v[82:83], v[50:51], v[82:83] op_sel_hi:[1,0]
.LBB0_928:
	v_cmp_neq_f32_e32 vcc, s85, v190
	s_mov_b64 s[2:3], 0
	s_nop 0
	v_cndmask_b32_e64 v192, 0, -v190, vcc
	v_cndmask_b32_e64 v192, v220, v192, s[38:39]
	v_fmamk_f32 v114, v114, 0x3e38aa3b, v192
	v_exp_f32_e32 v114, v114
	v_fmamk_f32 v115, v115, 0x3e38aa3b, v192
	v_exp_f32_e32 v193, v115
	v_fmamk_f32 v115, v116, 0x3e38aa3b, v192
	v_exp_f32_e32 v115, v115
	v_fmamk_f32 v116, v117, 0x3e38aa3b, v192
	v_exp_f32_e32 v194, v116
	v_fmamk_f32 v117, v118, 0x3e38aa3b, v192
	v_add_f32_e32 v116, 0, v114
	v_exp_f32_e32 v118, v117
	v_fmamk_f32 v117, v119, 0x3e38aa3b, v192
	v_add_f32_e32 v116, v193, v116
	v_exp_f32_e32 v119, v117
	v_fmamk_f32 v117, v120, 0x3e38aa3b, v192
	v_add_f32_e32 v116, v115, v116
	v_exp_f32_e32 v117, v117
	v_fmamk_f32 v120, v121, 0x3e38aa3b, v192
	v_add_f32_e32 v116, v194, v116
	v_exp_f32_e32 v120, v120
	v_fmamk_f32 v121, v122, 0x3e38aa3b, v192
	v_add_f32_e32 v116, v118, v116
	v_exp_f32_e32 v122, v121
	v_fmamk_f32 v121, v123, 0x3e38aa3b, v192
	v_add_f32_e32 v116, v119, v116
	v_exp_f32_e32 v123, v121
	v_fmamk_f32 v121, v124, 0x3e38aa3b, v192
	v_add_f32_e32 v116, v117, v116
	v_exp_f32_e32 v124, v121
	v_fmamk_f32 v121, v125, 0x3e38aa3b, v192
	v_add_f32_e32 v116, v120, v116
	v_exp_f32_e32 v125, v121
	v_fmamk_f32 v121, v126, 0x3e38aa3b, v192
	v_add_f32_e32 v116, v122, v116
	v_exp_f32_e32 v126, v121
	v_fmamk_f32 v121, v127, 0x3e38aa3b, v192
	v_add_f32_e32 v116, v123, v116
	v_exp_f32_e32 v127, v121
	v_fmamk_f32 v121, v128, 0x3e38aa3b, v192
	v_add_f32_e32 v116, v124, v116
	v_exp_f32_e32 v128, v121
	v_fmamk_f32 v121, v129, 0x3e38aa3b, v192
	v_add_f32_e32 v116, v125, v116
	v_exp_f32_e32 v129, v121
	v_fmamk_f32 v98, v98, 0x3e38aa3b, v192
	v_add_f32_e32 v116, v126, v116
	v_exp_f32_e32 v195, v98
	v_fmamk_f32 v98, v99, 0x3e38aa3b, v192
	v_add_f32_e32 v116, v127, v116
	v_exp_f32_e32 v196, v98
	v_fmamk_f32 v98, v100, 0x3e38aa3b, v192
	v_add_f32_e32 v116, v128, v116
	v_exp_f32_e32 v197, v98
	v_fmamk_f32 v98, v101, 0x3e38aa3b, v192
	v_add_f32_e32 v116, v129, v116
	v_exp_f32_e32 v198, v98
	v_add_f32_e32 v98, v195, v116
	v_add_f32_e32 v98, v196, v98
	v_add_f32_e32 v98, v197, v98
	v_add_f32_e32 v199, v198, v98
	v_fmamk_f32 v98, v102, 0x3e38aa3b, v192
	v_lshlrev_b32_e32 v102, 1, v183
	v_exp_f32_e32 v200, v98
	v_fmamk_f32 v98, v103, 0x3e38aa3b, v192
	v_add3_u32 v202, s23, v182, v102
	v_exp_f32_e32 v201, v98
	s_setprio 1
	ds_read_b128 v[98:101], v202 offset:9216
	v_fmamk_f32 v103, v104, 0x3e38aa3b, v192
	v_add3_u32 v204, s23, v184, v102
	v_cvt_pk_bf16_f32 v117, v117, v120
	v_cvt_pk_bf16_f32 v116, v118, v119
	v_cvt_pk_bf16_f32 v115, v115, v194
	v_cvt_pk_bf16_f32 v114, v114, v193
	v_exp_f32_e32 v203, v103
	ds_read_b128 v[118:121], v204 offset:9216
	s_waitcnt lgkmcnt(1)
	v_mfma_f32_32x32x16_bf16 v[66:81], v[98:101], v[114:117], v[66:81]
	v_fmamk_f32 v98, v105, 0x3e38aa3b, v192
	v_exp_f32_e32 v193, v98
	v_add_f32_e32 v98, v200, v199
	v_add_f32_e32 v98, v201, v98
	v_add_f32_e32 v98, v203, v98
	v_add_f32_e32 v194, v193, v98
	ds_read_b128 v[98:101], v202 offset:9248
	v_fmamk_f32 v102, v106, 0x3e38aa3b, v192
	s_waitcnt lgkmcnt(1)
	v_mfma_f32_32x32x16_bf16 v[82:97], v[118:121], v[114:117], v[82:97]
	v_exp_f32_e32 v118, v102
	ds_read_b128 v[102:105], v204 offset:9248
	v_cvt_pk_bf16_f32 v117, v128, v129
	v_cvt_pk_bf16_f32 v116, v126, v127
	v_cvt_pk_bf16_f32 v115, v124, v125
	v_cvt_pk_bf16_f32 v114, v122, v123
	v_fmamk_f32 v122, v109, 0x3e38aa3b, v192
	v_add_f32_e32 v119, v118, v194
	s_waitcnt lgkmcnt(1)
	v_mfma_f32_32x32x16_bf16 v[66:81], v[98:101], v[114:117], v[66:81]
	v_fmamk_f32 v98, v107, 0x3e38aa3b, v192
	v_exp_f32_e32 v120, v98
	v_fmamk_f32 v98, v108, 0x3e38aa3b, v192
	v_exp_f32_e32 v121, v98
	ds_read_b128 v[98:101], v202 offset:9280
	ds_read_b128 v[106:109], v204 offset:9280
	s_waitcnt lgkmcnt(2)
	v_mfma_f32_32x32x16_bf16 v[82:97], v[102:105], v[114:117], v[82:97]
	v_fmamk_f32 v102, v110, 0x3e38aa3b, v192
	v_exp_f32_e32 v110, v102
	v_cvt_pk_bf16_f32 v105, v203, v193
	v_cvt_pk_bf16_f32 v104, v200, v201
	v_cvt_pk_bf16_f32 v103, v197, v198
	v_cvt_pk_bf16_f32 v102, v195, v196
	v_exp_f32_e32 v114, v122
	v_add_f32_e32 v115, v120, v119
	s_waitcnt lgkmcnt(1)
	v_mfma_f32_32x32x16_bf16 v[66:81], v[98:101], v[102:105], v[66:81]
	v_fmamk_f32 v98, v111, 0x3e38aa3b, v192
	v_exp_f32_e32 v111, v98
	v_fmamk_f32 v98, v112, 0x3e38aa3b, v192
	v_exp_f32_e32 v112, v98
	ds_read_b128 v[98:101], v202 offset:9312
	v_fmac_f32_e32 v192, 0x3e38aa3b, v113
	v_exp_f32_e32 v113, v192
	s_waitcnt lgkmcnt(1)
	v_mfma_f32_32x32x16_bf16 v[82:97], v[106:109], v[102:105], v[82:97]
	ds_read_b128 v[106:109], v204 offset:9312
	v_cvt_pk_bf16_f32 v104, v110, v111
	v_cvt_pk_bf16_f32 v105, v112, v113
	v_cvt_pk_bf16_f32 v103, v121, v114
	v_cvt_pk_bf16_f32 v102, v118, v120
	s_waitcnt lgkmcnt(1)
	s_nop 0
	v_mfma_f32_32x32x16_bf16 v[66:81], v[98:101], v[102:105], v[66:81]
	v_add_f32_e32 v98, v121, v115
	v_add_f32_e32 v98, v114, v98
	v_add_f32_e32 v98, v110, v98
	v_add_f32_e32 v98, v111, v98
	v_add_f32_e32 v98, v112, v98
	v_add_f32_e32 v98, v113, v98
	v_add_f32_e32 v98, v191, v98
	s_waitcnt lgkmcnt(0)
	v_mfma_f32_32x32x16_bf16 v[82:97], v[106:109], v[102:105], v[82:97]
.LBB0_929:
	s_and_b64 vcc, exec, s[2:3]
	s_cbranch_vccz .LBB0_933
	s_nop 0
	v_add3_u32 v78, s23, v170, v173
	s_setprio 1
	ds_read_b128 v[66:69], v78
	ds_read_b128 v[70:73], v78 offset:16
	v_cmp_lt_i32_e32 vcc, -1, v187
	v_cmp_gt_i32_e64 s[38:39], 1, v187
	v_cmp_gt_i32_e64 s[40:41], 32, v187
	s_waitcnt lgkmcnt(1)
	v_mfma_f32_32x32x16_bf16 v[98:113], v[66:69], v[130:133], 0
	v_cmp_gt_i32_e64 s[42:43], 33, v187
	v_cmp_gt_i32_e64 s[44:45], 34, v187
	v_cmp_gt_i32_e64 s[46:47], 35, v187
	v_cmp_gt_i32_e64 s[48:49], 36, v187
	v_cmp_gt_i32_e64 s[50:51], 37, v187
	v_cmp_gt_i32_e64 s[52:53], 38, v187
	v_cmp_gt_i32_e64 s[56:57], 39, v187
	s_waitcnt lgkmcnt(0)
	v_mfma_f32_32x32x16_bf16 v[98:113], v[70:73], v[134:137], v[98:113]
	ds_read_b128 v[66:69], v78 offset:32
	ds_read_b128 v[70:73], v78 offset:48
	v_cmp_gt_i32_e64 s[58:59], 48, v187
	v_cmp_gt_i32_e64 s[60:61], 49, v187
	v_cmp_gt_i32_e64 s[62:63], 50, v187
	v_cmp_gt_i32_e64 s[64:65], 51, v187
	v_cmp_gt_i32_e64 s[66:67], 52, v187
	v_cmp_gt_i32_e64 s[68:69], 53, v187
	s_waitcnt lgkmcnt(1)
	v_mfma_f32_32x32x16_bf16 v[98:113], v[66:69], v[138:141], v[98:113]
	ds_read_b128 v[66:69], v78 offset:4608
	ds_read_b128 v[74:77], v78 offset:4624
	v_cmp_gt_i32_e64 s[70:71], 54, v187
	v_cmp_gt_i32_e64 s[54:55], 55, v187
	v_mov_b64_e32 v[96:97], v[64:65]
	v_mov_b32_e32 v190, v189
	v_mov_b64_e32 v[94:95], v[62:63]
	v_mov_b64_e32 v[92:93], v[60:61]
	s_waitcnt lgkmcnt(1)
	v_mfma_f32_32x32x16_bf16 v[114:129], v[66:69], v[130:133], 0
	ds_read_b128 v[66:69], v78 offset:4640
	ds_read_b128 v[78:81], v78 offset:4656
	v_mov_b64_e32 v[90:91], v[58:59]
	v_mov_b64_e32 v[88:89], v[56:57]
	v_mov_b64_e32 v[86:87], v[54:55]
	v_mov_b64_e32 v[84:85], v[52:53]
	v_mov_b64_e32 v[82:83], v[50:51]
	s_waitcnt lgkmcnt(2)
	v_mfma_f32_32x32x16_bf16 v[114:129], v[74:77], v[134:137], v[114:129]
	v_mfma_f32_32x32x16_bf16 v[98:113], v[70:73], v[142:145], v[98:113]
	s_waitcnt lgkmcnt(1)
	v_mfma_f32_32x32x16_bf16 v[114:129], v[66:69], v[138:141], v[114:129]
	s_nop 9
	v_cndmask_b32_e32 v195, v220, v98, vcc
	v_cmp_lt_i32_e32 vcc, 1, v187
	v_cndmask_b32_e64 v191, v99, v220, s[38:39]
	v_max3_f32 v70, v195, s85, v191
	v_cndmask_b32_e32 v192, v220, v100, vcc
	v_cmp_lt_i32_e32 vcc, 2, v187
	v_mov_b32_e32 v99, v188
	s_waitcnt lgkmcnt(0)
	v_mfma_f32_32x32x16_bf16 v[114:129], v[78:81], v[142:145], v[114:129]
	v_cndmask_b32_e32 v193, v220, v101, vcc
	v_cmp_lt_i32_e32 vcc, 3, v187
	v_max3_f32 v70, v70, v192, v193
	s_nop 0
	v_cndmask_b32_e32 v194, v220, v102, vcc
	v_cmp_lt_i32_e32 vcc, 4, v187
	s_nop 5
	v_cndmask_b32_e64 v196, v115, v220, s[42:43]
	v_cndmask_b32_e32 v101, v220, v103, vcc
	v_cmp_lt_i32_e32 vcc, 5, v187
	v_max3_f32 v70, v70, v194, v101
	v_cndmask_b32_e64 v197, v116, v220, s[44:45]
	v_cndmask_b32_e32 v102, v220, v104, vcc
	v_cmp_lt_i32_e32 vcc, 6, v187
	v_cndmask_b32_e64 v198, v117, v220, s[46:47]
	v_cndmask_b32_e64 v199, v118, v220, s[48:49]
	v_cndmask_b32_e32 v103, v220, v105, vcc
	v_cmp_lt_i32_e32 vcc, 15, v187
	v_max3_f32 v70, v70, v102, v103
	v_cndmask_b32_e64 v200, v119, v220, s[50:51]
	v_cndmask_b32_e32 v105, v220, v106, vcc
	v_cmp_lt_i32_e32 vcc, 16, v187
	v_cndmask_b32_e64 v202, v120, v220, s[52:53]
	v_cndmask_b32_e64 v203, v121, v220, s[56:57]
	v_cndmask_b32_e32 v104, v220, v107, vcc
	v_cmp_lt_i32_e32 vcc, 17, v187
	v_max3_f32 v70, v70, v105, v104
	v_cndmask_b32_e64 v204, v122, v220, s[58:59]
	v_cndmask_b32_e32 v106, v220, v108, vcc
	v_cmp_lt_i32_e32 vcc, 18, v187
	v_cndmask_b32_e64 v205, v123, v220, s[60:61]
	v_cndmask_b32_e64 v226, v124, v220, s[62:63]
	v_cndmask_b32_e32 v107, v220, v109, vcc
	v_cmp_lt_i32_e32 vcc, 19, v187
	v_max3_f32 v70, v70, v106, v107
	v_cndmask_b32_e64 v227, v125, v220, s[64:65]
	v_cndmask_b32_e32 v108, v220, v110, vcc
	v_cmp_lt_i32_e32 vcc, 20, v187
	v_cndmask_b32_e64 v228, v126, v220, s[66:67]
	v_cndmask_b32_e64 v229, v127, v220, s[68:69]
	v_cndmask_b32_e32 v109, v220, v111, vcc
	v_cmp_lt_i32_e32 vcc, 21, v187
	v_max3_f32 v66, v70, v108, v109
	v_cndmask_b32_e64 v201, v128, v220, s[70:71]
	v_cndmask_b32_e32 v110, v220, v112, vcc
	v_cmp_lt_i32_e32 vcc, 22, v187
	v_cndmask_b32_e64 v112, v114, v220, s[40:41]
	v_cndmask_b32_e64 v100, v129, v220, s[54:55]
	v_cndmask_b32_e32 v111, v220, v113, vcc
	v_max3_f32 v66, v66, v110, v111
	v_max3_f32 v66, v66, v112, v196
	v_max3_f32 v66, v66, v197, v198
	v_max3_f32 v66, v66, v199, v200
	v_max3_f32 v66, v66, v202, v203
	v_max3_f32 v66, v66, v204, v205
	v_max3_f32 v66, v66, v226, v227
	v_max3_f32 v66, v66, v228, v229
	v_max3_f32 v66, v66, v201, v100
	ds_bpermute_b32 v67, v167, v66
	s_waitcnt lgkmcnt(0)
	v_max_f32_e32 v67, v67, v67
	v_max_f32_e32 v66, v66, v67
	v_mul_f32_e32 v129, 0x3e38aa3b, v66
	v_add_f32_e32 v66, 0x40c00000, v189
	v_cmp_gt_f32_e32 vcc, v129, v66
	v_mov_b64_e32 v[80:81], v[48:49]
	v_mov_b64_e32 v[78:79], v[46:47]
	v_mov_b64_e32 v[76:77], v[44:45]
	v_mov_b64_e32 v[74:75], v[42:43]
	v_mov_b64_e32 v[72:73], v[40:41]
	v_mov_b64_e32 v[70:71], v[38:39]
	v_mov_b64_e32 v[68:69], v[36:37]
	v_mov_b64_e32 v[66:67], v[34:35]
	s_cbranch_vccz .LBB0_932
	v_cndmask_b32_e32 v190, v189, v129, vcc
	v_sub_f32_e32 v66, v189, v190
	v_exp_f32_e32 v66, v66
	s_nop 0
	v_cndmask_b32_e32 v82, 1.0, v66, vcc
	v_mul_f32_e32 v99, v188, v82
	v_pk_mul_f32 v[80:81], v[48:49], v[82:83] op_sel_hi:[1,0]
	v_pk_mul_f32 v[78:79], v[46:47], v[82:83] op_sel_hi:[1,0]
	v_pk_mul_f32 v[76:77], v[44:45], v[82:83] op_sel_hi:[1,0]
	v_pk_mul_f32 v[74:75], v[42:43], v[82:83] op_sel_hi:[1,0]
	v_pk_mul_f32 v[72:73], v[40:41], v[82:83] op_sel_hi:[1,0]
	v_pk_mul_f32 v[70:71], v[38:39], v[82:83] op_sel_hi:[1,0]
	v_pk_mul_f32 v[68:69], v[36:37], v[82:83] op_sel_hi:[1,0]
	v_pk_mul_f32 v[66:67], v[34:35], v[82:83] op_sel_hi:[1,0]
	v_pk_mul_f32 v[96:97], v[64:65], v[82:83] op_sel_hi:[1,0]
	v_pk_mul_f32 v[94:95], v[62:63], v[82:83] op_sel_hi:[1,0]
	v_pk_mul_f32 v[92:93], v[60:61], v[82:83] op_sel_hi:[1,0]
	v_pk_mul_f32 v[90:91], v[58:59], v[82:83] op_sel_hi:[1,0]
	v_pk_mul_f32 v[88:89], v[56:57], v[82:83] op_sel_hi:[1,0]
	v_pk_mul_f32 v[86:87], v[54:55], v[82:83] op_sel_hi:[1,0]
	v_pk_mul_f32 v[84:85], v[52:53], v[82:83] op_sel_hi:[1,0]
	v_pk_mul_f32 v[82:83], v[50:51], v[82:83] op_sel_hi:[1,0]
.LBB0_932:
	s_and_b64 vcc, s[54:55], s[70:71]
	v_cndmask_b32_e32 v127, v127, v229, vcc
	s_and_b64 vcc, vcc, s[68:69]
	v_cndmask_b32_e32 v126, v126, v228, vcc
	s_and_b64 vcc, vcc, s[66:67]
	v_cndmask_b32_e32 v125, v125, v227, vcc
	s_and_b64 vcc, vcc, s[64:65]
	v_cndmask_b32_e32 v124, v124, v226, vcc
	s_and_b64 vcc, vcc, s[62:63]
	v_cndmask_b32_e32 v123, v123, v205, vcc
	s_and_b64 vcc, vcc, s[60:61]
	v_cndmask_b32_e32 v122, v122, v204, vcc
	s_and_b64 vcc, vcc, s[58:59]
	v_cndmask_b32_e32 v121, v121, v203, vcc
	s_and_b64 vcc, vcc, s[56:57]
	v_cndmask_b32_e32 v120, v120, v202, vcc
	s_and_b64 vcc, vcc, s[52:53]
	v_cndmask_b32_e32 v119, v119, v200, vcc
	s_and_b64 vcc, vcc, s[50:51]
	v_cndmask_b32_e32 v118, v118, v199, vcc
	s_and_b64 vcc, vcc, s[48:49]
	v_cndmask_b32_e64 v98, v98, v195, s[38:39]
	v_cndmask_b32_e32 v117, v117, v198, vcc
	s_and_b64 vcc, vcc, s[46:47]
	v_cmp_neq_f32_e64 s[38:39], s85, v190
	v_cndmask_b32_e32 v116, v116, v197, vcc
	s_and_b64 vcc, vcc, s[44:45]
	v_cndmask_b32_e64 v129, 0, -v190, s[38:39]
	v_cndmask_b32_e32 v115, v115, v196, vcc
	s_and_b64 vcc, vcc, s[42:43]
	v_fmamk_f32 v98, v98, 0x3e38aa3b, v129
	v_cndmask_b32_e32 v112, v114, v112, vcc
	v_exp_f32_e32 v98, v98
	v_fmamk_f32 v114, v191, 0x3e38aa3b, v129
	v_exp_f32_e32 v114, v114
	v_fmamk_f32 v191, v192, 0x3e38aa3b, v129
	v_exp_f32_e32 v191, v191
	v_fmamk_f32 v192, v193, 0x3e38aa3b, v129
	s_and_b64 vcc, vcc, s[40:41]
	v_exp_f32_e32 v192, v192
	v_fmamk_f32 v193, v194, 0x3e38aa3b, v129
	v_cndmask_b32_e32 v111, v113, v111, vcc
	v_add_f32_e32 v113, 0, v98
	v_exp_f32_e32 v193, v193
	v_fmamk_f32 v101, v101, 0x3e38aa3b, v129
	v_add_f32_e32 v113, v114, v113
	v_exp_f32_e32 v101, v101
	v_fmamk_f32 v102, v102, 0x3e38aa3b, v129
	v_add_f32_e32 v113, v191, v113
	v_exp_f32_e32 v194, v102
	v_fmamk_f32 v102, v103, 0x3e38aa3b, v129
	v_add_f32_e32 v113, v192, v113
	v_exp_f32_e32 v195, v102
	v_fmamk_f32 v102, v105, 0x3e38aa3b, v129
	v_add_f32_e32 v113, v193, v113
	v_exp_f32_e32 v196, v102
	v_fmamk_f32 v103, v104, 0x3e38aa3b, v129
	v_add_f32_e32 v102, v101, v113
	v_exp_f32_e32 v197, v103
	v_fmamk_f32 v103, v106, 0x3e38aa3b, v129
	v_add_f32_e32 v102, v194, v102
	v_exp_f32_e32 v198, v103
	v_fmamk_f32 v103, v107, 0x3e38aa3b, v129
	v_add_f32_e32 v102, v195, v102
	v_exp_f32_e32 v199, v103
	v_fmamk_f32 v103, v108, 0x3e38aa3b, v129
	v_add_f32_e32 v102, v196, v102
	v_exp_f32_e32 v200, v103
	v_fmamk_f32 v103, v109, 0x3e38aa3b, v129
	v_cndmask_b32_e64 v128, v128, v201, s[54:55]
	v_add_f32_e32 v102, v197, v102
	v_exp_f32_e32 v201, v103
	v_fmamk_f32 v103, v110, 0x3e38aa3b, v129
	v_add_f32_e32 v102, v198, v102
	v_exp_f32_e32 v202, v103
	v_fmamk_f32 v103, v111, 0x3e38aa3b, v129
	v_add_f32_e32 v102, v199, v102
	v_exp_f32_e32 v203, v103
	v_fmamk_f32 v103, v112, 0x3e38aa3b, v129
	v_add_f32_e32 v102, v200, v102
	v_exp_f32_e32 v204, v103
	v_fmamk_f32 v103, v115, 0x3e38aa3b, v129
	v_add_f32_e32 v102, v201, v102
	v_exp_f32_e32 v205, v103
	v_fmamk_f32 v103, v116, 0x3e38aa3b, v129
	v_add_f32_e32 v102, v202, v102
	v_exp_f32_e32 v226, v103
	v_fmamk_f32 v103, v117, 0x3e38aa3b, v129
	v_add_f32_e32 v102, v203, v102
	v_exp_f32_e32 v227, v103
	v_fmamk_f32 v103, v118, 0x3e38aa3b, v129
	v_add_f32_e32 v102, v204, v102
	v_exp_f32_e32 v118, v103
	v_add_f32_e32 v102, v205, v102
	v_add_f32_e32 v102, v226, v102
	v_lshlrev_b32_e32 v107, 1, v183
	v_add_f32_e32 v102, v227, v102
	v_fmamk_f32 v106, v119, 0x3e38aa3b, v129
	v_add3_u32 v119, s23, v182, v107
	v_add_f32_e32 v228, v118, v102
	s_setprio 1
	ds_read_b128 v[102:105], v119 offset:9216
	v_exp_f32_e32 v229, v106
	v_add3_u32 v230, s23, v184, v107
	v_cvt_pk_bf16_f32 v109, v194, v195
	v_cvt_pk_bf16_f32 v108, v193, v101
	v_cvt_pk_bf16_f32 v107, v191, v192
	v_cvt_pk_bf16_f32 v106, v98, v114
	ds_read_b128 v[110:113], v119 offset:9248
	ds_read_b128 v[114:117], v230 offset:9216
	s_waitcnt lgkmcnt(2)
	v_mfma_f32_32x32x16_bf16 v[66:81], v[102:105], v[106:109], v[66:81]
	v_fmamk_f32 v102, v121, 0x3e38aa3b, v129
	v_fmamk_f32 v98, v120, 0x3e38aa3b, v129
	v_exp_f32_e32 v120, v102
	ds_read_b128 v[102:105], v230 offset:9248
	v_exp_f32_e32 v98, v98
	v_add_f32_e32 v101, v229, v228
	v_add_f32_e32 v101, v98, v101
	s_waitcnt lgkmcnt(1)
	v_mfma_f32_32x32x16_bf16 v[82:97], v[114:117], v[106:109], v[82:97]
	v_fmamk_f32 v106, v122, 0x3e38aa3b, v129
	v_exp_f32_e32 v121, v106
	v_cvt_pk_bf16_f32 v109, v202, v203
	v_cvt_pk_bf16_f32 v108, v200, v201
	v_cvt_pk_bf16_f32 v107, v198, v199
	v_cvt_pk_bf16_f32 v106, v196, v197
	v_add_f32_e32 v101, v120, v101
	v_add_f32_e32 v101, v121, v101
	v_mfma_f32_32x32x16_bf16 v[66:81], v[110:113], v[106:109], v[66:81]
	v_fmamk_f32 v110, v123, 0x3e38aa3b, v129
	v_exp_f32_e32 v122, v110
	v_fmamk_f32 v110, v124, 0x3e38aa3b, v129
	v_exp_f32_e32 v123, v110
	ds_read_b128 v[110:113], v119 offset:9280
	v_fmamk_f32 v124, v125, 0x3e38aa3b, v129
	v_fmamk_f32 v125, v126, 0x3e38aa3b, v129
	s_waitcnt lgkmcnt(1)
	v_mfma_f32_32x32x16_bf16 v[82:97], v[102:105], v[106:109], v[82:97]
	ds_read_b128 v[106:109], v230 offset:9280
	ds_read_b128 v[114:117], v119 offset:9312
	v_cvt_pk_bf16_f32 v105, v98, v120
	v_cvt_pk_bf16_f32 v104, v118, v229
	v_cvt_pk_bf16_f32 v103, v226, v227
	v_cvt_pk_bf16_f32 v102, v204, v205
	v_fmamk_f32 v118, v127, 0x3e38aa3b, v129
	v_exp_f32_e32 v98, v125
	s_waitcnt lgkmcnt(2)
	v_mfma_f32_32x32x16_bf16 v[66:81], v[110:113], v[102:105], v[66:81]
	v_fmamk_f32 v110, v128, 0x3e38aa3b, v129
	v_exp_f32_e32 v119, v110
	ds_read_b128 v[110:113], v230 offset:9312
	v_fmac_f32_e32 v129, 0x3e38aa3b, v100
	v_exp_f32_e32 v120, v129
	v_cvt_pk_bf16_f32 v100, v121, v122
	s_waitcnt lgkmcnt(2)
	v_mfma_f32_32x32x16_bf16 v[82:97], v[106:109], v[102:105], v[82:97]
	v_exp_f32_e32 v104, v118
	v_exp_f32_e32 v105, v124
	v_add_f32_e32 v106, v122, v101
	v_cvt_pk_bf16_f32 v103, v119, v120
	v_cvt_pk_bf16_f32 v102, v98, v104
	v_cvt_pk_bf16_f32 v101, v123, v105
	v_add_f32_e32 v106, v123, v106
	v_add_f32_e32 v105, v105, v106
	s_waitcnt lgkmcnt(1)
	v_mfma_f32_32x32x16_bf16 v[66:81], v[114:117], v[100:103], v[66:81]
	v_add_f32_e32 v98, v98, v105
	v_add_f32_e32 v98, v104, v98
	v_add_f32_e32 v98, v119, v98
	v_add_f32_e32 v98, v120, v98
	v_add_f32_e32 v98, v99, v98
	s_waitcnt lgkmcnt(0)
	v_mfma_f32_32x32x16_bf16 v[82:97], v[110:113], v[100:103], v[82:97]

.LBB0_934:
	s_andn2_b64 vcc, exec, s[2:3]
	s_cbranch_vccnz .LBB0_940
	s_cmp_lg_u32 s76, 1
	s_cbranch_scc1 .LBB0_939
	v_add3_u32 v102, s23, v170, v173
	s_setprio 1
	ds_read_b128 v[66:69], v102
	ds_read_b128 v[70:73], v102 offset:16
	ds_read_b128 v[74:77], v102 offset:32
	ds_read_b128 v[78:81], v102 offset:48
	s_waitcnt lgkmcnt(3)
	v_mfma_f32_32x32x16_bf16 v[82:97], v[66:69], v[130:133], 0
	ds_read_b128 v[66:69], v102 offset:4608
	ds_read_b128 v[98:101], v102 offset:4624
	s_waitcnt lgkmcnt(4)
	v_mfma_f32_32x32x16_bf16 v[82:97], v[70:73], v[134:137], v[82:97]
	s_waitcnt lgkmcnt(3)
	v_mfma_f32_32x32x16_bf16 v[82:97], v[74:77], v[138:141], v[82:97]
	s_waitcnt lgkmcnt(2)
	v_mfma_f32_32x32x16_bf16 v[82:97], v[78:81], v[142:145], v[82:97]
	s_waitcnt lgkmcnt(1)
	v_mfma_f32_32x32x16_bf16 v[66:81], v[66:69], v[130:133], 0
	s_waitcnt lgkmcnt(0)
	v_mfma_f32_32x32x16_bf16 v[66:81], v[98:101], v[134:137], v[66:81]
	ds_read_b128 v[98:101], v102 offset:4640
	s_waitcnt lgkmcnt(0)
	v_mfma_f32_32x32x16_bf16 v[66:81], v[98:101], v[138:141], v[66:81]
	ds_read_b128 v[98:101], v102 offset:4656
	s_waitcnt lgkmcnt(0)
	v_mfma_f32_32x32x16_bf16 v[66:81], v[98:101], v[142:145], v[66:81]
	s_nop 1
	v_max3_f32 v98, v82, s85, v83
	v_max3_f32 v98, v98, v84, v85
	v_max3_f32 v98, v98, v86, v87
	v_max3_f32 v98, v98, v88, v89
	v_max3_f32 v98, v98, v90, v91
	v_max3_f32 v98, v98, v92, v93
	v_max3_f32 v98, v98, v94, v95
	v_max3_f32 v98, v98, v96, v97
	s_nop 1
	v_max3_f32 v98, v98, v66, v67
	v_max3_f32 v98, v98, v68, v69
	v_max3_f32 v98, v98, v70, v71
	v_max3_f32 v98, v98, v72, v73
	v_max3_f32 v98, v98, v74, v75
	v_max3_f32 v98, v98, v76, v77
	v_max3_f32 v98, v98, v78, v79
	v_max3_f32 v98, v98, v80, v81
	ds_bpermute_b32 v99, v167, v98
	s_waitcnt lgkmcnt(0)
	v_max_f32_e32 v99, v99, v99
	v_max_f32_e32 v98, v98, v99
	v_mul_f32_e32 v98, 0x3e38aa3b, v98
	v_add_f32_e32 v99, 0x40c00000, v189
	v_cmp_gt_f32_e32 vcc, v98, v99
	s_cbranch_vccz .LBB0_938
	s_nop 0
	v_cndmask_b32_e32 v99, v189, v98, vcc
	v_sub_f32_e32 v98, v189, v99
	v_exp_f32_e32 v98, v98
	v_mov_b32_e32 v189, v99
	v_cndmask_b32_e32 v98, 1.0, v98, vcc
	v_mul_f32_e32 v188, v188, v98
	v_pk_mul_f32 v[48:49], v[48:49], v[98:99] op_sel_hi:[1,0]
	v_pk_mul_f32 v[46:47], v[46:47], v[98:99] op_sel_hi:[1,0]
	v_pk_mul_f32 v[44:45], v[44:45], v[98:99] op_sel_hi:[1,0]
	v_pk_mul_f32 v[42:43], v[42:43], v[98:99] op_sel_hi:[1,0]
	v_pk_mul_f32 v[40:41], v[40:41], v[98:99] op_sel_hi:[1,0]
	v_pk_mul_f32 v[38:39], v[38:39], v[98:99] op_sel_hi:[1,0]
	v_pk_mul_f32 v[36:37], v[36:37], v[98:99] op_sel_hi:[1,0]
	v_pk_mul_f32 v[34:35], v[34:35], v[98:99] op_sel_hi:[1,0]
	v_pk_mul_f32 v[64:65], v[64:65], v[98:99] op_sel_hi:[1,0]
	v_pk_mul_f32 v[62:63], v[62:63], v[98:99] op_sel_hi:[1,0]
	v_pk_mul_f32 v[60:61], v[60:61], v[98:99] op_sel_hi:[1,0]
	v_pk_mul_f32 v[58:59], v[58:59], v[98:99] op_sel_hi:[1,0]
	v_pk_mul_f32 v[56:57], v[56:57], v[98:99] op_sel_hi:[1,0]
	v_pk_mul_f32 v[54:55], v[54:55], v[98:99] op_sel_hi:[1,0]
	v_pk_mul_f32 v[52:53], v[52:53], v[98:99] op_sel_hi:[1,0]
	v_pk_mul_f32 v[50:51], v[50:51], v[98:99] op_sel_hi:[1,0]
.LBB0_938:
	v_cmp_neq_f32_e32 vcc, s85, v189
	s_nop 1
	v_cndmask_b32_e64 v98, 0, -v189, vcc
	v_fmamk_f32 v82, v82, 0x3e38aa3b, v98
	v_exp_f32_e32 v82, v82
	v_fmamk_f32 v83, v83, 0x3e38aa3b, v98
	v_exp_f32_e32 v99, v83
	v_fmamk_f32 v83, v84, 0x3e38aa3b, v98
	v_exp_f32_e32 v83, v83
	v_fmamk_f32 v84, v85, 0x3e38aa3b, v98
	v_exp_f32_e32 v100, v84
	v_fmamk_f32 v85, v86, 0x3e38aa3b, v98
	v_add_f32_e32 v84, 0, v82
	v_exp_f32_e32 v86, v85
	v_fmamk_f32 v85, v87, 0x3e38aa3b, v98
	v_add_f32_e32 v84, v99, v84
	v_exp_f32_e32 v87, v85
	v_fmamk_f32 v85, v88, 0x3e38aa3b, v98
	v_add_f32_e32 v84, v83, v84
	v_exp_f32_e32 v85, v85
	v_fmamk_f32 v88, v89, 0x3e38aa3b, v98
	v_add_f32_e32 v84, v100, v84
	v_exp_f32_e32 v88, v88
	v_fmamk_f32 v89, v90, 0x3e38aa3b, v98
	v_add_f32_e32 v84, v86, v84
	v_exp_f32_e32 v90, v89
	v_fmamk_f32 v89, v91, 0x3e38aa3b, v98
	v_add_f32_e32 v84, v87, v84
	v_exp_f32_e32 v91, v89
	v_fmamk_f32 v89, v92, 0x3e38aa3b, v98
	v_add_f32_e32 v84, v85, v84
	v_exp_f32_e32 v92, v89
	v_fmamk_f32 v89, v93, 0x3e38aa3b, v98
	v_add_f32_e32 v84, v88, v84
	v_exp_f32_e32 v93, v89
	v_fmamk_f32 v89, v94, 0x3e38aa3b, v98
	v_add_f32_e32 v84, v90, v84
	v_exp_f32_e32 v94, v89
	v_fmamk_f32 v89, v95, 0x3e38aa3b, v98
	v_add_f32_e32 v84, v91, v84
	v_exp_f32_e32 v95, v89
	v_fmamk_f32 v89, v96, 0x3e38aa3b, v98
	v_add_f32_e32 v84, v92, v84
	v_exp_f32_e32 v96, v89
	v_fmamk_f32 v89, v97, 0x3e38aa3b, v98
	v_add_f32_e32 v84, v93, v84
	v_exp_f32_e32 v97, v89
	v_fmamk_f32 v66, v66, 0x3e38aa3b, v98
	v_add_f32_e32 v84, v94, v84
	v_exp_f32_e32 v101, v66
	v_fmamk_f32 v66, v67, 0x3e38aa3b, v98
	v_add_f32_e32 v84, v95, v84
	v_exp_f32_e32 v102, v66
	v_fmamk_f32 v66, v68, 0x3e38aa3b, v98
	v_add_f32_e32 v84, v96, v84
	v_exp_f32_e32 v103, v66
	v_fmamk_f32 v66, v69, 0x3e38aa3b, v98
	v_add_f32_e32 v84, v97, v84
	v_exp_f32_e32 v104, v66
	v_add_f32_e32 v66, v101, v84
	v_add_f32_e32 v66, v102, v66
	v_add_f32_e32 v66, v103, v66
	v_add_f32_e32 v105, v104, v66
	v_fmamk_f32 v66, v70, 0x3e38aa3b, v98
	v_lshlrev_b32_e32 v70, 1, v183
	v_exp_f32_e32 v106, v66
	v_fmamk_f32 v66, v71, 0x3e38aa3b, v98
	v_add3_u32 v108, s23, v182, v70
	v_exp_f32_e32 v107, v66
	s_setprio 1
	ds_read_b128 v[66:69], v108 offset:9216
	v_fmamk_f32 v71, v72, 0x3e38aa3b, v98
	v_add3_u32 v110, s23, v184, v70
	v_cvt_pk_bf16_f32 v85, v85, v88
	v_cvt_pk_bf16_f32 v84, v86, v87
	v_cvt_pk_bf16_f32 v83, v83, v100
	v_cvt_pk_bf16_f32 v82, v82, v99
	v_exp_f32_e32 v109, v71
	ds_read_b128 v[86:89], v110 offset:9216
	s_waitcnt lgkmcnt(1)
	v_mfma_f32_32x32x16_bf16 v[34:49], v[66:69], v[82:85], v[34:49]
	v_fmamk_f32 v66, v73, 0x3e38aa3b, v98
	v_exp_f32_e32 v99, v66
	v_add_f32_e32 v66, v106, v105
	v_add_f32_e32 v66, v107, v66
	v_add_f32_e32 v66, v109, v66
	v_add_f32_e32 v100, v99, v66
	ds_read_b128 v[66:69], v108 offset:9248
	v_fmamk_f32 v70, v74, 0x3e38aa3b, v98
	s_waitcnt lgkmcnt(1)
	v_mfma_f32_32x32x16_bf16 v[50:65], v[86:89], v[82:85], v[50:65]
	v_exp_f32_e32 v86, v70
	ds_read_b128 v[70:73], v110 offset:9248
	v_cvt_pk_bf16_f32 v85, v96, v97
	v_cvt_pk_bf16_f32 v84, v94, v95
	v_cvt_pk_bf16_f32 v83, v92, v93
	v_cvt_pk_bf16_f32 v82, v90, v91
	v_fmamk_f32 v90, v77, 0x3e38aa3b, v98
	v_add_f32_e32 v87, v86, v100
	s_waitcnt lgkmcnt(1)
	v_mfma_f32_32x32x16_bf16 v[34:49], v[66:69], v[82:85], v[34:49]
	v_fmamk_f32 v66, v75, 0x3e38aa3b, v98
	v_exp_f32_e32 v88, v66
	v_fmamk_f32 v66, v76, 0x3e38aa3b, v98
	v_exp_f32_e32 v89, v66
	ds_read_b128 v[66:69], v108 offset:9280
	ds_read_b128 v[74:77], v110 offset:9280
	s_waitcnt lgkmcnt(2)
	v_mfma_f32_32x32x16_bf16 v[50:65], v[70:73], v[82:85], v[50:65]
	v_fmamk_f32 v70, v78, 0x3e38aa3b, v98
	v_exp_f32_e32 v78, v70
	v_cvt_pk_bf16_f32 v73, v109, v99
	v_cvt_pk_bf16_f32 v72, v106, v107
	v_cvt_pk_bf16_f32 v71, v103, v104
	v_cvt_pk_bf16_f32 v70, v101, v102
	v_exp_f32_e32 v82, v90
	v_add_f32_e32 v83, v88, v87
	s_waitcnt lgkmcnt(1)
	v_mfma_f32_32x32x16_bf16 v[34:49], v[66:69], v[70:73], v[34:49]
	v_fmamk_f32 v66, v79, 0x3e38aa3b, v98
	v_exp_f32_e32 v79, v66
	v_fmamk_f32 v66, v80, 0x3e38aa3b, v98
	v_exp_f32_e32 v80, v66
	ds_read_b128 v[66:69], v108 offset:9312
	v_fmac_f32_e32 v98, 0x3e38aa3b, v81
	v_exp_f32_e32 v81, v98
	s_waitcnt lgkmcnt(1)
	v_mfma_f32_32x32x16_bf16 v[50:65], v[74:77], v[70:73], v[50:65]
	ds_read_b128 v[74:77], v110 offset:9312
	v_cvt_pk_bf16_f32 v72, v78, v79
	v_cvt_pk_bf16_f32 v73, v80, v81
	v_cvt_pk_bf16_f32 v71, v89, v82
	v_cvt_pk_bf16_f32 v70, v86, v88
	s_waitcnt lgkmcnt(1)
	s_nop 0
	v_mfma_f32_32x32x16_bf16 v[34:49], v[66:69], v[70:73], v[34:49]
	v_add_f32_e32 v66, v89, v83
	v_add_f32_e32 v66, v82, v66
	v_add_f32_e32 v66, v78, v66
	v_add_f32_e32 v66, v79, v66
	v_add_f32_e32 v66, v80, v66
	v_add_f32_e32 v66, v81, v66
	v_add_f32_e32 v188, v188, v66
	s_waitcnt lgkmcnt(0)
	v_mfma_f32_32x32x16_bf16 v[50:65], v[74:77], v[70:73], v[50:65]

.LBB0_940:
	s_add_i32 s16, s16, 64
	s_add_i32 s2, s22, 1
	s_cmp_lg_u32 s22, s15
	s_mov_b64 s[22:23], 0x4000
	v_subrev_u32_e32 v185, 64, v185
	v_lshl_add_u64 v[176:177], v[176:177], 0, s[28:29]
	v_lshl_add_u64 v[180:181], v[180:181], 0, s[22:23]
	s_waitcnt lgkmcnt(0)
	s_setprio 0
	s_barrier
	s_cbranch_scc1 .LBB0_915
	v_mul_f32_e32 v34, 0xbfb8aa3b, v168
	v_exp_f32_e32 v34, v34
	s_nop 0
	v_add_f32_e32 v34, 1.0, v34
	v_div_scale_f32 v35, s[2:3], v34, v34, 1.0
	v_rcp_f32_e32 v36, v35
	s_nop 0
	v_fma_f32 v37, -v35, v36, 1.0
	v_fmac_f32_e32 v36, v37, v36
	v_div_scale_f32 v37, vcc, 1.0, v34, 1.0
	v_mul_f32_e32 v38, v37, v36
	v_fma_f32 v39, -v35, v38, v37
	v_fmac_f32_e32 v38, v39, v36
	v_fma_f32 v35, -v35, v38, v37
	v_div_fmas_f32 v35, v35, v36, v38
	v_div_fixup_f32 v34, v35, v34, 1.0
	v_mul_f32_e32 v35, 0xbfb8aa3b, v169
	v_exp_f32_e32 v35, v35
	s_nop 0
	v_add_f32_e32 v35, 1.0, v35
	v_div_scale_f32 v36, s[2:3], v35, v35, 1.0
	v_rcp_f32_e32 v37, v36
	s_nop 0
	v_fma_f32 v38, -v36, v37, 1.0
	v_fmac_f32_e32 v37, v38, v37
	v_div_scale_f32 v38, vcc, 1.0, v35, 1.0
	v_mul_f32_e32 v39, v38, v37
	v_fma_f32 v40, -v36, v39, v38
	v_fmac_f32_e32 v39, v40, v37
	v_fma_f32 v36, -v36, v39, v38
	v_div_fmas_f32 v36, v36, v37, v39
	v_div_fixup_f32 v35, v36, v35, 1.0
	ds_bpermute_b32 v36, v167, v98
	v_mov_b32_e32 v167, v1
	s_waitcnt lgkmcnt(0)
	v_add_f32_e32 v36, v98, v36
	v_div_scale_f32 v37, s[2:3], v36, v36, 1.0
	v_rcp_f32_e32 v38, v37
	v_cmp_lt_f32_e64 s[38:39], 0, v36
	v_fma_f32 v39, -v37, v38, 1.0
	v_fmac_f32_e32 v38, v39, v38
	v_div_scale_f32 v39, vcc, 1.0, v36, 1.0
	v_mul_f32_e32 v40, v39, v38
	v_fma_f32 v41, -v37, v40, v39
	v_fmac_f32_e32 v40, v41, v38
	v_fma_f32 v37, -v37, v40, v39
	v_div_fmas_f32 v37, v37, v38, v40
	v_div_fixup_f32 v36, v37, v36, 1.0
	v_cndmask_b32_e64 v36, 0, v36, s[38:39]
	v_mul_f32_e32 v35, v35, v36
	v_mov_b32_e32 v36, v2
	v_mov_b32_e32 v37, v66
	v_mov_b32_e32 v66, v3
	v_pk_mul_f32 v[36:37], v[34:35], v[36:37]
	v_mov_b32_e32 v39, v82
	v_pk_mul_f32 v[2:3], v[34:35], v[66:67]
	v_mov_b32_e32 v82, v19
	v_add_f32_e32 v36, v36, v37
	v_add_f32_e32 v37, v2, v3
	v_pk_mul_f32 v[2:3], v[34:35], v[82:83]
	v_mov_b32_e32 v38, v18
	v_add_f32_e32 v19, v2, v3
	v_mov_b32_e32 v2, v4
	v_mov_b32_e32 v3, v68
	v_pk_mul_f32 v[38:39], v[34:35], v[38:39]
	v_pk_mul_f32 v[2:3], v[34:35], v[2:3]
	v_add_f32_e32 v18, v38, v39
	v_add_f32_e32 v38, v2, v3
	v_mov_b32_e32 v2, v20
	v_mov_b32_e32 v3, v84
	v_pk_mul_f32 v[2:3], v[34:35], v[2:3]
	v_mov_b32_e32 v68, v5
	v_add_f32_e32 v20, v2, v3
	v_pk_mul_f32 v[2:3], v[34:35], v[68:69]
	v_mov_b32_e32 v84, v21
	v_add_f32_e32 v39, v2, v3
	v_pk_mul_f32 v[2:3], v[34:35], v[84:85]
	v_lshlrev_b64 v[4:5], 1, v[164:165]
	v_add_f32_e32 v21, v2, v3
	v_mov_b32_e32 v2, v6
	v_mov_b32_e32 v3, v70
	v_pk_mul_f32 v[2:3], v[34:35], v[2:3]
	v_mov_b32_e32 v70, v7
	v_add_f32_e32 v40, v2, v3
	v_mov_b32_e32 v2, v22
	v_mov_b32_e32 v3, v86
	v_pk_mul_f32 v[2:3], v[34:35], v[2:3]
	v_mov_b32_e32 v86, v23
	v_add_f32_e32 v6, v2, v3
	v_pk_mul_f32 v[2:3], v[34:35], v[70:71]
	s_nop 0
	v_add_f32_e32 v22, v2, v3
	v_pk_mul_f32 v[2:3], v[34:35], v[86:87]
	s_nop 0
	v_add_f32_e32 v7, v2, v3
	v_mov_b32_e32 v2, v8
	v_mov_b32_e32 v3, v72
	v_pk_mul_f32 v[2:3], v[34:35], v[2:3]
	v_mov_b32_e32 v72, v9
	v_add_f32_e32 v23, v2, v3
	v_mov_b32_e32 v2, v24
	v_mov_b32_e32 v3, v88
	v_pk_mul_f32 v[2:3], v[34:35], v[2:3]
	v_mov_b32_e32 v88, v25
	v_add_f32_e32 v8, v2, v3
	v_pk_mul_f32 v[2:3], v[34:35], v[72:73]
	s_nop 0
	v_add_f32_e32 v41, v2, v3
	v_pk_mul_f32 v[2:3], v[34:35], v[88:89]
	s_nop 0
	v_add_f32_e32 v42, v2, v3
	v_mov_b32_e32 v2, v10
	v_mov_b32_e32 v3, v74
	v_pk_mul_f32 v[2:3], v[34:35], v[2:3]
	v_mov_b32_e32 v74, v11
	v_add_f32_e32 v43, v2, v3
	v_mov_b32_e32 v2, v26
	v_mov_b32_e32 v3, v90
	v_pk_mul_f32 v[2:3], v[34:35], v[2:3]
	v_mov_b32_e32 v90, v27
	v_add_f32_e32 v9, v2, v3
	v_pk_mul_f32 v[2:3], v[34:35], v[74:75]
	v_lshl_add_u64 v[10:11], s[72:73], 0, v[4:5]
	v_add_f32_e32 v56, v2, v3
	v_pk_mul_f32 v[2:3], v[34:35], v[90:91]
	v_lshl_add_u64 v[4:5], s[74:75], 0, v[4:5]
	v_add_f32_e32 v57, v2, v3
	v_mov_b32_e32 v2, v12
	v_mov_b32_e32 v3, v76
	v_pk_mul_f32 v[2:3], v[34:35], v[2:3]
	v_mov_b32_e32 v76, v13
	v_add_f32_e32 v58, v2, v3
	v_mov_b32_e32 v2, v28
	v_mov_b32_e32 v3, v92
	v_pk_mul_f32 v[2:3], v[34:35], v[2:3]
	v_mov_b32_e32 v92, v29
	v_add_f32_e32 v59, v2, v3
	v_pk_mul_f32 v[2:3], v[34:35], v[76:77]
	s_nop 0
	v_add_f32_e32 v60, v2, v3
	v_pk_mul_f32 v[2:3], v[34:35], v[92:93]
	s_nop 0
	v_add_f32_e32 v61, v2, v3
	v_mov_b32_e32 v2, v14
	v_mov_b32_e32 v3, v78
	v_pk_mul_f32 v[2:3], v[34:35], v[2:3]
	v_mov_b32_e32 v78, v15
	v_add_f32_e32 v62, v2, v3
	v_mov_b32_e32 v2, v30
	v_mov_b32_e32 v3, v94
	v_pk_mul_f32 v[2:3], v[34:35], v[2:3]
	v_mov_b32_e32 v94, v31
	v_add_f32_e32 v63, v2, v3
	v_pk_mul_f32 v[2:3], v[34:35], v[78:79]
	s_nop 0
	v_add_f32_e32 v64, v2, v3
	v_pk_mul_f32 v[2:3], v[34:35], v[94:95]
	s_nop 0
	v_add_f32_e32 v65, v2, v3
	v_mov_b32_e32 v2, v16
	v_mov_b32_e32 v3, v80
	v_pk_mul_f32 v[2:3], v[34:35], v[2:3]
	v_mov_b32_e32 v80, v17
	v_add_f32_e32 v66, v2, v3
	v_mov_b32_e32 v2, v32
	v_mov_b32_e32 v3, v96
	v_pk_mul_f32 v[2:3], v[34:35], v[2:3]
	v_mov_b32_e32 v96, v33
	v_add_f32_e32 v67, v2, v3
	v_pk_mul_f32 v[2:3], v[34:35], v[80:81]
	s_nop 0
	v_add_f32_e32 v68, v2, v3
	v_pk_mul_f32 v[2:3], v[34:35], v[96:97]
	s_nop 0
	v_add_f32_e32 v69, v2, v3
	v_lshlrev_b64 v[2:3], 1, v[162:163]
	v_lshl_add_u64 v[10:11], v[10:11], 0, v[2:3]
	v_lshl_add_u64 v[10:11], v[10:11], 0, v[166:167]
	global_load_dwordx2 v[12:13], v[10:11], off
	global_load_dwordx2 v[14:15], v[10:11], off offset:16
	global_load_dwordx2 v[16:17], v[10:11], off offset:32
	global_load_dwordx2 v[52:53], v[10:11], off offset:48
	global_load_dwordx2 v[24:25], v[10:11], off offset:64
	global_load_dwordx2 v[26:27], v[10:11], off offset:80
	global_load_dwordx2 v[54:55], v[10:11], off offset:96
	s_nop 0
	global_load_dwordx2 v[10:11], v[10:11], off offset:112
	s_waitcnt vmcnt(7)
	v_lshlrev_b32_e32 v28, 16, v12
	v_and_b32_e32 v12, 0xffff0000, v12
	v_add_f32_e32 v50, v37, v12
	v_lshlrev_b32_e32 v12, 16, v13
	v_add_f32_e32 v49, v38, v12
	v_and_b32_e32 v12, 0xffff0000, v13
	v_add_f32_e32 v48, v39, v12
	s_waitcnt vmcnt(3)
	v_lshlrev_b32_e32 v12, 16, v24
	v_add_f32_e32 v35, v18, v12
	v_and_b32_e32 v12, 0xffff0000, v24
	v_add_f32_e32 v34, v19, v12
	v_lshlrev_b32_e32 v12, 16, v25
	v_add_f32_e32 v33, v20, v12
	v_and_b32_e32 v12, 0xffff0000, v25
	v_add_f32_e32 v32, v21, v12
	v_lshlrev_b32_e32 v12, 16, v14
	v_add_f32_e32 v47, v40, v12
	v_and_b32_e32 v12, 0xffff0000, v14
	v_add_f32_e32 v46, v22, v12
	v_lshlrev_b32_e32 v12, 16, v15
	v_add_f32_e32 v45, v23, v12
	v_and_b32_e32 v12, 0xffff0000, v15
	v_add_f32_e32 v44, v41, v12
	s_waitcnt vmcnt(2)
	v_lshlrev_b32_e32 v12, 16, v26
	v_add_f32_e32 v31, v6, v12
	v_and_b32_e32 v6, 0xffff0000, v26
	v_add_f32_e32 v30, v7, v6
	v_lshlrev_b32_e32 v6, 16, v27
	v_add_f32_e32 v29, v8, v6
	v_and_b32_e32 v6, 0xffff0000, v27
	v_add_f32_e32 v51, v36, v28
	v_add_f32_e32 v28, v42, v6
	v_lshlrev_b32_e32 v6, 16, v16
	v_add_f32_e32 v43, v43, v6
	v_and_b32_e32 v6, 0xffff0000, v16
	v_add_f32_e32 v42, v56, v6
	v_lshlrev_b32_e32 v6, 16, v17
	v_add_f32_e32 v41, v58, v6
	v_and_b32_e32 v6, 0xffff0000, v17
	v_add_f32_e32 v40, v60, v6
	s_waitcnt vmcnt(1)
	v_lshlrev_b32_e32 v6, 16, v54
	v_add_f32_e32 v27, v9, v6
	v_and_b32_e32 v6, 0xffff0000, v54
	v_add_f32_e32 v26, v57, v6
	v_lshlrev_b32_e32 v6, 16, v55
	v_add_f32_e32 v25, v59, v6
	v_and_b32_e32 v6, 0xffff0000, v55
	v_add_f32_e32 v24, v61, v6
	v_lshlrev_b32_e32 v6, 16, v52
	v_add_f32_e32 v39, v62, v6
	v_and_b32_e32 v6, 0xffff0000, v52
	v_add_f32_e32 v38, v64, v6
	v_lshlrev_b32_e32 v6, 16, v53
	v_add_f32_e32 v37, v66, v6
	v_and_b32_e32 v6, 0xffff0000, v53
	v_add_f32_e32 v36, v68, v6
	s_waitcnt vmcnt(0)
	v_lshlrev_b32_e32 v6, 16, v10
	v_add_f32_e32 v23, v63, v6
	v_and_b32_e32 v6, 0xffff0000, v10
	v_add_f32_e32 v22, v65, v6
	v_lshlrev_b32_e32 v6, 16, v11
	v_add_f32_e32 v21, v67, v6
	v_and_b32_e32 v6, 0xffff0000, v11
	v_add_f32_e32 v20, v69, v6
	v_lshl_add_u64 v[6:7], v[4:5], 0, v[2:3]
	v_lshlrev_b64 v[4:5], 11, v[0:1]
	v_lshl_add_u64 v[4:5], s[18:19], 0, v[4:5]
	v_lshl_add_u64 v[4:5], v[4:5], 0, v[2:3]
	v_lshl_add_u64 v[2:3], v[6:7], 0, v[166:167]
	global_load_dwordx2 v[18:19], v[2:3], off
	global_load_dwordx2 v[16:17], v[2:3], off offset:16
	global_load_dwordx2 v[14:15], v[2:3], off offset:32
	global_load_dwordx2 v[12:13], v[2:3], off offset:48
	global_load_dwordx2 v[10:11], v[2:3], off offset:64
	global_load_dwordx2 v[8:9], v[2:3], off offset:80
	global_load_dwordx2 v[6:7], v[2:3], off offset:96
	s_nop 0
	global_load_dwordx2 v[2:3], v[2:3], off offset:112
	v_lshl_add_u64 v[4:5], v[4:5], 0, v[166:167]
	s_waitcnt vmcnt(7)
	v_lshlrev_b32_e32 v0, 16, v18
	v_mul_f32_e32 v52, 0xbfb8aa3b, v0
	v_exp_f32_e32 v52, v52
	v_and_b32_e32 v18, 0xffff0000, v18
	v_add_f32_e32 v52, 1.0, v52
	v_rcp_f32_e32 v52, v52
	s_nop 0
	v_mul_f32_e32 v0, v52, v0
	v_mul_f32_e32 v0, v51, v0
	v_mul_f32_e32 v51, 0xbfb8aa3b, v18
	v_exp_f32_e32 v51, v51
	s_nop 0
	v_add_f32_e32 v51, 1.0, v51
	v_rcp_f32_e32 v51, v51
	s_nop 0
	v_mul_f32_e32 v18, v51, v18
	v_mul_f32_e32 v18, v50, v18
	v_lshlrev_b32_e32 v50, 16, v19
	v_mul_f32_e32 v51, 0xbfb8aa3b, v50
	v_exp_f32_e32 v51, v51
	v_and_b32_e32 v19, 0xffff0000, v19
	v_cvt_pk_bf16_f32 v18, v0, v18
	s_waitcnt vmcnt(6)
	v_lshlrev_b32_e32 v0, 16, v16
	v_add_f32_e32 v51, 1.0, v51
	v_rcp_f32_e32 v51, v51
	v_and_b32_e32 v16, 0xffff0000, v16
	v_mul_f32_e32 v50, v51, v50
	v_mul_f32_e32 v49, v49, v50
	v_mul_f32_e32 v50, 0xbfb8aa3b, v19
	v_exp_f32_e32 v50, v50
	s_nop 0
	v_add_f32_e32 v50, 1.0, v50
	v_rcp_f32_e32 v50, v50
	s_nop 0
	v_mul_f32_e32 v19, v50, v19
	v_mul_f32_e32 v19, v48, v19
	v_cvt_pk_bf16_f32 v19, v49, v19
	global_store_dwordx2 v[4:5], v[18:19], off offset:1024
	v_mul_f32_e32 v18, 0xbfb8aa3b, v0
	v_exp_f32_e32 v18, v18
	s_nop 0
	v_add_f32_e32 v18, 1.0, v18
	v_rcp_f32_e32 v18, v18
	s_nop 0
	v_mul_f32_e32 v0, v18, v0
	v_mul_f32_e32 v18, 0xbfb8aa3b, v16
	v_exp_f32_e32 v18, v18
	v_mul_f32_e32 v0, v47, v0
	v_add_f32_e32 v18, 1.0, v18
	v_rcp_f32_e32 v18, v18
	s_nop 0
	v_mul_f32_e32 v16, v18, v16
	v_lshlrev_b32_e32 v18, 16, v17
	v_mul_f32_e32 v19, 0xbfb8aa3b, v18
	v_exp_f32_e32 v19, v19
	v_and_b32_e32 v17, 0xffff0000, v17
	v_mul_f32_e32 v16, v46, v16
	v_cvt_pk_bf16_f32 v16, v0, v16
	v_add_f32_e32 v19, 1.0, v19
	v_rcp_f32_e32 v19, v19
	s_waitcnt vmcnt(6)
	v_lshlrev_b32_e32 v0, 16, v14
	v_and_b32_e32 v14, 0xffff0000, v14
	v_mul_f32_e32 v18, v19, v18
	v_mul_f32_e32 v19, 0xbfb8aa3b, v17
	v_exp_f32_e32 v19, v19
	v_mul_f32_e32 v18, v45, v18
	v_add_f32_e32 v19, 1.0, v19
	v_rcp_f32_e32 v19, v19
	s_nop 0
	v_mul_f32_e32 v17, v19, v17
	v_mul_f32_e32 v17, v44, v17
	v_cvt_pk_bf16_f32 v17, v18, v17
	global_store_dwordx2 v[4:5], v[16:17], off offset:1040
	v_mul_f32_e32 v16, 0xbfb8aa3b, v0
	v_exp_f32_e32 v16, v16
	s_nop 0
	v_add_f32_e32 v16, 1.0, v16
	v_rcp_f32_e32 v16, v16
	s_nop 0
	v_mul_f32_e32 v0, v16, v0
	v_mul_f32_e32 v16, 0xbfb8aa3b, v14
	v_exp_f32_e32 v16, v16
	v_mul_f32_e32 v0, v43, v0
	v_add_f32_e32 v16, 1.0, v16
	v_rcp_f32_e32 v16, v16
	s_nop 0
	v_mul_f32_e32 v14, v16, v14
	v_lshlrev_b32_e32 v16, 16, v15
	v_mul_f32_e32 v17, 0xbfb8aa3b, v16
	v_exp_f32_e32 v17, v17
	v_and_b32_e32 v15, 0xffff0000, v15
	v_mul_f32_e32 v14, v42, v14
	v_cvt_pk_bf16_f32 v14, v0, v14
	v_add_f32_e32 v17, 1.0, v17
	v_rcp_f32_e32 v17, v17
	s_waitcnt vmcnt(6)
	v_lshlrev_b32_e32 v0, 16, v12
	v_and_b32_e32 v12, 0xffff0000, v12
	v_mul_f32_e32 v16, v17, v16
	v_mul_f32_e32 v17, 0xbfb8aa3b, v15
	v_exp_f32_e32 v17, v17
	v_mul_f32_e32 v16, v41, v16
	v_add_f32_e32 v17, 1.0, v17
	v_rcp_f32_e32 v17, v17
	s_nop 0
	v_mul_f32_e32 v15, v17, v15
	v_mul_f32_e32 v15, v40, v15
	v_cvt_pk_bf16_f32 v15, v16, v15
	global_store_dwordx2 v[4:5], v[14:15], off offset:1056
	v_mul_f32_e32 v14, 0xbfb8aa3b, v0
	v_exp_f32_e32 v14, v14
	s_nop 0
	v_add_f32_e32 v14, 1.0, v14
	v_rcp_f32_e32 v14, v14
	s_nop 0
	v_mul_f32_e32 v0, v14, v0
	v_mul_f32_e32 v14, 0xbfb8aa3b, v12
	v_exp_f32_e32 v14, v14
	v_mul_f32_e32 v0, v39, v0
	v_add_f32_e32 v14, 1.0, v14
	v_rcp_f32_e32 v14, v14
	s_nop 0
	v_mul_f32_e32 v12, v14, v12
	v_lshlrev_b32_e32 v14, 16, v13
	v_mul_f32_e32 v15, 0xbfb8aa3b, v14
	v_exp_f32_e32 v15, v15
	v_and_b32_e32 v13, 0xffff0000, v13
	v_mul_f32_e32 v12, v38, v12
	v_cvt_pk_bf16_f32 v12, v0, v12
	v_add_f32_e32 v15, 1.0, v15
	v_rcp_f32_e32 v15, v15
	s_waitcnt vmcnt(6)
	v_lshlrev_b32_e32 v0, 16, v10
	v_and_b32_e32 v10, 0xffff0000, v10
	v_mul_f32_e32 v14, v15, v14
	v_mul_f32_e32 v15, 0xbfb8aa3b, v13
	v_exp_f32_e32 v15, v15
	v_mul_f32_e32 v14, v37, v14
	v_add_f32_e32 v15, 1.0, v15
	v_rcp_f32_e32 v15, v15
	s_nop 0
	v_mul_f32_e32 v13, v15, v13
	v_mul_f32_e32 v13, v36, v13
	v_cvt_pk_bf16_f32 v13, v14, v13
	global_store_dwordx2 v[4:5], v[12:13], off offset:1072
	v_mul_f32_e32 v12, 0xbfb8aa3b, v0
	v_exp_f32_e32 v12, v12
	s_nop 0
	v_add_f32_e32 v12, 1.0, v12
	v_rcp_f32_e32 v12, v12
	s_nop 0
	v_mul_f32_e32 v0, v12, v0
	v_mul_f32_e32 v12, 0xbfb8aa3b, v10
	v_exp_f32_e32 v12, v12
	v_mul_f32_e32 v0, v35, v0
	v_add_f32_e32 v12, 1.0, v12
	v_rcp_f32_e32 v12, v12
	s_nop 0
	v_mul_f32_e32 v10, v12, v10
	v_lshlrev_b32_e32 v12, 16, v11
	v_mul_f32_e32 v13, 0xbfb8aa3b, v12
	v_exp_f32_e32 v13, v13
	v_and_b32_e32 v11, 0xffff0000, v11
	v_mul_f32_e32 v10, v34, v10
	v_cvt_pk_bf16_f32 v10, v0, v10
	v_add_f32_e32 v13, 1.0, v13
	v_rcp_f32_e32 v13, v13
	s_waitcnt vmcnt(6)
	v_lshlrev_b32_e32 v0, 16, v8
	v_and_b32_e32 v8, 0xffff0000, v8
	v_mul_f32_e32 v12, v13, v12
	v_mul_f32_e32 v13, 0xbfb8aa3b, v11
	v_exp_f32_e32 v13, v13
	v_mul_f32_e32 v12, v33, v12
	v_add_f32_e32 v13, 1.0, v13
	v_rcp_f32_e32 v13, v13
	s_nop 0
	v_mul_f32_e32 v11, v13, v11
	v_mul_f32_e32 v11, v32, v11
	v_cvt_pk_bf16_f32 v11, v12, v11
	global_store_dwordx2 v[4:5], v[10:11], off offset:1088
	v_mul_f32_e32 v10, 0xbfb8aa3b, v0
	v_exp_f32_e32 v10, v10
	s_nop 0
	v_add_f32_e32 v10, 1.0, v10
	v_rcp_f32_e32 v10, v10
	s_nop 0
	v_mul_f32_e32 v0, v10, v0
	v_mul_f32_e32 v10, 0xbfb8aa3b, v8
	v_exp_f32_e32 v10, v10
	v_mul_f32_e32 v0, v31, v0
	v_add_f32_e32 v10, 1.0, v10
	v_rcp_f32_e32 v10, v10
	s_nop 0
	v_mul_f32_e32 v8, v10, v8
	v_lshlrev_b32_e32 v10, 16, v9
	v_mul_f32_e32 v11, 0xbfb8aa3b, v10
	v_exp_f32_e32 v11, v11
	v_and_b32_e32 v9, 0xffff0000, v9
	v_mul_f32_e32 v8, v30, v8
	v_cvt_pk_bf16_f32 v8, v0, v8
	v_add_f32_e32 v11, 1.0, v11
	v_rcp_f32_e32 v11, v11
	s_waitcnt vmcnt(6)
	v_lshlrev_b32_e32 v0, 16, v6
	v_and_b32_e32 v6, 0xffff0000, v6
	v_mul_f32_e32 v10, v11, v10
	v_mul_f32_e32 v11, 0xbfb8aa3b, v9
	v_exp_f32_e32 v11, v11
	v_mul_f32_e32 v10, v29, v10
	v_add_f32_e32 v11, 1.0, v11
	v_rcp_f32_e32 v11, v11
	s_nop 0
	v_mul_f32_e32 v9, v11, v9
	v_mul_f32_e32 v9, v28, v9
	v_cvt_pk_bf16_f32 v9, v10, v9
	global_store_dwordx2 v[4:5], v[8:9], off offset:1104
	v_mul_f32_e32 v8, 0xbfb8aa3b, v0
	v_exp_f32_e32 v8, v8
	s_nop 0
	v_add_f32_e32 v8, 1.0, v8
	v_rcp_f32_e32 v8, v8
	s_nop 0
	v_mul_f32_e32 v0, v8, v0
	v_mul_f32_e32 v8, 0xbfb8aa3b, v6
	v_exp_f32_e32 v8, v8
	v_mul_f32_e32 v0, v27, v0
	v_add_f32_e32 v8, 1.0, v8
	v_rcp_f32_e32 v8, v8
	s_nop 0
	v_mul_f32_e32 v6, v8, v6
	v_lshlrev_b32_e32 v8, 16, v7
	v_mul_f32_e32 v9, 0xbfb8aa3b, v8
	v_exp_f32_e32 v9, v9
	v_and_b32_e32 v7, 0xffff0000, v7
	v_mul_f32_e32 v6, v26, v6
	v_cvt_pk_bf16_f32 v6, v0, v6
	v_add_f32_e32 v9, 1.0, v9
	v_rcp_f32_e32 v9, v9
	s_waitcnt vmcnt(6)
	v_lshlrev_b32_e32 v0, 16, v2
	v_and_b32_e32 v2, 0xffff0000, v2
	v_mul_f32_e32 v8, v9, v8
	v_mul_f32_e32 v9, 0xbfb8aa3b, v7
	v_exp_f32_e32 v9, v9
	v_mul_f32_e32 v8, v25, v8
	v_add_f32_e32 v9, 1.0, v9
	v_rcp_f32_e32 v9, v9
	s_nop 0
	v_mul_f32_e32 v7, v9, v7
	v_mul_f32_e32 v7, v24, v7
	v_cvt_pk_bf16_f32 v7, v8, v7
	global_store_dwordx2 v[4:5], v[6:7], off offset:1120
	v_mul_f32_e32 v6, 0xbfb8aa3b, v0
	v_exp_f32_e32 v6, v6
	s_nop 0
	v_add_f32_e32 v6, 1.0, v6
	v_rcp_f32_e32 v6, v6
	s_nop 0
	v_mul_f32_e32 v0, v6, v0
	v_mul_f32_e32 v6, 0xbfb8aa3b, v2
	v_exp_f32_e32 v6, v6
	v_mul_f32_e32 v0, v23, v0
	v_add_f32_e32 v6, 1.0, v6
	v_rcp_f32_e32 v6, v6
	s_nop 0
	v_mul_f32_e32 v2, v6, v2
	v_lshlrev_b32_e32 v6, 16, v3
	v_mul_f32_e32 v7, 0xbfb8aa3b, v6
	v_exp_f32_e32 v7, v7
	v_and_b32_e32 v3, 0xffff0000, v3
	v_mul_f32_e32 v2, v22, v2
	v_cvt_pk_bf16_f32 v2, v0, v2
	v_add_f32_e32 v7, 1.0, v7
	v_rcp_f32_e32 v7, v7
	s_nop 0
	v_mul_f32_e32 v6, v7, v6
	v_mul_f32_e32 v7, 0xbfb8aa3b, v3
	v_exp_f32_e32 v7, v7
	v_mul_f32_e32 v6, v21, v6
	v_add_f32_e32 v7, 1.0, v7
	v_rcp_f32_e32 v7, v7
	s_nop 0
	v_mul_f32_e32 v3, v7, v3
	v_mul_f32_e32 v3, v20, v3
	v_cvt_pk_bf16_f32 v3, v6, v3
	global_store_dwordx2 v[4:5], v[2:3], off offset:1136
	s_branch .LBB0_875

.LBB0_1003:
	s_barrier
	s_waitcnt vmcnt(9)
	ds_write_b128 v184, v[134:137]
	ds_write_b128 v184, v[142:145] offset:4608
	s_waitcnt vmcnt(8)
	ds_write_b128 v184, v[138:141] offset:9216
	s_waitcnt vmcnt(7)
	ds_write_b128 v184, v[150:153] offset:13824
	ds_write_b128 v184, v[130:133] offset:18432
	s_waitcnt vmcnt(6)
	ds_write_b128 v184, v[146:149] offset:23040
	s_waitcnt vmcnt(5)
	ds_write_b128 v184, v[154:157] offset:27648
	s_waitcnt vmcnt(4)
	ds_write_b128 v184, v[158:161] offset:32256
	s_waitcnt vmcnt(3)
	ds_write_b128 v184, v[162:165] offset:36864
	s_waitcnt vmcnt(2)
	ds_write_b128 v184, v[166:169] offset:41472
	s_waitcnt vmcnt(1)
	ds_write_b128 v184, v[170:173] offset:46080
	s_waitcnt vmcnt(0)
	ds_write_b128 v184, v[174:177] offset:50688
	s_waitcnt lgkmcnt(0)
	s_barrier
	s_setprio 2
	s_mov_b32 vcc_hi, 0
	ds_read_b128 v[244:247], v227
	ds_read_b128 v[210:213], v228 offset:18432
	ds_read_b128 v[248:251], v227 offset:4608
	ds_read_b128 v[214:217], v228 offset:23040
	ds_read_b128 v[218:221], v228 offset:27648
	ds_read_b128 v[222:225], v228 offset:32256
	s_waitcnt lgkmcnt(4)
	v_mfma_f32_32x32x16_bf16 v[114:129], v[210:213], v[244:247], v[114:129]
	s_add_u32 vcc_lo, s22, 0x80
	v_lshl_add_u64 v[238:239], v[194:195], 0, vcc
	global_load_dwordx4 v[130:133], v[238:239], off
	ds_read_b128 v[252:255], v227 offset:32
	s_waitcnt lgkmcnt(4)
	v_mfma_f32_32x32x16_bf16 v[82:97], v[210:213], v[248:251], v[82:97]
	s_add_u32 vcc_lo, s22, 0x80
	v_lshl_add_u64 v[178:179], v[192:193], 0, vcc
	global_load_dwordx4 v[134:137], v[178:179], off
	ds_read_b128 v[210:213], v228 offset:18464
	s_waitcnt lgkmcnt(4)
	v_mfma_f32_32x32x16_bf16 v[98:113], v[214:217], v[244:247], v[98:113]
	s_add_u32 vcc_lo, s22, 0x10080
	v_lshl_add_u64 v[238:239], v[192:193], 0, vcc
	global_load_dwordx4 v[142:145], v[238:239], off
	ds_read_b128 v[230:233], v227 offset:4640
	v_mfma_f32_32x32x16_bf16 v[66:81], v[214:217], v[248:251], v[66:81]
	s_add_u32 vcc_lo, s22, 0x20080
	v_lshl_add_u64 v[178:179], v[192:193], 0, vcc
	global_load_dwordx4 v[138:141], v[178:179], off
	ds_read_b128 v[214:217], v228 offset:23072
	s_waitcnt lgkmcnt(5)
	v_mfma_f32_32x32x16_bf16 v[50:65], v[218:221], v[244:247], v[50:65]
	s_add_u32 vcc_lo, s22, 0x30080
	v_lshl_add_u64 v[238:239], v[192:193], 0, vcc
	global_load_dwordx4 v[150:153], v[238:239], off
	v_mfma_f32_32x32x16_bf16 v[18:33], v[218:221], v[248:251], v[18:33]
	s_add_u32 vcc_lo, s22, 0x10080
	v_lshl_add_u64 v[178:179], v[194:195], 0, vcc
	global_load_dwordx4 v[146:149], v[178:179], off
	ds_read_b128 v[218:221], v228 offset:27680
	s_waitcnt lgkmcnt(5)
	v_mfma_f32_32x32x16_bf16 v[34:49], v[222:225], v[244:247], v[34:49]
	s_add_u32 vcc_lo, s22, 0x20080
	v_lshl_add_u64 v[238:239], v[194:195], 0, vcc
	global_load_dwordx4 v[154:157], v[238:239], off
	v_mfma_f32_32x32x16_bf16 v[2:17], v[222:225], v[248:251], v[2:17]
	s_add_u32 vcc_lo, s22, 0x30080
	v_lshl_add_u64 v[178:179], v[194:195], 0, vcc
	global_load_dwordx4 v[158:161], v[178:179], off
	ds_read_b128 v[222:225], v228 offset:32288
	s_waitcnt lgkmcnt(4)
	v_mfma_f32_32x32x16_bf16 v[114:129], v[210:213], v[252:255], v[114:129]
	s_add_u32 vcc_lo, s22, 0x40080
	v_lshl_add_u64 v[238:239], v[194:195], 0, vcc
	global_load_dwordx4 v[162:165], v[238:239], off
	ds_read_b128 v[244:247], v227 offset:64
	s_waitcnt lgkmcnt(4)
	v_mfma_f32_32x32x16_bf16 v[82:97], v[210:213], v[230:233], v[82:97]
	s_add_u32 vcc_lo, s22, 0x50080
	v_lshl_add_u64 v[178:179], v[194:195], 0, vcc
	global_load_dwordx4 v[166:169], v[178:179], off
	ds_read_b128 v[210:213], v228 offset:18496
	s_waitcnt lgkmcnt(4)
	v_mfma_f32_32x32x16_bf16 v[98:113], v[214:217], v[252:255], v[98:113]
	s_add_u32 vcc_lo, s22, 0x60080
	v_lshl_add_u64 v[238:239], v[194:195], 0, vcc
	global_load_dwordx4 v[170:173], v[238:239], off
	ds_read_b128 v[248:251], v227 offset:4672
	v_mfma_f32_32x32x16_bf16 v[66:81], v[214:217], v[230:233], v[66:81]
	s_add_u32 vcc_lo, s22, 0x70080
	v_lshl_add_u64 v[178:179], v[194:195], 0, vcc
	global_load_dwordx4 v[174:177], v[178:179], off
	ds_read_b128 v[214:217], v228 offset:23104
	s_waitcnt lgkmcnt(5)
	v_mfma_f32_32x32x16_bf16 v[50:65], v[218:221], v[252:255], v[50:65]
	v_mfma_f32_32x32x16_bf16 v[18:33], v[218:221], v[230:233], v[18:33]
	ds_read_b128 v[218:221], v228 offset:27712
	s_waitcnt lgkmcnt(5)
	v_mfma_f32_32x32x16_bf16 v[34:49], v[222:225], v[252:255], v[34:49]
	v_mfma_f32_32x32x16_bf16 v[2:17], v[222:225], v[230:233], v[2:17]
	ds_read_b128 v[222:225], v228 offset:32320
	s_waitcnt lgkmcnt(4)
	v_mfma_f32_32x32x16_bf16 v[114:129], v[210:213], v[244:247], v[114:129]
	ds_read_b128 v[252:255], v227 offset:96
	s_waitcnt lgkmcnt(4)
	v_mfma_f32_32x32x16_bf16 v[82:97], v[210:213], v[248:251], v[82:97]
	ds_read_b128 v[210:213], v228 offset:18528
	s_waitcnt lgkmcnt(4)
	v_mfma_f32_32x32x16_bf16 v[98:113], v[214:217], v[244:247], v[98:113]
	ds_read_b128 v[230:233], v227 offset:4704
	v_mfma_f32_32x32x16_bf16 v[66:81], v[214:217], v[248:251], v[66:81]
	ds_read_b128 v[214:217], v228 offset:23136
	s_waitcnt lgkmcnt(5)
	v_mfma_f32_32x32x16_bf16 v[50:65], v[218:221], v[244:247], v[50:65]
	v_mfma_f32_32x32x16_bf16 v[18:33], v[218:221], v[248:251], v[18:33]
	ds_read_b128 v[218:221], v228 offset:27744
	s_waitcnt lgkmcnt(5)
	v_mfma_f32_32x32x16_bf16 v[34:49], v[222:225], v[244:247], v[34:49]
	v_mfma_f32_32x32x16_bf16 v[2:17], v[222:225], v[248:251], v[2:17]
	ds_read_b128 v[222:225], v228 offset:32352
	s_waitcnt lgkmcnt(4)
	v_mfma_f32_32x32x16_bf16 v[114:129], v[210:213], v[252:255], v[114:129]
	s_waitcnt lgkmcnt(3)
	v_mfma_f32_32x32x16_bf16 v[82:97], v[210:213], v[230:233], v[82:97]
	s_waitcnt lgkmcnt(2)
	v_mfma_f32_32x32x16_bf16 v[98:113], v[214:217], v[252:255], v[98:113]
	v_mfma_f32_32x32x16_bf16 v[66:81], v[214:217], v[230:233], v[66:81]
	s_waitcnt lgkmcnt(1)
	v_mfma_f32_32x32x16_bf16 v[50:65], v[218:221], v[252:255], v[50:65]
	v_mfma_f32_32x32x16_bf16 v[18:33], v[218:221], v[230:233], v[18:33]
	s_waitcnt lgkmcnt(0)
	v_mfma_f32_32x32x16_bf16 v[34:49], v[222:225], v[252:255], v[34:49]
	v_mfma_f32_32x32x16_bf16 v[2:17], v[222:225], v[230:233], v[2:17]
	s_setprio 0
	s_add_u32 s22, s22, 0x80
	s_addc_u32 s23, s23, 0
	s_cmpk_eq_i32 s22, 0x780
	s_cbranch_scc0 .LBB0_1003
	v_mov_b32_e32 v210, 64
	v_xor_b32_e32 v211, 32, v209
	v_xor_b32_e32 v212, 16, v209
	v_xor_b32_e32 v213, 8, v209
	v_xor_b32_e32 v214, 4, v209
	v_xor_b32_e32 v215, 2, v209
	v_xor_b32_e32 v216, 1, v209
	v_mov_b32_e32 v217, 2
	v_bfrev_b32_e32 v218, 32
	v_bfrev_b32_e32 v219, 64
	v_mov_b32_e32 v220, 0xff800000
	v_mov_b32_e32 v221, 0x80
	v_mov_b32_e32 v222, 0x200
	v_mov_b32_e32 v223, 0x2000
	v_mov_b32_e32 v224, 0x461c4000
	v_mov_b32_e32 v225, 0x63
	v_mov_b64_e32 v[178:179], 0xf500000
	s_setprio 0
	s_barrier
	s_waitcnt vmcnt(10)
	ds_write_b128 v184, v[134:137]
	s_waitcnt vmcnt(9)
	ds_write_b128 v184, v[142:145] offset:4608
	s_waitcnt vmcnt(8)
	ds_write_b128 v184, v[138:141] offset:9216
	s_waitcnt vmcnt(7)
	ds_write_b128 v184, v[150:153] offset:13824
	ds_write_b128 v184, v[130:133] offset:18432
	s_waitcnt vmcnt(6)
	ds_write_b128 v184, v[146:149] offset:23040
	s_waitcnt vmcnt(5)
	ds_write_b128 v184, v[154:157] offset:27648
	s_waitcnt vmcnt(4)
	ds_write_b128 v184, v[158:161] offset:32256
	s_waitcnt vmcnt(3)
	ds_write_b128 v184, v[162:165] offset:36864
	s_waitcnt vmcnt(2)
	ds_write_b128 v184, v[166:169] offset:41472
	s_waitcnt vmcnt(1)
	ds_write_b128 v184, v[170:173] offset:46080
	s_waitcnt vmcnt(0)
	ds_write_b128 v184, v[174:177] offset:50688
	s_waitcnt lgkmcnt(0)
	s_setprio 0
	s_barrier
	s_setprio 1
	ds_read_b128 v[130:133], v227 offset:4608
	ds_read_b128 v[134:137], v228 offset:23040
	ds_read_b128 v[138:141], v227
	ds_read_b128 v[142:145], v227 offset:32
	ds_read_b128 v[146:149], v228 offset:18432
	ds_read_b128 v[150:153], v228 offset:18464
	s_waitcnt lgkmcnt(1)
	v_mfma_f32_32x32x16_bf16 v[114:129], v[146:149], v[138:141], v[114:129]
	v_add_u32_e32 v166, s2, v185
	v_or_b32_e32 v168, v166, v198
	v_ashrrev_i32_e32 v169, 31, v168
	v_cndmask_b32_e64 v167, 0, 1, s[42:43]
	v_cmp_ne_u32_e64 s[40:41], 1, v167
	s_andn2_b64 vcc, exec, s[42:43]
	v_mfma_f32_32x32x16_bf16 v[82:97], v[146:149], v[130:133], v[82:97]
	v_mfma_f32_32x32x16_bf16 v[98:113], v[134:137], v[138:141], v[98:113]
	v_mfma_f32_32x32x16_bf16 v[66:81], v[134:137], v[130:133], v[66:81]
	ds_read_b128 v[134:137], v228 offset:27648
	ds_read_b128 v[146:149], v228 offset:32256
	s_waitcnt lgkmcnt(1)
	v_mfma_f32_32x32x16_bf16 v[50:65], v[134:137], v[138:141], v[50:65]
	v_mfma_f32_32x32x16_bf16 v[18:33], v[134:137], v[130:133], v[18:33]
	s_waitcnt lgkmcnt(0)
	v_mfma_f32_32x32x16_bf16 v[2:17], v[146:149], v[130:133], v[2:17]
	ds_read_b128 v[130:133], v227 offset:4640
	ds_read_b128 v[134:137], v228 offset:23072
	v_mfma_f32_32x32x16_bf16 v[34:49], v[146:149], v[138:141], v[34:49]
	s_waitcnt lgkmcnt(0)
	v_mfma_f32_32x32x16_bf16 v[98:113], v[134:137], v[142:145], v[98:113]
	v_mfma_f32_32x32x16_bf16 v[66:81], v[134:137], v[130:133], v[66:81]
	ds_read_b128 v[134:137], v228 offset:27680
	ds_read_b128 v[138:141], v228 offset:32288
	v_mfma_f32_32x32x16_bf16 v[114:129], v[150:153], v[142:145], v[114:129]
	v_mfma_f32_32x32x16_bf16 v[82:97], v[150:153], v[130:133], v[82:97]
	v_lshlrev_b64 v[150:151], 10, v[168:169]
	s_waitcnt lgkmcnt(1)
	v_mfma_f32_32x32x16_bf16 v[50:65], v[134:137], v[142:145], v[50:65]
	v_mfma_f32_32x32x16_bf16 v[18:33], v[134:137], v[130:133], v[18:33]
	s_waitcnt lgkmcnt(0)
	v_mfma_f32_32x32x16_bf16 v[34:49], v[138:141], v[142:145], v[34:49]
	v_mfma_f32_32x32x16_bf16 v[2:17], v[138:141], v[130:133], v[2:17]
	ds_read_b128 v[130:133], v227 offset:64
	ds_read_b128 v[134:137], v227 offset:4672
	ds_read_b128 v[138:141], v228 offset:18496
	ds_read_b128 v[142:145], v228 offset:23104
	s_waitcnt lgkmcnt(1)
	v_mfma_f32_32x32x16_bf16 v[114:129], v[138:141], v[130:133], v[114:129]
	v_mfma_f32_32x32x16_bf16 v[82:97], v[138:141], v[134:137], v[82:97]
	s_waitcnt lgkmcnt(0)
	v_mfma_f32_32x32x16_bf16 v[98:113], v[142:145], v[130:133], v[98:113]
	v_mfma_f32_32x32x16_bf16 v[66:81], v[142:145], v[134:137], v[66:81]
	ds_read_b128 v[138:141], v228 offset:27712
	ds_read_b128 v[142:145], v228 offset:32320
	s_waitcnt lgkmcnt(1)
	v_mfma_f32_32x32x16_bf16 v[50:65], v[138:141], v[130:133], v[50:65]
	v_mfma_f32_32x32x16_bf16 v[18:33], v[138:141], v[134:137], v[18:33]
	s_waitcnt lgkmcnt(0)
	v_mfma_f32_32x32x16_bf16 v[34:49], v[142:145], v[130:133], v[34:49]
	v_mfma_f32_32x32x16_bf16 v[2:17], v[142:145], v[134:137], v[2:17]
	ds_read_b128 v[130:133], v227 offset:96
	ds_read_b128 v[134:137], v227 offset:4704
	ds_read_b128 v[138:141], v228 offset:18528
	ds_read_b128 v[142:145], v228 offset:23136
	s_waitcnt lgkmcnt(1)
	v_mfma_f32_32x32x16_bf16 v[114:129], v[138:141], v[130:133], v[114:129]
	v_mfma_f32_32x32x16_bf16 v[82:97], v[138:141], v[134:137], v[82:97]
	s_waitcnt lgkmcnt(0)
	v_mfma_f32_32x32x16_bf16 v[98:113], v[142:145], v[130:133], v[98:113]
	v_mfma_f32_32x32x16_bf16 v[66:81], v[142:145], v[134:137], v[66:81]
	ds_read_b128 v[138:141], v228 offset:27744
	ds_read_b128 v[142:145], v228 offset:32352
	s_waitcnt lgkmcnt(0)
	s_setprio 0
	s_barrier
	v_mfma_f32_32x32x16_bf16 v[50:65], v[138:141], v[130:133], v[50:65]
	v_mfma_f32_32x32x16_bf16 v[34:49], v[142:145], v[130:133], v[34:49]
	v_ashrrev_i32_e32 v132, 11, v166
	v_add_u32_e32 v0, s8, v132
	v_mov_b64_e32 v[130:131], s[46:47]
	v_mfma_f32_32x32x16_bf16 v[18:33], v[138:141], v[134:137], v[18:33]
	v_or_b32_e32 v138, s3, v197
	v_mad_i64_i32 v[130:131], s[2:3], v0, s20, v[130:131]
	s_mov_b64 s[2:3], 0xc902000
	v_ashrrev_i32_e32 v139, 31, v138
	v_lshl_add_u64 v[140:141], v[130:131], 0, s[2:3]
	v_lshlrev_b32_e32 v0, 2, v186
	v_mfma_f32_32x32x16_bf16 v[2:17], v[142:145], v[134:137], v[2:17]
	v_lshlrev_b64 v[144:145], 2, v[138:139]
	v_lshl_add_u64 v[130:131], v[140:141], 0, v[144:145]
	v_lshl_add_u64 v[130:131], v[130:131], 0, v[0:1]
	global_load_dwordx4 v[134:137], v[130:131], off
	v_lshlrev_b32_e32 v130, 10, v132
	v_ashrrev_i32_e32 v131, 31, v130
	v_lshl_add_u64 v[130:131], v[130:131], 2, s[36:37]
	v_lshl_add_u64 v[130:131], v[130:131], 0, v[144:145]
	v_lshl_add_u64 v[142:143], v[130:131], 0, v[0:1]
	global_load_dwordx4 v[130:133], v[142:143], off
	ds_write_b128 v199, v[114:117]
	ds_write_b128 v199, v[118:121] offset:32
	ds_write_b128 v199, v[122:125] offset:64
	ds_write_b128 v199, v[126:129] offset:96
	ds_write_b128 v199, v[98:101] offset:128
	ds_write_b128 v199, v[102:105] offset:160
	ds_write_b128 v199, v[106:109] offset:192
	ds_write_b128 v199, v[110:113] offset:224
	v_lshl_add_u64 v[170:171], v[188:189], 0, v[144:145]
	v_lshlrev_b64 v[98:99], 12, v[168:169]
	v_lshl_add_u64 v[144:145], v[170:171], 0, v[98:99]
	v_or_b32_e32 v98, 4, v168
	v_ashrrev_i32_e32 v99, 31, v98
	v_lshlrev_b64 v[98:99], 12, v[98:99]
	v_lshl_add_u64 v[146:147], v[170:171], 0, v[98:99]
	v_or_b32_e32 v98, 8, v168
	v_ashrrev_i32_e32 v99, 31, v98
	v_lshlrev_b64 v[98:99], 12, v[98:99]
	v_lshl_add_u64 v[148:149], v[170:171], 0, v[98:99]
	v_or_b32_e32 v98, 12, v168
	v_ashrrev_i32_e32 v99, 31, v98
	v_lshlrev_b64 v[98:99], 12, v[98:99]
	v_lshl_add_u64 v[152:153], v[170:171], 0, v[98:99]
	v_or_b32_e32 v98, 16, v168
	v_ashrrev_i32_e32 v99, 31, v98
	v_lshlrev_b64 v[98:99], 12, v[98:99]
	v_lshl_add_u64 v[156:157], v[170:171], 0, v[98:99]
	v_or_b32_e32 v98, 20, v168
	v_ashrrev_i32_e32 v99, 31, v98
	v_lshlrev_b64 v[98:99], 12, v[98:99]
	v_lshl_add_u64 v[158:159], v[170:171], 0, v[98:99]
	v_or_b32_e32 v98, 24, v168
	v_ashrrev_i32_e32 v99, 31, v98
	v_lshlrev_b64 v[98:99], 12, v[98:99]
	v_lshl_add_u64 v[160:161], v[170:171], 0, v[98:99]
	v_or_b32_e32 v98, 28, v168
	v_ashrrev_i32_e32 v99, 31, v98
	v_lshlrev_b64 v[98:99], 12, v[98:99]
	global_load_dwordx4 v[126:129], v[144:145], off
	global_load_dwordx4 v[122:125], v[146:147], off
	v_lshl_add_u64 v[162:163], v[170:171], 0, v[98:99]
	global_load_dwordx4 v[118:121], v[148:149], off
	global_load_dwordx4 v[114:117], v[152:153], off
	global_load_dwordx4 v[110:113], v[156:157], off
	global_load_dwordx4 v[106:109], v[158:159], off
	global_load_dwordx4 v[102:105], v[160:161], off
	global_load_dwordx4 v[98:101], v[162:163], off
	ds_read_b128 v[172:175], v229
	v_or_b32_e32 v164, v138, v186
	v_mov_b32_e32 v165, v139
	v_lshl_add_u64 v[154:155], v[150:151], 0, v[164:165]
	s_mov_b64 s[2:3], -1
	s_waitcnt vmcnt(7) lgkmcnt(0)
	v_pk_fma_f32 v[128:129], v[136:137], v[174:175], v[128:129]
	v_pk_fma_f32 v[126:127], v[134:135], v[172:173], v[126:127]
	v_lshl_add_u64 v[172:173], v[154:155], 2, s[44:45]
	global_store_dwordx4 v[172:173], v[126:129], off
	s_cbranch_vccnz .LBB0_1006
	s_mov_b64 s[2:3], 0

.LBB0_1197:
	s_waitcnt vmcnt(0)
	s_waitcnt lgkmcnt(0)
	s_setprio 0
	s_barrier
	s_mov_b64 s[18:19], exec
	v_readlane_b32 s2, v243, 1
	v_readlane_b32 s3, v243, 2
	s_and_b64 s[2:3], s[18:19], s[2:3]
	s_mov_b64 exec, s[2:3]
	s_cbranch_execnz .LBB0_1198
	s_getpc_b64 s[98:99]
